# norm phases: non-temporal (nt) hint on the streaming f32 row loads
# baseline (speedup 1.0000x reference)
; __device__ __forceinline__ int obid() { int b = blockIdx.x; asm volatile("" : "+s"(b)); return b; }
; __device__ __forceinline__ int otid() { int t = threadIdx.x; asm volatile("" : "+v"(t)); return t; }
; #define PN_LOAD(dst, rw) do { const float* s_ = (rw) < NLAT ? hlat + (size_t)(rw) * 1024 : hctx + (size_t)((rw) - NLAT) * 1024; \
;         _Pragma("unroll") for (int i = 0; i < 4; ++i) dst[i] = *(const float4*)(s_ + i * 256 + lane * 4); } while (0)
; __device__ __forceinline__ void p_norm(const float* hlat, const float* hctx, const float* g, const float* modl, int sh_off, int sc_off, bf16_t* A, int M,
;                                        const float* part, const float* cgate, float* hcout) {
;     const int tid = otid(), lane = tid & 63, wave = tid >> 6;
;     const int stride = gridDim.x * 8;
;     int row = obid() * 8 + wave;
;     float4 v[4], nv[4];
;     ...
;     if (row < M) PN_LOAD(v, row);
;     while (row < M) {
;         const int nrow = row + stride;
;         if (nrow < M) PN_LOAD(nv, nrow);
;         const int r = row < NLAT ? (row >> 11) : 16;
;         float ss = 0.f;
; #pragma unroll
;         for (int i = 0; i < 4; ++i) {
;             if (part != nullptr && row >= NLAT) {
;                 const size_t po = (size_t)(row - NLAT) * 1024 + i * 256 + lane * 4;
;                 const float4 p0 = *(const float4*)(part + po), p1 = *(const float4*)(part + (size_t)4096 * 1024 + po), cg = *(const float4*)(cgate + i * 256 + lane * 4);
;                 v[i].x += cg.x * (p0.x + p1.x); v[i].y += cg.y * (p0.y + p1.y); v[i].z += cg.z * (p0.z + p1.z); v[i].w += cg.w * (p0.w + p1.w);
;                 *(float4*)(hcout + po) = v[i];
;             }
;             ss += v[i].x * v[i].x + v[i].y * v[i].y + v[i].z * v[i].z + v[i].w * v[i].w; }
;         ss = wave_sum(ss);
;         const float rstd = rsqrtf(ss * (1.0f / 1024.0f) + EPS);
.LBB0_406:
	s_load_dwordx2 s[6:7], s[16:17], 0x0
	s_mul_hi_u32 s5, s8, 0x66000
	s_mov_b32 s9, s55
	v_mov_b32_e32 v14, v253
	s_waitcnt lgkmcnt(0)
	v_writelane_b32 v255, s6, 41
	v_ashrrev_i32_e32 v1, 6, v14
	s_nop 0
	v_writelane_b32 v255, s7, 42
	s_mul_i32 s6, s8, 0x66000
	s_add_u32 s6, s56, s6
	s_addc_u32 s7, s57, s5
	v_writelane_b32 v255, s6, 43
	s_mov_b32 s5, s63
	s_lshl_b32 s5, s5, 3
	v_writelane_b32 v255, s7, 44
	v_writelane_b32 v255, s8, 45
	s_lshl_b32 s6, s8, 10
	s_mov_b32 s7, s55
	v_writelane_b32 v255, s9, 46
	v_writelane_b32 v255, s6, 47
	v_add_u32_e32 v50, s5, v1
	s_waitcnt vmcnt(0) lgkmcnt(0)
	v_readlane_b32 s100, v255, 45
	s_load_dwordx2 s[48:49], s[0:1], 0x30
	s_cmp_eq_u32 s100, 0
	s_cselect_b32 s101, 0, 0xe8
	s_load_dwordx2 s[46:47], s[0:1], s101
	s_load_dwordx2 s[16:17], s[0:1], 0x10
	s_mul_i32 s101, s100, 0x66000
	s_add_u32 s50, s56, s101
	s_addc_u32 s51, s57, 0
	s_sub_u32 s20, s101, 0x66000
	s_cmp_eq_u32 s100, 0
	s_cselect_b32 s20, 0, s20
	s_add_u32 s20, s20, 0x65000
	s_add_u32 s20, s56, s20
	s_addc_u32 s21, s57, 0
	s_add_u32 s98, s50, 0x1000
	s_addc_u32 s99, s51, 0
	s_lshl_b32 s101, s100, 12
	v_and_b32_e32 v240, 63, v253
	v_lshlrev_b32_e32 v241, 4, v240
	v_lshrrev_b32_e32 v148, 7, v50
	v_lshlrev_b32_e32 v146, 4, v50
	v_lshl_add_u32 v144, v146, 12, v241
	v_lshlrev_b32_e32 v146, 11, v146
	v_lshl_add_u32 v146, v240, 3, v146
	v_mul_u32_u24_e32 v148, 0x6000, v148
	v_add_u32_e32 v148, v148, v241
	s_waitcnt lgkmcnt(0)
	s_add_u32 s48, s48, s101
	s_addc_u32 s49, s49, 0
	s_cmp_eq_u32 s100, 0
	s_cselect_b32 s16, s16, s64
	s_cselect_b32 s17, s17, s65
	s_cmp_eq_u32 s100, 0
	s_cbranch_scc1 .Lnorm_P1_alt
	global_load_dwordx4 v[80:83], v144, s[46:47] nt
	global_load_dwordx4 v[84:87], v144, s[46:47] offset:1024 nt
	global_load_dwordx4 v[88:91], v144, s[46:47] offset:2048 nt
	global_load_dwordx4 v[92:95], v144, s[46:47] offset:3072 nt
	v_add_u32_e32 v144, 0x1000, v144
	global_load_dwordx4 v[34:37], v148, s[98:99]
	global_load_dwordx4 v[38:41], v148, s[98:99] offset:1024
	global_load_dwordx4 v[42:45], v148, s[98:99] offset:2048
	global_load_dwordx4 v[46:49], v148, s[98:99] offset:3072
	global_load_dwordx4 v[224:227], v148, s[50:51]
	global_load_dwordx4 v[228:231], v148, s[50:51] offset:1024
	global_load_dwordx4 v[232:235], v148, s[50:51] offset:2048
	global_load_dwordx4 v[236:239], v148, s[50:51] offset:3072
	global_load_dwordx4 v[188:191], v241, s[48:49]
	global_load_dwordx4 v[192:195], v241, s[48:49] offset:1024
	global_load_dwordx4 v[196:199], v241, s[48:49] offset:2048
	global_load_dwordx4 v[200:203], v241, s[48:49] offset:3072
	global_load_dwordx4 v[96:99], v144, s[46:47] nt
	global_load_dwordx4 v[100:103], v144, s[46:47] offset:1024 nt
	global_load_dwordx4 v[104:107], v144, s[46:47] offset:2048 nt
	global_load_dwordx4 v[108:111], v144, s[46:47] offset:3072 nt
	v_add_u32_e32 v144, 0x1000, v144
	global_load_dwordx4 v[112:115], v144, s[46:47] nt
	global_load_dwordx4 v[116:119], v144, s[46:47] offset:1024 nt
	global_load_dwordx4 v[120:123], v144, s[46:47] offset:2048 nt
	global_load_dwordx4 v[124:127], v144, s[46:47] offset:3072 nt
	v_add_u32_e32 v144, 0x1000, v144
	global_load_dwordx4 v[128:131], v144, s[46:47] nt
	global_load_dwordx4 v[132:135], v144, s[46:47] offset:1024 nt
	global_load_dwordx4 v[136:139], v144, s[46:47] offset:2048 nt
	global_load_dwordx4 v[140:143], v144, s[46:47] offset:3072 nt
	v_add_u32_e32 v144, 0x1000, v144
	global_load_dwordx4 v[156:159], v144, s[46:47] nt
	global_load_dwordx4 v[160:163], v144, s[46:47] offset:1024 nt
	global_load_dwordx4 v[164:167], v144, s[46:47] offset:2048 nt
	global_load_dwordx4 v[168:171], v144, s[46:47] offset:3072 nt
	v_add_u32_e32 v144, 0x1000, v144
	global_load_dwordx4 v[172:175], v144, s[46:47] nt
	global_load_dwordx4 v[176:179], v144, s[46:47] offset:1024 nt
	global_load_dwordx4 v[180:183], v144, s[46:47] offset:2048 nt
	global_load_dwordx4 v[184:187], v144, s[46:47] offset:3072 nt
	v_add_u32_e32 v144, 0x1000, v144
	s_waitcnt vmcnt(32)
	v_pk_mul_f32 v[242:243], v[80:81], v[80:81]
	v_pk_mul_f32 v[244:245], v[84:85], v[84:85]
	v_pk_mul_f32 v[246:247], v[82:83], v[82:83]
	v_pk_mul_f32 v[248:249], v[86:87], v[86:87]
	v_add_f32_e32 v204, v245, v244
	v_add_f32_e32 v205, v243, v242
	v_add_f32_e32 v204, v248, v204
	v_add_f32_e32 v205, v246, v205
	v_add_f32_e32 v204, v249, v204
	v_add_f32_e32 v205, v247, v205
	v_pk_mul_f32 v[242:243], v[88:89], v[88:89]
	v_pk_mul_f32 v[244:245], v[92:93], v[92:93]
	v_pk_mul_f32 v[246:247], v[90:91], v[90:91]
	v_pk_mul_f32 v[248:249], v[94:95], v[94:95]
	v_add_f32_e32 v206, v243, v242
	v_add_f32_e32 v207, v245, v244
	v_add_f32_e32 v206, v246, v206
	v_add_f32_e32 v207, v248, v207
	v_add_f32_e32 v206, v247, v206
	v_add_f32_e32 v207, v249, v207
	v_add_f32_e32 v204, v205, v204
	v_add_f32_e32 v204, v204, v206
	v_add_f32_e32 v204, v204, v207
	ds_swizzle_b32 v205, v204 offset:swizzle(SWAP,1)
	s_waitcnt lgkmcnt(0)
	v_add_f32_e32 v204, v204, v205
	ds_swizzle_b32 v205, v204 offset:swizzle(SWAP,2)
	s_waitcnt lgkmcnt(0)
	v_add_f32_e32 v204, v204, v205
	ds_swizzle_b32 v205, v204 offset:swizzle(SWAP,4)
	s_waitcnt lgkmcnt(0)
	v_add_f32_e32 v204, v204, v205
	ds_swizzle_b32 v205, v204 offset:swizzle(SWAP,8)
	s_waitcnt lgkmcnt(0)
	v_add_f32_e32 v204, v204, v205
	ds_swizzle_b32 v205, v204 offset:swizzle(SWAP,16)
	s_waitcnt lgkmcnt(0)
	v_add_f32_e32 v204, v204, v205
	v_mov_b32_e32 v205, v204
	s_nop 1
	v_permlane32_swap_b32_e32 v204, v205
	v_add_f32_e32 v204, v204, v205
	v_mov_b32_e32 v205, 0x358637bd
	v_fmamk_f32 v204, v204, 0x3a800000, v205
	v_rsq_f32_e32 v204, v204
	s_nop 0
	s_waitcnt vmcnt(20)
; __device__ __forceinline__ unsigned pk2(float lo, float hi) { const g_f32x2 f = {lo, hi}; return __builtin_bit_cast(unsigned, __builtin_convertvector(f, g_bf16x2)); }
; __device__ __forceinline__ void p_norm(const float* hlat, const float* hctx, const float* g, const float* modl, int sh_off, int sc_off, bf16_t* A, int M,
;                                        const float* part, const float* cgate, float* hcout) {
;     ...
;         float ss = 0.f;
; #pragma unroll
;         for (int i = 0; i < 4; ++i) {
;             if (part != nullptr && row >= NLAT) {
;                 const size_t po = (size_t)(row - NLAT) * 1024 + i * 256 + lane * 4;
;                 const float4 p0 = *(const float4*)(part + po), p1 = *(const float4*)(part + (size_t)4096 * 1024 + po), cg = *(const float4*)(cgate + i * 256 + lane * 4);
;                 v[i].x += cg.x * (p0.x + p1.x); v[i].y += cg.y * (p0.y + p1.y); v[i].z += cg.z * (p0.z + p1.z); v[i].w += cg.w * (p0.w + p1.w);
;                 *(float4*)(hcout + po) = v[i];
;             }
;             ss += v[i].x * v[i].x + v[i].y * v[i].y + v[i].z * v[i].z + v[i].w * v[i].w; }
;         ss = wave_sum(ss);
;         const float rstd = rsqrtf(ss * (1.0f / 1024.0f) + EPS);
;         const float* mr = modl + (size_t)r * 6144;
; #pragma unroll
;         for (int i = 0; i < 4; ++i) {
;             const int k = i * 256 + lane * 4;
;             const float4 gg = *(const float4*)(g + k), scv = *(const float4*)(mr + sc_off + k), shv = *(const float4*)(mr + sh_off + k);
;             const float o0 = v[i].x * rstd * gg.x * (1.0f + scv.x) + shv.x, o1 = v[i].y * rstd * gg.y * (1.0f + scv.y) + shv.y;
;             const float o2 = v[i].z * rstd * gg.z * (1.0f + scv.z) + shv.z, o3 = v[i].w * rstd * gg.w * (1.0f + scv.w) + shv.w;
;             uint2 w; w.x = pk2(o0, o1); w.y = pk2(o2, o3);
;             *(uint2*)(A + (size_t)row * 1024 + k) = w;
;         }
; #pragma unroll
;         for (int i = 0; i < 4; ++i) v[i] = nv[i];
;         row = nrow;
	v_pk_add_f32 v[34:35], v[34:35], 1.0 op_sel_hi:[1,0]
	v_pk_add_f32 v[36:37], v[36:37], 1.0 op_sel_hi:[1,0]
	v_pk_add_f32 v[38:39], v[38:39], 1.0 op_sel_hi:[1,0]
	v_pk_add_f32 v[40:41], v[40:41], 1.0 op_sel_hi:[1,0]
	v_pk_add_f32 v[42:43], v[42:43], 1.0 op_sel_hi:[1,0]
	v_pk_add_f32 v[44:45], v[44:45], 1.0 op_sel_hi:[1,0]
	v_pk_add_f32 v[46:47], v[46:47], 1.0 op_sel_hi:[1,0]
	v_pk_add_f32 v[48:49], v[48:49], 1.0 op_sel_hi:[1,0]
	v_pk_mul_f32 v[80:81], v[80:81], v[204:205] op_sel_hi:[1,0]
	v_pk_mul_f32 v[82:83], v[82:83], v[204:205] op_sel_hi:[1,0]
	v_pk_mul_f32 v[80:81], v[188:189], v[80:81]
	v_pk_mul_f32 v[82:83], v[190:191], v[82:83]
	v_pk_fma_f32 v[80:81], v[34:35], v[80:81], v[224:225]
	v_pk_fma_f32 v[82:83], v[36:37], v[82:83], v[226:227]
	v_cvt_pk_bf16_f32 v80, v80, v81
	v_cvt_pk_bf16_f32 v81, v82, v83
	global_store_dwordx2 v146, v[80:81], s[66:67]
	v_pk_mul_f32 v[84:85], v[84:85], v[204:205] op_sel_hi:[1,0]
	v_pk_mul_f32 v[86:87], v[86:87], v[204:205] op_sel_hi:[1,0]
	v_pk_mul_f32 v[84:85], v[192:193], v[84:85]
	v_pk_mul_f32 v[86:87], v[194:195], v[86:87]
	v_pk_fma_f32 v[84:85], v[38:39], v[84:85], v[228:229]
	v_pk_fma_f32 v[86:87], v[40:41], v[86:87], v[230:231]
	v_cvt_pk_bf16_f32 v84, v84, v85
	v_cvt_pk_bf16_f32 v85, v86, v87
	global_store_dwordx2 v146, v[84:85], s[66:67] offset:512
	v_pk_mul_f32 v[88:89], v[88:89], v[204:205] op_sel_hi:[1,0]
	v_pk_mul_f32 v[90:91], v[90:91], v[204:205] op_sel_hi:[1,0]
	v_pk_mul_f32 v[88:89], v[196:197], v[88:89]
	v_pk_mul_f32 v[90:91], v[198:199], v[90:91]
	v_pk_fma_f32 v[88:89], v[42:43], v[88:89], v[232:233]
	v_pk_fma_f32 v[90:91], v[44:45], v[90:91], v[234:235]
	v_cvt_pk_bf16_f32 v88, v88, v89
	v_cvt_pk_bf16_f32 v89, v90, v91
	global_store_dwordx2 v146, v[88:89], s[66:67] offset:1024
	v_pk_mul_f32 v[92:93], v[92:93], v[204:205] op_sel_hi:[1,0]
	v_pk_mul_f32 v[94:95], v[94:95], v[204:205] op_sel_hi:[1,0]
	v_pk_mul_f32 v[92:93], v[200:201], v[92:93]
	v_pk_mul_f32 v[94:95], v[202:203], v[94:95]
	v_pk_fma_f32 v[92:93], v[46:47], v[92:93], v[236:237]
	v_pk_fma_f32 v[94:95], v[48:49], v[94:95], v[238:239]
	v_cvt_pk_bf16_f32 v92, v92, v93
	v_cvt_pk_bf16_f32 v93, v94, v95
	global_store_dwordx2 v146, v[92:93], s[66:67] offset:1536
	v_add_u32_e32 v146, 0x800, v146
	global_load_dwordx4 v[80:83], v144, s[46:47] nt
	global_load_dwordx4 v[84:87], v144, s[46:47] offset:1024 nt
	global_load_dwordx4 v[88:91], v144, s[46:47] offset:2048 nt
	global_load_dwordx4 v[92:95], v144, s[46:47] offset:3072 nt
	v_add_u32_e32 v144, 0x1000, v144
	s_waitcnt vmcnt(24)
	v_pk_mul_f32 v[242:243], v[96:97], v[96:97]
	v_pk_mul_f32 v[244:245], v[100:101], v[100:101]
	v_pk_mul_f32 v[246:247], v[98:99], v[98:99]
	v_pk_mul_f32 v[248:249], v[102:103], v[102:103]
	v_add_f32_e32 v204, v245, v244
	v_add_f32_e32 v205, v243, v242
	v_add_f32_e32 v204, v248, v204
	v_add_f32_e32 v205, v246, v205
	v_add_f32_e32 v204, v249, v204
	v_add_f32_e32 v205, v247, v205
	v_pk_mul_f32 v[242:243], v[104:105], v[104:105]
	v_pk_mul_f32 v[244:245], v[108:109], v[108:109]
	v_pk_mul_f32 v[246:247], v[106:107], v[106:107]
	v_pk_mul_f32 v[248:249], v[110:111], v[110:111]
	v_add_f32_e32 v206, v243, v242
	v_add_f32_e32 v207, v245, v244
	v_add_f32_e32 v206, v246, v206
	v_add_f32_e32 v207, v248, v207
	v_add_f32_e32 v206, v247, v206
	v_add_f32_e32 v207, v249, v207
	v_add_f32_e32 v204, v205, v204
	v_add_f32_e32 v204, v204, v206
	v_add_f32_e32 v204, v204, v207
	ds_swizzle_b32 v205, v204 offset:swizzle(SWAP,1)
	s_waitcnt lgkmcnt(0)
	v_add_f32_e32 v204, v204, v205
	ds_swizzle_b32 v205, v204 offset:swizzle(SWAP,2)
	s_waitcnt lgkmcnt(0)
	v_add_f32_e32 v204, v204, v205
	ds_swizzle_b32 v205, v204 offset:swizzle(SWAP,4)
	s_waitcnt lgkmcnt(0)
	v_add_f32_e32 v204, v204, v205
	ds_swizzle_b32 v205, v204 offset:swizzle(SWAP,8)
	s_waitcnt lgkmcnt(0)
	v_add_f32_e32 v204, v204, v205
	ds_swizzle_b32 v205, v204 offset:swizzle(SWAP,16)
	s_waitcnt lgkmcnt(0)
	v_add_f32_e32 v204, v204, v205
	v_mov_b32_e32 v205, v204
	s_nop 1
	v_permlane32_swap_b32_e32 v204, v205
	v_add_f32_e32 v204, v204, v205
	v_mov_b32_e32 v205, 0x358637bd
	v_fmamk_f32 v204, v204, 0x3a800000, v205
	v_rsq_f32_e32 v204, v204
	s_nop 0
	v_pk_mul_f32 v[96:97], v[96:97], v[204:205] op_sel_hi:[1,0]
	v_pk_mul_f32 v[98:99], v[98:99], v[204:205] op_sel_hi:[1,0]
	v_pk_mul_f32 v[96:97], v[188:189], v[96:97]
	v_pk_mul_f32 v[98:99], v[190:191], v[98:99]
	v_pk_fma_f32 v[96:97], v[34:35], v[96:97], v[224:225]
	v_pk_fma_f32 v[98:99], v[36:37], v[98:99], v[226:227]
	v_cvt_pk_bf16_f32 v96, v96, v97
	v_cvt_pk_bf16_f32 v97, v98, v99
	global_store_dwordx2 v146, v[96:97], s[66:67]
	v_pk_mul_f32 v[100:101], v[100:101], v[204:205] op_sel_hi:[1,0]
	v_pk_mul_f32 v[102:103], v[102:103], v[204:205] op_sel_hi:[1,0]
	v_pk_mul_f32 v[100:101], v[192:193], v[100:101]
	v_pk_mul_f32 v[102:103], v[194:195], v[102:103]
	v_pk_fma_f32 v[100:101], v[38:39], v[100:101], v[228:229]
	v_pk_fma_f32 v[102:103], v[40:41], v[102:103], v[230:231]
	v_cvt_pk_bf16_f32 v100, v100, v101
	v_cvt_pk_bf16_f32 v101, v102, v103
	global_store_dwordx2 v146, v[100:101], s[66:67] offset:512
	v_pk_mul_f32 v[104:105], v[104:105], v[204:205] op_sel_hi:[1,0]
	v_pk_mul_f32 v[106:107], v[106:107], v[204:205] op_sel_hi:[1,0]
	v_pk_mul_f32 v[104:105], v[196:197], v[104:105]
	v_pk_mul_f32 v[106:107], v[198:199], v[106:107]
	v_pk_fma_f32 v[104:105], v[42:43], v[104:105], v[232:233]
	v_pk_fma_f32 v[106:107], v[44:45], v[106:107], v[234:235]
	v_cvt_pk_bf16_f32 v104, v104, v105
	v_cvt_pk_bf16_f32 v105, v106, v107
	global_store_dwordx2 v146, v[104:105], s[66:67] offset:1024
	v_pk_mul_f32 v[108:109], v[108:109], v[204:205] op_sel_hi:[1,0]
	v_pk_mul_f32 v[110:111], v[110:111], v[204:205] op_sel_hi:[1,0]
	v_pk_mul_f32 v[108:109], v[200:201], v[108:109]
	v_pk_mul_f32 v[110:111], v[202:203], v[110:111]
	v_pk_fma_f32 v[108:109], v[46:47], v[108:109], v[236:237]
	v_pk_fma_f32 v[110:111], v[48:49], v[110:111], v[238:239]
	v_cvt_pk_bf16_f32 v108, v108, v109
	v_cvt_pk_bf16_f32 v109, v110, v111
	global_store_dwordx2 v146, v[108:109], s[66:67] offset:1536
	v_add_u32_e32 v146, 0x800, v146
	global_load_dwordx4 v[96:99], v144, s[46:47] nt
	global_load_dwordx4 v[100:103], v144, s[46:47] offset:1024 nt
	global_load_dwordx4 v[104:107], v144, s[46:47] offset:2048 nt
	global_load_dwordx4 v[108:111], v144, s[46:47] offset:3072 nt
	v_add_u32_e32 v144, 0x1000, v144
	s_waitcnt vmcnt(28)
; __device__ __forceinline__ unsigned pk2(float lo, float hi) { const g_f32x2 f = {lo, hi}; return __builtin_bit_cast(unsigned, __builtin_convertvector(f, g_bf16x2)); }
; __device__ __forceinline__ void p_norm(const float* hlat, const float* hctx, const float* g, const float* modl, int sh_off, int sc_off, bf16_t* A, int M,
;                                        const float* part, const float* cgate, float* hcout) {
;     ...
;         float ss = 0.f;
; #pragma unroll
;         for (int i = 0; i < 4; ++i) {
;             if (part != nullptr && row >= NLAT) {
;                 const size_t po = (size_t)(row - NLAT) * 1024 + i * 256 + lane * 4;
;                 const float4 p0 = *(const float4*)(part + po), p1 = *(const float4*)(part + (size_t)4096 * 1024 + po), cg = *(const float4*)(cgate + i * 256 + lane * 4);
;                 v[i].x += cg.x * (p0.x + p1.x); v[i].y += cg.y * (p0.y + p1.y); v[i].z += cg.z * (p0.z + p1.z); v[i].w += cg.w * (p0.w + p1.w);
;                 *(float4*)(hcout + po) = v[i];
;             }
;             ss += v[i].x * v[i].x + v[i].y * v[i].y + v[i].z * v[i].z + v[i].w * v[i].w; }
;         ss = wave_sum(ss);
;         const float rstd = rsqrtf(ss * (1.0f / 1024.0f) + EPS);
;         const float* mr = modl + (size_t)r * 6144;
; #pragma unroll
;         for (int i = 0; i < 4; ++i) {
;             const int k = i * 256 + lane * 4;
;             const float4 gg = *(const float4*)(g + k), scv = *(const float4*)(mr + sc_off + k), shv = *(const float4*)(mr + sh_off + k);
;             const float o0 = v[i].x * rstd * gg.x * (1.0f + scv.x) + shv.x, o1 = v[i].y * rstd * gg.y * (1.0f + scv.y) + shv.y;
;             const float o2 = v[i].z * rstd * gg.z * (1.0f + scv.z) + shv.z, o3 = v[i].w * rstd * gg.w * (1.0f + scv.w) + shv.w;
;             uint2 w; w.x = pk2(o0, o1); w.y = pk2(o2, o3);
;             *(uint2*)(A + (size_t)row * 1024 + k) = w;
;         }
; #pragma unroll
;         for (int i = 0; i < 4; ++i) v[i] = nv[i];
;         row = nrow;
	v_pk_mul_f32 v[242:243], v[112:113], v[112:113]
	v_pk_mul_f32 v[244:245], v[116:117], v[116:117]
	v_pk_mul_f32 v[246:247], v[114:115], v[114:115]
	v_pk_mul_f32 v[248:249], v[118:119], v[118:119]
	v_add_f32_e32 v204, v245, v244
	v_add_f32_e32 v205, v243, v242
	v_add_f32_e32 v204, v248, v204
	v_add_f32_e32 v205, v246, v205
	v_add_f32_e32 v204, v249, v204
	v_add_f32_e32 v205, v247, v205
	v_pk_mul_f32 v[242:243], v[120:121], v[120:121]
	v_pk_mul_f32 v[244:245], v[124:125], v[124:125]
	v_pk_mul_f32 v[246:247], v[122:123], v[122:123]
	v_pk_mul_f32 v[248:249], v[126:127], v[126:127]
	v_add_f32_e32 v206, v243, v242
	v_add_f32_e32 v207, v245, v244
	v_add_f32_e32 v206, v246, v206
	v_add_f32_e32 v207, v248, v207
	v_add_f32_e32 v206, v247, v206
	v_add_f32_e32 v207, v249, v207
	v_add_f32_e32 v204, v205, v204
	v_add_f32_e32 v204, v204, v206
	v_add_f32_e32 v204, v204, v207
	ds_swizzle_b32 v205, v204 offset:swizzle(SWAP,1)
	s_waitcnt lgkmcnt(0)
	v_add_f32_e32 v204, v204, v205
	ds_swizzle_b32 v205, v204 offset:swizzle(SWAP,2)
	s_waitcnt lgkmcnt(0)
	v_add_f32_e32 v204, v204, v205
	ds_swizzle_b32 v205, v204 offset:swizzle(SWAP,4)
	s_waitcnt lgkmcnt(0)
	v_add_f32_e32 v204, v204, v205
	ds_swizzle_b32 v205, v204 offset:swizzle(SWAP,8)
	s_waitcnt lgkmcnt(0)
	v_add_f32_e32 v204, v204, v205
	ds_swizzle_b32 v205, v204 offset:swizzle(SWAP,16)
	s_waitcnt lgkmcnt(0)
	v_add_f32_e32 v204, v204, v205
	v_mov_b32_e32 v205, v204
	s_nop 1
	v_permlane32_swap_b32_e32 v204, v205
	v_add_f32_e32 v204, v204, v205
	v_mov_b32_e32 v205, 0x358637bd
	v_fmamk_f32 v204, v204, 0x3a800000, v205
	v_rsq_f32_e32 v204, v204
	s_nop 0
	v_pk_mul_f32 v[112:113], v[112:113], v[204:205] op_sel_hi:[1,0]
	v_pk_mul_f32 v[114:115], v[114:115], v[204:205] op_sel_hi:[1,0]
	v_pk_mul_f32 v[112:113], v[188:189], v[112:113]
	v_pk_mul_f32 v[114:115], v[190:191], v[114:115]
	v_pk_fma_f32 v[112:113], v[34:35], v[112:113], v[224:225]
	v_pk_fma_f32 v[114:115], v[36:37], v[114:115], v[226:227]
	v_cvt_pk_bf16_f32 v112, v112, v113
	v_cvt_pk_bf16_f32 v113, v114, v115
	global_store_dwordx2 v146, v[112:113], s[66:67]
	v_pk_mul_f32 v[116:117], v[116:117], v[204:205] op_sel_hi:[1,0]
	v_pk_mul_f32 v[118:119], v[118:119], v[204:205] op_sel_hi:[1,0]
	v_pk_mul_f32 v[116:117], v[192:193], v[116:117]
	v_pk_mul_f32 v[118:119], v[194:195], v[118:119]
	v_pk_fma_f32 v[116:117], v[38:39], v[116:117], v[228:229]
	v_pk_fma_f32 v[118:119], v[40:41], v[118:119], v[230:231]
	v_cvt_pk_bf16_f32 v116, v116, v117
	v_cvt_pk_bf16_f32 v117, v118, v119
	global_store_dwordx2 v146, v[116:117], s[66:67] offset:512
	v_pk_mul_f32 v[120:121], v[120:121], v[204:205] op_sel_hi:[1,0]
	v_pk_mul_f32 v[122:123], v[122:123], v[204:205] op_sel_hi:[1,0]
	v_pk_mul_f32 v[120:121], v[196:197], v[120:121]
	v_pk_mul_f32 v[122:123], v[198:199], v[122:123]
	v_pk_fma_f32 v[120:121], v[42:43], v[120:121], v[232:233]
	v_pk_fma_f32 v[122:123], v[44:45], v[122:123], v[234:235]
	v_cvt_pk_bf16_f32 v120, v120, v121
	v_cvt_pk_bf16_f32 v121, v122, v123
	global_store_dwordx2 v146, v[120:121], s[66:67] offset:1024
	v_pk_mul_f32 v[124:125], v[124:125], v[204:205] op_sel_hi:[1,0]
	v_pk_mul_f32 v[126:127], v[126:127], v[204:205] op_sel_hi:[1,0]
	v_pk_mul_f32 v[124:125], v[200:201], v[124:125]
	v_pk_mul_f32 v[126:127], v[202:203], v[126:127]
	v_pk_fma_f32 v[124:125], v[46:47], v[124:125], v[236:237]
	v_pk_fma_f32 v[126:127], v[48:49], v[126:127], v[238:239]
	v_cvt_pk_bf16_f32 v124, v124, v125
	v_cvt_pk_bf16_f32 v125, v126, v127
	global_store_dwordx2 v146, v[124:125], s[66:67] offset:1536
	v_add_u32_e32 v146, 0x800, v146
	global_load_dwordx4 v[112:115], v144, s[46:47] nt
	global_load_dwordx4 v[116:119], v144, s[46:47] offset:1024 nt
	global_load_dwordx4 v[120:123], v144, s[46:47] offset:2048 nt
	global_load_dwordx4 v[124:127], v144, s[46:47] offset:3072 nt
	v_add_u32_e32 v144, 0x1000, v144
	s_waitcnt vmcnt(32)
	v_pk_mul_f32 v[242:243], v[128:129], v[128:129]
	v_pk_mul_f32 v[244:245], v[132:133], v[132:133]
	v_pk_mul_f32 v[246:247], v[130:131], v[130:131]
	v_pk_mul_f32 v[248:249], v[134:135], v[134:135]
	v_add_f32_e32 v204, v245, v244
	v_add_f32_e32 v205, v243, v242
	v_add_f32_e32 v204, v248, v204
	v_add_f32_e32 v205, v246, v205
	v_add_f32_e32 v204, v249, v204
	v_add_f32_e32 v205, v247, v205
	v_pk_mul_f32 v[242:243], v[136:137], v[136:137]
	v_pk_mul_f32 v[244:245], v[140:141], v[140:141]
	v_pk_mul_f32 v[246:247], v[138:139], v[138:139]
	v_pk_mul_f32 v[248:249], v[142:143], v[142:143]
	v_add_f32_e32 v206, v243, v242
	v_add_f32_e32 v207, v245, v244
	v_add_f32_e32 v206, v246, v206
	v_add_f32_e32 v207, v248, v207
	v_add_f32_e32 v206, v247, v206
	v_add_f32_e32 v207, v249, v207
	v_add_f32_e32 v204, v205, v204
	v_add_f32_e32 v204, v204, v206
	v_add_f32_e32 v204, v204, v207
	ds_swizzle_b32 v205, v204 offset:swizzle(SWAP,1)
	s_waitcnt lgkmcnt(0)
	v_add_f32_e32 v204, v204, v205
	ds_swizzle_b32 v205, v204 offset:swizzle(SWAP,2)
	s_waitcnt lgkmcnt(0)
	v_add_f32_e32 v204, v204, v205
	ds_swizzle_b32 v205, v204 offset:swizzle(SWAP,4)
	s_waitcnt lgkmcnt(0)
	v_add_f32_e32 v204, v204, v205
	ds_swizzle_b32 v205, v204 offset:swizzle(SWAP,8)
	s_waitcnt lgkmcnt(0)
	v_add_f32_e32 v204, v204, v205
	ds_swizzle_b32 v205, v204 offset:swizzle(SWAP,16)
	s_waitcnt lgkmcnt(0)
; __device__ __forceinline__ unsigned pk2(float lo, float hi) { const g_f32x2 f = {lo, hi}; return __builtin_bit_cast(unsigned, __builtin_convertvector(f, g_bf16x2)); }
; __device__ __forceinline__ void p_norm(const float* hlat, const float* hctx, const float* g, const float* modl, int sh_off, int sc_off, bf16_t* A, int M,
;                                        const float* part, const float* cgate, float* hcout) {
;     ...
;         float ss = 0.f;
; #pragma unroll
;         for (int i = 0; i < 4; ++i) {
;             if (part != nullptr && row >= NLAT) {
;                 const size_t po = (size_t)(row - NLAT) * 1024 + i * 256 + lane * 4;
;                 const float4 p0 = *(const float4*)(part + po), p1 = *(const float4*)(part + (size_t)4096 * 1024 + po), cg = *(const float4*)(cgate + i * 256 + lane * 4);
;                 v[i].x += cg.x * (p0.x + p1.x); v[i].y += cg.y * (p0.y + p1.y); v[i].z += cg.z * (p0.z + p1.z); v[i].w += cg.w * (p0.w + p1.w);
;                 *(float4*)(hcout + po) = v[i];
;             }
;             ss += v[i].x * v[i].x + v[i].y * v[i].y + v[i].z * v[i].z + v[i].w * v[i].w; }
;         ss = wave_sum(ss);
;         const float rstd = rsqrtf(ss * (1.0f / 1024.0f) + EPS);
;         const float* mr = modl + (size_t)r * 6144;
; #pragma unroll
;         for (int i = 0; i < 4; ++i) {
;             const int k = i * 256 + lane * 4;
;             const float4 gg = *(const float4*)(g + k), scv = *(const float4*)(mr + sc_off + k), shv = *(const float4*)(mr + sh_off + k);
;             const float o0 = v[i].x * rstd * gg.x * (1.0f + scv.x) + shv.x, o1 = v[i].y * rstd * gg.y * (1.0f + scv.y) + shv.y;
;             const float o2 = v[i].z * rstd * gg.z * (1.0f + scv.z) + shv.z, o3 = v[i].w * rstd * gg.w * (1.0f + scv.w) + shv.w;
;             uint2 w; w.x = pk2(o0, o1); w.y = pk2(o2, o3);
;             *(uint2*)(A + (size_t)row * 1024 + k) = w;
;         }
; #pragma unroll
;         for (int i = 0; i < 4; ++i) v[i] = nv[i];
;         row = nrow;
	v_add_f32_e32 v204, v204, v205
	v_mov_b32_e32 v205, v204
	s_nop 1
	v_permlane32_swap_b32_e32 v204, v205
	v_add_f32_e32 v204, v204, v205
	v_mov_b32_e32 v205, 0x358637bd
	v_fmamk_f32 v204, v204, 0x3a800000, v205
	v_rsq_f32_e32 v204, v204
	s_nop 0
	v_pk_mul_f32 v[128:129], v[128:129], v[204:205] op_sel_hi:[1,0]
	v_pk_mul_f32 v[130:131], v[130:131], v[204:205] op_sel_hi:[1,0]
	v_pk_mul_f32 v[128:129], v[188:189], v[128:129]
	v_pk_mul_f32 v[130:131], v[190:191], v[130:131]
	v_pk_fma_f32 v[128:129], v[34:35], v[128:129], v[224:225]
	v_pk_fma_f32 v[130:131], v[36:37], v[130:131], v[226:227]
	v_cvt_pk_bf16_f32 v128, v128, v129
	v_cvt_pk_bf16_f32 v129, v130, v131
	global_store_dwordx2 v146, v[128:129], s[66:67]
	v_pk_mul_f32 v[132:133], v[132:133], v[204:205] op_sel_hi:[1,0]
	v_pk_mul_f32 v[134:135], v[134:135], v[204:205] op_sel_hi:[1,0]
	v_pk_mul_f32 v[132:133], v[192:193], v[132:133]
	v_pk_mul_f32 v[134:135], v[194:195], v[134:135]
	v_pk_fma_f32 v[132:133], v[38:39], v[132:133], v[228:229]
	v_pk_fma_f32 v[134:135], v[40:41], v[134:135], v[230:231]
	v_cvt_pk_bf16_f32 v132, v132, v133
	v_cvt_pk_bf16_f32 v133, v134, v135
	global_store_dwordx2 v146, v[132:133], s[66:67] offset:512
	v_pk_mul_f32 v[136:137], v[136:137], v[204:205] op_sel_hi:[1,0]
	v_pk_mul_f32 v[138:139], v[138:139], v[204:205] op_sel_hi:[1,0]
	v_pk_mul_f32 v[136:137], v[196:197], v[136:137]
	v_pk_mul_f32 v[138:139], v[198:199], v[138:139]
	v_pk_fma_f32 v[136:137], v[42:43], v[136:137], v[232:233]
	v_pk_fma_f32 v[138:139], v[44:45], v[138:139], v[234:235]
	v_cvt_pk_bf16_f32 v136, v136, v137
	v_cvt_pk_bf16_f32 v137, v138, v139
	global_store_dwordx2 v146, v[136:137], s[66:67] offset:1024
	v_pk_mul_f32 v[140:141], v[140:141], v[204:205] op_sel_hi:[1,0]
	v_pk_mul_f32 v[142:143], v[142:143], v[204:205] op_sel_hi:[1,0]
	v_pk_mul_f32 v[140:141], v[200:201], v[140:141]
	v_pk_mul_f32 v[142:143], v[202:203], v[142:143]
	v_pk_fma_f32 v[140:141], v[46:47], v[140:141], v[236:237]
	v_pk_fma_f32 v[142:143], v[48:49], v[142:143], v[238:239]
	v_cvt_pk_bf16_f32 v140, v140, v141
	v_cvt_pk_bf16_f32 v141, v142, v143
	global_store_dwordx2 v146, v[140:141], s[66:67] offset:1536
	v_add_u32_e32 v146, 0x800, v146
	global_load_dwordx4 v[128:131], v144, s[46:47] nt
	global_load_dwordx4 v[132:135], v144, s[46:47] offset:1024 nt
	global_load_dwordx4 v[136:139], v144, s[46:47] offset:2048 nt
	global_load_dwordx4 v[140:143], v144, s[46:47] offset:3072 nt
	v_add_u32_e32 v144, 0x1000, v144
	s_waitcnt vmcnt(36)
	v_pk_mul_f32 v[242:243], v[156:157], v[156:157]
	v_pk_mul_f32 v[244:245], v[160:161], v[160:161]
	v_pk_mul_f32 v[246:247], v[158:159], v[158:159]
	v_pk_mul_f32 v[248:249], v[162:163], v[162:163]
	v_add_f32_e32 v204, v245, v244
	v_add_f32_e32 v205, v243, v242
	v_add_f32_e32 v204, v248, v204
	v_add_f32_e32 v205, v246, v205
	v_add_f32_e32 v204, v249, v204
	v_add_f32_e32 v205, v247, v205
	v_pk_mul_f32 v[242:243], v[164:165], v[164:165]
	v_pk_mul_f32 v[244:245], v[168:169], v[168:169]
	v_pk_mul_f32 v[246:247], v[166:167], v[166:167]
	v_pk_mul_f32 v[248:249], v[170:171], v[170:171]
	v_add_f32_e32 v206, v243, v242
	v_add_f32_e32 v207, v245, v244
	v_add_f32_e32 v206, v246, v206
	v_add_f32_e32 v207, v248, v207
	v_add_f32_e32 v206, v247, v206
	v_add_f32_e32 v207, v249, v207
	v_add_f32_e32 v204, v205, v204
	v_add_f32_e32 v204, v204, v206
	v_add_f32_e32 v204, v204, v207
	ds_swizzle_b32 v205, v204 offset:swizzle(SWAP,1)
	s_waitcnt lgkmcnt(0)
	v_add_f32_e32 v204, v204, v205
	ds_swizzle_b32 v205, v204 offset:swizzle(SWAP,2)
	s_waitcnt lgkmcnt(0)
	v_add_f32_e32 v204, v204, v205
	ds_swizzle_b32 v205, v204 offset:swizzle(SWAP,4)
	s_waitcnt lgkmcnt(0)
	v_add_f32_e32 v204, v204, v205
	ds_swizzle_b32 v205, v204 offset:swizzle(SWAP,8)
	s_waitcnt lgkmcnt(0)
	v_add_f32_e32 v204, v204, v205
	ds_swizzle_b32 v205, v204 offset:swizzle(SWAP,16)
	s_waitcnt lgkmcnt(0)
	v_add_f32_e32 v204, v204, v205
	v_mov_b32_e32 v205, v204
	s_nop 1
	v_permlane32_swap_b32_e32 v204, v205
	v_add_f32_e32 v204, v204, v205
	v_mov_b32_e32 v205, 0x358637bd
	v_fmamk_f32 v204, v204, 0x3a800000, v205
	v_rsq_f32_e32 v204, v204
	s_nop 0
	v_pk_mul_f32 v[156:157], v[156:157], v[204:205] op_sel_hi:[1,0]
	v_pk_mul_f32 v[158:159], v[158:159], v[204:205] op_sel_hi:[1,0]
	v_pk_mul_f32 v[156:157], v[188:189], v[156:157]
	v_pk_mul_f32 v[158:159], v[190:191], v[158:159]
	v_pk_fma_f32 v[156:157], v[34:35], v[156:157], v[224:225]
	v_pk_fma_f32 v[158:159], v[36:37], v[158:159], v[226:227]
	v_cvt_pk_bf16_f32 v156, v156, v157
	v_cvt_pk_bf16_f32 v157, v158, v159
	global_store_dwordx2 v146, v[156:157], s[66:67]
	v_pk_mul_f32 v[160:161], v[160:161], v[204:205] op_sel_hi:[1,0]
	v_pk_mul_f32 v[162:163], v[162:163], v[204:205] op_sel_hi:[1,0]
	v_pk_mul_f32 v[160:161], v[192:193], v[160:161]
	v_pk_mul_f32 v[162:163], v[194:195], v[162:163]
	v_pk_fma_f32 v[160:161], v[38:39], v[160:161], v[228:229]
	v_pk_fma_f32 v[162:163], v[40:41], v[162:163], v[230:231]
	v_cvt_pk_bf16_f32 v160, v160, v161
	v_cvt_pk_bf16_f32 v161, v162, v163
	global_store_dwordx2 v146, v[160:161], s[66:67] offset:512
	v_pk_mul_f32 v[164:165], v[164:165], v[204:205] op_sel_hi:[1,0]
	v_pk_mul_f32 v[166:167], v[166:167], v[204:205] op_sel_hi:[1,0]
	v_pk_mul_f32 v[164:165], v[196:197], v[164:165]
	v_pk_mul_f32 v[166:167], v[198:199], v[166:167]
	v_pk_fma_f32 v[164:165], v[42:43], v[164:165], v[232:233]
	v_pk_fma_f32 v[166:167], v[44:45], v[166:167], v[234:235]
	v_cvt_pk_bf16_f32 v164, v164, v165
	v_cvt_pk_bf16_f32 v165, v166, v167
	global_store_dwordx2 v146, v[164:165], s[66:67] offset:1024
	v_pk_mul_f32 v[168:169], v[168:169], v[204:205] op_sel_hi:[1,0]
	v_pk_mul_f32 v[170:171], v[170:171], v[204:205] op_sel_hi:[1,0]
	v_pk_mul_f32 v[168:169], v[200:201], v[168:169]
	v_pk_mul_f32 v[170:171], v[202:203], v[170:171]
	v_pk_fma_f32 v[168:169], v[46:47], v[168:169], v[236:237]
	v_pk_fma_f32 v[170:171], v[48:49], v[170:171], v[238:239]
	v_cvt_pk_bf16_f32 v168, v168, v169
	v_cvt_pk_bf16_f32 v169, v170, v171
	global_store_dwordx2 v146, v[168:169], s[66:67] offset:1536
	v_add_u32_e32 v146, 0x800, v146
	global_load_dwordx4 v[156:159], v144, s[46:47] nt
	global_load_dwordx4 v[160:163], v144, s[46:47] offset:1024 nt
	global_load_dwordx4 v[164:167], v144, s[46:47] offset:2048 nt
	global_load_dwordx4 v[168:171], v144, s[46:47] offset:3072 nt
	v_add_u32_e32 v144, 0x1000, v144
	s_waitcnt vmcnt(40)
; __device__ __forceinline__ unsigned pk2(float lo, float hi) { const g_f32x2 f = {lo, hi}; return __builtin_bit_cast(unsigned, __builtin_convertvector(f, g_bf16x2)); }
; __device__ __forceinline__ void p_norm(const float* hlat, const float* hctx, const float* g, const float* modl, int sh_off, int sc_off, bf16_t* A, int M,
;                                        const float* part, const float* cgate, float* hcout) {
;     ...
;         float ss = 0.f;
; #pragma unroll
;         for (int i = 0; i < 4; ++i) {
;             if (part != nullptr && row >= NLAT) {
;                 const size_t po = (size_t)(row - NLAT) * 1024 + i * 256 + lane * 4;
;                 const float4 p0 = *(const float4*)(part + po), p1 = *(const float4*)(part + (size_t)4096 * 1024 + po), cg = *(const float4*)(cgate + i * 256 + lane * 4);
;                 v[i].x += cg.x * (p0.x + p1.x); v[i].y += cg.y * (p0.y + p1.y); v[i].z += cg.z * (p0.z + p1.z); v[i].w += cg.w * (p0.w + p1.w);
;                 *(float4*)(hcout + po) = v[i];
;             }
;             ss += v[i].x * v[i].x + v[i].y * v[i].y + v[i].z * v[i].z + v[i].w * v[i].w; }
;         ss = wave_sum(ss);
;         const float rstd = rsqrtf(ss * (1.0f / 1024.0f) + EPS);
;         const float* mr = modl + (size_t)r * 6144;
; #pragma unroll
;         for (int i = 0; i < 4; ++i) {
;             const int k = i * 256 + lane * 4;
;             const float4 gg = *(const float4*)(g + k), scv = *(const float4*)(mr + sc_off + k), shv = *(const float4*)(mr + sh_off + k);
;             const float o0 = v[i].x * rstd * gg.x * (1.0f + scv.x) + shv.x, o1 = v[i].y * rstd * gg.y * (1.0f + scv.y) + shv.y;
;             const float o2 = v[i].z * rstd * gg.z * (1.0f + scv.z) + shv.z, o3 = v[i].w * rstd * gg.w * (1.0f + scv.w) + shv.w;
;             uint2 w; w.x = pk2(o0, o1); w.y = pk2(o2, o3);
;             *(uint2*)(A + (size_t)row * 1024 + k) = w;
;         }
; #pragma unroll
;         for (int i = 0; i < 4; ++i) v[i] = nv[i];
;         row = nrow;
	v_pk_mul_f32 v[242:243], v[172:173], v[172:173]
	v_pk_mul_f32 v[244:245], v[176:177], v[176:177]
	v_pk_mul_f32 v[246:247], v[174:175], v[174:175]
	v_pk_mul_f32 v[248:249], v[178:179], v[178:179]
	v_add_f32_e32 v204, v245, v244
	v_add_f32_e32 v205, v243, v242
	v_add_f32_e32 v204, v248, v204
	v_add_f32_e32 v205, v246, v205
	v_add_f32_e32 v204, v249, v204
	v_add_f32_e32 v205, v247, v205
	v_pk_mul_f32 v[242:243], v[180:181], v[180:181]
	v_pk_mul_f32 v[244:245], v[184:185], v[184:185]
	v_pk_mul_f32 v[246:247], v[182:183], v[182:183]
	v_pk_mul_f32 v[248:249], v[186:187], v[186:187]
	v_add_f32_e32 v206, v243, v242
	v_add_f32_e32 v207, v245, v244
	v_add_f32_e32 v206, v246, v206
	v_add_f32_e32 v207, v248, v207
	v_add_f32_e32 v206, v247, v206
	v_add_f32_e32 v207, v249, v207
	v_add_f32_e32 v204, v205, v204
	v_add_f32_e32 v204, v204, v206
	v_add_f32_e32 v204, v204, v207
	ds_swizzle_b32 v205, v204 offset:swizzle(SWAP,1)
	s_waitcnt lgkmcnt(0)
	v_add_f32_e32 v204, v204, v205
	ds_swizzle_b32 v205, v204 offset:swizzle(SWAP,2)
	s_waitcnt lgkmcnt(0)
	v_add_f32_e32 v204, v204, v205
	ds_swizzle_b32 v205, v204 offset:swizzle(SWAP,4)
	s_waitcnt lgkmcnt(0)
	v_add_f32_e32 v204, v204, v205
	ds_swizzle_b32 v205, v204 offset:swizzle(SWAP,8)
	s_waitcnt lgkmcnt(0)
	v_add_f32_e32 v204, v204, v205
	ds_swizzle_b32 v205, v204 offset:swizzle(SWAP,16)
	s_waitcnt lgkmcnt(0)
	v_add_f32_e32 v204, v204, v205
	v_mov_b32_e32 v205, v204
	s_nop 1
	v_permlane32_swap_b32_e32 v204, v205
	v_add_f32_e32 v204, v204, v205
	v_mov_b32_e32 v205, 0x358637bd
	v_fmamk_f32 v204, v204, 0x3a800000, v205
	v_rsq_f32_e32 v204, v204
	s_nop 0
	v_pk_mul_f32 v[172:173], v[172:173], v[204:205] op_sel_hi:[1,0]
	v_pk_mul_f32 v[174:175], v[174:175], v[204:205] op_sel_hi:[1,0]
	v_pk_mul_f32 v[172:173], v[188:189], v[172:173]
	v_pk_mul_f32 v[174:175], v[190:191], v[174:175]
	v_pk_fma_f32 v[172:173], v[34:35], v[172:173], v[224:225]
	v_pk_fma_f32 v[174:175], v[36:37], v[174:175], v[226:227]
	v_cvt_pk_bf16_f32 v172, v172, v173
	v_cvt_pk_bf16_f32 v173, v174, v175
	global_store_dwordx2 v146, v[172:173], s[66:67]
	v_pk_mul_f32 v[176:177], v[176:177], v[204:205] op_sel_hi:[1,0]
	v_pk_mul_f32 v[178:179], v[178:179], v[204:205] op_sel_hi:[1,0]
	v_pk_mul_f32 v[176:177], v[192:193], v[176:177]
	v_pk_mul_f32 v[178:179], v[194:195], v[178:179]
	v_pk_fma_f32 v[176:177], v[38:39], v[176:177], v[228:229]
	v_pk_fma_f32 v[178:179], v[40:41], v[178:179], v[230:231]
	v_cvt_pk_bf16_f32 v176, v176, v177
	v_cvt_pk_bf16_f32 v177, v178, v179
	global_store_dwordx2 v146, v[176:177], s[66:67] offset:512
	v_pk_mul_f32 v[180:181], v[180:181], v[204:205] op_sel_hi:[1,0]
	v_pk_mul_f32 v[182:183], v[182:183], v[204:205] op_sel_hi:[1,0]
	v_pk_mul_f32 v[180:181], v[196:197], v[180:181]
	v_pk_mul_f32 v[182:183], v[198:199], v[182:183]
	v_pk_fma_f32 v[180:181], v[42:43], v[180:181], v[232:233]
	v_pk_fma_f32 v[182:183], v[44:45], v[182:183], v[234:235]
	v_cvt_pk_bf16_f32 v180, v180, v181
	v_cvt_pk_bf16_f32 v181, v182, v183
	global_store_dwordx2 v146, v[180:181], s[66:67] offset:1024
	v_pk_mul_f32 v[184:185], v[184:185], v[204:205] op_sel_hi:[1,0]
	v_pk_mul_f32 v[186:187], v[186:187], v[204:205] op_sel_hi:[1,0]
	v_pk_mul_f32 v[184:185], v[200:201], v[184:185]
	v_pk_mul_f32 v[186:187], v[202:203], v[186:187]
	v_pk_fma_f32 v[184:185], v[46:47], v[184:185], v[236:237]
	v_pk_fma_f32 v[186:187], v[48:49], v[186:187], v[238:239]
	v_cvt_pk_bf16_f32 v184, v184, v185
	v_cvt_pk_bf16_f32 v185, v186, v187
	global_store_dwordx2 v146, v[184:185], s[66:67] offset:1536
	v_add_u32_e32 v146, 0x800, v146
	global_load_dwordx4 v[172:175], v144, s[46:47] nt
	global_load_dwordx4 v[176:179], v144, s[46:47] offset:1024 nt
	global_load_dwordx4 v[180:183], v144, s[46:47] offset:2048 nt
	global_load_dwordx4 v[184:187], v144, s[46:47] offset:3072 nt
	v_add_u32_e32 v144, 0x1000, v144
	s_waitcnt vmcnt(40)
	v_pk_mul_f32 v[242:243], v[80:81], v[80:81]
	v_pk_mul_f32 v[244:245], v[84:85], v[84:85]
	v_pk_mul_f32 v[246:247], v[82:83], v[82:83]
	v_pk_mul_f32 v[248:249], v[86:87], v[86:87]
	v_add_f32_e32 v204, v245, v244
	v_add_f32_e32 v205, v243, v242
	v_add_f32_e32 v204, v248, v204
	v_add_f32_e32 v205, v246, v205
	v_add_f32_e32 v204, v249, v204
	v_add_f32_e32 v205, v247, v205
	v_pk_mul_f32 v[242:243], v[88:89], v[88:89]
	v_pk_mul_f32 v[244:245], v[92:93], v[92:93]
	v_pk_mul_f32 v[246:247], v[90:91], v[90:91]
	v_pk_mul_f32 v[248:249], v[94:95], v[94:95]
	v_add_f32_e32 v206, v243, v242
	v_add_f32_e32 v207, v245, v244
	v_add_f32_e32 v206, v246, v206
	v_add_f32_e32 v207, v248, v207
	v_add_f32_e32 v206, v247, v206
	v_add_f32_e32 v207, v249, v207
	v_add_f32_e32 v204, v205, v204
	v_add_f32_e32 v204, v204, v206
	v_add_f32_e32 v204, v204, v207
	ds_swizzle_b32 v205, v204 offset:swizzle(SWAP,1)
	s_waitcnt lgkmcnt(0)
	v_add_f32_e32 v204, v204, v205
	ds_swizzle_b32 v205, v204 offset:swizzle(SWAP,2)
	s_waitcnt lgkmcnt(0)
	v_add_f32_e32 v204, v204, v205
	ds_swizzle_b32 v205, v204 offset:swizzle(SWAP,4)
	s_waitcnt lgkmcnt(0)
	v_add_f32_e32 v204, v204, v205
	ds_swizzle_b32 v205, v204 offset:swizzle(SWAP,8)
	s_waitcnt lgkmcnt(0)
	v_add_f32_e32 v204, v204, v205
	ds_swizzle_b32 v205, v204 offset:swizzle(SWAP,16)
	s_waitcnt lgkmcnt(0)
; __device__ __forceinline__ unsigned pk2(float lo, float hi) { const g_f32x2 f = {lo, hi}; return __builtin_bit_cast(unsigned, __builtin_convertvector(f, g_bf16x2)); }
; __device__ __forceinline__ void p_norm(const float* hlat, const float* hctx, const float* g, const float* modl, int sh_off, int sc_off, bf16_t* A, int M,
;                                        const float* part, const float* cgate, float* hcout) {
;     ...
;         float ss = 0.f;
; #pragma unroll
;         for (int i = 0; i < 4; ++i) {
;             if (part != nullptr && row >= NLAT) {
;                 const size_t po = (size_t)(row - NLAT) * 1024 + i * 256 + lane * 4;
;                 const float4 p0 = *(const float4*)(part + po), p1 = *(const float4*)(part + (size_t)4096 * 1024 + po), cg = *(const float4*)(cgate + i * 256 + lane * 4);
;                 v[i].x += cg.x * (p0.x + p1.x); v[i].y += cg.y * (p0.y + p1.y); v[i].z += cg.z * (p0.z + p1.z); v[i].w += cg.w * (p0.w + p1.w);
;                 *(float4*)(hcout + po) = v[i];
;             }
;             ss += v[i].x * v[i].x + v[i].y * v[i].y + v[i].z * v[i].z + v[i].w * v[i].w; }
;         ss = wave_sum(ss);
;         const float rstd = rsqrtf(ss * (1.0f / 1024.0f) + EPS);
;         const float* mr = modl + (size_t)r * 6144;
; #pragma unroll
;         for (int i = 0; i < 4; ++i) {
;             const int k = i * 256 + lane * 4;
;             const float4 gg = *(const float4*)(g + k), scv = *(const float4*)(mr + sc_off + k), shv = *(const float4*)(mr + sh_off + k);
;             const float o0 = v[i].x * rstd * gg.x * (1.0f + scv.x) + shv.x, o1 = v[i].y * rstd * gg.y * (1.0f + scv.y) + shv.y;
;             const float o2 = v[i].z * rstd * gg.z * (1.0f + scv.z) + shv.z, o3 = v[i].w * rstd * gg.w * (1.0f + scv.w) + shv.w;
;             uint2 w; w.x = pk2(o0, o1); w.y = pk2(o2, o3);
;             *(uint2*)(A + (size_t)row * 1024 + k) = w;
;         }
; #pragma unroll
;         for (int i = 0; i < 4; ++i) v[i] = nv[i];
;         row = nrow;
	v_add_f32_e32 v204, v204, v205
	v_mov_b32_e32 v205, v204
	s_nop 1
	v_permlane32_swap_b32_e32 v204, v205
	v_add_f32_e32 v204, v204, v205
	v_mov_b32_e32 v205, 0x358637bd
	v_fmamk_f32 v204, v204, 0x3a800000, v205
	v_rsq_f32_e32 v204, v204
	s_nop 0
	v_pk_mul_f32 v[80:81], v[80:81], v[204:205] op_sel_hi:[1,0]
	v_pk_mul_f32 v[82:83], v[82:83], v[204:205] op_sel_hi:[1,0]
	v_pk_mul_f32 v[80:81], v[188:189], v[80:81]
	v_pk_mul_f32 v[82:83], v[190:191], v[82:83]
	v_pk_fma_f32 v[80:81], v[34:35], v[80:81], v[224:225]
	v_pk_fma_f32 v[82:83], v[36:37], v[82:83], v[226:227]
	v_cvt_pk_bf16_f32 v80, v80, v81
	v_cvt_pk_bf16_f32 v81, v82, v83
	global_store_dwordx2 v146, v[80:81], s[66:67]
	v_pk_mul_f32 v[84:85], v[84:85], v[204:205] op_sel_hi:[1,0]
	v_pk_mul_f32 v[86:87], v[86:87], v[204:205] op_sel_hi:[1,0]
	v_pk_mul_f32 v[84:85], v[192:193], v[84:85]
	v_pk_mul_f32 v[86:87], v[194:195], v[86:87]
	v_pk_fma_f32 v[84:85], v[38:39], v[84:85], v[228:229]
	v_pk_fma_f32 v[86:87], v[40:41], v[86:87], v[230:231]
	v_cvt_pk_bf16_f32 v84, v84, v85
	v_cvt_pk_bf16_f32 v85, v86, v87
	global_store_dwordx2 v146, v[84:85], s[66:67] offset:512
	v_pk_mul_f32 v[88:89], v[88:89], v[204:205] op_sel_hi:[1,0]
	v_pk_mul_f32 v[90:91], v[90:91], v[204:205] op_sel_hi:[1,0]
	v_pk_mul_f32 v[88:89], v[196:197], v[88:89]
	v_pk_mul_f32 v[90:91], v[198:199], v[90:91]
	v_pk_fma_f32 v[88:89], v[42:43], v[88:89], v[232:233]
	v_pk_fma_f32 v[90:91], v[44:45], v[90:91], v[234:235]
	v_cvt_pk_bf16_f32 v88, v88, v89
	v_cvt_pk_bf16_f32 v89, v90, v91
	global_store_dwordx2 v146, v[88:89], s[66:67] offset:1024
	v_pk_mul_f32 v[92:93], v[92:93], v[204:205] op_sel_hi:[1,0]
	v_pk_mul_f32 v[94:95], v[94:95], v[204:205] op_sel_hi:[1,0]
	v_pk_mul_f32 v[92:93], v[200:201], v[92:93]
	v_pk_mul_f32 v[94:95], v[202:203], v[94:95]
	v_pk_fma_f32 v[92:93], v[46:47], v[92:93], v[236:237]
	v_pk_fma_f32 v[94:95], v[48:49], v[94:95], v[238:239]
	v_cvt_pk_bf16_f32 v92, v92, v93
	v_cvt_pk_bf16_f32 v93, v94, v95
	global_store_dwordx2 v146, v[92:93], s[66:67] offset:1536
	v_add_u32_e32 v146, 0x800, v146
	global_load_dwordx4 v[80:83], v144, s[46:47] nt
	global_load_dwordx4 v[84:87], v144, s[46:47] offset:1024 nt
	global_load_dwordx4 v[88:91], v144, s[46:47] offset:2048 nt
	global_load_dwordx4 v[92:95], v144, s[46:47] offset:3072 nt
	v_add_u32_e32 v144, 0x1000, v144
	s_waitcnt vmcnt(40)
	v_pk_mul_f32 v[242:243], v[96:97], v[96:97]
	v_pk_mul_f32 v[244:245], v[100:101], v[100:101]
	v_pk_mul_f32 v[246:247], v[98:99], v[98:99]
	v_pk_mul_f32 v[248:249], v[102:103], v[102:103]
	v_add_f32_e32 v204, v245, v244
	v_add_f32_e32 v205, v243, v242
	v_add_f32_e32 v204, v248, v204
	v_add_f32_e32 v205, v246, v205
	v_add_f32_e32 v204, v249, v204
	v_add_f32_e32 v205, v247, v205
	v_pk_mul_f32 v[242:243], v[104:105], v[104:105]
	v_pk_mul_f32 v[244:245], v[108:109], v[108:109]
	v_pk_mul_f32 v[246:247], v[106:107], v[106:107]
	v_pk_mul_f32 v[248:249], v[110:111], v[110:111]
	v_add_f32_e32 v206, v243, v242
	v_add_f32_e32 v207, v245, v244
	v_add_f32_e32 v206, v246, v206
	v_add_f32_e32 v207, v248, v207
	v_add_f32_e32 v206, v247, v206
	v_add_f32_e32 v207, v249, v207
	v_add_f32_e32 v204, v205, v204
	v_add_f32_e32 v204, v204, v206
	v_add_f32_e32 v204, v204, v207
	ds_swizzle_b32 v205, v204 offset:swizzle(SWAP,1)
	s_waitcnt lgkmcnt(0)
	v_add_f32_e32 v204, v204, v205
	ds_swizzle_b32 v205, v204 offset:swizzle(SWAP,2)
	s_waitcnt lgkmcnt(0)
	v_add_f32_e32 v204, v204, v205
	ds_swizzle_b32 v205, v204 offset:swizzle(SWAP,4)
	s_waitcnt lgkmcnt(0)
	v_add_f32_e32 v204, v204, v205
	ds_swizzle_b32 v205, v204 offset:swizzle(SWAP,8)
	s_waitcnt lgkmcnt(0)
	v_add_f32_e32 v204, v204, v205
	ds_swizzle_b32 v205, v204 offset:swizzle(SWAP,16)
	s_waitcnt lgkmcnt(0)
	v_add_f32_e32 v204, v204, v205
	v_mov_b32_e32 v205, v204
	s_nop 1
	v_permlane32_swap_b32_e32 v204, v205
	v_add_f32_e32 v204, v204, v205
	v_mov_b32_e32 v205, 0x358637bd
	v_fmamk_f32 v204, v204, 0x3a800000, v205
	v_rsq_f32_e32 v204, v204
	s_nop 0
	v_pk_mul_f32 v[96:97], v[96:97], v[204:205] op_sel_hi:[1,0]
	v_pk_mul_f32 v[98:99], v[98:99], v[204:205] op_sel_hi:[1,0]
	v_pk_mul_f32 v[96:97], v[188:189], v[96:97]
	v_pk_mul_f32 v[98:99], v[190:191], v[98:99]
	v_pk_fma_f32 v[96:97], v[34:35], v[96:97], v[224:225]
	v_pk_fma_f32 v[98:99], v[36:37], v[98:99], v[226:227]
	v_cvt_pk_bf16_f32 v96, v96, v97
	v_cvt_pk_bf16_f32 v97, v98, v99
	global_store_dwordx2 v146, v[96:97], s[66:67]
	v_pk_mul_f32 v[100:101], v[100:101], v[204:205] op_sel_hi:[1,0]
	v_pk_mul_f32 v[102:103], v[102:103], v[204:205] op_sel_hi:[1,0]
	v_pk_mul_f32 v[100:101], v[192:193], v[100:101]
	v_pk_mul_f32 v[102:103], v[194:195], v[102:103]
	v_pk_fma_f32 v[100:101], v[38:39], v[100:101], v[228:229]
	v_pk_fma_f32 v[102:103], v[40:41], v[102:103], v[230:231]
	v_cvt_pk_bf16_f32 v100, v100, v101
	v_cvt_pk_bf16_f32 v101, v102, v103
	global_store_dwordx2 v146, v[100:101], s[66:67] offset:512
	v_pk_mul_f32 v[104:105], v[104:105], v[204:205] op_sel_hi:[1,0]
	v_pk_mul_f32 v[106:107], v[106:107], v[204:205] op_sel_hi:[1,0]
	v_pk_mul_f32 v[104:105], v[196:197], v[104:105]
	v_pk_mul_f32 v[106:107], v[198:199], v[106:107]
	v_pk_fma_f32 v[104:105], v[42:43], v[104:105], v[232:233]
	v_pk_fma_f32 v[106:107], v[44:45], v[106:107], v[234:235]
	v_cvt_pk_bf16_f32 v104, v104, v105
	v_cvt_pk_bf16_f32 v105, v106, v107
	global_store_dwordx2 v146, v[104:105], s[66:67] offset:1024
	v_pk_mul_f32 v[108:109], v[108:109], v[204:205] op_sel_hi:[1,0]
	v_pk_mul_f32 v[110:111], v[110:111], v[204:205] op_sel_hi:[1,0]
	v_pk_mul_f32 v[108:109], v[200:201], v[108:109]
	v_pk_mul_f32 v[110:111], v[202:203], v[110:111]
	v_pk_fma_f32 v[108:109], v[46:47], v[108:109], v[236:237]
	v_pk_fma_f32 v[110:111], v[48:49], v[110:111], v[238:239]
	v_cvt_pk_bf16_f32 v108, v108, v109
	v_cvt_pk_bf16_f32 v109, v110, v111
	global_store_dwordx2 v146, v[108:109], s[66:67] offset:1536
	v_add_u32_e32 v146, 0x800, v146
	global_load_dwordx4 v[96:99], v144, s[46:47] nt
	global_load_dwordx4 v[100:103], v144, s[46:47] offset:1024 nt
	global_load_dwordx4 v[104:107], v144, s[46:47] offset:2048 nt
	global_load_dwordx4 v[108:111], v144, s[46:47] offset:3072 nt
	v_add_u32_e32 v144, 0x1000, v144
	s_waitcnt vmcnt(40)
; __device__ __forceinline__ unsigned pk2(float lo, float hi) { const g_f32x2 f = {lo, hi}; return __builtin_bit_cast(unsigned, __builtin_convertvector(f, g_bf16x2)); }
; __device__ __forceinline__ void p_norm(const float* hlat, const float* hctx, const float* g, const float* modl, int sh_off, int sc_off, bf16_t* A, int M,
;                                        const float* part, const float* cgate, float* hcout) {
;     ...
;         float ss = 0.f;
; #pragma unroll
;         for (int i = 0; i < 4; ++i) {
;             if (part != nullptr && row >= NLAT) {
;                 const size_t po = (size_t)(row - NLAT) * 1024 + i * 256 + lane * 4;
;                 const float4 p0 = *(const float4*)(part + po), p1 = *(const float4*)(part + (size_t)4096 * 1024 + po), cg = *(const float4*)(cgate + i * 256 + lane * 4);
;                 v[i].x += cg.x * (p0.x + p1.x); v[i].y += cg.y * (p0.y + p1.y); v[i].z += cg.z * (p0.z + p1.z); v[i].w += cg.w * (p0.w + p1.w);
;                 *(float4*)(hcout + po) = v[i];
;             }
;             ss += v[i].x * v[i].x + v[i].y * v[i].y + v[i].z * v[i].z + v[i].w * v[i].w; }
;         ss = wave_sum(ss);
;         const float rstd = rsqrtf(ss * (1.0f / 1024.0f) + EPS);
;         const float* mr = modl + (size_t)r * 6144;
; #pragma unroll
;         for (int i = 0; i < 4; ++i) {
;             const int k = i * 256 + lane * 4;
;             const float4 gg = *(const float4*)(g + k), scv = *(const float4*)(mr + sc_off + k), shv = *(const float4*)(mr + sh_off + k);
;             const float o0 = v[i].x * rstd * gg.x * (1.0f + scv.x) + shv.x, o1 = v[i].y * rstd * gg.y * (1.0f + scv.y) + shv.y;
;             const float o2 = v[i].z * rstd * gg.z * (1.0f + scv.z) + shv.z, o3 = v[i].w * rstd * gg.w * (1.0f + scv.w) + shv.w;
;             uint2 w; w.x = pk2(o0, o1); w.y = pk2(o2, o3);
;             *(uint2*)(A + (size_t)row * 1024 + k) = w;
;         }
; #pragma unroll
;         for (int i = 0; i < 4; ++i) v[i] = nv[i];
;         row = nrow;
	v_pk_mul_f32 v[242:243], v[112:113], v[112:113]
	v_pk_mul_f32 v[244:245], v[116:117], v[116:117]
	v_pk_mul_f32 v[246:247], v[114:115], v[114:115]
	v_pk_mul_f32 v[248:249], v[118:119], v[118:119]
	v_add_f32_e32 v204, v245, v244
	v_add_f32_e32 v205, v243, v242
	v_add_f32_e32 v204, v248, v204
	v_add_f32_e32 v205, v246, v205
	v_add_f32_e32 v204, v249, v204
	v_add_f32_e32 v205, v247, v205
	v_pk_mul_f32 v[242:243], v[120:121], v[120:121]
	v_pk_mul_f32 v[244:245], v[124:125], v[124:125]
	v_pk_mul_f32 v[246:247], v[122:123], v[122:123]
	v_pk_mul_f32 v[248:249], v[126:127], v[126:127]
	v_add_f32_e32 v206, v243, v242
	v_add_f32_e32 v207, v245, v244
	v_add_f32_e32 v206, v246, v206
	v_add_f32_e32 v207, v248, v207
	v_add_f32_e32 v206, v247, v206
	v_add_f32_e32 v207, v249, v207
	v_add_f32_e32 v204, v205, v204
	v_add_f32_e32 v204, v204, v206
	v_add_f32_e32 v204, v204, v207
	ds_swizzle_b32 v205, v204 offset:swizzle(SWAP,1)
	s_waitcnt lgkmcnt(0)
	v_add_f32_e32 v204, v204, v205
	ds_swizzle_b32 v205, v204 offset:swizzle(SWAP,2)
	s_waitcnt lgkmcnt(0)
	v_add_f32_e32 v204, v204, v205
	ds_swizzle_b32 v205, v204 offset:swizzle(SWAP,4)
	s_waitcnt lgkmcnt(0)
	v_add_f32_e32 v204, v204, v205
	ds_swizzle_b32 v205, v204 offset:swizzle(SWAP,8)
	s_waitcnt lgkmcnt(0)
	v_add_f32_e32 v204, v204, v205
	ds_swizzle_b32 v205, v204 offset:swizzle(SWAP,16)
	s_waitcnt lgkmcnt(0)
	v_add_f32_e32 v204, v204, v205
	v_mov_b32_e32 v205, v204
	s_nop 1
	v_permlane32_swap_b32_e32 v204, v205
	v_add_f32_e32 v204, v204, v205
	v_mov_b32_e32 v205, 0x358637bd
	v_fmamk_f32 v204, v204, 0x3a800000, v205
	v_rsq_f32_e32 v204, v204
	s_nop 0
	v_pk_mul_f32 v[112:113], v[112:113], v[204:205] op_sel_hi:[1,0]
	v_pk_mul_f32 v[114:115], v[114:115], v[204:205] op_sel_hi:[1,0]
	v_pk_mul_f32 v[112:113], v[188:189], v[112:113]
	v_pk_mul_f32 v[114:115], v[190:191], v[114:115]
	v_pk_fma_f32 v[112:113], v[34:35], v[112:113], v[224:225]
	v_pk_fma_f32 v[114:115], v[36:37], v[114:115], v[226:227]
	v_cvt_pk_bf16_f32 v112, v112, v113
	v_cvt_pk_bf16_f32 v113, v114, v115
	global_store_dwordx2 v146, v[112:113], s[66:67]
	v_pk_mul_f32 v[116:117], v[116:117], v[204:205] op_sel_hi:[1,0]
	v_pk_mul_f32 v[118:119], v[118:119], v[204:205] op_sel_hi:[1,0]
	v_pk_mul_f32 v[116:117], v[192:193], v[116:117]
	v_pk_mul_f32 v[118:119], v[194:195], v[118:119]
	v_pk_fma_f32 v[116:117], v[38:39], v[116:117], v[228:229]
	v_pk_fma_f32 v[118:119], v[40:41], v[118:119], v[230:231]
	v_cvt_pk_bf16_f32 v116, v116, v117
	v_cvt_pk_bf16_f32 v117, v118, v119
	global_store_dwordx2 v146, v[116:117], s[66:67] offset:512
	v_pk_mul_f32 v[120:121], v[120:121], v[204:205] op_sel_hi:[1,0]
	v_pk_mul_f32 v[122:123], v[122:123], v[204:205] op_sel_hi:[1,0]
	v_pk_mul_f32 v[120:121], v[196:197], v[120:121]
	v_pk_mul_f32 v[122:123], v[198:199], v[122:123]
	v_pk_fma_f32 v[120:121], v[42:43], v[120:121], v[232:233]
	v_pk_fma_f32 v[122:123], v[44:45], v[122:123], v[234:235]
	v_cvt_pk_bf16_f32 v120, v120, v121
	v_cvt_pk_bf16_f32 v121, v122, v123
	global_store_dwordx2 v146, v[120:121], s[66:67] offset:1024
	v_pk_mul_f32 v[124:125], v[124:125], v[204:205] op_sel_hi:[1,0]
	v_pk_mul_f32 v[126:127], v[126:127], v[204:205] op_sel_hi:[1,0]
	v_pk_mul_f32 v[124:125], v[200:201], v[124:125]
	v_pk_mul_f32 v[126:127], v[202:203], v[126:127]
	v_pk_fma_f32 v[124:125], v[46:47], v[124:125], v[236:237]
	v_pk_fma_f32 v[126:127], v[48:49], v[126:127], v[238:239]
	v_cvt_pk_bf16_f32 v124, v124, v125
	v_cvt_pk_bf16_f32 v125, v126, v127
	global_store_dwordx2 v146, v[124:125], s[66:67] offset:1536
	v_add_u32_e32 v146, 0x800, v146
	global_load_dwordx4 v[112:115], v144, s[46:47] nt
	global_load_dwordx4 v[116:119], v144, s[46:47] offset:1024 nt
	global_load_dwordx4 v[120:123], v144, s[46:47] offset:2048 nt
	global_load_dwordx4 v[124:127], v144, s[46:47] offset:3072 nt
	v_add_u32_e32 v144, 0x1000, v144
	s_waitcnt vmcnt(40)
	v_pk_mul_f32 v[242:243], v[128:129], v[128:129]
	v_pk_mul_f32 v[244:245], v[132:133], v[132:133]
	v_pk_mul_f32 v[246:247], v[130:131], v[130:131]
	v_pk_mul_f32 v[248:249], v[134:135], v[134:135]
	v_add_f32_e32 v204, v245, v244
	v_add_f32_e32 v205, v243, v242
	v_add_f32_e32 v204, v248, v204
	v_add_f32_e32 v205, v246, v205
	v_add_f32_e32 v204, v249, v204
	v_add_f32_e32 v205, v247, v205
	v_pk_mul_f32 v[242:243], v[136:137], v[136:137]
	v_pk_mul_f32 v[244:245], v[140:141], v[140:141]
	v_pk_mul_f32 v[246:247], v[138:139], v[138:139]
	v_pk_mul_f32 v[248:249], v[142:143], v[142:143]
	v_add_f32_e32 v206, v243, v242
	v_add_f32_e32 v207, v245, v244
	v_add_f32_e32 v206, v246, v206
	v_add_f32_e32 v207, v248, v207
	v_add_f32_e32 v206, v247, v206
	v_add_f32_e32 v207, v249, v207
	v_add_f32_e32 v204, v205, v204
	v_add_f32_e32 v204, v204, v206
	v_add_f32_e32 v204, v204, v207
	ds_swizzle_b32 v205, v204 offset:swizzle(SWAP,1)
	s_waitcnt lgkmcnt(0)
	v_add_f32_e32 v204, v204, v205
	ds_swizzle_b32 v205, v204 offset:swizzle(SWAP,2)
	s_waitcnt lgkmcnt(0)
	v_add_f32_e32 v204, v204, v205
	ds_swizzle_b32 v205, v204 offset:swizzle(SWAP,4)
	s_waitcnt lgkmcnt(0)
	v_add_f32_e32 v204, v204, v205
	ds_swizzle_b32 v205, v204 offset:swizzle(SWAP,8)
	s_waitcnt lgkmcnt(0)
	v_add_f32_e32 v204, v204, v205
	ds_swizzle_b32 v205, v204 offset:swizzle(SWAP,16)
	s_waitcnt lgkmcnt(0)
; __device__ __forceinline__ unsigned pk2(float lo, float hi) { const g_f32x2 f = {lo, hi}; return __builtin_bit_cast(unsigned, __builtin_convertvector(f, g_bf16x2)); }
; #define PN_LOAD(dst, rw) do { const float* s_ = (rw) < NLAT ? hlat + (size_t)(rw) * 1024 : hctx + (size_t)((rw) - NLAT) * 1024; \
;         _Pragma("unroll") for (int i = 0; i < 4; ++i) dst[i] = *(const float4*)(s_ + i * 256 + lane * 4); } while (0)
; __device__ __forceinline__ void p_norm(const float* hlat, const float* hctx, const float* g, const float* modl, int sh_off, int sc_off, bf16_t* A, int M,
;                                        const float* part, const float* cgate, float* hcout) {
;     ...
;     if (row < M) PN_LOAD(v, row);
;     while (row < M) {
;         const int nrow = row + stride;
;         if (nrow < M) PN_LOAD(nv, nrow);
;         const int r = row < NLAT ? (row >> 11) : 16;
;         float ss = 0.f;
; #pragma unroll
;         for (int i = 0; i < 4; ++i) {
;             if (part != nullptr && row >= NLAT) {
;                 const size_t po = (size_t)(row - NLAT) * 1024 + i * 256 + lane * 4;
;                 const float4 p0 = *(const float4*)(part + po), p1 = *(const float4*)(part + (size_t)4096 * 1024 + po), cg = *(const float4*)(cgate + i * 256 + lane * 4);
;                 v[i].x += cg.x * (p0.x + p1.x); v[i].y += cg.y * (p0.y + p1.y); v[i].z += cg.z * (p0.z + p1.z); v[i].w += cg.w * (p0.w + p1.w);
;                 *(float4*)(hcout + po) = v[i];
;             }
;             ss += v[i].x * v[i].x + v[i].y * v[i].y + v[i].z * v[i].z + v[i].w * v[i].w; }
;         ss = wave_sum(ss);
;         const float rstd = rsqrtf(ss * (1.0f / 1024.0f) + EPS);
;         const float* mr = modl + (size_t)r * 6144;
; #pragma unroll
;         for (int i = 0; i < 4; ++i) {
;             const int k = i * 256 + lane * 4;
;             const float4 gg = *(const float4*)(g + k), scv = *(const float4*)(mr + sc_off + k), shv = *(const float4*)(mr + sh_off + k);
;             const float o0 = v[i].x * rstd * gg.x * (1.0f + scv.x) + shv.x, o1 = v[i].y * rstd * gg.y * (1.0f + scv.y) + shv.y;
;             const float o2 = v[i].z * rstd * gg.z * (1.0f + scv.z) + shv.z, o3 = v[i].w * rstd * gg.w * (1.0f + scv.w) + shv.w;
;             uint2 w; w.x = pk2(o0, o1); w.y = pk2(o2, o3);
;             *(uint2*)(A + (size_t)row * 1024 + k) = w;
;         }
	v_add_f32_e32 v204, v204, v205
	v_mov_b32_e32 v205, v204
	s_nop 1
	v_permlane32_swap_b32_e32 v204, v205
	v_add_f32_e32 v204, v204, v205
	v_mov_b32_e32 v205, 0x358637bd
	v_fmamk_f32 v204, v204, 0x3a800000, v205
	v_rsq_f32_e32 v204, v204
	s_nop 0
	v_pk_mul_f32 v[128:129], v[128:129], v[204:205] op_sel_hi:[1,0]
	v_pk_mul_f32 v[130:131], v[130:131], v[204:205] op_sel_hi:[1,0]
	v_pk_mul_f32 v[128:129], v[188:189], v[128:129]
	v_pk_mul_f32 v[130:131], v[190:191], v[130:131]
	v_pk_fma_f32 v[128:129], v[34:35], v[128:129], v[224:225]
	v_pk_fma_f32 v[130:131], v[36:37], v[130:131], v[226:227]
	v_cvt_pk_bf16_f32 v128, v128, v129
	v_cvt_pk_bf16_f32 v129, v130, v131
	global_store_dwordx2 v146, v[128:129], s[66:67]
	v_pk_mul_f32 v[132:133], v[132:133], v[204:205] op_sel_hi:[1,0]
	v_pk_mul_f32 v[134:135], v[134:135], v[204:205] op_sel_hi:[1,0]
	v_pk_mul_f32 v[132:133], v[192:193], v[132:133]
	v_pk_mul_f32 v[134:135], v[194:195], v[134:135]
	v_pk_fma_f32 v[132:133], v[38:39], v[132:133], v[228:229]
	v_pk_fma_f32 v[134:135], v[40:41], v[134:135], v[230:231]
	v_cvt_pk_bf16_f32 v132, v132, v133
	v_cvt_pk_bf16_f32 v133, v134, v135
	global_store_dwordx2 v146, v[132:133], s[66:67] offset:512
	v_pk_mul_f32 v[136:137], v[136:137], v[204:205] op_sel_hi:[1,0]
	v_pk_mul_f32 v[138:139], v[138:139], v[204:205] op_sel_hi:[1,0]
	v_pk_mul_f32 v[136:137], v[196:197], v[136:137]
	v_pk_mul_f32 v[138:139], v[198:199], v[138:139]
	v_pk_fma_f32 v[136:137], v[42:43], v[136:137], v[232:233]
	v_pk_fma_f32 v[138:139], v[44:45], v[138:139], v[234:235]
	v_cvt_pk_bf16_f32 v136, v136, v137
	v_cvt_pk_bf16_f32 v137, v138, v139
	global_store_dwordx2 v146, v[136:137], s[66:67] offset:1024
	v_pk_mul_f32 v[140:141], v[140:141], v[204:205] op_sel_hi:[1,0]
	v_pk_mul_f32 v[142:143], v[142:143], v[204:205] op_sel_hi:[1,0]
	v_pk_mul_f32 v[140:141], v[200:201], v[140:141]
	v_pk_mul_f32 v[142:143], v[202:203], v[142:143]
	v_pk_fma_f32 v[140:141], v[46:47], v[140:141], v[236:237]
	v_pk_fma_f32 v[142:143], v[48:49], v[142:143], v[238:239]
	v_cvt_pk_bf16_f32 v140, v140, v141
	v_cvt_pk_bf16_f32 v141, v142, v143
	global_store_dwordx2 v146, v[140:141], s[66:67] offset:1536
	v_add_u32_e32 v146, 0x800, v146
	global_load_dwordx4 v[128:131], v144, s[46:47] nt
	global_load_dwordx4 v[132:135], v144, s[46:47] offset:1024 nt
	global_load_dwordx4 v[136:139], v144, s[46:47] offset:2048 nt
	global_load_dwordx4 v[140:143], v144, s[46:47] offset:3072 nt
	v_add_u32_e32 v144, 0x1000, v144
	s_waitcnt vmcnt(40)
	v_pk_mul_f32 v[242:243], v[156:157], v[156:157]
	v_pk_mul_f32 v[244:245], v[160:161], v[160:161]
	v_pk_mul_f32 v[246:247], v[158:159], v[158:159]
	v_pk_mul_f32 v[248:249], v[162:163], v[162:163]
	v_add_f32_e32 v204, v245, v244
	v_add_f32_e32 v205, v243, v242
	v_add_f32_e32 v204, v248, v204
	v_add_f32_e32 v205, v246, v205
	v_add_f32_e32 v204, v249, v204
	v_add_f32_e32 v205, v247, v205
	v_pk_mul_f32 v[242:243], v[164:165], v[164:165]
	v_pk_mul_f32 v[244:245], v[168:169], v[168:169]
	v_pk_mul_f32 v[246:247], v[166:167], v[166:167]
	v_pk_mul_f32 v[248:249], v[170:171], v[170:171]
	v_add_f32_e32 v206, v243, v242
	v_add_f32_e32 v207, v245, v244
	v_add_f32_e32 v206, v246, v206
	v_add_f32_e32 v207, v248, v207
	v_add_f32_e32 v206, v247, v206
	v_add_f32_e32 v207, v249, v207
	v_add_f32_e32 v204, v205, v204
	v_add_f32_e32 v204, v204, v206
	v_add_f32_e32 v204, v204, v207
	ds_swizzle_b32 v205, v204 offset:swizzle(SWAP,1)
	s_waitcnt lgkmcnt(0)
	v_add_f32_e32 v204, v204, v205
	ds_swizzle_b32 v205, v204 offset:swizzle(SWAP,2)
	s_waitcnt lgkmcnt(0)
	v_add_f32_e32 v204, v204, v205
	ds_swizzle_b32 v205, v204 offset:swizzle(SWAP,4)
	s_waitcnt lgkmcnt(0)
	v_add_f32_e32 v204, v204, v205
	ds_swizzle_b32 v205, v204 offset:swizzle(SWAP,8)
	s_waitcnt lgkmcnt(0)
	v_add_f32_e32 v204, v204, v205
	ds_swizzle_b32 v205, v204 offset:swizzle(SWAP,16)
	s_waitcnt lgkmcnt(0)
	v_add_f32_e32 v204, v204, v205
	v_mov_b32_e32 v205, v204
	s_nop 1
	v_permlane32_swap_b32_e32 v204, v205
	v_add_f32_e32 v204, v204, v205
	v_mov_b32_e32 v205, 0x358637bd
	v_fmamk_f32 v204, v204, 0x3a800000, v205
	v_rsq_f32_e32 v204, v204
	s_nop 0
	v_pk_mul_f32 v[156:157], v[156:157], v[204:205] op_sel_hi:[1,0]
	v_pk_mul_f32 v[158:159], v[158:159], v[204:205] op_sel_hi:[1,0]
	v_pk_mul_f32 v[156:157], v[188:189], v[156:157]
	v_pk_mul_f32 v[158:159], v[190:191], v[158:159]
	v_pk_fma_f32 v[156:157], v[34:35], v[156:157], v[224:225]
	v_pk_fma_f32 v[158:159], v[36:37], v[158:159], v[226:227]
	v_cvt_pk_bf16_f32 v156, v156, v157
	v_cvt_pk_bf16_f32 v157, v158, v159
	global_store_dwordx2 v146, v[156:157], s[66:67]
	v_pk_mul_f32 v[160:161], v[160:161], v[204:205] op_sel_hi:[1,0]
	v_pk_mul_f32 v[162:163], v[162:163], v[204:205] op_sel_hi:[1,0]
	v_pk_mul_f32 v[160:161], v[192:193], v[160:161]
	v_pk_mul_f32 v[162:163], v[194:195], v[162:163]
	v_pk_fma_f32 v[160:161], v[38:39], v[160:161], v[228:229]
	v_pk_fma_f32 v[162:163], v[40:41], v[162:163], v[230:231]
	v_cvt_pk_bf16_f32 v160, v160, v161
	v_cvt_pk_bf16_f32 v161, v162, v163
	global_store_dwordx2 v146, v[160:161], s[66:67] offset:512
	v_pk_mul_f32 v[164:165], v[164:165], v[204:205] op_sel_hi:[1,0]
	v_pk_mul_f32 v[166:167], v[166:167], v[204:205] op_sel_hi:[1,0]
	v_pk_mul_f32 v[164:165], v[196:197], v[164:165]
	v_pk_mul_f32 v[166:167], v[198:199], v[166:167]
	v_pk_fma_f32 v[164:165], v[42:43], v[164:165], v[232:233]
	v_pk_fma_f32 v[166:167], v[44:45], v[166:167], v[234:235]
	v_cvt_pk_bf16_f32 v164, v164, v165
	v_cvt_pk_bf16_f32 v165, v166, v167
	global_store_dwordx2 v146, v[164:165], s[66:67] offset:1024
	v_pk_mul_f32 v[168:169], v[168:169], v[204:205] op_sel_hi:[1,0]
	v_pk_mul_f32 v[170:171], v[170:171], v[204:205] op_sel_hi:[1,0]
	v_pk_mul_f32 v[168:169], v[200:201], v[168:169]
	v_pk_mul_f32 v[170:171], v[202:203], v[170:171]
	v_pk_fma_f32 v[168:169], v[46:47], v[168:169], v[236:237]
	v_pk_fma_f32 v[170:171], v[48:49], v[170:171], v[238:239]
	v_cvt_pk_bf16_f32 v168, v168, v169
	v_cvt_pk_bf16_f32 v169, v170, v171
	global_store_dwordx2 v146, v[168:169], s[66:67] offset:1536
	v_add_u32_e32 v146, 0x800, v146
	v_lshl_add_u32 v144, v50, 13, v241
	v_mov_b32_e32 v152, v144
	v_add_u32_e32 v150, 0x1000000, v144
	global_load_dwordx4 v[156:159], v144, s[16:17]
	global_load_dwordx4 v[160:163], v144, s[16:17] offset:1024
	global_load_dwordx4 v[164:167], v144, s[16:17] offset:2048
	global_load_dwordx4 v[168:171], v144, s[16:17] offset:3072
	v_add_u32_e32 v144, 0x1000, v144
	s_waitcnt vmcnt(40)
; __device__ __forceinline__ unsigned pk2(float lo, float hi) { const g_f32x2 f = {lo, hi}; return __builtin_bit_cast(unsigned, __builtin_convertvector(f, g_bf16x2)); }
; #define PN_LOAD(dst, rw) do { const float* s_ = (rw) < NLAT ? hlat + (size_t)(rw) * 1024 : hctx + (size_t)((rw) - NLAT) * 1024; \
;         _Pragma("unroll") for (int i = 0; i < 4; ++i) dst[i] = *(const float4*)(s_ + i * 256 + lane * 4); } while (0)
; __device__ __forceinline__ void p_norm(const float* hlat, const float* hctx, const float* g, const float* modl, int sh_off, int sc_off, bf16_t* A, int M,
;                                        const float* part, const float* cgate, float* hcout) {
;     ...
;     if (row < M) PN_LOAD(v, row);
;     while (row < M) {
;         const int nrow = row + stride;
;         if (nrow < M) PN_LOAD(nv, nrow);
;         const int r = row < NLAT ? (row >> 11) : 16;
;         float ss = 0.f;
; #pragma unroll
;         for (int i = 0; i < 4; ++i) {
;             if (part != nullptr && row >= NLAT) {
;                 const size_t po = (size_t)(row - NLAT) * 1024 + i * 256 + lane * 4;
;                 const float4 p0 = *(const float4*)(part + po), p1 = *(const float4*)(part + (size_t)4096 * 1024 + po), cg = *(const float4*)(cgate + i * 256 + lane * 4);
;                 v[i].x += cg.x * (p0.x + p1.x); v[i].y += cg.y * (p0.y + p1.y); v[i].z += cg.z * (p0.z + p1.z); v[i].w += cg.w * (p0.w + p1.w);
;                 *(float4*)(hcout + po) = v[i];
;             }
;             ss += v[i].x * v[i].x + v[i].y * v[i].y + v[i].z * v[i].z + v[i].w * v[i].w; }
;         ss = wave_sum(ss);
;         const float rstd = rsqrtf(ss * (1.0f / 1024.0f) + EPS);
;         const float* mr = modl + (size_t)r * 6144;
; #pragma unroll
;         for (int i = 0; i < 4; ++i) {
;             const int k = i * 256 + lane * 4;
;             const float4 gg = *(const float4*)(g + k), scv = *(const float4*)(mr + sc_off + k), shv = *(const float4*)(mr + sh_off + k);
;             const float o0 = v[i].x * rstd * gg.x * (1.0f + scv.x) + shv.x, o1 = v[i].y * rstd * gg.y * (1.0f + scv.y) + shv.y;
;             const float o2 = v[i].z * rstd * gg.z * (1.0f + scv.z) + shv.z, o3 = v[i].w * rstd * gg.w * (1.0f + scv.w) + shv.w;
;             uint2 w; w.x = pk2(o0, o1); w.y = pk2(o2, o3);
;             *(uint2*)(A + (size_t)row * 1024 + k) = w;
;         }
	v_pk_mul_f32 v[242:243], v[172:173], v[172:173]
	v_pk_mul_f32 v[244:245], v[176:177], v[176:177]
	v_pk_mul_f32 v[246:247], v[174:175], v[174:175]
	v_pk_mul_f32 v[248:249], v[178:179], v[178:179]
	v_add_f32_e32 v204, v245, v244
	v_add_f32_e32 v205, v243, v242
	v_add_f32_e32 v204, v248, v204
	v_add_f32_e32 v205, v246, v205
	v_add_f32_e32 v204, v249, v204
	v_add_f32_e32 v205, v247, v205
	v_pk_mul_f32 v[242:243], v[180:181], v[180:181]
	v_pk_mul_f32 v[244:245], v[184:185], v[184:185]
	v_pk_mul_f32 v[246:247], v[182:183], v[182:183]
	v_pk_mul_f32 v[248:249], v[186:187], v[186:187]
	v_add_f32_e32 v206, v243, v242
	v_add_f32_e32 v207, v245, v244
	v_add_f32_e32 v206, v246, v206
	v_add_f32_e32 v207, v248, v207
	v_add_f32_e32 v206, v247, v206
	v_add_f32_e32 v207, v249, v207
	v_add_f32_e32 v204, v205, v204
	v_add_f32_e32 v204, v204, v206
	v_add_f32_e32 v204, v204, v207
	ds_swizzle_b32 v205, v204 offset:swizzle(SWAP,1)
	s_waitcnt lgkmcnt(0)
	v_add_f32_e32 v204, v204, v205
	ds_swizzle_b32 v205, v204 offset:swizzle(SWAP,2)
	s_waitcnt lgkmcnt(0)
	v_add_f32_e32 v204, v204, v205
	ds_swizzle_b32 v205, v204 offset:swizzle(SWAP,4)
	s_waitcnt lgkmcnt(0)
	v_add_f32_e32 v204, v204, v205
	ds_swizzle_b32 v205, v204 offset:swizzle(SWAP,8)
	s_waitcnt lgkmcnt(0)
	v_add_f32_e32 v204, v204, v205
	ds_swizzle_b32 v205, v204 offset:swizzle(SWAP,16)
	s_waitcnt lgkmcnt(0)
	v_add_f32_e32 v204, v204, v205
	v_mov_b32_e32 v205, v204
	s_nop 1
	v_permlane32_swap_b32_e32 v204, v205
	v_add_f32_e32 v204, v204, v205
	v_mov_b32_e32 v205, 0x358637bd
	v_fmamk_f32 v204, v204, 0x3a800000, v205
	v_rsq_f32_e32 v204, v204
	s_nop 0
	v_pk_mul_f32 v[172:173], v[172:173], v[204:205] op_sel_hi:[1,0]
	v_pk_mul_f32 v[174:175], v[174:175], v[204:205] op_sel_hi:[1,0]
	v_pk_mul_f32 v[172:173], v[188:189], v[172:173]
	v_pk_mul_f32 v[174:175], v[190:191], v[174:175]
	v_pk_fma_f32 v[172:173], v[34:35], v[172:173], v[224:225]
	v_pk_fma_f32 v[174:175], v[36:37], v[174:175], v[226:227]
	v_cvt_pk_bf16_f32 v172, v172, v173
	v_cvt_pk_bf16_f32 v173, v174, v175
	global_store_dwordx2 v146, v[172:173], s[66:67]
	v_pk_mul_f32 v[176:177], v[176:177], v[204:205] op_sel_hi:[1,0]
	v_pk_mul_f32 v[178:179], v[178:179], v[204:205] op_sel_hi:[1,0]
	v_pk_mul_f32 v[176:177], v[192:193], v[176:177]
	v_pk_mul_f32 v[178:179], v[194:195], v[178:179]
	v_pk_fma_f32 v[176:177], v[38:39], v[176:177], v[228:229]
	v_pk_fma_f32 v[178:179], v[40:41], v[178:179], v[230:231]
	v_cvt_pk_bf16_f32 v176, v176, v177
	v_cvt_pk_bf16_f32 v177, v178, v179
	global_store_dwordx2 v146, v[176:177], s[66:67] offset:512
	v_pk_mul_f32 v[180:181], v[180:181], v[204:205] op_sel_hi:[1,0]
	v_pk_mul_f32 v[182:183], v[182:183], v[204:205] op_sel_hi:[1,0]
	v_pk_mul_f32 v[180:181], v[196:197], v[180:181]
	v_pk_mul_f32 v[182:183], v[198:199], v[182:183]
	v_pk_fma_f32 v[180:181], v[42:43], v[180:181], v[232:233]
	v_pk_fma_f32 v[182:183], v[44:45], v[182:183], v[234:235]
	v_cvt_pk_bf16_f32 v180, v180, v181
	v_cvt_pk_bf16_f32 v181, v182, v183
	global_store_dwordx2 v146, v[180:181], s[66:67] offset:1024
	v_pk_mul_f32 v[184:185], v[184:185], v[204:205] op_sel_hi:[1,0]
	v_pk_mul_f32 v[186:187], v[186:187], v[204:205] op_sel_hi:[1,0]
	v_pk_mul_f32 v[184:185], v[200:201], v[184:185]
	v_pk_mul_f32 v[186:187], v[202:203], v[186:187]
	v_pk_fma_f32 v[184:185], v[46:47], v[184:185], v[236:237]
	v_pk_fma_f32 v[186:187], v[48:49], v[186:187], v[238:239]
	v_cvt_pk_bf16_f32 v184, v184, v185
	v_cvt_pk_bf16_f32 v185, v186, v187
	global_store_dwordx2 v146, v[184:185], s[66:67] offset:1536
	v_add_u32_e32 v146, 0x800, v146
	global_load_dwordx4 v[172:175], v144, s[16:17]
	global_load_dwordx4 v[176:179], v144, s[16:17] offset:1024
	global_load_dwordx4 v[180:183], v144, s[16:17] offset:2048
	global_load_dwordx4 v[184:187], v144, s[16:17] offset:3072
	v_add_u32_e32 v144, 0x1000, v144
	s_waitcnt vmcnt(40)
	v_pk_mul_f32 v[242:243], v[80:81], v[80:81]
	v_pk_mul_f32 v[244:245], v[84:85], v[84:85]
	v_pk_mul_f32 v[246:247], v[82:83], v[82:83]
	v_pk_mul_f32 v[248:249], v[86:87], v[86:87]
	v_add_f32_e32 v204, v245, v244
	v_add_f32_e32 v205, v243, v242
	v_add_f32_e32 v204, v248, v204
	v_add_f32_e32 v205, v246, v205
	v_add_f32_e32 v204, v249, v204
	v_add_f32_e32 v205, v247, v205
	v_pk_mul_f32 v[242:243], v[88:89], v[88:89]
	v_pk_mul_f32 v[244:245], v[92:93], v[92:93]
	v_pk_mul_f32 v[246:247], v[90:91], v[90:91]
	v_pk_mul_f32 v[248:249], v[94:95], v[94:95]
	v_add_f32_e32 v206, v243, v242
	v_add_f32_e32 v207, v245, v244
	v_add_f32_e32 v206, v246, v206
	v_add_f32_e32 v207, v248, v207
	v_add_f32_e32 v206, v247, v206
	v_add_f32_e32 v207, v249, v207
	v_add_f32_e32 v204, v205, v204
	v_add_f32_e32 v204, v204, v206
	v_add_f32_e32 v204, v204, v207
	ds_swizzle_b32 v205, v204 offset:swizzle(SWAP,1)
	s_waitcnt lgkmcnt(0)
	v_add_f32_e32 v204, v204, v205
	ds_swizzle_b32 v205, v204 offset:swizzle(SWAP,2)
	s_waitcnt lgkmcnt(0)
	v_add_f32_e32 v204, v204, v205
	ds_swizzle_b32 v205, v204 offset:swizzle(SWAP,4)
	s_waitcnt lgkmcnt(0)
	v_add_f32_e32 v204, v204, v205
	ds_swizzle_b32 v205, v204 offset:swizzle(SWAP,8)
	s_waitcnt lgkmcnt(0)
	v_add_f32_e32 v204, v204, v205
	ds_swizzle_b32 v205, v204 offset:swizzle(SWAP,16)
	s_waitcnt lgkmcnt(0)
; __device__ __forceinline__ unsigned pk2(float lo, float hi) { const g_f32x2 f = {lo, hi}; return __builtin_bit_cast(unsigned, __builtin_convertvector(f, g_bf16x2)); }
; #define PN_LOAD(dst, rw) do { const float* s_ = (rw) < NLAT ? hlat + (size_t)(rw) * 1024 : hctx + (size_t)((rw) - NLAT) * 1024; \
;         _Pragma("unroll") for (int i = 0; i < 4; ++i) dst[i] = *(const float4*)(s_ + i * 256 + lane * 4); } while (0)
; __device__ __forceinline__ void p_norm(const float* hlat, const float* hctx, const float* g, const float* modl, int sh_off, int sc_off, bf16_t* A, int M,
;                                        const float* part, const float* cgate, float* hcout) {
;     ...
;     if (row < M) PN_LOAD(v, row);
;     while (row < M) {
;         const int nrow = row + stride;
;         if (nrow < M) PN_LOAD(nv, nrow);
;         const int r = row < NLAT ? (row >> 11) : 16;
;         float ss = 0.f;
; #pragma unroll
;         for (int i = 0; i < 4; ++i) {
;             if (part != nullptr && row >= NLAT) {
;                 const size_t po = (size_t)(row - NLAT) * 1024 + i * 256 + lane * 4;
;                 const float4 p0 = *(const float4*)(part + po), p1 = *(const float4*)(part + (size_t)4096 * 1024 + po), cg = *(const float4*)(cgate + i * 256 + lane * 4);
;                 v[i].x += cg.x * (p0.x + p1.x); v[i].y += cg.y * (p0.y + p1.y); v[i].z += cg.z * (p0.z + p1.z); v[i].w += cg.w * (p0.w + p1.w);
;                 *(float4*)(hcout + po) = v[i];
;             }
;             ss += v[i].x * v[i].x + v[i].y * v[i].y + v[i].z * v[i].z + v[i].w * v[i].w; }
;         ss = wave_sum(ss);
;         const float rstd = rsqrtf(ss * (1.0f / 1024.0f) + EPS);
;         const float* mr = modl + (size_t)r * 6144;
; #pragma unroll
;         for (int i = 0; i < 4; ++i) {
;             const int k = i * 256 + lane * 4;
;             const float4 gg = *(const float4*)(g + k), scv = *(const float4*)(mr + sc_off + k), shv = *(const float4*)(mr + sh_off + k);
;             const float o0 = v[i].x * rstd * gg.x * (1.0f + scv.x) + shv.x, o1 = v[i].y * rstd * gg.y * (1.0f + scv.y) + shv.y;
;             const float o2 = v[i].z * rstd * gg.z * (1.0f + scv.z) + shv.z, o3 = v[i].w * rstd * gg.w * (1.0f + scv.w) + shv.w;
;             uint2 w; w.x = pk2(o0, o1); w.y = pk2(o2, o3);
;             *(uint2*)(A + (size_t)row * 1024 + k) = w;
;         }
	v_add_f32_e32 v204, v204, v205
	v_mov_b32_e32 v205, v204
	s_nop 1
	v_permlane32_swap_b32_e32 v204, v205
	v_add_f32_e32 v204, v204, v205
	v_mov_b32_e32 v205, 0x358637bd
	v_fmamk_f32 v204, v204, 0x3a800000, v205
	v_rsq_f32_e32 v204, v204
	s_nop 0
	v_pk_mul_f32 v[80:81], v[80:81], v[204:205] op_sel_hi:[1,0]
	v_pk_mul_f32 v[82:83], v[82:83], v[204:205] op_sel_hi:[1,0]
	v_pk_mul_f32 v[80:81], v[188:189], v[80:81]
	v_pk_mul_f32 v[82:83], v[190:191], v[82:83]
	v_pk_fma_f32 v[80:81], v[34:35], v[80:81], v[224:225]
	v_pk_fma_f32 v[82:83], v[36:37], v[82:83], v[226:227]
	v_cvt_pk_bf16_f32 v80, v80, v81
	v_cvt_pk_bf16_f32 v81, v82, v83
	global_store_dwordx2 v146, v[80:81], s[66:67]
	v_pk_mul_f32 v[84:85], v[84:85], v[204:205] op_sel_hi:[1,0]
	v_pk_mul_f32 v[86:87], v[86:87], v[204:205] op_sel_hi:[1,0]
	v_pk_mul_f32 v[84:85], v[192:193], v[84:85]
	v_pk_mul_f32 v[86:87], v[194:195], v[86:87]
	v_pk_fma_f32 v[84:85], v[38:39], v[84:85], v[228:229]
	v_pk_fma_f32 v[86:87], v[40:41], v[86:87], v[230:231]
	v_cvt_pk_bf16_f32 v84, v84, v85
	v_cvt_pk_bf16_f32 v85, v86, v87
	global_store_dwordx2 v146, v[84:85], s[66:67] offset:512
	v_pk_mul_f32 v[88:89], v[88:89], v[204:205] op_sel_hi:[1,0]
	v_pk_mul_f32 v[90:91], v[90:91], v[204:205] op_sel_hi:[1,0]
	v_pk_mul_f32 v[88:89], v[196:197], v[88:89]
	v_pk_mul_f32 v[90:91], v[198:199], v[90:91]
	v_pk_fma_f32 v[88:89], v[42:43], v[88:89], v[232:233]
	v_pk_fma_f32 v[90:91], v[44:45], v[90:91], v[234:235]
	v_cvt_pk_bf16_f32 v88, v88, v89
	v_cvt_pk_bf16_f32 v89, v90, v91
	global_store_dwordx2 v146, v[88:89], s[66:67] offset:1024
	v_pk_mul_f32 v[92:93], v[92:93], v[204:205] op_sel_hi:[1,0]
	v_pk_mul_f32 v[94:95], v[94:95], v[204:205] op_sel_hi:[1,0]
	v_pk_mul_f32 v[92:93], v[200:201], v[92:93]
	v_pk_mul_f32 v[94:95], v[202:203], v[94:95]
	v_pk_fma_f32 v[92:93], v[46:47], v[92:93], v[236:237]
	v_pk_fma_f32 v[94:95], v[48:49], v[94:95], v[238:239]
	v_cvt_pk_bf16_f32 v92, v92, v93
	v_cvt_pk_bf16_f32 v93, v94, v95
	global_store_dwordx2 v146, v[92:93], s[66:67] offset:1536
	v_add_u32_e32 v146, 0x800, v146
	global_load_dwordx4 v[8:11], v241, s[20:21]
	global_load_dwordx4 v[52:55], v241, s[20:21] offset:1024
	global_load_dwordx4 v[60:63], v241, s[20:21] offset:2048
	global_load_dwordx4 v[64:67], v241, s[20:21] offset:3072
	s_waitcnt vmcnt(40)
	v_pk_mul_f32 v[242:243], v[96:97], v[96:97]
	v_pk_mul_f32 v[244:245], v[100:101], v[100:101]
	v_pk_mul_f32 v[246:247], v[98:99], v[98:99]
	v_pk_mul_f32 v[248:249], v[102:103], v[102:103]
	v_add_f32_e32 v204, v245, v244
	v_add_f32_e32 v205, v243, v242
	v_add_f32_e32 v204, v248, v204
	v_add_f32_e32 v205, v246, v205
	v_add_f32_e32 v204, v249, v204
	v_add_f32_e32 v205, v247, v205
	v_pk_mul_f32 v[242:243], v[104:105], v[104:105]
	v_pk_mul_f32 v[244:245], v[108:109], v[108:109]
	v_pk_mul_f32 v[246:247], v[106:107], v[106:107]
	v_pk_mul_f32 v[248:249], v[110:111], v[110:111]
	v_add_f32_e32 v206, v243, v242
	v_add_f32_e32 v207, v245, v244
	v_add_f32_e32 v206, v246, v206
	v_add_f32_e32 v207, v248, v207
	v_add_f32_e32 v206, v247, v206
	v_add_f32_e32 v207, v249, v207
	v_add_f32_e32 v204, v205, v204
	v_add_f32_e32 v204, v204, v206
	v_add_f32_e32 v204, v204, v207
	ds_swizzle_b32 v205, v204 offset:swizzle(SWAP,1)
	s_waitcnt lgkmcnt(0)
	v_add_f32_e32 v204, v204, v205
	ds_swizzle_b32 v205, v204 offset:swizzle(SWAP,2)
	s_waitcnt lgkmcnt(0)
	v_add_f32_e32 v204, v204, v205
	ds_swizzle_b32 v205, v204 offset:swizzle(SWAP,4)
	s_waitcnt lgkmcnt(0)
	v_add_f32_e32 v204, v204, v205
	ds_swizzle_b32 v205, v204 offset:swizzle(SWAP,8)
	s_waitcnt lgkmcnt(0)
	v_add_f32_e32 v204, v204, v205
	ds_swizzle_b32 v205, v204 offset:swizzle(SWAP,16)
	s_waitcnt lgkmcnt(0)
	v_add_f32_e32 v204, v204, v205
	v_mov_b32_e32 v205, v204
	s_nop 1
	v_permlane32_swap_b32_e32 v204, v205
	v_add_f32_e32 v204, v204, v205
	v_mov_b32_e32 v205, 0x358637bd
	v_fmamk_f32 v204, v204, 0x3a800000, v205
	v_rsq_f32_e32 v204, v204
	s_nop 0
	v_pk_mul_f32 v[96:97], v[96:97], v[204:205] op_sel_hi:[1,0]
	v_pk_mul_f32 v[98:99], v[98:99], v[204:205] op_sel_hi:[1,0]
	v_pk_mul_f32 v[96:97], v[188:189], v[96:97]
	v_pk_mul_f32 v[98:99], v[190:191], v[98:99]
	v_pk_fma_f32 v[96:97], v[34:35], v[96:97], v[224:225]
	v_pk_fma_f32 v[98:99], v[36:37], v[98:99], v[226:227]
	v_cvt_pk_bf16_f32 v96, v96, v97
	v_cvt_pk_bf16_f32 v97, v98, v99
	global_store_dwordx2 v146, v[96:97], s[66:67]
	v_pk_mul_f32 v[100:101], v[100:101], v[204:205] op_sel_hi:[1,0]
	v_pk_mul_f32 v[102:103], v[102:103], v[204:205] op_sel_hi:[1,0]
	v_pk_mul_f32 v[100:101], v[192:193], v[100:101]
	v_pk_mul_f32 v[102:103], v[194:195], v[102:103]
	v_pk_fma_f32 v[100:101], v[38:39], v[100:101], v[228:229]
	v_pk_fma_f32 v[102:103], v[40:41], v[102:103], v[230:231]
	v_cvt_pk_bf16_f32 v100, v100, v101
	v_cvt_pk_bf16_f32 v101, v102, v103
	global_store_dwordx2 v146, v[100:101], s[66:67] offset:512
	v_pk_mul_f32 v[104:105], v[104:105], v[204:205] op_sel_hi:[1,0]
	v_pk_mul_f32 v[106:107], v[106:107], v[204:205] op_sel_hi:[1,0]
	v_pk_mul_f32 v[104:105], v[196:197], v[104:105]
	v_pk_mul_f32 v[106:107], v[198:199], v[106:107]
	v_pk_fma_f32 v[104:105], v[42:43], v[104:105], v[232:233]
	v_pk_fma_f32 v[106:107], v[44:45], v[106:107], v[234:235]
	v_cvt_pk_bf16_f32 v104, v104, v105
	v_cvt_pk_bf16_f32 v105, v106, v107
	global_store_dwordx2 v146, v[104:105], s[66:67] offset:1024
	v_pk_mul_f32 v[108:109], v[108:109], v[204:205] op_sel_hi:[1,0]
	v_pk_mul_f32 v[110:111], v[110:111], v[204:205] op_sel_hi:[1,0]
	v_pk_mul_f32 v[108:109], v[200:201], v[108:109]
	v_pk_mul_f32 v[110:111], v[202:203], v[110:111]
	v_pk_fma_f32 v[108:109], v[46:47], v[108:109], v[236:237]
	v_pk_fma_f32 v[110:111], v[48:49], v[110:111], v[238:239]
	v_cvt_pk_bf16_f32 v108, v108, v109
	v_cvt_pk_bf16_f32 v109, v110, v111
	global_store_dwordx2 v146, v[108:109], s[66:67] offset:1536
	v_add_u32_e32 v146, 0x800, v146
	global_load_dwordx4 v[80:83], v152, s[70:71]
	global_load_dwordx4 v[84:87], v152, s[70:71] offset:1024
	global_load_dwordx4 v[88:91], v152, s[70:71] offset:2048
	global_load_dwordx4 v[92:95], v152, s[70:71] offset:3072
	global_load_dwordx4 v[96:99], v150, s[70:71]
	global_load_dwordx4 v[100:103], v150, s[70:71] offset:1024
	global_load_dwordx4 v[104:107], v150, s[70:71] offset:2048
	global_load_dwordx4 v[108:111], v150, s[70:71] offset:3072
	s_waitcnt vmcnt(44)
; __device__ __forceinline__ unsigned pk2(float lo, float hi) { const g_f32x2 f = {lo, hi}; return __builtin_bit_cast(unsigned, __builtin_convertvector(f, g_bf16x2)); }
; #define PN_LOAD(dst, rw) do { const float* s_ = (rw) < NLAT ? hlat + (size_t)(rw) * 1024 : hctx + (size_t)((rw) - NLAT) * 1024; \
;         _Pragma("unroll") for (int i = 0; i < 4; ++i) dst[i] = *(const float4*)(s_ + i * 256 + lane * 4); } while (0)
; __device__ __forceinline__ void p_norm(const float* hlat, const float* hctx, const float* g, const float* modl, int sh_off, int sc_off, bf16_t* A, int M,
;                                        const float* part, const float* cgate, float* hcout) {
;     ...
;     if (row < M) PN_LOAD(v, row);
;     while (row < M) {
;         const int nrow = row + stride;
;         if (nrow < M) PN_LOAD(nv, nrow);
;         const int r = row < NLAT ? (row >> 11) : 16;
;         float ss = 0.f;
; #pragma unroll
;         for (int i = 0; i < 4; ++i) {
;             if (part != nullptr && row >= NLAT) {
;                 const size_t po = (size_t)(row - NLAT) * 1024 + i * 256 + lane * 4;
;                 const float4 p0 = *(const float4*)(part + po), p1 = *(const float4*)(part + (size_t)4096 * 1024 + po), cg = *(const float4*)(cgate + i * 256 + lane * 4);
;                 v[i].x += cg.x * (p0.x + p1.x); v[i].y += cg.y * (p0.y + p1.y); v[i].z += cg.z * (p0.z + p1.z); v[i].w += cg.w * (p0.w + p1.w);
;                 *(float4*)(hcout + po) = v[i];
;             }
;             ss += v[i].x * v[i].x + v[i].y * v[i].y + v[i].z * v[i].z + v[i].w * v[i].w; }
;         ss = wave_sum(ss);
;         const float rstd = rsqrtf(ss * (1.0f / 1024.0f) + EPS);
;         const float* mr = modl + (size_t)r * 6144;
; #pragma unroll
;         for (int i = 0; i < 4; ++i) {
;             const int k = i * 256 + lane * 4;
;             const float4 gg = *(const float4*)(g + k), scv = *(const float4*)(mr + sc_off + k), shv = *(const float4*)(mr + sh_off + k);
;             const float o0 = v[i].x * rstd * gg.x * (1.0f + scv.x) + shv.x, o1 = v[i].y * rstd * gg.y * (1.0f + scv.y) + shv.y;
;             const float o2 = v[i].z * rstd * gg.z * (1.0f + scv.z) + shv.z, o3 = v[i].w * rstd * gg.w * (1.0f + scv.w) + shv.w;
;             uint2 w; w.x = pk2(o0, o1); w.y = pk2(o2, o3);
;             *(uint2*)(A + (size_t)row * 1024 + k) = w;
;         }
	v_pk_mul_f32 v[242:243], v[112:113], v[112:113]
	v_pk_mul_f32 v[244:245], v[116:117], v[116:117]
	v_pk_mul_f32 v[246:247], v[114:115], v[114:115]
	v_pk_mul_f32 v[248:249], v[118:119], v[118:119]
	v_add_f32_e32 v204, v245, v244
	v_add_f32_e32 v205, v243, v242
	v_add_f32_e32 v204, v248, v204
	v_add_f32_e32 v205, v246, v205
	v_add_f32_e32 v204, v249, v204
	v_add_f32_e32 v205, v247, v205
	v_pk_mul_f32 v[242:243], v[120:121], v[120:121]
	v_pk_mul_f32 v[244:245], v[124:125], v[124:125]
	v_pk_mul_f32 v[246:247], v[122:123], v[122:123]
	v_pk_mul_f32 v[248:249], v[126:127], v[126:127]
	v_add_f32_e32 v206, v243, v242
	v_add_f32_e32 v207, v245, v244
	v_add_f32_e32 v206, v246, v206
	v_add_f32_e32 v207, v248, v207
	v_add_f32_e32 v206, v247, v206
	v_add_f32_e32 v207, v249, v207
	v_add_f32_e32 v204, v205, v204
	v_add_f32_e32 v204, v204, v206
	v_add_f32_e32 v204, v204, v207
	ds_swizzle_b32 v205, v204 offset:swizzle(SWAP,1)
	s_waitcnt lgkmcnt(0)
	v_add_f32_e32 v204, v204, v205
	ds_swizzle_b32 v205, v204 offset:swizzle(SWAP,2)
	s_waitcnt lgkmcnt(0)
	v_add_f32_e32 v204, v204, v205
	ds_swizzle_b32 v205, v204 offset:swizzle(SWAP,4)
	s_waitcnt lgkmcnt(0)
	v_add_f32_e32 v204, v204, v205
	ds_swizzle_b32 v205, v204 offset:swizzle(SWAP,8)
	s_waitcnt lgkmcnt(0)
	v_add_f32_e32 v204, v204, v205
	ds_swizzle_b32 v205, v204 offset:swizzle(SWAP,16)
	s_waitcnt lgkmcnt(0)
	v_add_f32_e32 v204, v204, v205
	v_mov_b32_e32 v205, v204
	s_nop 1
	v_permlane32_swap_b32_e32 v204, v205
	v_add_f32_e32 v204, v204, v205
	v_mov_b32_e32 v205, 0x358637bd
	v_fmamk_f32 v204, v204, 0x3a800000, v205
	v_rsq_f32_e32 v204, v204
	s_nop 0
	v_pk_mul_f32 v[112:113], v[112:113], v[204:205] op_sel_hi:[1,0]
	v_pk_mul_f32 v[114:115], v[114:115], v[204:205] op_sel_hi:[1,0]
	v_pk_mul_f32 v[112:113], v[188:189], v[112:113]
	v_pk_mul_f32 v[114:115], v[190:191], v[114:115]
	v_pk_fma_f32 v[112:113], v[34:35], v[112:113], v[224:225]
	v_pk_fma_f32 v[114:115], v[36:37], v[114:115], v[226:227]
	v_cvt_pk_bf16_f32 v112, v112, v113
	v_cvt_pk_bf16_f32 v113, v114, v115
	global_store_dwordx2 v146, v[112:113], s[66:67]
	v_pk_mul_f32 v[116:117], v[116:117], v[204:205] op_sel_hi:[1,0]
	v_pk_mul_f32 v[118:119], v[118:119], v[204:205] op_sel_hi:[1,0]
	v_pk_mul_f32 v[116:117], v[192:193], v[116:117]
	v_pk_mul_f32 v[118:119], v[194:195], v[118:119]
	v_pk_fma_f32 v[116:117], v[38:39], v[116:117], v[228:229]
	v_pk_fma_f32 v[118:119], v[40:41], v[118:119], v[230:231]
	v_cvt_pk_bf16_f32 v116, v116, v117
	v_cvt_pk_bf16_f32 v117, v118, v119
	global_store_dwordx2 v146, v[116:117], s[66:67] offset:512
	v_pk_mul_f32 v[120:121], v[120:121], v[204:205] op_sel_hi:[1,0]
	v_pk_mul_f32 v[122:123], v[122:123], v[204:205] op_sel_hi:[1,0]
	v_pk_mul_f32 v[120:121], v[196:197], v[120:121]
	v_pk_mul_f32 v[122:123], v[198:199], v[122:123]
	v_pk_fma_f32 v[120:121], v[42:43], v[120:121], v[232:233]
	v_pk_fma_f32 v[122:123], v[44:45], v[122:123], v[234:235]
	v_cvt_pk_bf16_f32 v120, v120, v121
	v_cvt_pk_bf16_f32 v121, v122, v123
	global_store_dwordx2 v146, v[120:121], s[66:67] offset:1024
	v_pk_mul_f32 v[124:125], v[124:125], v[204:205] op_sel_hi:[1,0]
	v_pk_mul_f32 v[126:127], v[126:127], v[204:205] op_sel_hi:[1,0]
	v_pk_mul_f32 v[124:125], v[200:201], v[124:125]
	v_pk_mul_f32 v[126:127], v[202:203], v[126:127]
	v_pk_fma_f32 v[124:125], v[46:47], v[124:125], v[236:237]
	v_pk_fma_f32 v[126:127], v[48:49], v[126:127], v[238:239]
	v_cvt_pk_bf16_f32 v124, v124, v125
	v_cvt_pk_bf16_f32 v125, v126, v127
	global_store_dwordx2 v146, v[124:125], s[66:67] offset:1536
	v_add_u32_e32 v146, 0x800, v146
	v_add_u32_e32 v207, 0x1000, v152
	global_load_dwordx4 v[112:115], v207, s[70:71]
	global_load_dwordx4 v[116:119], v207, s[70:71] offset:1024
	global_load_dwordx4 v[120:123], v207, s[70:71] offset:2048
	global_load_dwordx4 v[124:127], v207, s[70:71] offset:3072
	s_waitcnt vmcnt(44)
	v_pk_mul_f32 v[242:243], v[128:129], v[128:129]
	v_pk_mul_f32 v[244:245], v[132:133], v[132:133]
	v_pk_mul_f32 v[246:247], v[130:131], v[130:131]
	v_pk_mul_f32 v[248:249], v[134:135], v[134:135]
	v_add_f32_e32 v204, v245, v244
	v_add_f32_e32 v205, v243, v242
	v_add_f32_e32 v204, v248, v204
	v_add_f32_e32 v205, v246, v205
	v_add_f32_e32 v204, v249, v204
	v_add_f32_e32 v205, v247, v205
	v_pk_mul_f32 v[242:243], v[136:137], v[136:137]
	v_pk_mul_f32 v[244:245], v[140:141], v[140:141]
	v_pk_mul_f32 v[246:247], v[138:139], v[138:139]
	v_pk_mul_f32 v[248:249], v[142:143], v[142:143]
	v_add_f32_e32 v206, v243, v242
	v_add_f32_e32 v207, v245, v244
	v_add_f32_e32 v206, v246, v206
	v_add_f32_e32 v207, v248, v207
	v_add_f32_e32 v206, v247, v206
	v_add_f32_e32 v207, v249, v207
	v_add_f32_e32 v204, v205, v204
	v_add_f32_e32 v204, v204, v206
	v_add_f32_e32 v204, v204, v207
	ds_swizzle_b32 v205, v204 offset:swizzle(SWAP,1)
	s_waitcnt lgkmcnt(0)
	v_add_f32_e32 v204, v204, v205
	ds_swizzle_b32 v205, v204 offset:swizzle(SWAP,2)
	s_waitcnt lgkmcnt(0)
	v_add_f32_e32 v204, v204, v205
	ds_swizzle_b32 v205, v204 offset:swizzle(SWAP,4)
	s_waitcnt lgkmcnt(0)
	v_add_f32_e32 v204, v204, v205
	ds_swizzle_b32 v205, v204 offset:swizzle(SWAP,8)
	s_waitcnt lgkmcnt(0)
	v_add_f32_e32 v204, v204, v205
	ds_swizzle_b32 v205, v204 offset:swizzle(SWAP,16)
	s_waitcnt lgkmcnt(0)
; __device__ __forceinline__ unsigned pk2(float lo, float hi) { const g_f32x2 f = {lo, hi}; return __builtin_bit_cast(unsigned, __builtin_convertvector(f, g_bf16x2)); }
; #define PN_LOAD(dst, rw) do { const float* s_ = (rw) < NLAT ? hlat + (size_t)(rw) * 1024 : hctx + (size_t)((rw) - NLAT) * 1024; \
;         _Pragma("unroll") for (int i = 0; i < 4; ++i) dst[i] = *(const float4*)(s_ + i * 256 + lane * 4); } while (0)
; __device__ __forceinline__ void p_norm(const float* hlat, const float* hctx, const float* g, const float* modl, int sh_off, int sc_off, bf16_t* A, int M,
;                                        const float* part, const float* cgate, float* hcout) {
;     ...
;     if (row < M) PN_LOAD(v, row);
;     while (row < M) {
;         const int nrow = row + stride;
;         if (nrow < M) PN_LOAD(nv, nrow);
;         const int r = row < NLAT ? (row >> 11) : 16;
;         float ss = 0.f;
; #pragma unroll
;         for (int i = 0; i < 4; ++i) {
;             if (part != nullptr && row >= NLAT) {
;                 const size_t po = (size_t)(row - NLAT) * 1024 + i * 256 + lane * 4;
;                 const float4 p0 = *(const float4*)(part + po), p1 = *(const float4*)(part + (size_t)4096 * 1024 + po), cg = *(const float4*)(cgate + i * 256 + lane * 4);
;                 v[i].x += cg.x * (p0.x + p1.x); v[i].y += cg.y * (p0.y + p1.y); v[i].z += cg.z * (p0.z + p1.z); v[i].w += cg.w * (p0.w + p1.w);
;                 *(float4*)(hcout + po) = v[i];
;             }
;             ss += v[i].x * v[i].x + v[i].y * v[i].y + v[i].z * v[i].z + v[i].w * v[i].w; }
;         ss = wave_sum(ss);
;         const float rstd = rsqrtf(ss * (1.0f / 1024.0f) + EPS);
;         const float* mr = modl + (size_t)r * 6144;
; #pragma unroll
;         for (int i = 0; i < 4; ++i) {
;             const int k = i * 256 + lane * 4;
;             const float4 gg = *(const float4*)(g + k), scv = *(const float4*)(mr + sc_off + k), shv = *(const float4*)(mr + sh_off + k);
;             const float o0 = v[i].x * rstd * gg.x * (1.0f + scv.x) + shv.x, o1 = v[i].y * rstd * gg.y * (1.0f + scv.y) + shv.y;
;             const float o2 = v[i].z * rstd * gg.z * (1.0f + scv.z) + shv.z, o3 = v[i].w * rstd * gg.w * (1.0f + scv.w) + shv.w;
;             uint2 w; w.x = pk2(o0, o1); w.y = pk2(o2, o3);
;             *(uint2*)(A + (size_t)row * 1024 + k) = w;
;         }
	v_add_f32_e32 v204, v204, v205
	v_mov_b32_e32 v205, v204
	s_nop 1
	v_permlane32_swap_b32_e32 v204, v205
	v_add_f32_e32 v204, v204, v205
	v_mov_b32_e32 v205, 0x358637bd
	v_fmamk_f32 v204, v204, 0x3a800000, v205
	v_rsq_f32_e32 v204, v204
	s_nop 0
	v_pk_mul_f32 v[128:129], v[128:129], v[204:205] op_sel_hi:[1,0]
	v_pk_mul_f32 v[130:131], v[130:131], v[204:205] op_sel_hi:[1,0]
	v_pk_mul_f32 v[128:129], v[188:189], v[128:129]
	v_pk_mul_f32 v[130:131], v[190:191], v[130:131]
	v_pk_fma_f32 v[128:129], v[34:35], v[128:129], v[224:225]
	v_pk_fma_f32 v[130:131], v[36:37], v[130:131], v[226:227]
	v_cvt_pk_bf16_f32 v128, v128, v129
	v_cvt_pk_bf16_f32 v129, v130, v131
	global_store_dwordx2 v146, v[128:129], s[66:67]
	v_pk_mul_f32 v[132:133], v[132:133], v[204:205] op_sel_hi:[1,0]
	v_pk_mul_f32 v[134:135], v[134:135], v[204:205] op_sel_hi:[1,0]
	v_pk_mul_f32 v[132:133], v[192:193], v[132:133]
	v_pk_mul_f32 v[134:135], v[194:195], v[134:135]
	v_pk_fma_f32 v[132:133], v[38:39], v[132:133], v[228:229]
	v_pk_fma_f32 v[134:135], v[40:41], v[134:135], v[230:231]
	v_cvt_pk_bf16_f32 v132, v132, v133
	v_cvt_pk_bf16_f32 v133, v134, v135
	global_store_dwordx2 v146, v[132:133], s[66:67] offset:512
	v_pk_mul_f32 v[136:137], v[136:137], v[204:205] op_sel_hi:[1,0]
	v_pk_mul_f32 v[138:139], v[138:139], v[204:205] op_sel_hi:[1,0]
	v_pk_mul_f32 v[136:137], v[196:197], v[136:137]
	v_pk_mul_f32 v[138:139], v[198:199], v[138:139]
	v_pk_fma_f32 v[136:137], v[42:43], v[136:137], v[232:233]
	v_pk_fma_f32 v[138:139], v[44:45], v[138:139], v[234:235]
	v_cvt_pk_bf16_f32 v136, v136, v137
	v_cvt_pk_bf16_f32 v137, v138, v139
	global_store_dwordx2 v146, v[136:137], s[66:67] offset:1024
	v_pk_mul_f32 v[140:141], v[140:141], v[204:205] op_sel_hi:[1,0]
	v_pk_mul_f32 v[142:143], v[142:143], v[204:205] op_sel_hi:[1,0]
	v_pk_mul_f32 v[140:141], v[200:201], v[140:141]
	v_pk_mul_f32 v[142:143], v[202:203], v[142:143]
	v_pk_fma_f32 v[140:141], v[46:47], v[140:141], v[236:237]
	v_pk_fma_f32 v[142:143], v[48:49], v[142:143], v[238:239]
	v_cvt_pk_bf16_f32 v140, v140, v141
	v_cvt_pk_bf16_f32 v141, v142, v143
	global_store_dwordx2 v146, v[140:141], s[66:67] offset:1536
	v_add_u32_e32 v146, 0x800, v146
	v_add_u32_e32 v151, 0x60000, v241
	global_load_dwordx4 v[34:37], v151, s[98:99]
	global_load_dwordx4 v[38:41], v151, s[98:99] offset:1024
	global_load_dwordx4 v[42:45], v151, s[98:99] offset:2048
	global_load_dwordx4 v[46:49], v151, s[98:99] offset:3072
	global_load_dwordx4 v[224:227], v151, s[50:51]
	global_load_dwordx4 v[228:231], v151, s[50:51] offset:1024
	global_load_dwordx4 v[232:235], v151, s[50:51] offset:2048
	global_load_dwordx4 v[236:239], v151, s[50:51] offset:3072
	v_add_u32_e32 v207, 0x1000, v150
	global_load_dwordx4 v[128:131], v207, s[70:71]
	global_load_dwordx4 v[132:135], v207, s[70:71] offset:1024
	global_load_dwordx4 v[136:139], v207, s[70:71] offset:2048
	global_load_dwordx4 v[140:143], v207, s[70:71] offset:3072
	s_waitcnt vmcnt(24)
	v_pk_add_f32 v[80:81], v[80:81], v[96:97]
	v_pk_add_f32 v[82:83], v[82:83], v[98:99]
	v_pk_fma_f32 v[156:157], v[80:81], v[8:9], v[156:157]
	v_pk_fma_f32 v[158:159], v[82:83], v[10:11], v[158:159]
	global_store_dwordx4 v152, v[156:159], s[64:65]
	v_pk_add_f32 v[84:85], v[84:85], v[100:101]
	v_pk_add_f32 v[86:87], v[86:87], v[102:103]
	v_pk_fma_f32 v[160:161], v[84:85], v[52:53], v[160:161]
	v_pk_fma_f32 v[162:163], v[86:87], v[54:55], v[162:163]
	global_store_dwordx4 v152, v[160:163], s[64:65] offset:1024
	v_pk_add_f32 v[88:89], v[88:89], v[104:105]
	v_pk_add_f32 v[90:91], v[90:91], v[106:107]
	v_pk_fma_f32 v[164:165], v[88:89], v[60:61], v[164:165]
	v_pk_fma_f32 v[166:167], v[90:91], v[62:63], v[166:167]
	global_store_dwordx4 v152, v[164:167], s[64:65] offset:2048
	v_pk_add_f32 v[92:93], v[92:93], v[108:109]
	v_pk_add_f32 v[94:95], v[94:95], v[110:111]
	v_pk_fma_f32 v[168:169], v[92:93], v[64:65], v[168:169]
	v_pk_fma_f32 v[170:171], v[94:95], v[66:67], v[170:171]
	global_store_dwordx4 v152, v[168:171], s[64:65] offset:3072
	v_add_u32_e32 v152, 0x1000, v152
	v_pk_mul_f32 v[242:243], v[156:157], v[156:157]
	v_pk_mul_f32 v[244:245], v[160:161], v[160:161]
	v_pk_mul_f32 v[246:247], v[158:159], v[158:159]
	v_pk_mul_f32 v[248:249], v[162:163], v[162:163]
	v_add_f32_e32 v204, v245, v244
	v_add_f32_e32 v205, v243, v242
	v_add_f32_e32 v204, v248, v204
	v_add_f32_e32 v205, v246, v205
	v_add_f32_e32 v204, v249, v204
	v_add_f32_e32 v205, v247, v205
	v_pk_mul_f32 v[242:243], v[164:165], v[164:165]
	v_pk_mul_f32 v[244:245], v[168:169], v[168:169]
	v_pk_mul_f32 v[246:247], v[166:167], v[166:167]
	v_pk_mul_f32 v[248:249], v[170:171], v[170:171]
	v_add_f32_e32 v206, v243, v242
	v_add_f32_e32 v207, v245, v244
	v_add_f32_e32 v206, v246, v206
	v_add_f32_e32 v207, v248, v207
	v_add_f32_e32 v206, v247, v206
	v_add_f32_e32 v207, v249, v207
	v_add_f32_e32 v204, v205, v204
	v_add_f32_e32 v204, v204, v206
	v_add_f32_e32 v204, v204, v207
	ds_swizzle_b32 v205, v204 offset:swizzle(SWAP,1)
	s_waitcnt lgkmcnt(0)
	v_add_f32_e32 v204, v204, v205
	ds_swizzle_b32 v205, v204 offset:swizzle(SWAP,2)
	s_waitcnt lgkmcnt(0)
	v_add_f32_e32 v204, v204, v205
	ds_swizzle_b32 v205, v204 offset:swizzle(SWAP,4)
	s_waitcnt lgkmcnt(0)
	v_add_f32_e32 v204, v204, v205
	ds_swizzle_b32 v205, v204 offset:swizzle(SWAP,8)
	s_waitcnt lgkmcnt(0)
	v_add_f32_e32 v204, v204, v205
	ds_swizzle_b32 v205, v204 offset:swizzle(SWAP,16)
	s_waitcnt lgkmcnt(0)
	v_add_f32_e32 v204, v204, v205
	v_mov_b32_e32 v205, v204
	s_nop 1
	v_permlane32_swap_b32_e32 v204, v205
	v_add_f32_e32 v204, v204, v205
	v_mov_b32_e32 v205, 0x358637bd
	v_fmamk_f32 v204, v204, 0x3a800000, v205
	v_rsq_f32_e32 v204, v204
	s_nop 0
	s_waitcnt vmcnt(8)
; __device__ __forceinline__ unsigned pk2(float lo, float hi) { const g_f32x2 f = {lo, hi}; return __builtin_bit_cast(unsigned, __builtin_convertvector(f, g_bf16x2)); }
; __device__ __forceinline__ void p_norm(const float* hlat, const float* hctx, const float* g, const float* modl, int sh_off, int sc_off, bf16_t* A, int M,
;                                        const float* part, const float* cgate, float* hcout) {
;     ...
;             if (part != nullptr && row >= NLAT) {
;                 const size_t po = (size_t)(row - NLAT) * 1024 + i * 256 + lane * 4;
;                 const float4 p0 = *(const float4*)(part + po), p1 = *(const float4*)(part + (size_t)4096 * 1024 + po), cg = *(const float4*)(cgate + i * 256 + lane * 4);
;                 v[i].x += cg.x * (p0.x + p1.x); v[i].y += cg.y * (p0.y + p1.y); v[i].z += cg.z * (p0.z + p1.z); v[i].w += cg.w * (p0.w + p1.w);
;                 *(float4*)(hcout + po) = v[i];
;             }
;             ss += v[i].x * v[i].x + v[i].y * v[i].y + v[i].z * v[i].z + v[i].w * v[i].w; }
;         ss = wave_sum(ss);
;         const float rstd = rsqrtf(ss * (1.0f / 1024.0f) + EPS);
;         const float* mr = modl + (size_t)r * 6144;
; #pragma unroll
;         for (int i = 0; i < 4; ++i) {
;             const int k = i * 256 + lane * 4;
;             const float4 gg = *(const float4*)(g + k), scv = *(const float4*)(mr + sc_off + k), shv = *(const float4*)(mr + sh_off + k);
;             const float o0 = v[i].x * rstd * gg.x * (1.0f + scv.x) + shv.x, o1 = v[i].y * rstd * gg.y * (1.0f + scv.y) + shv.y;
;             const float o2 = v[i].z * rstd * gg.z * (1.0f + scv.z) + shv.z, o3 = v[i].w * rstd * gg.w * (1.0f + scv.w) + shv.w;
;             uint2 w; w.x = pk2(o0, o1); w.y = pk2(o2, o3);
;             *(uint2*)(A + (size_t)row * 1024 + k) = w;
;         }
	v_pk_add_f32 v[34:35], v[34:35], 1.0 op_sel_hi:[1,0]
	v_pk_add_f32 v[36:37], v[36:37], 1.0 op_sel_hi:[1,0]
	v_pk_add_f32 v[38:39], v[38:39], 1.0 op_sel_hi:[1,0]
	v_pk_add_f32 v[40:41], v[40:41], 1.0 op_sel_hi:[1,0]
	v_pk_add_f32 v[42:43], v[42:43], 1.0 op_sel_hi:[1,0]
	v_pk_add_f32 v[44:45], v[44:45], 1.0 op_sel_hi:[1,0]
	v_pk_add_f32 v[46:47], v[46:47], 1.0 op_sel_hi:[1,0]
	v_pk_add_f32 v[48:49], v[48:49], 1.0 op_sel_hi:[1,0]
	v_lshlrev_b32_e32 v146, 12, v50
	v_lshl_add_u32 v146, v240, 3, v146
	v_add_u32_e32 v146, 0x4000000, v146
	v_pk_mul_f32 v[156:157], v[156:157], v[204:205] op_sel_hi:[1,0]
	v_pk_mul_f32 v[158:159], v[158:159], v[204:205] op_sel_hi:[1,0]
	v_pk_mul_f32 v[156:157], v[188:189], v[156:157]
	v_pk_mul_f32 v[158:159], v[190:191], v[158:159]
	v_pk_fma_f32 v[156:157], v[34:35], v[156:157], v[224:225]
	v_pk_fma_f32 v[158:159], v[36:37], v[158:159], v[226:227]
	v_cvt_pk_bf16_f32 v156, v156, v157
	v_cvt_pk_bf16_f32 v157, v158, v159
	global_store_dwordx2 v146, v[156:157], s[66:67]
	v_pk_mul_f32 v[160:161], v[160:161], v[204:205] op_sel_hi:[1,0]
	v_pk_mul_f32 v[162:163], v[162:163], v[204:205] op_sel_hi:[1,0]
	v_pk_mul_f32 v[160:161], v[192:193], v[160:161]
	v_pk_mul_f32 v[162:163], v[194:195], v[162:163]
	v_pk_fma_f32 v[160:161], v[38:39], v[160:161], v[228:229]
	v_pk_fma_f32 v[162:163], v[40:41], v[162:163], v[230:231]
	v_cvt_pk_bf16_f32 v160, v160, v161
	v_cvt_pk_bf16_f32 v161, v162, v163
	global_store_dwordx2 v146, v[160:161], s[66:67] offset:512
	v_pk_mul_f32 v[164:165], v[164:165], v[204:205] op_sel_hi:[1,0]
	v_pk_mul_f32 v[166:167], v[166:167], v[204:205] op_sel_hi:[1,0]
	v_pk_mul_f32 v[164:165], v[196:197], v[164:165]
	v_pk_mul_f32 v[166:167], v[198:199], v[166:167]
	v_pk_fma_f32 v[164:165], v[42:43], v[164:165], v[232:233]
	v_pk_fma_f32 v[166:167], v[44:45], v[166:167], v[234:235]
	v_cvt_pk_bf16_f32 v164, v164, v165
	v_cvt_pk_bf16_f32 v165, v166, v167
	global_store_dwordx2 v146, v[164:165], s[66:67] offset:1024
	v_pk_mul_f32 v[168:169], v[168:169], v[204:205] op_sel_hi:[1,0]
	v_pk_mul_f32 v[170:171], v[170:171], v[204:205] op_sel_hi:[1,0]
	v_pk_mul_f32 v[168:169], v[200:201], v[168:169]
	v_pk_mul_f32 v[170:171], v[202:203], v[170:171]
	v_pk_fma_f32 v[168:169], v[46:47], v[168:169], v[236:237]
	v_pk_fma_f32 v[170:171], v[48:49], v[170:171], v[238:239]
	v_cvt_pk_bf16_f32 v168, v168, v169
	v_cvt_pk_bf16_f32 v169, v170, v171
	global_store_dwordx2 v146, v[168:169], s[66:67] offset:1536
	v_add_u32_e32 v146, 0x800, v146
	s_waitcnt vmcnt(8)
	v_pk_add_f32 v[112:113], v[112:113], v[128:129]
	v_pk_add_f32 v[114:115], v[114:115], v[130:131]
	v_pk_fma_f32 v[172:173], v[112:113], v[8:9], v[172:173]
	v_pk_fma_f32 v[174:175], v[114:115], v[10:11], v[174:175]
	global_store_dwordx4 v152, v[172:175], s[64:65]
	v_pk_add_f32 v[116:117], v[116:117], v[132:133]
	v_pk_add_f32 v[118:119], v[118:119], v[134:135]
	v_pk_fma_f32 v[176:177], v[116:117], v[52:53], v[176:177]
	v_pk_fma_f32 v[178:179], v[118:119], v[54:55], v[178:179]
	global_store_dwordx4 v152, v[176:179], s[64:65] offset:1024
	v_pk_add_f32 v[120:121], v[120:121], v[136:137]
	v_pk_add_f32 v[122:123], v[122:123], v[138:139]
	v_pk_fma_f32 v[180:181], v[120:121], v[60:61], v[180:181]
	v_pk_fma_f32 v[182:183], v[122:123], v[62:63], v[182:183]
	global_store_dwordx4 v152, v[180:183], s[64:65] offset:2048
	v_pk_add_f32 v[124:125], v[124:125], v[140:141]
	v_pk_add_f32 v[126:127], v[126:127], v[142:143]
	v_pk_fma_f32 v[184:185], v[124:125], v[64:65], v[184:185]
	v_pk_fma_f32 v[186:187], v[126:127], v[66:67], v[186:187]
	global_store_dwordx4 v152, v[184:187], s[64:65] offset:3072
	v_add_u32_e32 v152, 0x1000, v152
	v_pk_mul_f32 v[242:243], v[172:173], v[172:173]
	v_pk_mul_f32 v[244:245], v[176:177], v[176:177]
	v_pk_mul_f32 v[246:247], v[174:175], v[174:175]
	v_pk_mul_f32 v[248:249], v[178:179], v[178:179]
	v_add_f32_e32 v204, v245, v244
	v_add_f32_e32 v205, v243, v242
	v_add_f32_e32 v204, v248, v204
	v_add_f32_e32 v205, v246, v205
	v_add_f32_e32 v204, v249, v204
	v_add_f32_e32 v205, v247, v205
	v_pk_mul_f32 v[242:243], v[180:181], v[180:181]
	v_pk_mul_f32 v[244:245], v[184:185], v[184:185]
	v_pk_mul_f32 v[246:247], v[182:183], v[182:183]
	v_pk_mul_f32 v[248:249], v[186:187], v[186:187]
	v_add_f32_e32 v206, v243, v242
	v_add_f32_e32 v207, v245, v244
	v_add_f32_e32 v206, v246, v206
	v_add_f32_e32 v207, v248, v207
	v_add_f32_e32 v206, v247, v206
	v_add_f32_e32 v207, v249, v207
	v_add_f32_e32 v204, v205, v204
	v_add_f32_e32 v204, v204, v206
	v_add_f32_e32 v204, v204, v207
	ds_swizzle_b32 v205, v204 offset:swizzle(SWAP,1)
	s_waitcnt lgkmcnt(0)
	v_add_f32_e32 v204, v204, v205
	ds_swizzle_b32 v205, v204 offset:swizzle(SWAP,2)
	s_waitcnt lgkmcnt(0)
	v_add_f32_e32 v204, v204, v205
	ds_swizzle_b32 v205, v204 offset:swizzle(SWAP,4)
	s_waitcnt lgkmcnt(0)
	v_add_f32_e32 v204, v204, v205
	ds_swizzle_b32 v205, v204 offset:swizzle(SWAP,8)
	s_waitcnt lgkmcnt(0)
	v_add_f32_e32 v204, v204, v205
	ds_swizzle_b32 v205, v204 offset:swizzle(SWAP,16)
	s_waitcnt lgkmcnt(0)
; __device__ __forceinline__ unsigned pk2(float lo, float hi) { const g_f32x2 f = {lo, hi}; return __builtin_bit_cast(unsigned, __builtin_convertvector(f, g_bf16x2)); }
; #define PN_LOAD(dst, rw) do { const float* s_ = (rw) < NLAT ? hlat + (size_t)(rw) * 1024 : hctx + (size_t)((rw) - NLAT) * 1024; \
;         _Pragma("unroll") for (int i = 0; i < 4; ++i) dst[i] = *(const float4*)(s_ + i * 256 + lane * 4); } while (0)
; __device__ __forceinline__ void p_norm(const float* hlat, const float* hctx, const float* g, const float* modl, int sh_off, int sc_off, bf16_t* A, int M,
;                                        const float* part, const float* cgate, float* hcout) {
;     ...
;     if (row < M) PN_LOAD(v, row);
;     while (row < M) {
;         const int nrow = row + stride;
;         if (nrow < M) PN_LOAD(nv, nrow);
;         const int r = row < NLAT ? (row >> 11) : 16;
;         float ss = 0.f;
; #pragma unroll
;         for (int i = 0; i < 4; ++i) {
;             if (part != nullptr && row >= NLAT) {
;                 const size_t po = (size_t)(row - NLAT) * 1024 + i * 256 + lane * 4;
;                 const float4 p0 = *(const float4*)(part + po), p1 = *(const float4*)(part + (size_t)4096 * 1024 + po), cg = *(const float4*)(cgate + i * 256 + lane * 4);
;                 v[i].x += cg.x * (p0.x + p1.x); v[i].y += cg.y * (p0.y + p1.y); v[i].z += cg.z * (p0.z + p1.z); v[i].w += cg.w * (p0.w + p1.w);
;                 *(float4*)(hcout + po) = v[i];
;             }
;             ss += v[i].x * v[i].x + v[i].y * v[i].y + v[i].z * v[i].z + v[i].w * v[i].w; }
;         ss = wave_sum(ss);
;         const float rstd = rsqrtf(ss * (1.0f / 1024.0f) + EPS);
;         const float* mr = modl + (size_t)r * 6144;
; #pragma unroll
;         for (int i = 0; i < 4; ++i) {
;             const int k = i * 256 + lane * 4;
;             const float4 gg = *(const float4*)(g + k), scv = *(const float4*)(mr + sc_off + k), shv = *(const float4*)(mr + sh_off + k);
;             const float o0 = v[i].x * rstd * gg.x * (1.0f + scv.x) + shv.x, o1 = v[i].y * rstd * gg.y * (1.0f + scv.y) + shv.y;
;             const float o2 = v[i].z * rstd * gg.z * (1.0f + scv.z) + shv.z, o3 = v[i].w * rstd * gg.w * (1.0f + scv.w) + shv.w;
;             uint2 w; w.x = pk2(o0, o1); w.y = pk2(o2, o3);
;             *(uint2*)(A + (size_t)row * 1024 + k) = w;
;         }
	v_add_f32_e32 v204, v204, v205
	v_mov_b32_e32 v205, v204
	s_nop 1
	v_permlane32_swap_b32_e32 v204, v205
	v_add_f32_e32 v204, v204, v205
	v_mov_b32_e32 v205, 0x358637bd
	v_fmamk_f32 v204, v204, 0x3a800000, v205
	v_rsq_f32_e32 v204, v204
	s_nop 0
	v_pk_mul_f32 v[172:173], v[172:173], v[204:205] op_sel_hi:[1,0]
	v_pk_mul_f32 v[174:175], v[174:175], v[204:205] op_sel_hi:[1,0]
	v_pk_mul_f32 v[172:173], v[188:189], v[172:173]
	v_pk_mul_f32 v[174:175], v[190:191], v[174:175]
	v_pk_fma_f32 v[172:173], v[34:35], v[172:173], v[224:225]
	v_pk_fma_f32 v[174:175], v[36:37], v[174:175], v[226:227]
	v_cvt_pk_bf16_f32 v172, v172, v173
	v_cvt_pk_bf16_f32 v173, v174, v175
	global_store_dwordx2 v146, v[172:173], s[66:67]
	v_pk_mul_f32 v[176:177], v[176:177], v[204:205] op_sel_hi:[1,0]
	v_pk_mul_f32 v[178:179], v[178:179], v[204:205] op_sel_hi:[1,0]
	v_pk_mul_f32 v[176:177], v[192:193], v[176:177]
	v_pk_mul_f32 v[178:179], v[194:195], v[178:179]
	v_pk_fma_f32 v[176:177], v[38:39], v[176:177], v[228:229]
	v_pk_fma_f32 v[178:179], v[40:41], v[178:179], v[230:231]
	v_cvt_pk_bf16_f32 v176, v176, v177
	v_cvt_pk_bf16_f32 v177, v178, v179
	global_store_dwordx2 v146, v[176:177], s[66:67] offset:512
	v_pk_mul_f32 v[180:181], v[180:181], v[204:205] op_sel_hi:[1,0]
	v_pk_mul_f32 v[182:183], v[182:183], v[204:205] op_sel_hi:[1,0]
	v_pk_mul_f32 v[180:181], v[196:197], v[180:181]
	v_pk_mul_f32 v[182:183], v[198:199], v[182:183]
	v_pk_fma_f32 v[180:181], v[42:43], v[180:181], v[232:233]
	v_pk_fma_f32 v[182:183], v[44:45], v[182:183], v[234:235]
	v_cvt_pk_bf16_f32 v180, v180, v181
	v_cvt_pk_bf16_f32 v181, v182, v183
	global_store_dwordx2 v146, v[180:181], s[66:67] offset:1024
	v_pk_mul_f32 v[184:185], v[184:185], v[204:205] op_sel_hi:[1,0]
	v_pk_mul_f32 v[186:187], v[186:187], v[204:205] op_sel_hi:[1,0]
	v_pk_mul_f32 v[184:185], v[200:201], v[184:185]
	v_pk_mul_f32 v[186:187], v[202:203], v[186:187]
	v_pk_fma_f32 v[184:185], v[46:47], v[184:185], v[236:237]
	v_pk_fma_f32 v[186:187], v[48:49], v[186:187], v[238:239]
	v_cvt_pk_bf16_f32 v184, v184, v185
	v_cvt_pk_bf16_f32 v185, v186, v187
	global_store_dwordx2 v146, v[184:185], s[66:67] offset:1536
	v_add_u32_e32 v146, 0x800, v146
	s_branch .Lnorm_P1_end
.Lnorm_P1_alt:
	global_load_dwordx4 v[80:83], v144, s[46:47] nt
	global_load_dwordx4 v[84:87], v144, s[46:47] offset:1024 nt
	global_load_dwordx4 v[88:91], v144, s[46:47] offset:2048 nt
	global_load_dwordx4 v[92:95], v144, s[46:47] offset:3072 nt
	v_add_u32_e32 v144, 0x1000, v144
	global_load_dwordx4 v[34:37], v148, s[98:99]
	global_load_dwordx4 v[38:41], v148, s[98:99] offset:1024
	global_load_dwordx4 v[42:45], v148, s[98:99] offset:2048
	global_load_dwordx4 v[46:49], v148, s[98:99] offset:3072
	global_load_dwordx4 v[224:227], v148, s[50:51]
	global_load_dwordx4 v[228:231], v148, s[50:51] offset:1024
	global_load_dwordx4 v[232:235], v148, s[50:51] offset:2048
	global_load_dwordx4 v[236:239], v148, s[50:51] offset:3072
	global_load_dwordx4 v[188:191], v241, s[48:49]
	global_load_dwordx4 v[192:195], v241, s[48:49] offset:1024
	global_load_dwordx4 v[196:199], v241, s[48:49] offset:2048
	global_load_dwordx4 v[200:203], v241, s[48:49] offset:3072
	global_load_dwordx4 v[96:99], v144, s[46:47] nt
	global_load_dwordx4 v[100:103], v144, s[46:47] offset:1024 nt
	global_load_dwordx4 v[104:107], v144, s[46:47] offset:2048 nt
	global_load_dwordx4 v[108:111], v144, s[46:47] offset:3072 nt
	v_add_u32_e32 v144, 0x1000, v144
	global_load_dwordx4 v[112:115], v144, s[46:47] nt
	global_load_dwordx4 v[116:119], v144, s[46:47] offset:1024 nt
	global_load_dwordx4 v[120:123], v144, s[46:47] offset:2048 nt
	global_load_dwordx4 v[124:127], v144, s[46:47] offset:3072 nt
	v_add_u32_e32 v144, 0x1000, v144
	global_load_dwordx4 v[128:131], v144, s[46:47] nt
	global_load_dwordx4 v[132:135], v144, s[46:47] offset:1024 nt
	global_load_dwordx4 v[136:139], v144, s[46:47] offset:2048 nt
	global_load_dwordx4 v[140:143], v144, s[46:47] offset:3072 nt
	v_add_u32_e32 v144, 0x1000, v144
	global_load_dwordx4 v[156:159], v144, s[46:47] nt
	global_load_dwordx4 v[160:163], v144, s[46:47] offset:1024 nt
	global_load_dwordx4 v[164:167], v144, s[46:47] offset:2048 nt
	global_load_dwordx4 v[168:171], v144, s[46:47] offset:3072 nt
	v_add_u32_e32 v144, 0x1000, v144
	global_load_dwordx4 v[172:175], v144, s[46:47] nt
	global_load_dwordx4 v[176:179], v144, s[46:47] offset:1024 nt
	global_load_dwordx4 v[180:183], v144, s[46:47] offset:2048 nt
	global_load_dwordx4 v[184:187], v144, s[46:47] offset:3072 nt
	v_add_u32_e32 v144, 0x1000, v144
	s_waitcnt vmcnt(32)
	v_pk_mul_f32 v[242:243], v[80:81], v[80:81]
	v_pk_mul_f32 v[244:245], v[84:85], v[84:85]
	v_pk_mul_f32 v[246:247], v[82:83], v[82:83]
	v_pk_mul_f32 v[248:249], v[86:87], v[86:87]
	v_add_f32_e32 v204, v245, v244
	v_add_f32_e32 v205, v243, v242
	v_add_f32_e32 v204, v248, v204
	v_add_f32_e32 v205, v246, v205
	v_add_f32_e32 v204, v249, v204
	v_add_f32_e32 v205, v247, v205
	v_pk_mul_f32 v[242:243], v[88:89], v[88:89]
	v_pk_mul_f32 v[244:245], v[92:93], v[92:93]
	v_pk_mul_f32 v[246:247], v[90:91], v[90:91]
	v_pk_mul_f32 v[248:249], v[94:95], v[94:95]
	v_add_f32_e32 v206, v243, v242
	v_add_f32_e32 v207, v245, v244
	v_add_f32_e32 v206, v246, v206
	v_add_f32_e32 v207, v248, v207
	v_add_f32_e32 v206, v247, v206
	v_add_f32_e32 v207, v249, v207
	v_add_f32_e32 v204, v205, v204
	v_add_f32_e32 v204, v204, v206
	v_add_f32_e32 v204, v204, v207
	ds_swizzle_b32 v205, v204 offset:swizzle(SWAP,1)
	s_waitcnt lgkmcnt(0)
	v_add_f32_e32 v204, v204, v205
	ds_swizzle_b32 v205, v204 offset:swizzle(SWAP,2)
	s_waitcnt lgkmcnt(0)
	v_add_f32_e32 v204, v204, v205
	ds_swizzle_b32 v205, v204 offset:swizzle(SWAP,4)
	s_waitcnt lgkmcnt(0)
; __device__ __forceinline__ unsigned pk2(float lo, float hi) { const g_f32x2 f = {lo, hi}; return __builtin_bit_cast(unsigned, __builtin_convertvector(f, g_bf16x2)); }
; #define PN_LOAD(dst, rw) do { const float* s_ = (rw) < NLAT ? hlat + (size_t)(rw) * 1024 : hctx + (size_t)((rw) - NLAT) * 1024; \
;         _Pragma("unroll") for (int i = 0; i < 4; ++i) dst[i] = *(const float4*)(s_ + i * 256 + lane * 4); } while (0)
; __device__ __forceinline__ void p_norm(const float* hlat, const float* hctx, const float* g, const float* modl, int sh_off, int sc_off, bf16_t* A, int M,
;                                        const float* part, const float* cgate, float* hcout) {
;     ...
;     if (row < M) PN_LOAD(v, row);
;     while (row < M) {
;         const int nrow = row + stride;
;         if (nrow < M) PN_LOAD(nv, nrow);
;         const int r = row < NLAT ? (row >> 11) : 16;
;         float ss = 0.f;
; #pragma unroll
;         for (int i = 0; i < 4; ++i) {
;             if (part != nullptr && row >= NLAT) {
;                 const size_t po = (size_t)(row - NLAT) * 1024 + i * 256 + lane * 4;
;                 const float4 p0 = *(const float4*)(part + po), p1 = *(const float4*)(part + (size_t)4096 * 1024 + po), cg = *(const float4*)(cgate + i * 256 + lane * 4);
;                 v[i].x += cg.x * (p0.x + p1.x); v[i].y += cg.y * (p0.y + p1.y); v[i].z += cg.z * (p0.z + p1.z); v[i].w += cg.w * (p0.w + p1.w);
;                 *(float4*)(hcout + po) = v[i];
;             }
;             ss += v[i].x * v[i].x + v[i].y * v[i].y + v[i].z * v[i].z + v[i].w * v[i].w; }
;         ss = wave_sum(ss);
;         const float rstd = rsqrtf(ss * (1.0f / 1024.0f) + EPS);
;         const float* mr = modl + (size_t)r * 6144;
; #pragma unroll
;         for (int i = 0; i < 4; ++i) {
;             const int k = i * 256 + lane * 4;
;             const float4 gg = *(const float4*)(g + k), scv = *(const float4*)(mr + sc_off + k), shv = *(const float4*)(mr + sh_off + k);
;             const float o0 = v[i].x * rstd * gg.x * (1.0f + scv.x) + shv.x, o1 = v[i].y * rstd * gg.y * (1.0f + scv.y) + shv.y;
;             const float o2 = v[i].z * rstd * gg.z * (1.0f + scv.z) + shv.z, o3 = v[i].w * rstd * gg.w * (1.0f + scv.w) + shv.w;
;             uint2 w; w.x = pk2(o0, o1); w.y = pk2(o2, o3);
;             *(uint2*)(A + (size_t)row * 1024 + k) = w;
;         }
	v_add_f32_e32 v204, v204, v205
	ds_swizzle_b32 v205, v204 offset:swizzle(SWAP,8)
	s_waitcnt lgkmcnt(0)
	v_add_f32_e32 v204, v204, v205
	ds_swizzle_b32 v205, v204 offset:swizzle(SWAP,16)
	s_waitcnt lgkmcnt(0)
	v_add_f32_e32 v204, v204, v205
	v_mov_b32_e32 v205, v204
	s_nop 1
	v_permlane32_swap_b32_e32 v204, v205
	v_add_f32_e32 v204, v204, v205
	v_mov_b32_e32 v205, 0x358637bd
	v_fmamk_f32 v204, v204, 0x3a800000, v205
	v_rsq_f32_e32 v204, v204
	s_nop 0
	s_waitcnt vmcnt(20)
	v_pk_add_f32 v[34:35], v[34:35], 1.0 op_sel_hi:[1,0]
	v_pk_add_f32 v[36:37], v[36:37], 1.0 op_sel_hi:[1,0]
	v_pk_add_f32 v[38:39], v[38:39], 1.0 op_sel_hi:[1,0]
	v_pk_add_f32 v[40:41], v[40:41], 1.0 op_sel_hi:[1,0]
	v_pk_add_f32 v[42:43], v[42:43], 1.0 op_sel_hi:[1,0]
	v_pk_add_f32 v[44:45], v[44:45], 1.0 op_sel_hi:[1,0]
	v_pk_add_f32 v[46:47], v[46:47], 1.0 op_sel_hi:[1,0]
	v_pk_add_f32 v[48:49], v[48:49], 1.0 op_sel_hi:[1,0]
	v_pk_mul_f32 v[80:81], v[80:81], v[204:205] op_sel_hi:[1,0]
	v_pk_mul_f32 v[82:83], v[82:83], v[204:205] op_sel_hi:[1,0]
	v_pk_mul_f32 v[80:81], v[188:189], v[80:81]
	v_pk_mul_f32 v[82:83], v[190:191], v[82:83]
	v_pk_fma_f32 v[80:81], v[34:35], v[80:81], v[224:225]
	v_pk_fma_f32 v[82:83], v[36:37], v[82:83], v[226:227]
	v_cvt_pk_bf16_f32 v80, v80, v81
	v_cvt_pk_bf16_f32 v81, v82, v83
	global_store_dwordx2 v146, v[80:81], s[66:67]
	v_pk_mul_f32 v[84:85], v[84:85], v[204:205] op_sel_hi:[1,0]
	v_pk_mul_f32 v[86:87], v[86:87], v[204:205] op_sel_hi:[1,0]
	v_pk_mul_f32 v[84:85], v[192:193], v[84:85]
	v_pk_mul_f32 v[86:87], v[194:195], v[86:87]
	v_pk_fma_f32 v[84:85], v[38:39], v[84:85], v[228:229]
	v_pk_fma_f32 v[86:87], v[40:41], v[86:87], v[230:231]
	v_cvt_pk_bf16_f32 v84, v84, v85
	v_cvt_pk_bf16_f32 v85, v86, v87
	global_store_dwordx2 v146, v[84:85], s[66:67] offset:512
	v_pk_mul_f32 v[88:89], v[88:89], v[204:205] op_sel_hi:[1,0]
	v_pk_mul_f32 v[90:91], v[90:91], v[204:205] op_sel_hi:[1,0]
	v_pk_mul_f32 v[88:89], v[196:197], v[88:89]
	v_pk_mul_f32 v[90:91], v[198:199], v[90:91]
	v_pk_fma_f32 v[88:89], v[42:43], v[88:89], v[232:233]
	v_pk_fma_f32 v[90:91], v[44:45], v[90:91], v[234:235]
	v_cvt_pk_bf16_f32 v88, v88, v89
	v_cvt_pk_bf16_f32 v89, v90, v91
	global_store_dwordx2 v146, v[88:89], s[66:67] offset:1024
	v_pk_mul_f32 v[92:93], v[92:93], v[204:205] op_sel_hi:[1,0]
	v_pk_mul_f32 v[94:95], v[94:95], v[204:205] op_sel_hi:[1,0]
	v_pk_mul_f32 v[92:93], v[200:201], v[92:93]
	v_pk_mul_f32 v[94:95], v[202:203], v[94:95]
	v_pk_fma_f32 v[92:93], v[46:47], v[92:93], v[236:237]
	v_pk_fma_f32 v[94:95], v[48:49], v[94:95], v[238:239]
	v_cvt_pk_bf16_f32 v92, v92, v93
	v_cvt_pk_bf16_f32 v93, v94, v95
	global_store_dwordx2 v146, v[92:93], s[66:67] offset:1536
	v_add_u32_e32 v146, 0x800, v146
	global_load_dwordx4 v[80:83], v144, s[46:47] nt
	global_load_dwordx4 v[84:87], v144, s[46:47] offset:1024 nt
	global_load_dwordx4 v[88:91], v144, s[46:47] offset:2048 nt
	global_load_dwordx4 v[92:95], v144, s[46:47] offset:3072 nt
	v_add_u32_e32 v144, 0x1000, v144
	s_waitcnt vmcnt(24)
	v_pk_mul_f32 v[242:243], v[96:97], v[96:97]
	v_pk_mul_f32 v[244:245], v[100:101], v[100:101]
	v_pk_mul_f32 v[246:247], v[98:99], v[98:99]
	v_pk_mul_f32 v[248:249], v[102:103], v[102:103]
	v_add_f32_e32 v204, v245, v244
	v_add_f32_e32 v205, v243, v242
	v_add_f32_e32 v204, v248, v204
	v_add_f32_e32 v205, v246, v205
	v_add_f32_e32 v204, v249, v204
	v_add_f32_e32 v205, v247, v205
	v_pk_mul_f32 v[242:243], v[104:105], v[104:105]
	v_pk_mul_f32 v[244:245], v[108:109], v[108:109]
	v_pk_mul_f32 v[246:247], v[106:107], v[106:107]
	v_pk_mul_f32 v[248:249], v[110:111], v[110:111]
	v_add_f32_e32 v206, v243, v242
	v_add_f32_e32 v207, v245, v244
	v_add_f32_e32 v206, v246, v206
	v_add_f32_e32 v207, v248, v207
	v_add_f32_e32 v206, v247, v206
	v_add_f32_e32 v207, v249, v207
	v_add_f32_e32 v204, v205, v204
	v_add_f32_e32 v204, v204, v206
	v_add_f32_e32 v204, v204, v207
	ds_swizzle_b32 v205, v204 offset:swizzle(SWAP,1)
	s_waitcnt lgkmcnt(0)
	v_add_f32_e32 v204, v204, v205
	ds_swizzle_b32 v205, v204 offset:swizzle(SWAP,2)
	s_waitcnt lgkmcnt(0)
	v_add_f32_e32 v204, v204, v205
	ds_swizzle_b32 v205, v204 offset:swizzle(SWAP,4)
	s_waitcnt lgkmcnt(0)
	v_add_f32_e32 v204, v204, v205
	ds_swizzle_b32 v205, v204 offset:swizzle(SWAP,8)
	s_waitcnt lgkmcnt(0)
	v_add_f32_e32 v204, v204, v205
	ds_swizzle_b32 v205, v204 offset:swizzle(SWAP,16)
	s_waitcnt lgkmcnt(0)
	v_add_f32_e32 v204, v204, v205
	v_mov_b32_e32 v205, v204
	s_nop 1
	v_permlane32_swap_b32_e32 v204, v205
	v_add_f32_e32 v204, v204, v205
	v_mov_b32_e32 v205, 0x358637bd
	v_fmamk_f32 v204, v204, 0x3a800000, v205
	v_rsq_f32_e32 v204, v204
	s_nop 0
	v_pk_mul_f32 v[96:97], v[96:97], v[204:205] op_sel_hi:[1,0]
	v_pk_mul_f32 v[98:99], v[98:99], v[204:205] op_sel_hi:[1,0]
	v_pk_mul_f32 v[96:97], v[188:189], v[96:97]
	v_pk_mul_f32 v[98:99], v[190:191], v[98:99]
	v_pk_fma_f32 v[96:97], v[34:35], v[96:97], v[224:225]
	v_pk_fma_f32 v[98:99], v[36:37], v[98:99], v[226:227]
	v_cvt_pk_bf16_f32 v96, v96, v97
	v_cvt_pk_bf16_f32 v97, v98, v99
	global_store_dwordx2 v146, v[96:97], s[66:67]
	v_pk_mul_f32 v[100:101], v[100:101], v[204:205] op_sel_hi:[1,0]
	v_pk_mul_f32 v[102:103], v[102:103], v[204:205] op_sel_hi:[1,0]
	v_pk_mul_f32 v[100:101], v[192:193], v[100:101]
	v_pk_mul_f32 v[102:103], v[194:195], v[102:103]
	v_pk_fma_f32 v[100:101], v[38:39], v[100:101], v[228:229]
	v_pk_fma_f32 v[102:103], v[40:41], v[102:103], v[230:231]
	v_cvt_pk_bf16_f32 v100, v100, v101
	v_cvt_pk_bf16_f32 v101, v102, v103
	global_store_dwordx2 v146, v[100:101], s[66:67] offset:512
	v_pk_mul_f32 v[104:105], v[104:105], v[204:205] op_sel_hi:[1,0]
	v_pk_mul_f32 v[106:107], v[106:107], v[204:205] op_sel_hi:[1,0]
	v_pk_mul_f32 v[104:105], v[196:197], v[104:105]
	v_pk_mul_f32 v[106:107], v[198:199], v[106:107]
	v_pk_fma_f32 v[104:105], v[42:43], v[104:105], v[232:233]
	v_pk_fma_f32 v[106:107], v[44:45], v[106:107], v[234:235]
	v_cvt_pk_bf16_f32 v104, v104, v105
	v_cvt_pk_bf16_f32 v105, v106, v107
	global_store_dwordx2 v146, v[104:105], s[66:67] offset:1024
	v_pk_mul_f32 v[108:109], v[108:109], v[204:205] op_sel_hi:[1,0]
	v_pk_mul_f32 v[110:111], v[110:111], v[204:205] op_sel_hi:[1,0]
	v_pk_mul_f32 v[108:109], v[200:201], v[108:109]
	v_pk_mul_f32 v[110:111], v[202:203], v[110:111]
	v_pk_fma_f32 v[108:109], v[46:47], v[108:109], v[236:237]
	v_pk_fma_f32 v[110:111], v[48:49], v[110:111], v[238:239]
	v_cvt_pk_bf16_f32 v108, v108, v109
	v_cvt_pk_bf16_f32 v109, v110, v111
	global_store_dwordx2 v146, v[108:109], s[66:67] offset:1536
	v_add_u32_e32 v146, 0x800, v146
	global_load_dwordx4 v[96:99], v144, s[46:47] nt
	global_load_dwordx4 v[100:103], v144, s[46:47] offset:1024 nt
	global_load_dwordx4 v[104:107], v144, s[46:47] offset:2048 nt
	global_load_dwordx4 v[108:111], v144, s[46:47] offset:3072 nt
	v_add_u32_e32 v144, 0x1000, v144
	s_waitcnt vmcnt(28)
; __device__ __forceinline__ unsigned pk2(float lo, float hi) { const g_f32x2 f = {lo, hi}; return __builtin_bit_cast(unsigned, __builtin_convertvector(f, g_bf16x2)); }
; #define PN_LOAD(dst, rw) do { const float* s_ = (rw) < NLAT ? hlat + (size_t)(rw) * 1024 : hctx + (size_t)((rw) - NLAT) * 1024; \
;         _Pragma("unroll") for (int i = 0; i < 4; ++i) dst[i] = *(const float4*)(s_ + i * 256 + lane * 4); } while (0)
; __device__ __forceinline__ void p_norm(const float* hlat, const float* hctx, const float* g, const float* modl, int sh_off, int sc_off, bf16_t* A, int M,
;                                        const float* part, const float* cgate, float* hcout) {
;     ...
;     if (row < M) PN_LOAD(v, row);
;     while (row < M) {
;         const int nrow = row + stride;
;         if (nrow < M) PN_LOAD(nv, nrow);
;         const int r = row < NLAT ? (row >> 11) : 16;
;         float ss = 0.f;
; #pragma unroll
;         for (int i = 0; i < 4; ++i) {
;             if (part != nullptr && row >= NLAT) {
;                 const size_t po = (size_t)(row - NLAT) * 1024 + i * 256 + lane * 4;
;                 const float4 p0 = *(const float4*)(part + po), p1 = *(const float4*)(part + (size_t)4096 * 1024 + po), cg = *(const float4*)(cgate + i * 256 + lane * 4);
;                 v[i].x += cg.x * (p0.x + p1.x); v[i].y += cg.y * (p0.y + p1.y); v[i].z += cg.z * (p0.z + p1.z); v[i].w += cg.w * (p0.w + p1.w);
;                 *(float4*)(hcout + po) = v[i];
;             }
;             ss += v[i].x * v[i].x + v[i].y * v[i].y + v[i].z * v[i].z + v[i].w * v[i].w; }
;         ss = wave_sum(ss);
;         const float rstd = rsqrtf(ss * (1.0f / 1024.0f) + EPS);
;         const float* mr = modl + (size_t)r * 6144;
; #pragma unroll
;         for (int i = 0; i < 4; ++i) {
;             const int k = i * 256 + lane * 4;
;             const float4 gg = *(const float4*)(g + k), scv = *(const float4*)(mr + sc_off + k), shv = *(const float4*)(mr + sh_off + k);
;             const float o0 = v[i].x * rstd * gg.x * (1.0f + scv.x) + shv.x, o1 = v[i].y * rstd * gg.y * (1.0f + scv.y) + shv.y;
;             const float o2 = v[i].z * rstd * gg.z * (1.0f + scv.z) + shv.z, o3 = v[i].w * rstd * gg.w * (1.0f + scv.w) + shv.w;
;             uint2 w; w.x = pk2(o0, o1); w.y = pk2(o2, o3);
;             *(uint2*)(A + (size_t)row * 1024 + k) = w;
;         }
	v_pk_mul_f32 v[242:243], v[112:113], v[112:113]
	v_pk_mul_f32 v[244:245], v[116:117], v[116:117]
	v_pk_mul_f32 v[246:247], v[114:115], v[114:115]
	v_pk_mul_f32 v[248:249], v[118:119], v[118:119]
	v_add_f32_e32 v204, v245, v244
	v_add_f32_e32 v205, v243, v242
	v_add_f32_e32 v204, v248, v204
	v_add_f32_e32 v205, v246, v205
	v_add_f32_e32 v204, v249, v204
	v_add_f32_e32 v205, v247, v205
	v_pk_mul_f32 v[242:243], v[120:121], v[120:121]
	v_pk_mul_f32 v[244:245], v[124:125], v[124:125]
	v_pk_mul_f32 v[246:247], v[122:123], v[122:123]
	v_pk_mul_f32 v[248:249], v[126:127], v[126:127]
	v_add_f32_e32 v206, v243, v242
	v_add_f32_e32 v207, v245, v244
	v_add_f32_e32 v206, v246, v206
	v_add_f32_e32 v207, v248, v207
	v_add_f32_e32 v206, v247, v206
	v_add_f32_e32 v207, v249, v207
	v_add_f32_e32 v204, v205, v204
	v_add_f32_e32 v204, v204, v206
	v_add_f32_e32 v204, v204, v207
	ds_swizzle_b32 v205, v204 offset:swizzle(SWAP,1)
	s_waitcnt lgkmcnt(0)
	v_add_f32_e32 v204, v204, v205
	ds_swizzle_b32 v205, v204 offset:swizzle(SWAP,2)
	s_waitcnt lgkmcnt(0)
	v_add_f32_e32 v204, v204, v205
	ds_swizzle_b32 v205, v204 offset:swizzle(SWAP,4)
	s_waitcnt lgkmcnt(0)
	v_add_f32_e32 v204, v204, v205
	ds_swizzle_b32 v205, v204 offset:swizzle(SWAP,8)
	s_waitcnt lgkmcnt(0)
	v_add_f32_e32 v204, v204, v205
	ds_swizzle_b32 v205, v204 offset:swizzle(SWAP,16)
	s_waitcnt lgkmcnt(0)
	v_add_f32_e32 v204, v204, v205
	v_mov_b32_e32 v205, v204
	s_nop 1
	v_permlane32_swap_b32_e32 v204, v205
	v_add_f32_e32 v204, v204, v205
	v_mov_b32_e32 v205, 0x358637bd
	v_fmamk_f32 v204, v204, 0x3a800000, v205
	v_rsq_f32_e32 v204, v204
	s_nop 0
	v_pk_mul_f32 v[112:113], v[112:113], v[204:205] op_sel_hi:[1,0]
	v_pk_mul_f32 v[114:115], v[114:115], v[204:205] op_sel_hi:[1,0]
	v_pk_mul_f32 v[112:113], v[188:189], v[112:113]
	v_pk_mul_f32 v[114:115], v[190:191], v[114:115]
	v_pk_fma_f32 v[112:113], v[34:35], v[112:113], v[224:225]
	v_pk_fma_f32 v[114:115], v[36:37], v[114:115], v[226:227]
	v_cvt_pk_bf16_f32 v112, v112, v113
	v_cvt_pk_bf16_f32 v113, v114, v115
	global_store_dwordx2 v146, v[112:113], s[66:67]
	v_pk_mul_f32 v[116:117], v[116:117], v[204:205] op_sel_hi:[1,0]
	v_pk_mul_f32 v[118:119], v[118:119], v[204:205] op_sel_hi:[1,0]
	v_pk_mul_f32 v[116:117], v[192:193], v[116:117]
	v_pk_mul_f32 v[118:119], v[194:195], v[118:119]
	v_pk_fma_f32 v[116:117], v[38:39], v[116:117], v[228:229]
	v_pk_fma_f32 v[118:119], v[40:41], v[118:119], v[230:231]
	v_cvt_pk_bf16_f32 v116, v116, v117
	v_cvt_pk_bf16_f32 v117, v118, v119
	global_store_dwordx2 v146, v[116:117], s[66:67] offset:512
	v_pk_mul_f32 v[120:121], v[120:121], v[204:205] op_sel_hi:[1,0]
	v_pk_mul_f32 v[122:123], v[122:123], v[204:205] op_sel_hi:[1,0]
	v_pk_mul_f32 v[120:121], v[196:197], v[120:121]
	v_pk_mul_f32 v[122:123], v[198:199], v[122:123]
	v_pk_fma_f32 v[120:121], v[42:43], v[120:121], v[232:233]
	v_pk_fma_f32 v[122:123], v[44:45], v[122:123], v[234:235]
	v_cvt_pk_bf16_f32 v120, v120, v121
	v_cvt_pk_bf16_f32 v121, v122, v123
	global_store_dwordx2 v146, v[120:121], s[66:67] offset:1024
	v_pk_mul_f32 v[124:125], v[124:125], v[204:205] op_sel_hi:[1,0]
	v_pk_mul_f32 v[126:127], v[126:127], v[204:205] op_sel_hi:[1,0]
	v_pk_mul_f32 v[124:125], v[200:201], v[124:125]
	v_pk_mul_f32 v[126:127], v[202:203], v[126:127]
	v_pk_fma_f32 v[124:125], v[46:47], v[124:125], v[236:237]
	v_pk_fma_f32 v[126:127], v[48:49], v[126:127], v[238:239]
	v_cvt_pk_bf16_f32 v124, v124, v125
	v_cvt_pk_bf16_f32 v125, v126, v127
	global_store_dwordx2 v146, v[124:125], s[66:67] offset:1536
	v_add_u32_e32 v146, 0x800, v146
	global_load_dwordx4 v[112:115], v144, s[46:47] nt
	global_load_dwordx4 v[116:119], v144, s[46:47] offset:1024 nt
	global_load_dwordx4 v[120:123], v144, s[46:47] offset:2048 nt
	global_load_dwordx4 v[124:127], v144, s[46:47] offset:3072 nt
	v_add_u32_e32 v144, 0x1000, v144
	s_waitcnt vmcnt(32)
	v_pk_mul_f32 v[242:243], v[128:129], v[128:129]
	v_pk_mul_f32 v[244:245], v[132:133], v[132:133]
	v_pk_mul_f32 v[246:247], v[130:131], v[130:131]
	v_pk_mul_f32 v[248:249], v[134:135], v[134:135]
	v_add_f32_e32 v204, v245, v244
	v_add_f32_e32 v205, v243, v242
	v_add_f32_e32 v204, v248, v204
	v_add_f32_e32 v205, v246, v205
	v_add_f32_e32 v204, v249, v204
	v_add_f32_e32 v205, v247, v205
	v_pk_mul_f32 v[242:243], v[136:137], v[136:137]
	v_pk_mul_f32 v[244:245], v[140:141], v[140:141]
	v_pk_mul_f32 v[246:247], v[138:139], v[138:139]
	v_pk_mul_f32 v[248:249], v[142:143], v[142:143]
	v_add_f32_e32 v206, v243, v242
	v_add_f32_e32 v207, v245, v244
	v_add_f32_e32 v206, v246, v206
	v_add_f32_e32 v207, v248, v207
	v_add_f32_e32 v206, v247, v206
	v_add_f32_e32 v207, v249, v207
	v_add_f32_e32 v204, v205, v204
	v_add_f32_e32 v204, v204, v206
	v_add_f32_e32 v204, v204, v207
	ds_swizzle_b32 v205, v204 offset:swizzle(SWAP,1)
	s_waitcnt lgkmcnt(0)
	v_add_f32_e32 v204, v204, v205
	ds_swizzle_b32 v205, v204 offset:swizzle(SWAP,2)
	s_waitcnt lgkmcnt(0)
	v_add_f32_e32 v204, v204, v205
	ds_swizzle_b32 v205, v204 offset:swizzle(SWAP,4)
	s_waitcnt lgkmcnt(0)
	v_add_f32_e32 v204, v204, v205
	ds_swizzle_b32 v205, v204 offset:swizzle(SWAP,8)
	s_waitcnt lgkmcnt(0)
	v_add_f32_e32 v204, v204, v205
	ds_swizzle_b32 v205, v204 offset:swizzle(SWAP,16)
	s_waitcnt lgkmcnt(0)
; __device__ __forceinline__ unsigned pk2(float lo, float hi) { const g_f32x2 f = {lo, hi}; return __builtin_bit_cast(unsigned, __builtin_convertvector(f, g_bf16x2)); }
; #define PN_LOAD(dst, rw) do { const float* s_ = (rw) < NLAT ? hlat + (size_t)(rw) * 1024 : hctx + (size_t)((rw) - NLAT) * 1024; \
;         _Pragma("unroll") for (int i = 0; i < 4; ++i) dst[i] = *(const float4*)(s_ + i * 256 + lane * 4); } while (0)
; __device__ __forceinline__ void p_norm(const float* hlat, const float* hctx, const float* g, const float* modl, int sh_off, int sc_off, bf16_t* A, int M,
;                                        const float* part, const float* cgate, float* hcout) {
;     ...
;     if (row < M) PN_LOAD(v, row);
;     while (row < M) {
;         const int nrow = row + stride;
;         if (nrow < M) PN_LOAD(nv, nrow);
;         const int r = row < NLAT ? (row >> 11) : 16;
;         float ss = 0.f;
; #pragma unroll
;         for (int i = 0; i < 4; ++i) {
;             if (part != nullptr && row >= NLAT) {
;                 const size_t po = (size_t)(row - NLAT) * 1024 + i * 256 + lane * 4;
;                 const float4 p0 = *(const float4*)(part + po), p1 = *(const float4*)(part + (size_t)4096 * 1024 + po), cg = *(const float4*)(cgate + i * 256 + lane * 4);
;                 v[i].x += cg.x * (p0.x + p1.x); v[i].y += cg.y * (p0.y + p1.y); v[i].z += cg.z * (p0.z + p1.z); v[i].w += cg.w * (p0.w + p1.w);
;                 *(float4*)(hcout + po) = v[i];
;             }
;             ss += v[i].x * v[i].x + v[i].y * v[i].y + v[i].z * v[i].z + v[i].w * v[i].w; }
;         ss = wave_sum(ss);
;         const float rstd = rsqrtf(ss * (1.0f / 1024.0f) + EPS);
;         const float* mr = modl + (size_t)r * 6144;
; #pragma unroll
;         for (int i = 0; i < 4; ++i) {
;             const int k = i * 256 + lane * 4;
;             const float4 gg = *(const float4*)(g + k), scv = *(const float4*)(mr + sc_off + k), shv = *(const float4*)(mr + sh_off + k);
;             const float o0 = v[i].x * rstd * gg.x * (1.0f + scv.x) + shv.x, o1 = v[i].y * rstd * gg.y * (1.0f + scv.y) + shv.y;
;             const float o2 = v[i].z * rstd * gg.z * (1.0f + scv.z) + shv.z, o3 = v[i].w * rstd * gg.w * (1.0f + scv.w) + shv.w;
;             uint2 w; w.x = pk2(o0, o1); w.y = pk2(o2, o3);
;             *(uint2*)(A + (size_t)row * 1024 + k) = w;
;         }
	v_add_f32_e32 v204, v204, v205
	v_mov_b32_e32 v205, v204
	s_nop 1
	v_permlane32_swap_b32_e32 v204, v205
	v_add_f32_e32 v204, v204, v205
	v_mov_b32_e32 v205, 0x358637bd
	v_fmamk_f32 v204, v204, 0x3a800000, v205
	v_rsq_f32_e32 v204, v204
	s_nop 0
	v_pk_mul_f32 v[128:129], v[128:129], v[204:205] op_sel_hi:[1,0]
	v_pk_mul_f32 v[130:131], v[130:131], v[204:205] op_sel_hi:[1,0]
	v_pk_mul_f32 v[128:129], v[188:189], v[128:129]
	v_pk_mul_f32 v[130:131], v[190:191], v[130:131]
	v_pk_fma_f32 v[128:129], v[34:35], v[128:129], v[224:225]
	v_pk_fma_f32 v[130:131], v[36:37], v[130:131], v[226:227]
	v_cvt_pk_bf16_f32 v128, v128, v129
	v_cvt_pk_bf16_f32 v129, v130, v131
	global_store_dwordx2 v146, v[128:129], s[66:67]
	v_pk_mul_f32 v[132:133], v[132:133], v[204:205] op_sel_hi:[1,0]
	v_pk_mul_f32 v[134:135], v[134:135], v[204:205] op_sel_hi:[1,0]
	v_pk_mul_f32 v[132:133], v[192:193], v[132:133]
	v_pk_mul_f32 v[134:135], v[194:195], v[134:135]
	v_pk_fma_f32 v[132:133], v[38:39], v[132:133], v[228:229]
	v_pk_fma_f32 v[134:135], v[40:41], v[134:135], v[230:231]
	v_cvt_pk_bf16_f32 v132, v132, v133
	v_cvt_pk_bf16_f32 v133, v134, v135
	global_store_dwordx2 v146, v[132:133], s[66:67] offset:512
	v_pk_mul_f32 v[136:137], v[136:137], v[204:205] op_sel_hi:[1,0]
	v_pk_mul_f32 v[138:139], v[138:139], v[204:205] op_sel_hi:[1,0]
	v_pk_mul_f32 v[136:137], v[196:197], v[136:137]
	v_pk_mul_f32 v[138:139], v[198:199], v[138:139]
	v_pk_fma_f32 v[136:137], v[42:43], v[136:137], v[232:233]
	v_pk_fma_f32 v[138:139], v[44:45], v[138:139], v[234:235]
	v_cvt_pk_bf16_f32 v136, v136, v137
	v_cvt_pk_bf16_f32 v137, v138, v139
	global_store_dwordx2 v146, v[136:137], s[66:67] offset:1024
	v_pk_mul_f32 v[140:141], v[140:141], v[204:205] op_sel_hi:[1,0]
	v_pk_mul_f32 v[142:143], v[142:143], v[204:205] op_sel_hi:[1,0]
	v_pk_mul_f32 v[140:141], v[200:201], v[140:141]
	v_pk_mul_f32 v[142:143], v[202:203], v[142:143]
	v_pk_fma_f32 v[140:141], v[46:47], v[140:141], v[236:237]
	v_pk_fma_f32 v[142:143], v[48:49], v[142:143], v[238:239]
	v_cvt_pk_bf16_f32 v140, v140, v141
	v_cvt_pk_bf16_f32 v141, v142, v143
	global_store_dwordx2 v146, v[140:141], s[66:67] offset:1536
	v_add_u32_e32 v146, 0x800, v146
	global_load_dwordx4 v[128:131], v144, s[46:47] nt
	global_load_dwordx4 v[132:135], v144, s[46:47] offset:1024 nt
	global_load_dwordx4 v[136:139], v144, s[46:47] offset:2048 nt
	global_load_dwordx4 v[140:143], v144, s[46:47] offset:3072 nt
	v_add_u32_e32 v144, 0x1000, v144
	s_waitcnt vmcnt(36)
	v_pk_mul_f32 v[242:243], v[156:157], v[156:157]
	v_pk_mul_f32 v[244:245], v[160:161], v[160:161]
	v_pk_mul_f32 v[246:247], v[158:159], v[158:159]
	v_pk_mul_f32 v[248:249], v[162:163], v[162:163]
	v_add_f32_e32 v204, v245, v244
	v_add_f32_e32 v205, v243, v242
	v_add_f32_e32 v204, v248, v204
	v_add_f32_e32 v205, v246, v205
	v_add_f32_e32 v204, v249, v204
	v_add_f32_e32 v205, v247, v205
	v_pk_mul_f32 v[242:243], v[164:165], v[164:165]
	v_pk_mul_f32 v[244:245], v[168:169], v[168:169]
	v_pk_mul_f32 v[246:247], v[166:167], v[166:167]
	v_pk_mul_f32 v[248:249], v[170:171], v[170:171]
	v_add_f32_e32 v206, v243, v242
	v_add_f32_e32 v207, v245, v244
	v_add_f32_e32 v206, v246, v206
	v_add_f32_e32 v207, v248, v207
	v_add_f32_e32 v206, v247, v206
	v_add_f32_e32 v207, v249, v207
	v_add_f32_e32 v204, v205, v204
	v_add_f32_e32 v204, v204, v206
	v_add_f32_e32 v204, v204, v207
	ds_swizzle_b32 v205, v204 offset:swizzle(SWAP,1)
	s_waitcnt lgkmcnt(0)
	v_add_f32_e32 v204, v204, v205
	ds_swizzle_b32 v205, v204 offset:swizzle(SWAP,2)
	s_waitcnt lgkmcnt(0)
	v_add_f32_e32 v204, v204, v205
	ds_swizzle_b32 v205, v204 offset:swizzle(SWAP,4)
	s_waitcnt lgkmcnt(0)
	v_add_f32_e32 v204, v204, v205
	ds_swizzle_b32 v205, v204 offset:swizzle(SWAP,8)
	s_waitcnt lgkmcnt(0)
	v_add_f32_e32 v204, v204, v205
	ds_swizzle_b32 v205, v204 offset:swizzle(SWAP,16)
	s_waitcnt lgkmcnt(0)
	v_add_f32_e32 v204, v204, v205
	v_mov_b32_e32 v205, v204
	s_nop 1
	v_permlane32_swap_b32_e32 v204, v205
	v_add_f32_e32 v204, v204, v205
	v_mov_b32_e32 v205, 0x358637bd
	v_fmamk_f32 v204, v204, 0x3a800000, v205
	v_rsq_f32_e32 v204, v204
	s_nop 0
	v_pk_mul_f32 v[156:157], v[156:157], v[204:205] op_sel_hi:[1,0]
	v_pk_mul_f32 v[158:159], v[158:159], v[204:205] op_sel_hi:[1,0]
	v_pk_mul_f32 v[156:157], v[188:189], v[156:157]
	v_pk_mul_f32 v[158:159], v[190:191], v[158:159]
	v_pk_fma_f32 v[156:157], v[34:35], v[156:157], v[224:225]
	v_pk_fma_f32 v[158:159], v[36:37], v[158:159], v[226:227]
	v_cvt_pk_bf16_f32 v156, v156, v157
	v_cvt_pk_bf16_f32 v157, v158, v159
	global_store_dwordx2 v146, v[156:157], s[66:67]
	v_pk_mul_f32 v[160:161], v[160:161], v[204:205] op_sel_hi:[1,0]
	v_pk_mul_f32 v[162:163], v[162:163], v[204:205] op_sel_hi:[1,0]
	v_pk_mul_f32 v[160:161], v[192:193], v[160:161]
	v_pk_mul_f32 v[162:163], v[194:195], v[162:163]
	v_pk_fma_f32 v[160:161], v[38:39], v[160:161], v[228:229]
	v_pk_fma_f32 v[162:163], v[40:41], v[162:163], v[230:231]
	v_cvt_pk_bf16_f32 v160, v160, v161
	v_cvt_pk_bf16_f32 v161, v162, v163
	global_store_dwordx2 v146, v[160:161], s[66:67] offset:512
	v_pk_mul_f32 v[164:165], v[164:165], v[204:205] op_sel_hi:[1,0]
	v_pk_mul_f32 v[166:167], v[166:167], v[204:205] op_sel_hi:[1,0]
	v_pk_mul_f32 v[164:165], v[196:197], v[164:165]
	v_pk_mul_f32 v[166:167], v[198:199], v[166:167]
	v_pk_fma_f32 v[164:165], v[42:43], v[164:165], v[232:233]
	v_pk_fma_f32 v[166:167], v[44:45], v[166:167], v[234:235]
	v_cvt_pk_bf16_f32 v164, v164, v165
	v_cvt_pk_bf16_f32 v165, v166, v167
	global_store_dwordx2 v146, v[164:165], s[66:67] offset:1024
	v_pk_mul_f32 v[168:169], v[168:169], v[204:205] op_sel_hi:[1,0]
	v_pk_mul_f32 v[170:171], v[170:171], v[204:205] op_sel_hi:[1,0]
	v_pk_mul_f32 v[168:169], v[200:201], v[168:169]
	v_pk_mul_f32 v[170:171], v[202:203], v[170:171]
	v_pk_fma_f32 v[168:169], v[46:47], v[168:169], v[236:237]
	v_pk_fma_f32 v[170:171], v[48:49], v[170:171], v[238:239]
	v_cvt_pk_bf16_f32 v168, v168, v169
	v_cvt_pk_bf16_f32 v169, v170, v171
	global_store_dwordx2 v146, v[168:169], s[66:67] offset:1536
	v_add_u32_e32 v146, 0x800, v146
	global_load_dwordx4 v[156:159], v144, s[46:47] nt
	global_load_dwordx4 v[160:163], v144, s[46:47] offset:1024 nt
	global_load_dwordx4 v[164:167], v144, s[46:47] offset:2048 nt
	global_load_dwordx4 v[168:171], v144, s[46:47] offset:3072 nt
	v_add_u32_e32 v144, 0x1000, v144
	s_waitcnt vmcnt(40)
; __device__ __forceinline__ unsigned pk2(float lo, float hi) { const g_f32x2 f = {lo, hi}; return __builtin_bit_cast(unsigned, __builtin_convertvector(f, g_bf16x2)); }
; #define PN_LOAD(dst, rw) do { const float* s_ = (rw) < NLAT ? hlat + (size_t)(rw) * 1024 : hctx + (size_t)((rw) - NLAT) * 1024; \
;         _Pragma("unroll") for (int i = 0; i < 4; ++i) dst[i] = *(const float4*)(s_ + i * 256 + lane * 4); } while (0)
; __device__ __forceinline__ void p_norm(const float* hlat, const float* hctx, const float* g, const float* modl, int sh_off, int sc_off, bf16_t* A, int M,
;                                        const float* part, const float* cgate, float* hcout) {
;     ...
;     if (row < M) PN_LOAD(v, row);
;     while (row < M) {
;         const int nrow = row + stride;
;         if (nrow < M) PN_LOAD(nv, nrow);
;         const int r = row < NLAT ? (row >> 11) : 16;
;         float ss = 0.f;
; #pragma unroll
;         for (int i = 0; i < 4; ++i) {
;             if (part != nullptr && row >= NLAT) {
;                 const size_t po = (size_t)(row - NLAT) * 1024 + i * 256 + lane * 4;
;                 const float4 p0 = *(const float4*)(part + po), p1 = *(const float4*)(part + (size_t)4096 * 1024 + po), cg = *(const float4*)(cgate + i * 256 + lane * 4);
;                 v[i].x += cg.x * (p0.x + p1.x); v[i].y += cg.y * (p0.y + p1.y); v[i].z += cg.z * (p0.z + p1.z); v[i].w += cg.w * (p0.w + p1.w);
;                 *(float4*)(hcout + po) = v[i];
;             }
;             ss += v[i].x * v[i].x + v[i].y * v[i].y + v[i].z * v[i].z + v[i].w * v[i].w; }
;         ss = wave_sum(ss);
;         const float rstd = rsqrtf(ss * (1.0f / 1024.0f) + EPS);
;         const float* mr = modl + (size_t)r * 6144;
; #pragma unroll
;         for (int i = 0; i < 4; ++i) {
;             const int k = i * 256 + lane * 4;
;             const float4 gg = *(const float4*)(g + k), scv = *(const float4*)(mr + sc_off + k), shv = *(const float4*)(mr + sh_off + k);
;             const float o0 = v[i].x * rstd * gg.x * (1.0f + scv.x) + shv.x, o1 = v[i].y * rstd * gg.y * (1.0f + scv.y) + shv.y;
;             const float o2 = v[i].z * rstd * gg.z * (1.0f + scv.z) + shv.z, o3 = v[i].w * rstd * gg.w * (1.0f + scv.w) + shv.w;
;             uint2 w; w.x = pk2(o0, o1); w.y = pk2(o2, o3);
;             *(uint2*)(A + (size_t)row * 1024 + k) = w;
;         }
	v_pk_mul_f32 v[242:243], v[172:173], v[172:173]
	v_pk_mul_f32 v[244:245], v[176:177], v[176:177]
	v_pk_mul_f32 v[246:247], v[174:175], v[174:175]
	v_pk_mul_f32 v[248:249], v[178:179], v[178:179]
	v_add_f32_e32 v204, v245, v244
	v_add_f32_e32 v205, v243, v242
	v_add_f32_e32 v204, v248, v204
	v_add_f32_e32 v205, v246, v205
	v_add_f32_e32 v204, v249, v204
	v_add_f32_e32 v205, v247, v205
	v_pk_mul_f32 v[242:243], v[180:181], v[180:181]
	v_pk_mul_f32 v[244:245], v[184:185], v[184:185]
	v_pk_mul_f32 v[246:247], v[182:183], v[182:183]
	v_pk_mul_f32 v[248:249], v[186:187], v[186:187]
	v_add_f32_e32 v206, v243, v242
	v_add_f32_e32 v207, v245, v244
	v_add_f32_e32 v206, v246, v206
	v_add_f32_e32 v207, v248, v207
	v_add_f32_e32 v206, v247, v206
	v_add_f32_e32 v207, v249, v207
	v_add_f32_e32 v204, v205, v204
	v_add_f32_e32 v204, v204, v206
	v_add_f32_e32 v204, v204, v207
	ds_swizzle_b32 v205, v204 offset:swizzle(SWAP,1)
	s_waitcnt lgkmcnt(0)
	v_add_f32_e32 v204, v204, v205
	ds_swizzle_b32 v205, v204 offset:swizzle(SWAP,2)
	s_waitcnt lgkmcnt(0)
	v_add_f32_e32 v204, v204, v205
	ds_swizzle_b32 v205, v204 offset:swizzle(SWAP,4)
	s_waitcnt lgkmcnt(0)
	v_add_f32_e32 v204, v204, v205
	ds_swizzle_b32 v205, v204 offset:swizzle(SWAP,8)
	s_waitcnt lgkmcnt(0)
	v_add_f32_e32 v204, v204, v205
	ds_swizzle_b32 v205, v204 offset:swizzle(SWAP,16)
	s_waitcnt lgkmcnt(0)
	v_add_f32_e32 v204, v204, v205
	v_mov_b32_e32 v205, v204
	s_nop 1
	v_permlane32_swap_b32_e32 v204, v205
	v_add_f32_e32 v204, v204, v205
	v_mov_b32_e32 v205, 0x358637bd
	v_fmamk_f32 v204, v204, 0x3a800000, v205
	v_rsq_f32_e32 v204, v204
	s_nop 0
	v_pk_mul_f32 v[172:173], v[172:173], v[204:205] op_sel_hi:[1,0]
	v_pk_mul_f32 v[174:175], v[174:175], v[204:205] op_sel_hi:[1,0]
	v_pk_mul_f32 v[172:173], v[188:189], v[172:173]
	v_pk_mul_f32 v[174:175], v[190:191], v[174:175]
	v_pk_fma_f32 v[172:173], v[34:35], v[172:173], v[224:225]
	v_pk_fma_f32 v[174:175], v[36:37], v[174:175], v[226:227]
	v_cvt_pk_bf16_f32 v172, v172, v173
	v_cvt_pk_bf16_f32 v173, v174, v175
	global_store_dwordx2 v146, v[172:173], s[66:67]
	v_pk_mul_f32 v[176:177], v[176:177], v[204:205] op_sel_hi:[1,0]
	v_pk_mul_f32 v[178:179], v[178:179], v[204:205] op_sel_hi:[1,0]
	v_pk_mul_f32 v[176:177], v[192:193], v[176:177]
	v_pk_mul_f32 v[178:179], v[194:195], v[178:179]
	v_pk_fma_f32 v[176:177], v[38:39], v[176:177], v[228:229]
	v_pk_fma_f32 v[178:179], v[40:41], v[178:179], v[230:231]
	v_cvt_pk_bf16_f32 v176, v176, v177
	v_cvt_pk_bf16_f32 v177, v178, v179
	global_store_dwordx2 v146, v[176:177], s[66:67] offset:512
	v_pk_mul_f32 v[180:181], v[180:181], v[204:205] op_sel_hi:[1,0]
	v_pk_mul_f32 v[182:183], v[182:183], v[204:205] op_sel_hi:[1,0]
	v_pk_mul_f32 v[180:181], v[196:197], v[180:181]
	v_pk_mul_f32 v[182:183], v[198:199], v[182:183]
	v_pk_fma_f32 v[180:181], v[42:43], v[180:181], v[232:233]
	v_pk_fma_f32 v[182:183], v[44:45], v[182:183], v[234:235]
	v_cvt_pk_bf16_f32 v180, v180, v181
	v_cvt_pk_bf16_f32 v181, v182, v183
	global_store_dwordx2 v146, v[180:181], s[66:67] offset:1024
	v_pk_mul_f32 v[184:185], v[184:185], v[204:205] op_sel_hi:[1,0]
	v_pk_mul_f32 v[186:187], v[186:187], v[204:205] op_sel_hi:[1,0]
	v_pk_mul_f32 v[184:185], v[200:201], v[184:185]
	v_pk_mul_f32 v[186:187], v[202:203], v[186:187]
	v_pk_fma_f32 v[184:185], v[46:47], v[184:185], v[236:237]
	v_pk_fma_f32 v[186:187], v[48:49], v[186:187], v[238:239]
	v_cvt_pk_bf16_f32 v184, v184, v185
	v_cvt_pk_bf16_f32 v185, v186, v187
	global_store_dwordx2 v146, v[184:185], s[66:67] offset:1536
	v_add_u32_e32 v146, 0x800, v146
	global_load_dwordx4 v[172:175], v144, s[46:47] nt
	global_load_dwordx4 v[176:179], v144, s[46:47] offset:1024 nt
	global_load_dwordx4 v[180:183], v144, s[46:47] offset:2048 nt
	global_load_dwordx4 v[184:187], v144, s[46:47] offset:3072 nt
	v_add_u32_e32 v144, 0x1000, v144
	s_waitcnt vmcnt(40)
	v_pk_mul_f32 v[242:243], v[80:81], v[80:81]
	v_pk_mul_f32 v[244:245], v[84:85], v[84:85]
	v_pk_mul_f32 v[246:247], v[82:83], v[82:83]
	v_pk_mul_f32 v[248:249], v[86:87], v[86:87]
	v_add_f32_e32 v204, v245, v244
	v_add_f32_e32 v205, v243, v242
	v_add_f32_e32 v204, v248, v204
	v_add_f32_e32 v205, v246, v205
	v_add_f32_e32 v204, v249, v204
	v_add_f32_e32 v205, v247, v205
	v_pk_mul_f32 v[242:243], v[88:89], v[88:89]
	v_pk_mul_f32 v[244:245], v[92:93], v[92:93]
	v_pk_mul_f32 v[246:247], v[90:91], v[90:91]
	v_pk_mul_f32 v[248:249], v[94:95], v[94:95]
	v_add_f32_e32 v206, v243, v242
	v_add_f32_e32 v207, v245, v244
	v_add_f32_e32 v206, v246, v206
	v_add_f32_e32 v207, v248, v207
	v_add_f32_e32 v206, v247, v206
	v_add_f32_e32 v207, v249, v207
	v_add_f32_e32 v204, v205, v204
	v_add_f32_e32 v204, v204, v206
	v_add_f32_e32 v204, v204, v207
	ds_swizzle_b32 v205, v204 offset:swizzle(SWAP,1)
	s_waitcnt lgkmcnt(0)
	v_add_f32_e32 v204, v204, v205
	ds_swizzle_b32 v205, v204 offset:swizzle(SWAP,2)
	s_waitcnt lgkmcnt(0)
	v_add_f32_e32 v204, v204, v205
	ds_swizzle_b32 v205, v204 offset:swizzle(SWAP,4)
	s_waitcnt lgkmcnt(0)
	v_add_f32_e32 v204, v204, v205
	ds_swizzle_b32 v205, v204 offset:swizzle(SWAP,8)
	s_waitcnt lgkmcnt(0)
	v_add_f32_e32 v204, v204, v205
	ds_swizzle_b32 v205, v204 offset:swizzle(SWAP,16)
	s_waitcnt lgkmcnt(0)
; __device__ __forceinline__ unsigned pk2(float lo, float hi) { const g_f32x2 f = {lo, hi}; return __builtin_bit_cast(unsigned, __builtin_convertvector(f, g_bf16x2)); }
; #define PN_LOAD(dst, rw) do { const float* s_ = (rw) < NLAT ? hlat + (size_t)(rw) * 1024 : hctx + (size_t)((rw) - NLAT) * 1024; \
;         _Pragma("unroll") for (int i = 0; i < 4; ++i) dst[i] = *(const float4*)(s_ + i * 256 + lane * 4); } while (0)
; __device__ __forceinline__ void p_norm(const float* hlat, const float* hctx, const float* g, const float* modl, int sh_off, int sc_off, bf16_t* A, int M,
;                                        const float* part, const float* cgate, float* hcout) {
;     ...
;     if (row < M) PN_LOAD(v, row);
;     while (row < M) {
;         const int nrow = row + stride;
;         if (nrow < M) PN_LOAD(nv, nrow);
;         const int r = row < NLAT ? (row >> 11) : 16;
;         float ss = 0.f;
; #pragma unroll
;         for (int i = 0; i < 4; ++i) {
;             if (part != nullptr && row >= NLAT) {
;                 const size_t po = (size_t)(row - NLAT) * 1024 + i * 256 + lane * 4;
;                 const float4 p0 = *(const float4*)(part + po), p1 = *(const float4*)(part + (size_t)4096 * 1024 + po), cg = *(const float4*)(cgate + i * 256 + lane * 4);
;                 v[i].x += cg.x * (p0.x + p1.x); v[i].y += cg.y * (p0.y + p1.y); v[i].z += cg.z * (p0.z + p1.z); v[i].w += cg.w * (p0.w + p1.w);
;                 *(float4*)(hcout + po) = v[i];
;             }
;             ss += v[i].x * v[i].x + v[i].y * v[i].y + v[i].z * v[i].z + v[i].w * v[i].w; }
;         ss = wave_sum(ss);
;         const float rstd = rsqrtf(ss * (1.0f / 1024.0f) + EPS);
;         const float* mr = modl + (size_t)r * 6144;
; #pragma unroll
;         for (int i = 0; i < 4; ++i) {
;             const int k = i * 256 + lane * 4;
;             const float4 gg = *(const float4*)(g + k), scv = *(const float4*)(mr + sc_off + k), shv = *(const float4*)(mr + sh_off + k);
;             const float o0 = v[i].x * rstd * gg.x * (1.0f + scv.x) + shv.x, o1 = v[i].y * rstd * gg.y * (1.0f + scv.y) + shv.y;
;             const float o2 = v[i].z * rstd * gg.z * (1.0f + scv.z) + shv.z, o3 = v[i].w * rstd * gg.w * (1.0f + scv.w) + shv.w;
;             uint2 w; w.x = pk2(o0, o1); w.y = pk2(o2, o3);
;             *(uint2*)(A + (size_t)row * 1024 + k) = w;
;         }
	v_add_f32_e32 v204, v204, v205
	v_mov_b32_e32 v205, v204
	s_nop 1
	v_permlane32_swap_b32_e32 v204, v205
	v_add_f32_e32 v204, v204, v205
	v_mov_b32_e32 v205, 0x358637bd
	v_fmamk_f32 v204, v204, 0x3a800000, v205
	v_rsq_f32_e32 v204, v204
	s_nop 0
	v_pk_mul_f32 v[80:81], v[80:81], v[204:205] op_sel_hi:[1,0]
	v_pk_mul_f32 v[82:83], v[82:83], v[204:205] op_sel_hi:[1,0]
	v_pk_mul_f32 v[80:81], v[188:189], v[80:81]
	v_pk_mul_f32 v[82:83], v[190:191], v[82:83]
	v_pk_fma_f32 v[80:81], v[34:35], v[80:81], v[224:225]
	v_pk_fma_f32 v[82:83], v[36:37], v[82:83], v[226:227]
	v_cvt_pk_bf16_f32 v80, v80, v81
	v_cvt_pk_bf16_f32 v81, v82, v83
	global_store_dwordx2 v146, v[80:81], s[66:67]
	v_pk_mul_f32 v[84:85], v[84:85], v[204:205] op_sel_hi:[1,0]
	v_pk_mul_f32 v[86:87], v[86:87], v[204:205] op_sel_hi:[1,0]
	v_pk_mul_f32 v[84:85], v[192:193], v[84:85]
	v_pk_mul_f32 v[86:87], v[194:195], v[86:87]
	v_pk_fma_f32 v[84:85], v[38:39], v[84:85], v[228:229]
	v_pk_fma_f32 v[86:87], v[40:41], v[86:87], v[230:231]
	v_cvt_pk_bf16_f32 v84, v84, v85
	v_cvt_pk_bf16_f32 v85, v86, v87
	global_store_dwordx2 v146, v[84:85], s[66:67] offset:512
	v_pk_mul_f32 v[88:89], v[88:89], v[204:205] op_sel_hi:[1,0]
	v_pk_mul_f32 v[90:91], v[90:91], v[204:205] op_sel_hi:[1,0]
	v_pk_mul_f32 v[88:89], v[196:197], v[88:89]
	v_pk_mul_f32 v[90:91], v[198:199], v[90:91]
	v_pk_fma_f32 v[88:89], v[42:43], v[88:89], v[232:233]
	v_pk_fma_f32 v[90:91], v[44:45], v[90:91], v[234:235]
	v_cvt_pk_bf16_f32 v88, v88, v89
	v_cvt_pk_bf16_f32 v89, v90, v91
	global_store_dwordx2 v146, v[88:89], s[66:67] offset:1024
	v_pk_mul_f32 v[92:93], v[92:93], v[204:205] op_sel_hi:[1,0]
	v_pk_mul_f32 v[94:95], v[94:95], v[204:205] op_sel_hi:[1,0]
	v_pk_mul_f32 v[92:93], v[200:201], v[92:93]
	v_pk_mul_f32 v[94:95], v[202:203], v[94:95]
	v_pk_fma_f32 v[92:93], v[46:47], v[92:93], v[236:237]
	v_pk_fma_f32 v[94:95], v[48:49], v[94:95], v[238:239]
	v_cvt_pk_bf16_f32 v92, v92, v93
	v_cvt_pk_bf16_f32 v93, v94, v95
	global_store_dwordx2 v146, v[92:93], s[66:67] offset:1536
	v_add_u32_e32 v146, 0x800, v146
	global_load_dwordx4 v[80:83], v144, s[46:47] nt
	global_load_dwordx4 v[84:87], v144, s[46:47] offset:1024 nt
	global_load_dwordx4 v[88:91], v144, s[46:47] offset:2048 nt
	global_load_dwordx4 v[92:95], v144, s[46:47] offset:3072 nt
	v_add_u32_e32 v144, 0x1000, v144
	s_waitcnt vmcnt(40)
	v_pk_mul_f32 v[242:243], v[96:97], v[96:97]
	v_pk_mul_f32 v[244:245], v[100:101], v[100:101]
	v_pk_mul_f32 v[246:247], v[98:99], v[98:99]
	v_pk_mul_f32 v[248:249], v[102:103], v[102:103]
	v_add_f32_e32 v204, v245, v244
	v_add_f32_e32 v205, v243, v242
	v_add_f32_e32 v204, v248, v204
	v_add_f32_e32 v205, v246, v205
	v_add_f32_e32 v204, v249, v204
	v_add_f32_e32 v205, v247, v205
	v_pk_mul_f32 v[242:243], v[104:105], v[104:105]
	v_pk_mul_f32 v[244:245], v[108:109], v[108:109]
	v_pk_mul_f32 v[246:247], v[106:107], v[106:107]
	v_pk_mul_f32 v[248:249], v[110:111], v[110:111]
	v_add_f32_e32 v206, v243, v242
	v_add_f32_e32 v207, v245, v244
	v_add_f32_e32 v206, v246, v206
	v_add_f32_e32 v207, v248, v207
	v_add_f32_e32 v206, v247, v206
	v_add_f32_e32 v207, v249, v207
	v_add_f32_e32 v204, v205, v204
	v_add_f32_e32 v204, v204, v206
	v_add_f32_e32 v204, v204, v207
	ds_swizzle_b32 v205, v204 offset:swizzle(SWAP,1)
	s_waitcnt lgkmcnt(0)
	v_add_f32_e32 v204, v204, v205
	ds_swizzle_b32 v205, v204 offset:swizzle(SWAP,2)
	s_waitcnt lgkmcnt(0)
	v_add_f32_e32 v204, v204, v205
	ds_swizzle_b32 v205, v204 offset:swizzle(SWAP,4)
	s_waitcnt lgkmcnt(0)
	v_add_f32_e32 v204, v204, v205
	ds_swizzle_b32 v205, v204 offset:swizzle(SWAP,8)
	s_waitcnt lgkmcnt(0)
	v_add_f32_e32 v204, v204, v205
	ds_swizzle_b32 v205, v204 offset:swizzle(SWAP,16)
	s_waitcnt lgkmcnt(0)
	v_add_f32_e32 v204, v204, v205
	v_mov_b32_e32 v205, v204
	s_nop 1
	v_permlane32_swap_b32_e32 v204, v205
	v_add_f32_e32 v204, v204, v205
	v_mov_b32_e32 v205, 0x358637bd
	v_fmamk_f32 v204, v204, 0x3a800000, v205
	v_rsq_f32_e32 v204, v204
	s_nop 0
	v_pk_mul_f32 v[96:97], v[96:97], v[204:205] op_sel_hi:[1,0]
	v_pk_mul_f32 v[98:99], v[98:99], v[204:205] op_sel_hi:[1,0]
	v_pk_mul_f32 v[96:97], v[188:189], v[96:97]
	v_pk_mul_f32 v[98:99], v[190:191], v[98:99]
	v_pk_fma_f32 v[96:97], v[34:35], v[96:97], v[224:225]
	v_pk_fma_f32 v[98:99], v[36:37], v[98:99], v[226:227]
	v_cvt_pk_bf16_f32 v96, v96, v97
	v_cvt_pk_bf16_f32 v97, v98, v99
	global_store_dwordx2 v146, v[96:97], s[66:67]
	v_pk_mul_f32 v[100:101], v[100:101], v[204:205] op_sel_hi:[1,0]
	v_pk_mul_f32 v[102:103], v[102:103], v[204:205] op_sel_hi:[1,0]
	v_pk_mul_f32 v[100:101], v[192:193], v[100:101]
	v_pk_mul_f32 v[102:103], v[194:195], v[102:103]
	v_pk_fma_f32 v[100:101], v[38:39], v[100:101], v[228:229]
	v_pk_fma_f32 v[102:103], v[40:41], v[102:103], v[230:231]
	v_cvt_pk_bf16_f32 v100, v100, v101
	v_cvt_pk_bf16_f32 v101, v102, v103
	global_store_dwordx2 v146, v[100:101], s[66:67] offset:512
	v_pk_mul_f32 v[104:105], v[104:105], v[204:205] op_sel_hi:[1,0]
	v_pk_mul_f32 v[106:107], v[106:107], v[204:205] op_sel_hi:[1,0]
	v_pk_mul_f32 v[104:105], v[196:197], v[104:105]
	v_pk_mul_f32 v[106:107], v[198:199], v[106:107]
	v_pk_fma_f32 v[104:105], v[42:43], v[104:105], v[232:233]
	v_pk_fma_f32 v[106:107], v[44:45], v[106:107], v[234:235]
	v_cvt_pk_bf16_f32 v104, v104, v105
	v_cvt_pk_bf16_f32 v105, v106, v107
	global_store_dwordx2 v146, v[104:105], s[66:67] offset:1024
	v_pk_mul_f32 v[108:109], v[108:109], v[204:205] op_sel_hi:[1,0]
	v_pk_mul_f32 v[110:111], v[110:111], v[204:205] op_sel_hi:[1,0]
	v_pk_mul_f32 v[108:109], v[200:201], v[108:109]
	v_pk_mul_f32 v[110:111], v[202:203], v[110:111]
	v_pk_fma_f32 v[108:109], v[46:47], v[108:109], v[236:237]
	v_pk_fma_f32 v[110:111], v[48:49], v[110:111], v[238:239]
	v_cvt_pk_bf16_f32 v108, v108, v109
	v_cvt_pk_bf16_f32 v109, v110, v111
	global_store_dwordx2 v146, v[108:109], s[66:67] offset:1536
	v_add_u32_e32 v146, 0x800, v146
	global_load_dwordx4 v[96:99], v144, s[46:47] nt
	global_load_dwordx4 v[100:103], v144, s[46:47] offset:1024 nt
	global_load_dwordx4 v[104:107], v144, s[46:47] offset:2048 nt
	global_load_dwordx4 v[108:111], v144, s[46:47] offset:3072 nt
	v_add_u32_e32 v144, 0x1000, v144
	s_waitcnt vmcnt(40)
; __device__ __forceinline__ unsigned pk2(float lo, float hi) { const g_f32x2 f = {lo, hi}; return __builtin_bit_cast(unsigned, __builtin_convertvector(f, g_bf16x2)); }
; #define PN_LOAD(dst, rw) do { const float* s_ = (rw) < NLAT ? hlat + (size_t)(rw) * 1024 : hctx + (size_t)((rw) - NLAT) * 1024; \
;         _Pragma("unroll") for (int i = 0; i < 4; ++i) dst[i] = *(const float4*)(s_ + i * 256 + lane * 4); } while (0)
; __device__ __forceinline__ void p_norm(const float* hlat, const float* hctx, const float* g, const float* modl, int sh_off, int sc_off, bf16_t* A, int M,
;                                        const float* part, const float* cgate, float* hcout) {
;     ...
;     if (row < M) PN_LOAD(v, row);
;     while (row < M) {
;         const int nrow = row + stride;
;         if (nrow < M) PN_LOAD(nv, nrow);
;         const int r = row < NLAT ? (row >> 11) : 16;
;         float ss = 0.f;
; #pragma unroll
;         for (int i = 0; i < 4; ++i) {
;             if (part != nullptr && row >= NLAT) {
;                 const size_t po = (size_t)(row - NLAT) * 1024 + i * 256 + lane * 4;
;                 const float4 p0 = *(const float4*)(part + po), p1 = *(const float4*)(part + (size_t)4096 * 1024 + po), cg = *(const float4*)(cgate + i * 256 + lane * 4);
;                 v[i].x += cg.x * (p0.x + p1.x); v[i].y += cg.y * (p0.y + p1.y); v[i].z += cg.z * (p0.z + p1.z); v[i].w += cg.w * (p0.w + p1.w);
;                 *(float4*)(hcout + po) = v[i];
;             }
;             ss += v[i].x * v[i].x + v[i].y * v[i].y + v[i].z * v[i].z + v[i].w * v[i].w; }
;         ss = wave_sum(ss);
;         const float rstd = rsqrtf(ss * (1.0f / 1024.0f) + EPS);
;         const float* mr = modl + (size_t)r * 6144;
; #pragma unroll
;         for (int i = 0; i < 4; ++i) {
;             const int k = i * 256 + lane * 4;
;             const float4 gg = *(const float4*)(g + k), scv = *(const float4*)(mr + sc_off + k), shv = *(const float4*)(mr + sh_off + k);
;             const float o0 = v[i].x * rstd * gg.x * (1.0f + scv.x) + shv.x, o1 = v[i].y * rstd * gg.y * (1.0f + scv.y) + shv.y;
;             const float o2 = v[i].z * rstd * gg.z * (1.0f + scv.z) + shv.z, o3 = v[i].w * rstd * gg.w * (1.0f + scv.w) + shv.w;
;             uint2 w; w.x = pk2(o0, o1); w.y = pk2(o2, o3);
;             *(uint2*)(A + (size_t)row * 1024 + k) = w;
;         }
	v_pk_mul_f32 v[242:243], v[112:113], v[112:113]
	v_pk_mul_f32 v[244:245], v[116:117], v[116:117]
	v_pk_mul_f32 v[246:247], v[114:115], v[114:115]
	v_pk_mul_f32 v[248:249], v[118:119], v[118:119]
	v_add_f32_e32 v204, v245, v244
	v_add_f32_e32 v205, v243, v242
	v_add_f32_e32 v204, v248, v204
	v_add_f32_e32 v205, v246, v205
	v_add_f32_e32 v204, v249, v204
	v_add_f32_e32 v205, v247, v205
	v_pk_mul_f32 v[242:243], v[120:121], v[120:121]
	v_pk_mul_f32 v[244:245], v[124:125], v[124:125]
	v_pk_mul_f32 v[246:247], v[122:123], v[122:123]
	v_pk_mul_f32 v[248:249], v[126:127], v[126:127]
	v_add_f32_e32 v206, v243, v242
	v_add_f32_e32 v207, v245, v244
	v_add_f32_e32 v206, v246, v206
	v_add_f32_e32 v207, v248, v207
	v_add_f32_e32 v206, v247, v206
	v_add_f32_e32 v207, v249, v207
	v_add_f32_e32 v204, v205, v204
	v_add_f32_e32 v204, v204, v206
	v_add_f32_e32 v204, v204, v207
	ds_swizzle_b32 v205, v204 offset:swizzle(SWAP,1)
	s_waitcnt lgkmcnt(0)
	v_add_f32_e32 v204, v204, v205
	ds_swizzle_b32 v205, v204 offset:swizzle(SWAP,2)
	s_waitcnt lgkmcnt(0)
	v_add_f32_e32 v204, v204, v205
	ds_swizzle_b32 v205, v204 offset:swizzle(SWAP,4)
	s_waitcnt lgkmcnt(0)
	v_add_f32_e32 v204, v204, v205
	ds_swizzle_b32 v205, v204 offset:swizzle(SWAP,8)
	s_waitcnt lgkmcnt(0)
	v_add_f32_e32 v204, v204, v205
	ds_swizzle_b32 v205, v204 offset:swizzle(SWAP,16)
	s_waitcnt lgkmcnt(0)
	v_add_f32_e32 v204, v204, v205
	v_mov_b32_e32 v205, v204
	s_nop 1
	v_permlane32_swap_b32_e32 v204, v205
	v_add_f32_e32 v204, v204, v205
	v_mov_b32_e32 v205, 0x358637bd
	v_fmamk_f32 v204, v204, 0x3a800000, v205
	v_rsq_f32_e32 v204, v204
	s_nop 0
	v_pk_mul_f32 v[112:113], v[112:113], v[204:205] op_sel_hi:[1,0]
	v_pk_mul_f32 v[114:115], v[114:115], v[204:205] op_sel_hi:[1,0]
	v_pk_mul_f32 v[112:113], v[188:189], v[112:113]
	v_pk_mul_f32 v[114:115], v[190:191], v[114:115]
	v_pk_fma_f32 v[112:113], v[34:35], v[112:113], v[224:225]
	v_pk_fma_f32 v[114:115], v[36:37], v[114:115], v[226:227]
	v_cvt_pk_bf16_f32 v112, v112, v113
	v_cvt_pk_bf16_f32 v113, v114, v115
	global_store_dwordx2 v146, v[112:113], s[66:67]
	v_pk_mul_f32 v[116:117], v[116:117], v[204:205] op_sel_hi:[1,0]
	v_pk_mul_f32 v[118:119], v[118:119], v[204:205] op_sel_hi:[1,0]
	v_pk_mul_f32 v[116:117], v[192:193], v[116:117]
	v_pk_mul_f32 v[118:119], v[194:195], v[118:119]
	v_pk_fma_f32 v[116:117], v[38:39], v[116:117], v[228:229]
	v_pk_fma_f32 v[118:119], v[40:41], v[118:119], v[230:231]
	v_cvt_pk_bf16_f32 v116, v116, v117
	v_cvt_pk_bf16_f32 v117, v118, v119
	global_store_dwordx2 v146, v[116:117], s[66:67] offset:512
	v_pk_mul_f32 v[120:121], v[120:121], v[204:205] op_sel_hi:[1,0]
	v_pk_mul_f32 v[122:123], v[122:123], v[204:205] op_sel_hi:[1,0]
	v_pk_mul_f32 v[120:121], v[196:197], v[120:121]
	v_pk_mul_f32 v[122:123], v[198:199], v[122:123]
	v_pk_fma_f32 v[120:121], v[42:43], v[120:121], v[232:233]
	v_pk_fma_f32 v[122:123], v[44:45], v[122:123], v[234:235]
	v_cvt_pk_bf16_f32 v120, v120, v121
	v_cvt_pk_bf16_f32 v121, v122, v123
	global_store_dwordx2 v146, v[120:121], s[66:67] offset:1024
	v_pk_mul_f32 v[124:125], v[124:125], v[204:205] op_sel_hi:[1,0]
	v_pk_mul_f32 v[126:127], v[126:127], v[204:205] op_sel_hi:[1,0]
	v_pk_mul_f32 v[124:125], v[200:201], v[124:125]
	v_pk_mul_f32 v[126:127], v[202:203], v[126:127]
	v_pk_fma_f32 v[124:125], v[46:47], v[124:125], v[236:237]
	v_pk_fma_f32 v[126:127], v[48:49], v[126:127], v[238:239]
	v_cvt_pk_bf16_f32 v124, v124, v125
	v_cvt_pk_bf16_f32 v125, v126, v127
	global_store_dwordx2 v146, v[124:125], s[66:67] offset:1536
	v_add_u32_e32 v146, 0x800, v146
	global_load_dwordx4 v[112:115], v144, s[46:47] nt
	global_load_dwordx4 v[116:119], v144, s[46:47] offset:1024 nt
	global_load_dwordx4 v[120:123], v144, s[46:47] offset:2048 nt
	global_load_dwordx4 v[124:127], v144, s[46:47] offset:3072 nt
	v_add_u32_e32 v144, 0x1000, v144
	s_waitcnt vmcnt(40)
	v_pk_mul_f32 v[242:243], v[128:129], v[128:129]
	v_pk_mul_f32 v[244:245], v[132:133], v[132:133]
	v_pk_mul_f32 v[246:247], v[130:131], v[130:131]
	v_pk_mul_f32 v[248:249], v[134:135], v[134:135]
	v_add_f32_e32 v204, v245, v244
	v_add_f32_e32 v205, v243, v242
	v_add_f32_e32 v204, v248, v204
	v_add_f32_e32 v205, v246, v205
	v_add_f32_e32 v204, v249, v204
	v_add_f32_e32 v205, v247, v205
	v_pk_mul_f32 v[242:243], v[136:137], v[136:137]
	v_pk_mul_f32 v[244:245], v[140:141], v[140:141]
	v_pk_mul_f32 v[246:247], v[138:139], v[138:139]
	v_pk_mul_f32 v[248:249], v[142:143], v[142:143]
	v_add_f32_e32 v206, v243, v242
	v_add_f32_e32 v207, v245, v244
	v_add_f32_e32 v206, v246, v206
	v_add_f32_e32 v207, v248, v207
	v_add_f32_e32 v206, v247, v206
	v_add_f32_e32 v207, v249, v207
	v_add_f32_e32 v204, v205, v204
	v_add_f32_e32 v204, v204, v206
	v_add_f32_e32 v204, v204, v207
	ds_swizzle_b32 v205, v204 offset:swizzle(SWAP,1)
	s_waitcnt lgkmcnt(0)
	v_add_f32_e32 v204, v204, v205
	ds_swizzle_b32 v205, v204 offset:swizzle(SWAP,2)
	s_waitcnt lgkmcnt(0)
	v_add_f32_e32 v204, v204, v205
	ds_swizzle_b32 v205, v204 offset:swizzle(SWAP,4)
	s_waitcnt lgkmcnt(0)
	v_add_f32_e32 v204, v204, v205
	ds_swizzle_b32 v205, v204 offset:swizzle(SWAP,8)
	s_waitcnt lgkmcnt(0)
	v_add_f32_e32 v204, v204, v205
	ds_swizzle_b32 v205, v204 offset:swizzle(SWAP,16)
	s_waitcnt lgkmcnt(0)
; __device__ __forceinline__ unsigned pk2(float lo, float hi) { const g_f32x2 f = {lo, hi}; return __builtin_bit_cast(unsigned, __builtin_convertvector(f, g_bf16x2)); }
; #define PN_LOAD(dst, rw) do { const float* s_ = (rw) < NLAT ? hlat + (size_t)(rw) * 1024 : hctx + (size_t)((rw) - NLAT) * 1024; \
;         _Pragma("unroll") for (int i = 0; i < 4; ++i) dst[i] = *(const float4*)(s_ + i * 256 + lane * 4); } while (0)
; __device__ __forceinline__ void p_norm(const float* hlat, const float* hctx, const float* g, const float* modl, int sh_off, int sc_off, bf16_t* A, int M,
;                                        const float* part, const float* cgate, float* hcout) {
;     ...
;     if (row < M) PN_LOAD(v, row);
;     while (row < M) {
;         const int nrow = row + stride;
;         if (nrow < M) PN_LOAD(nv, nrow);
;         const int r = row < NLAT ? (row >> 11) : 16;
;         float ss = 0.f;
; #pragma unroll
;         for (int i = 0; i < 4; ++i) {
;             if (part != nullptr && row >= NLAT) {
;                 const size_t po = (size_t)(row - NLAT) * 1024 + i * 256 + lane * 4;
;                 const float4 p0 = *(const float4*)(part + po), p1 = *(const float4*)(part + (size_t)4096 * 1024 + po), cg = *(const float4*)(cgate + i * 256 + lane * 4);
;                 v[i].x += cg.x * (p0.x + p1.x); v[i].y += cg.y * (p0.y + p1.y); v[i].z += cg.z * (p0.z + p1.z); v[i].w += cg.w * (p0.w + p1.w);
;                 *(float4*)(hcout + po) = v[i];
;             }
;             ss += v[i].x * v[i].x + v[i].y * v[i].y + v[i].z * v[i].z + v[i].w * v[i].w; }
;         ss = wave_sum(ss);
;         const float rstd = rsqrtf(ss * (1.0f / 1024.0f) + EPS);
;         const float* mr = modl + (size_t)r * 6144;
; #pragma unroll
;         for (int i = 0; i < 4; ++i) {
;             const int k = i * 256 + lane * 4;
;             const float4 gg = *(const float4*)(g + k), scv = *(const float4*)(mr + sc_off + k), shv = *(const float4*)(mr + sh_off + k);
;             const float o0 = v[i].x * rstd * gg.x * (1.0f + scv.x) + shv.x, o1 = v[i].y * rstd * gg.y * (1.0f + scv.y) + shv.y;
;             const float o2 = v[i].z * rstd * gg.z * (1.0f + scv.z) + shv.z, o3 = v[i].w * rstd * gg.w * (1.0f + scv.w) + shv.w;
;             uint2 w; w.x = pk2(o0, o1); w.y = pk2(o2, o3);
;             *(uint2*)(A + (size_t)row * 1024 + k) = w;
;         }
	v_add_f32_e32 v204, v204, v205
	v_mov_b32_e32 v205, v204
	s_nop 1
	v_permlane32_swap_b32_e32 v204, v205
	v_add_f32_e32 v204, v204, v205
	v_mov_b32_e32 v205, 0x358637bd
	v_fmamk_f32 v204, v204, 0x3a800000, v205
	v_rsq_f32_e32 v204, v204
	s_nop 0
	v_pk_mul_f32 v[128:129], v[128:129], v[204:205] op_sel_hi:[1,0]
	v_pk_mul_f32 v[130:131], v[130:131], v[204:205] op_sel_hi:[1,0]
	v_pk_mul_f32 v[128:129], v[188:189], v[128:129]
	v_pk_mul_f32 v[130:131], v[190:191], v[130:131]
	v_pk_fma_f32 v[128:129], v[34:35], v[128:129], v[224:225]
	v_pk_fma_f32 v[130:131], v[36:37], v[130:131], v[226:227]
	v_cvt_pk_bf16_f32 v128, v128, v129
	v_cvt_pk_bf16_f32 v129, v130, v131
	global_store_dwordx2 v146, v[128:129], s[66:67]
	v_pk_mul_f32 v[132:133], v[132:133], v[204:205] op_sel_hi:[1,0]
	v_pk_mul_f32 v[134:135], v[134:135], v[204:205] op_sel_hi:[1,0]
	v_pk_mul_f32 v[132:133], v[192:193], v[132:133]
	v_pk_mul_f32 v[134:135], v[194:195], v[134:135]
	v_pk_fma_f32 v[132:133], v[38:39], v[132:133], v[228:229]
	v_pk_fma_f32 v[134:135], v[40:41], v[134:135], v[230:231]
	v_cvt_pk_bf16_f32 v132, v132, v133
	v_cvt_pk_bf16_f32 v133, v134, v135
	global_store_dwordx2 v146, v[132:133], s[66:67] offset:512
	v_pk_mul_f32 v[136:137], v[136:137], v[204:205] op_sel_hi:[1,0]
	v_pk_mul_f32 v[138:139], v[138:139], v[204:205] op_sel_hi:[1,0]
	v_pk_mul_f32 v[136:137], v[196:197], v[136:137]
	v_pk_mul_f32 v[138:139], v[198:199], v[138:139]
	v_pk_fma_f32 v[136:137], v[42:43], v[136:137], v[232:233]
	v_pk_fma_f32 v[138:139], v[44:45], v[138:139], v[234:235]
	v_cvt_pk_bf16_f32 v136, v136, v137
	v_cvt_pk_bf16_f32 v137, v138, v139
	global_store_dwordx2 v146, v[136:137], s[66:67] offset:1024
	v_pk_mul_f32 v[140:141], v[140:141], v[204:205] op_sel_hi:[1,0]
	v_pk_mul_f32 v[142:143], v[142:143], v[204:205] op_sel_hi:[1,0]
	v_pk_mul_f32 v[140:141], v[200:201], v[140:141]
	v_pk_mul_f32 v[142:143], v[202:203], v[142:143]
	v_pk_fma_f32 v[140:141], v[46:47], v[140:141], v[236:237]
	v_pk_fma_f32 v[142:143], v[48:49], v[142:143], v[238:239]
	v_cvt_pk_bf16_f32 v140, v140, v141
	v_cvt_pk_bf16_f32 v141, v142, v143
	global_store_dwordx2 v146, v[140:141], s[66:67] offset:1536
	v_add_u32_e32 v146, 0x800, v146
	global_load_dwordx4 v[128:131], v144, s[46:47] nt
	global_load_dwordx4 v[132:135], v144, s[46:47] offset:1024 nt
	global_load_dwordx4 v[136:139], v144, s[46:47] offset:2048 nt
	global_load_dwordx4 v[140:143], v144, s[46:47] offset:3072 nt
	v_add_u32_e32 v144, 0x1000, v144
	s_waitcnt vmcnt(40)
	v_pk_mul_f32 v[242:243], v[156:157], v[156:157]
	v_pk_mul_f32 v[244:245], v[160:161], v[160:161]
	v_pk_mul_f32 v[246:247], v[158:159], v[158:159]
	v_pk_mul_f32 v[248:249], v[162:163], v[162:163]
	v_add_f32_e32 v204, v245, v244
	v_add_f32_e32 v205, v243, v242
	v_add_f32_e32 v204, v248, v204
	v_add_f32_e32 v205, v246, v205
	v_add_f32_e32 v204, v249, v204
	v_add_f32_e32 v205, v247, v205
	v_pk_mul_f32 v[242:243], v[164:165], v[164:165]
	v_pk_mul_f32 v[244:245], v[168:169], v[168:169]
	v_pk_mul_f32 v[246:247], v[166:167], v[166:167]
	v_pk_mul_f32 v[248:249], v[170:171], v[170:171]
	v_add_f32_e32 v206, v243, v242
	v_add_f32_e32 v207, v245, v244
	v_add_f32_e32 v206, v246, v206
	v_add_f32_e32 v207, v248, v207
	v_add_f32_e32 v206, v247, v206
	v_add_f32_e32 v207, v249, v207
	v_add_f32_e32 v204, v205, v204
	v_add_f32_e32 v204, v204, v206
	v_add_f32_e32 v204, v204, v207
	ds_swizzle_b32 v205, v204 offset:swizzle(SWAP,1)
	s_waitcnt lgkmcnt(0)
	v_add_f32_e32 v204, v204, v205
	ds_swizzle_b32 v205, v204 offset:swizzle(SWAP,2)
	s_waitcnt lgkmcnt(0)
	v_add_f32_e32 v204, v204, v205
	ds_swizzle_b32 v205, v204 offset:swizzle(SWAP,4)
	s_waitcnt lgkmcnt(0)
	v_add_f32_e32 v204, v204, v205
	ds_swizzle_b32 v205, v204 offset:swizzle(SWAP,8)
	s_waitcnt lgkmcnt(0)
	v_add_f32_e32 v204, v204, v205
	ds_swizzle_b32 v205, v204 offset:swizzle(SWAP,16)
	s_waitcnt lgkmcnt(0)
	v_add_f32_e32 v204, v204, v205
	v_mov_b32_e32 v205, v204
	s_nop 1
	v_permlane32_swap_b32_e32 v204, v205
	v_add_f32_e32 v204, v204, v205
	v_mov_b32_e32 v205, 0x358637bd
	v_fmamk_f32 v204, v204, 0x3a800000, v205
	v_rsq_f32_e32 v204, v204
	s_nop 0
	v_pk_mul_f32 v[156:157], v[156:157], v[204:205] op_sel_hi:[1,0]
	v_pk_mul_f32 v[158:159], v[158:159], v[204:205] op_sel_hi:[1,0]
	v_pk_mul_f32 v[156:157], v[188:189], v[156:157]
	v_pk_mul_f32 v[158:159], v[190:191], v[158:159]
	v_pk_fma_f32 v[156:157], v[34:35], v[156:157], v[224:225]
	v_pk_fma_f32 v[158:159], v[36:37], v[158:159], v[226:227]
	v_cvt_pk_bf16_f32 v156, v156, v157
	v_cvt_pk_bf16_f32 v157, v158, v159
	global_store_dwordx2 v146, v[156:157], s[66:67]
	v_pk_mul_f32 v[160:161], v[160:161], v[204:205] op_sel_hi:[1,0]
	v_pk_mul_f32 v[162:163], v[162:163], v[204:205] op_sel_hi:[1,0]
	v_pk_mul_f32 v[160:161], v[192:193], v[160:161]
	v_pk_mul_f32 v[162:163], v[194:195], v[162:163]
	v_pk_fma_f32 v[160:161], v[38:39], v[160:161], v[228:229]
	v_pk_fma_f32 v[162:163], v[40:41], v[162:163], v[230:231]
	v_cvt_pk_bf16_f32 v160, v160, v161
	v_cvt_pk_bf16_f32 v161, v162, v163
	global_store_dwordx2 v146, v[160:161], s[66:67] offset:512
	v_pk_mul_f32 v[164:165], v[164:165], v[204:205] op_sel_hi:[1,0]
	v_pk_mul_f32 v[166:167], v[166:167], v[204:205] op_sel_hi:[1,0]
	v_pk_mul_f32 v[164:165], v[196:197], v[164:165]
	v_pk_mul_f32 v[166:167], v[198:199], v[166:167]
	v_pk_fma_f32 v[164:165], v[42:43], v[164:165], v[232:233]
	v_pk_fma_f32 v[166:167], v[44:45], v[166:167], v[234:235]
	v_cvt_pk_bf16_f32 v164, v164, v165
	v_cvt_pk_bf16_f32 v165, v166, v167
	global_store_dwordx2 v146, v[164:165], s[66:67] offset:1024
	v_pk_mul_f32 v[168:169], v[168:169], v[204:205] op_sel_hi:[1,0]
	v_pk_mul_f32 v[170:171], v[170:171], v[204:205] op_sel_hi:[1,0]
	v_pk_mul_f32 v[168:169], v[200:201], v[168:169]
	v_pk_mul_f32 v[170:171], v[202:203], v[170:171]
	v_pk_fma_f32 v[168:169], v[46:47], v[168:169], v[236:237]
	v_pk_fma_f32 v[170:171], v[48:49], v[170:171], v[238:239]
	v_cvt_pk_bf16_f32 v168, v168, v169
	v_cvt_pk_bf16_f32 v169, v170, v171
	global_store_dwordx2 v146, v[168:169], s[66:67] offset:1536
	v_add_u32_e32 v146, 0x800, v146
	v_lshl_add_u32 v144, v50, 13, v241
	v_mov_b32_e32 v152, v144
	v_add_u32_e32 v150, 0x1000000, v144
	global_load_dwordx4 v[156:159], v144, s[16:17]
	global_load_dwordx4 v[160:163], v144, s[16:17] offset:1024
	global_load_dwordx4 v[164:167], v144, s[16:17] offset:2048
	global_load_dwordx4 v[168:171], v144, s[16:17] offset:3072
	v_add_u32_e32 v144, 0x1000, v144
	s_waitcnt vmcnt(40)
; __device__ __forceinline__ unsigned pk2(float lo, float hi) { const g_f32x2 f = {lo, hi}; return __builtin_bit_cast(unsigned, __builtin_convertvector(f, g_bf16x2)); }
; #define PN_LOAD(dst, rw) do { const float* s_ = (rw) < NLAT ? hlat + (size_t)(rw) * 1024 : hctx + (size_t)((rw) - NLAT) * 1024; \
;         _Pragma("unroll") for (int i = 0; i < 4; ++i) dst[i] = *(const float4*)(s_ + i * 256 + lane * 4); } while (0)
; __device__ __forceinline__ void p_norm(const float* hlat, const float* hctx, const float* g, const float* modl, int sh_off, int sc_off, bf16_t* A, int M,
;                                        const float* part, const float* cgate, float* hcout) {
;     ...
;     if (row < M) PN_LOAD(v, row);
;     while (row < M) {
;         const int nrow = row + stride;
;         if (nrow < M) PN_LOAD(nv, nrow);
;         const int r = row < NLAT ? (row >> 11) : 16;
;         float ss = 0.f;
; #pragma unroll
;         for (int i = 0; i < 4; ++i) {
;             if (part != nullptr && row >= NLAT) {
;                 const size_t po = (size_t)(row - NLAT) * 1024 + i * 256 + lane * 4;
;                 const float4 p0 = *(const float4*)(part + po), p1 = *(const float4*)(part + (size_t)4096 * 1024 + po), cg = *(const float4*)(cgate + i * 256 + lane * 4);
;                 v[i].x += cg.x * (p0.x + p1.x); v[i].y += cg.y * (p0.y + p1.y); v[i].z += cg.z * (p0.z + p1.z); v[i].w += cg.w * (p0.w + p1.w);
;                 *(float4*)(hcout + po) = v[i];
;             }
;             ss += v[i].x * v[i].x + v[i].y * v[i].y + v[i].z * v[i].z + v[i].w * v[i].w; }
;         ss = wave_sum(ss);
;         const float rstd = rsqrtf(ss * (1.0f / 1024.0f) + EPS);
;         const float* mr = modl + (size_t)r * 6144;
; #pragma unroll
;         for (int i = 0; i < 4; ++i) {
;             const int k = i * 256 + lane * 4;
;             const float4 gg = *(const float4*)(g + k), scv = *(const float4*)(mr + sc_off + k), shv = *(const float4*)(mr + sh_off + k);
;             const float o0 = v[i].x * rstd * gg.x * (1.0f + scv.x) + shv.x, o1 = v[i].y * rstd * gg.y * (1.0f + scv.y) + shv.y;
;             const float o2 = v[i].z * rstd * gg.z * (1.0f + scv.z) + shv.z, o3 = v[i].w * rstd * gg.w * (1.0f + scv.w) + shv.w;
;             uint2 w; w.x = pk2(o0, o1); w.y = pk2(o2, o3);
;             *(uint2*)(A + (size_t)row * 1024 + k) = w;
;         }
	v_pk_mul_f32 v[242:243], v[172:173], v[172:173]
	v_pk_mul_f32 v[244:245], v[176:177], v[176:177]
	v_pk_mul_f32 v[246:247], v[174:175], v[174:175]
	v_pk_mul_f32 v[248:249], v[178:179], v[178:179]
	v_add_f32_e32 v204, v245, v244
	v_add_f32_e32 v205, v243, v242
	v_add_f32_e32 v204, v248, v204
	v_add_f32_e32 v205, v246, v205
	v_add_f32_e32 v204, v249, v204
	v_add_f32_e32 v205, v247, v205
	v_pk_mul_f32 v[242:243], v[180:181], v[180:181]
	v_pk_mul_f32 v[244:245], v[184:185], v[184:185]
	v_pk_mul_f32 v[246:247], v[182:183], v[182:183]
	v_pk_mul_f32 v[248:249], v[186:187], v[186:187]
	v_add_f32_e32 v206, v243, v242
	v_add_f32_e32 v207, v245, v244
	v_add_f32_e32 v206, v246, v206
	v_add_f32_e32 v207, v248, v207
	v_add_f32_e32 v206, v247, v206
	v_add_f32_e32 v207, v249, v207
	v_add_f32_e32 v204, v205, v204
	v_add_f32_e32 v204, v204, v206
	v_add_f32_e32 v204, v204, v207
	ds_swizzle_b32 v205, v204 offset:swizzle(SWAP,1)
	s_waitcnt lgkmcnt(0)
	v_add_f32_e32 v204, v204, v205
	ds_swizzle_b32 v205, v204 offset:swizzle(SWAP,2)
	s_waitcnt lgkmcnt(0)
	v_add_f32_e32 v204, v204, v205
	ds_swizzle_b32 v205, v204 offset:swizzle(SWAP,4)
	s_waitcnt lgkmcnt(0)
	v_add_f32_e32 v204, v204, v205
	ds_swizzle_b32 v205, v204 offset:swizzle(SWAP,8)
	s_waitcnt lgkmcnt(0)
	v_add_f32_e32 v204, v204, v205
	ds_swizzle_b32 v205, v204 offset:swizzle(SWAP,16)
	s_waitcnt lgkmcnt(0)
	v_add_f32_e32 v204, v204, v205
	v_mov_b32_e32 v205, v204
	s_nop 1
	v_permlane32_swap_b32_e32 v204, v205
	v_add_f32_e32 v204, v204, v205
	v_mov_b32_e32 v205, 0x358637bd
	v_fmamk_f32 v204, v204, 0x3a800000, v205
	v_rsq_f32_e32 v204, v204
	s_nop 0
	v_pk_mul_f32 v[172:173], v[172:173], v[204:205] op_sel_hi:[1,0]
	v_pk_mul_f32 v[174:175], v[174:175], v[204:205] op_sel_hi:[1,0]
	v_pk_mul_f32 v[172:173], v[188:189], v[172:173]
	v_pk_mul_f32 v[174:175], v[190:191], v[174:175]
	v_pk_fma_f32 v[172:173], v[34:35], v[172:173], v[224:225]
	v_pk_fma_f32 v[174:175], v[36:37], v[174:175], v[226:227]
	v_cvt_pk_bf16_f32 v172, v172, v173
	v_cvt_pk_bf16_f32 v173, v174, v175
	global_store_dwordx2 v146, v[172:173], s[66:67]
	v_pk_mul_f32 v[176:177], v[176:177], v[204:205] op_sel_hi:[1,0]
	v_pk_mul_f32 v[178:179], v[178:179], v[204:205] op_sel_hi:[1,0]
	v_pk_mul_f32 v[176:177], v[192:193], v[176:177]
	v_pk_mul_f32 v[178:179], v[194:195], v[178:179]
	v_pk_fma_f32 v[176:177], v[38:39], v[176:177], v[228:229]
	v_pk_fma_f32 v[178:179], v[40:41], v[178:179], v[230:231]
	v_cvt_pk_bf16_f32 v176, v176, v177
	v_cvt_pk_bf16_f32 v177, v178, v179
	global_store_dwordx2 v146, v[176:177], s[66:67] offset:512
	v_pk_mul_f32 v[180:181], v[180:181], v[204:205] op_sel_hi:[1,0]
	v_pk_mul_f32 v[182:183], v[182:183], v[204:205] op_sel_hi:[1,0]
	v_pk_mul_f32 v[180:181], v[196:197], v[180:181]
	v_pk_mul_f32 v[182:183], v[198:199], v[182:183]
	v_pk_fma_f32 v[180:181], v[42:43], v[180:181], v[232:233]
	v_pk_fma_f32 v[182:183], v[44:45], v[182:183], v[234:235]
	v_cvt_pk_bf16_f32 v180, v180, v181
	v_cvt_pk_bf16_f32 v181, v182, v183
	global_store_dwordx2 v146, v[180:181], s[66:67] offset:1024
	v_pk_mul_f32 v[184:185], v[184:185], v[204:205] op_sel_hi:[1,0]
	v_pk_mul_f32 v[186:187], v[186:187], v[204:205] op_sel_hi:[1,0]
	v_pk_mul_f32 v[184:185], v[200:201], v[184:185]
	v_pk_mul_f32 v[186:187], v[202:203], v[186:187]
	v_pk_fma_f32 v[184:185], v[46:47], v[184:185], v[236:237]
	v_pk_fma_f32 v[186:187], v[48:49], v[186:187], v[238:239]
	v_cvt_pk_bf16_f32 v184, v184, v185
	v_cvt_pk_bf16_f32 v185, v186, v187
	global_store_dwordx2 v146, v[184:185], s[66:67] offset:1536
	v_add_u32_e32 v146, 0x800, v146
	global_load_dwordx4 v[172:175], v144, s[16:17]
	global_load_dwordx4 v[176:179], v144, s[16:17] offset:1024
	global_load_dwordx4 v[180:183], v144, s[16:17] offset:2048
	global_load_dwordx4 v[184:187], v144, s[16:17] offset:3072
	v_add_u32_e32 v144, 0x1000, v144
	s_waitcnt vmcnt(40)
	v_pk_mul_f32 v[242:243], v[80:81], v[80:81]
	v_pk_mul_f32 v[244:245], v[84:85], v[84:85]
	v_pk_mul_f32 v[246:247], v[82:83], v[82:83]
	v_pk_mul_f32 v[248:249], v[86:87], v[86:87]
	v_add_f32_e32 v204, v245, v244
	v_add_f32_e32 v205, v243, v242
	v_add_f32_e32 v204, v248, v204
	v_add_f32_e32 v205, v246, v205
	v_add_f32_e32 v204, v249, v204
	v_add_f32_e32 v205, v247, v205
	v_pk_mul_f32 v[242:243], v[88:89], v[88:89]
	v_pk_mul_f32 v[244:245], v[92:93], v[92:93]
	v_pk_mul_f32 v[246:247], v[90:91], v[90:91]
	v_pk_mul_f32 v[248:249], v[94:95], v[94:95]
	v_add_f32_e32 v206, v243, v242
	v_add_f32_e32 v207, v245, v244
	v_add_f32_e32 v206, v246, v206
	v_add_f32_e32 v207, v248, v207
	v_add_f32_e32 v206, v247, v206
	v_add_f32_e32 v207, v249, v207
	v_add_f32_e32 v204, v205, v204
	v_add_f32_e32 v204, v204, v206
	v_add_f32_e32 v204, v204, v207
	ds_swizzle_b32 v205, v204 offset:swizzle(SWAP,1)
	s_waitcnt lgkmcnt(0)
	v_add_f32_e32 v204, v204, v205
	ds_swizzle_b32 v205, v204 offset:swizzle(SWAP,2)
	s_waitcnt lgkmcnt(0)
	v_add_f32_e32 v204, v204, v205
	ds_swizzle_b32 v205, v204 offset:swizzle(SWAP,4)
	s_waitcnt lgkmcnt(0)
	v_add_f32_e32 v204, v204, v205
	ds_swizzle_b32 v205, v204 offset:swizzle(SWAP,8)
	s_waitcnt lgkmcnt(0)
	v_add_f32_e32 v204, v204, v205
	ds_swizzle_b32 v205, v204 offset:swizzle(SWAP,16)
	s_waitcnt lgkmcnt(0)
; __device__ __forceinline__ unsigned pk2(float lo, float hi) { const g_f32x2 f = {lo, hi}; return __builtin_bit_cast(unsigned, __builtin_convertvector(f, g_bf16x2)); }
; #define PN_LOAD(dst, rw) do { const float* s_ = (rw) < NLAT ? hlat + (size_t)(rw) * 1024 : hctx + (size_t)((rw) - NLAT) * 1024; \
;         _Pragma("unroll") for (int i = 0; i < 4; ++i) dst[i] = *(const float4*)(s_ + i * 256 + lane * 4); } while (0)
; __device__ __forceinline__ void p_norm(const float* hlat, const float* hctx, const float* g, const float* modl, int sh_off, int sc_off, bf16_t* A, int M,
;                                        const float* part, const float* cgate, float* hcout) {
;     ...
;     if (row < M) PN_LOAD(v, row);
;     while (row < M) {
;         const int nrow = row + stride;
;         if (nrow < M) PN_LOAD(nv, nrow);
;         const int r = row < NLAT ? (row >> 11) : 16;
;         float ss = 0.f;
; #pragma unroll
;         for (int i = 0; i < 4; ++i) {
;             if (part != nullptr && row >= NLAT) {
;                 const size_t po = (size_t)(row - NLAT) * 1024 + i * 256 + lane * 4;
;                 const float4 p0 = *(const float4*)(part + po), p1 = *(const float4*)(part + (size_t)4096 * 1024 + po), cg = *(const float4*)(cgate + i * 256 + lane * 4);
;                 v[i].x += cg.x * (p0.x + p1.x); v[i].y += cg.y * (p0.y + p1.y); v[i].z += cg.z * (p0.z + p1.z); v[i].w += cg.w * (p0.w + p1.w);
;                 *(float4*)(hcout + po) = v[i];
;             }
;             ss += v[i].x * v[i].x + v[i].y * v[i].y + v[i].z * v[i].z + v[i].w * v[i].w; }
;         ss = wave_sum(ss);
;         const float rstd = rsqrtf(ss * (1.0f / 1024.0f) + EPS);
;         const float* mr = modl + (size_t)r * 6144;
; #pragma unroll
;         for (int i = 0; i < 4; ++i) {
;             const int k = i * 256 + lane * 4;
;             const float4 gg = *(const float4*)(g + k), scv = *(const float4*)(mr + sc_off + k), shv = *(const float4*)(mr + sh_off + k);
;             const float o0 = v[i].x * rstd * gg.x * (1.0f + scv.x) + shv.x, o1 = v[i].y * rstd * gg.y * (1.0f + scv.y) + shv.y;
;             const float o2 = v[i].z * rstd * gg.z * (1.0f + scv.z) + shv.z, o3 = v[i].w * rstd * gg.w * (1.0f + scv.w) + shv.w;
;             uint2 w; w.x = pk2(o0, o1); w.y = pk2(o2, o3);
;             *(uint2*)(A + (size_t)row * 1024 + k) = w;
;         }
	v_add_f32_e32 v204, v204, v205
	v_mov_b32_e32 v205, v204
	s_nop 1
	v_permlane32_swap_b32_e32 v204, v205
	v_add_f32_e32 v204, v204, v205
	v_mov_b32_e32 v205, 0x358637bd
	v_fmamk_f32 v204, v204, 0x3a800000, v205
	v_rsq_f32_e32 v204, v204
	s_nop 0
	v_pk_mul_f32 v[80:81], v[80:81], v[204:205] op_sel_hi:[1,0]
	v_pk_mul_f32 v[82:83], v[82:83], v[204:205] op_sel_hi:[1,0]
	v_pk_mul_f32 v[80:81], v[188:189], v[80:81]
	v_pk_mul_f32 v[82:83], v[190:191], v[82:83]
	v_pk_fma_f32 v[80:81], v[34:35], v[80:81], v[224:225]
	v_pk_fma_f32 v[82:83], v[36:37], v[82:83], v[226:227]
	v_cvt_pk_bf16_f32 v80, v80, v81
	v_cvt_pk_bf16_f32 v81, v82, v83
	global_store_dwordx2 v146, v[80:81], s[66:67]
	v_pk_mul_f32 v[84:85], v[84:85], v[204:205] op_sel_hi:[1,0]
	v_pk_mul_f32 v[86:87], v[86:87], v[204:205] op_sel_hi:[1,0]
	v_pk_mul_f32 v[84:85], v[192:193], v[84:85]
	v_pk_mul_f32 v[86:87], v[194:195], v[86:87]
	v_pk_fma_f32 v[84:85], v[38:39], v[84:85], v[228:229]
	v_pk_fma_f32 v[86:87], v[40:41], v[86:87], v[230:231]
	v_cvt_pk_bf16_f32 v84, v84, v85
	v_cvt_pk_bf16_f32 v85, v86, v87
	global_store_dwordx2 v146, v[84:85], s[66:67] offset:512
	v_pk_mul_f32 v[88:89], v[88:89], v[204:205] op_sel_hi:[1,0]
	v_pk_mul_f32 v[90:91], v[90:91], v[204:205] op_sel_hi:[1,0]
	v_pk_mul_f32 v[88:89], v[196:197], v[88:89]
	v_pk_mul_f32 v[90:91], v[198:199], v[90:91]
	v_pk_fma_f32 v[88:89], v[42:43], v[88:89], v[232:233]
	v_pk_fma_f32 v[90:91], v[44:45], v[90:91], v[234:235]
	v_cvt_pk_bf16_f32 v88, v88, v89
	v_cvt_pk_bf16_f32 v89, v90, v91
	global_store_dwordx2 v146, v[88:89], s[66:67] offset:1024
	v_pk_mul_f32 v[92:93], v[92:93], v[204:205] op_sel_hi:[1,0]
	v_pk_mul_f32 v[94:95], v[94:95], v[204:205] op_sel_hi:[1,0]
	v_pk_mul_f32 v[92:93], v[200:201], v[92:93]
	v_pk_mul_f32 v[94:95], v[202:203], v[94:95]
	v_pk_fma_f32 v[92:93], v[46:47], v[92:93], v[236:237]
	v_pk_fma_f32 v[94:95], v[48:49], v[94:95], v[238:239]
	v_cvt_pk_bf16_f32 v92, v92, v93
	v_cvt_pk_bf16_f32 v93, v94, v95
	global_store_dwordx2 v146, v[92:93], s[66:67] offset:1536
	v_add_u32_e32 v146, 0x800, v146
	s_waitcnt vmcnt(36)
	v_pk_mul_f32 v[242:243], v[96:97], v[96:97]
	v_pk_mul_f32 v[244:245], v[100:101], v[100:101]
	v_pk_mul_f32 v[246:247], v[98:99], v[98:99]
	v_pk_mul_f32 v[248:249], v[102:103], v[102:103]
	v_add_f32_e32 v204, v245, v244
	v_add_f32_e32 v205, v243, v242
	v_add_f32_e32 v204, v248, v204
	v_add_f32_e32 v205, v246, v205
	v_add_f32_e32 v204, v249, v204
	v_add_f32_e32 v205, v247, v205
	v_pk_mul_f32 v[242:243], v[104:105], v[104:105]
	v_pk_mul_f32 v[244:245], v[108:109], v[108:109]
	v_pk_mul_f32 v[246:247], v[106:107], v[106:107]
	v_pk_mul_f32 v[248:249], v[110:111], v[110:111]
	v_add_f32_e32 v206, v243, v242
	v_add_f32_e32 v207, v245, v244
	v_add_f32_e32 v206, v246, v206
	v_add_f32_e32 v207, v248, v207
	v_add_f32_e32 v206, v247, v206
	v_add_f32_e32 v207, v249, v207
	v_add_f32_e32 v204, v205, v204
	v_add_f32_e32 v204, v204, v206
	v_add_f32_e32 v204, v204, v207
	ds_swizzle_b32 v205, v204 offset:swizzle(SWAP,1)
	s_waitcnt lgkmcnt(0)
	v_add_f32_e32 v204, v204, v205
	ds_swizzle_b32 v205, v204 offset:swizzle(SWAP,2)
	s_waitcnt lgkmcnt(0)
	v_add_f32_e32 v204, v204, v205
	ds_swizzle_b32 v205, v204 offset:swizzle(SWAP,4)
	s_waitcnt lgkmcnt(0)
	v_add_f32_e32 v204, v204, v205
	ds_swizzle_b32 v205, v204 offset:swizzle(SWAP,8)
	s_waitcnt lgkmcnt(0)
	v_add_f32_e32 v204, v204, v205
	ds_swizzle_b32 v205, v204 offset:swizzle(SWAP,16)
	s_waitcnt lgkmcnt(0)
	v_add_f32_e32 v204, v204, v205
	v_mov_b32_e32 v205, v204
	s_nop 1
	v_permlane32_swap_b32_e32 v204, v205
	v_add_f32_e32 v204, v204, v205
	v_mov_b32_e32 v205, 0x358637bd
	v_fmamk_f32 v204, v204, 0x3a800000, v205
	v_rsq_f32_e32 v204, v204
	s_nop 0
	v_pk_mul_f32 v[96:97], v[96:97], v[204:205] op_sel_hi:[1,0]
	v_pk_mul_f32 v[98:99], v[98:99], v[204:205] op_sel_hi:[1,0]
	v_pk_mul_f32 v[96:97], v[188:189], v[96:97]
	v_pk_mul_f32 v[98:99], v[190:191], v[98:99]
	v_pk_fma_f32 v[96:97], v[34:35], v[96:97], v[224:225]
	v_pk_fma_f32 v[98:99], v[36:37], v[98:99], v[226:227]
	v_cvt_pk_bf16_f32 v96, v96, v97
	v_cvt_pk_bf16_f32 v97, v98, v99
	global_store_dwordx2 v146, v[96:97], s[66:67]
	v_pk_mul_f32 v[100:101], v[100:101], v[204:205] op_sel_hi:[1,0]
	v_pk_mul_f32 v[102:103], v[102:103], v[204:205] op_sel_hi:[1,0]
	v_pk_mul_f32 v[100:101], v[192:193], v[100:101]
	v_pk_mul_f32 v[102:103], v[194:195], v[102:103]
	v_pk_fma_f32 v[100:101], v[38:39], v[100:101], v[228:229]
	v_pk_fma_f32 v[102:103], v[40:41], v[102:103], v[230:231]
	v_cvt_pk_bf16_f32 v100, v100, v101
	v_cvt_pk_bf16_f32 v101, v102, v103
	global_store_dwordx2 v146, v[100:101], s[66:67] offset:512
	v_pk_mul_f32 v[104:105], v[104:105], v[204:205] op_sel_hi:[1,0]
	v_pk_mul_f32 v[106:107], v[106:107], v[204:205] op_sel_hi:[1,0]
	v_pk_mul_f32 v[104:105], v[196:197], v[104:105]
	v_pk_mul_f32 v[106:107], v[198:199], v[106:107]
	v_pk_fma_f32 v[104:105], v[42:43], v[104:105], v[232:233]
	v_pk_fma_f32 v[106:107], v[44:45], v[106:107], v[234:235]
	v_cvt_pk_bf16_f32 v104, v104, v105
	v_cvt_pk_bf16_f32 v105, v106, v107
	global_store_dwordx2 v146, v[104:105], s[66:67] offset:1024
	v_pk_mul_f32 v[108:109], v[108:109], v[204:205] op_sel_hi:[1,0]
	v_pk_mul_f32 v[110:111], v[110:111], v[204:205] op_sel_hi:[1,0]
	v_pk_mul_f32 v[108:109], v[200:201], v[108:109]
	v_pk_mul_f32 v[110:111], v[202:203], v[110:111]
	v_pk_fma_f32 v[108:109], v[46:47], v[108:109], v[236:237]
	v_pk_fma_f32 v[110:111], v[48:49], v[110:111], v[238:239]
	v_cvt_pk_bf16_f32 v108, v108, v109
	v_cvt_pk_bf16_f32 v109, v110, v111
	global_store_dwordx2 v146, v[108:109], s[66:67] offset:1536
	v_add_u32_e32 v146, 0x800, v146
	s_waitcnt vmcnt(32)
; __device__ __forceinline__ unsigned pk2(float lo, float hi) { const g_f32x2 f = {lo, hi}; return __builtin_bit_cast(unsigned, __builtin_convertvector(f, g_bf16x2)); }
; #define PN_LOAD(dst, rw) do { const float* s_ = (rw) < NLAT ? hlat + (size_t)(rw) * 1024 : hctx + (size_t)((rw) - NLAT) * 1024; \
;         _Pragma("unroll") for (int i = 0; i < 4; ++i) dst[i] = *(const float4*)(s_ + i * 256 + lane * 4); } while (0)
; __device__ __forceinline__ void p_norm(const float* hlat, const float* hctx, const float* g, const float* modl, int sh_off, int sc_off, bf16_t* A, int M,
;                                        const float* part, const float* cgate, float* hcout) {
;     ...
;     if (row < M) PN_LOAD(v, row);
;     while (row < M) {
;         const int nrow = row + stride;
;         if (nrow < M) PN_LOAD(nv, nrow);
;         const int r = row < NLAT ? (row >> 11) : 16;
;         float ss = 0.f;
; #pragma unroll
;         for (int i = 0; i < 4; ++i) {
;             if (part != nullptr && row >= NLAT) {
;                 const size_t po = (size_t)(row - NLAT) * 1024 + i * 256 + lane * 4;
;                 const float4 p0 = *(const float4*)(part + po), p1 = *(const float4*)(part + (size_t)4096 * 1024 + po), cg = *(const float4*)(cgate + i * 256 + lane * 4);
;                 v[i].x += cg.x * (p0.x + p1.x); v[i].y += cg.y * (p0.y + p1.y); v[i].z += cg.z * (p0.z + p1.z); v[i].w += cg.w * (p0.w + p1.w);
;                 *(float4*)(hcout + po) = v[i];
;             }
;             ss += v[i].x * v[i].x + v[i].y * v[i].y + v[i].z * v[i].z + v[i].w * v[i].w; }
;         ss = wave_sum(ss);
;         const float rstd = rsqrtf(ss * (1.0f / 1024.0f) + EPS);
;         const float* mr = modl + (size_t)r * 6144;
; #pragma unroll
;         for (int i = 0; i < 4; ++i) {
;             const int k = i * 256 + lane * 4;
;             const float4 gg = *(const float4*)(g + k), scv = *(const float4*)(mr + sc_off + k), shv = *(const float4*)(mr + sh_off + k);
;             const float o0 = v[i].x * rstd * gg.x * (1.0f + scv.x) + shv.x, o1 = v[i].y * rstd * gg.y * (1.0f + scv.y) + shv.y;
;             const float o2 = v[i].z * rstd * gg.z * (1.0f + scv.z) + shv.z, o3 = v[i].w * rstd * gg.w * (1.0f + scv.w) + shv.w;
;             uint2 w; w.x = pk2(o0, o1); w.y = pk2(o2, o3);
;             *(uint2*)(A + (size_t)row * 1024 + k) = w;
;         }
	v_pk_mul_f32 v[242:243], v[112:113], v[112:113]
	v_pk_mul_f32 v[244:245], v[116:117], v[116:117]
	v_pk_mul_f32 v[246:247], v[114:115], v[114:115]
	v_pk_mul_f32 v[248:249], v[118:119], v[118:119]
	v_add_f32_e32 v204, v245, v244
	v_add_f32_e32 v205, v243, v242
	v_add_f32_e32 v204, v248, v204
	v_add_f32_e32 v205, v246, v205
	v_add_f32_e32 v204, v249, v204
	v_add_f32_e32 v205, v247, v205
	v_pk_mul_f32 v[242:243], v[120:121], v[120:121]
	v_pk_mul_f32 v[244:245], v[124:125], v[124:125]
	v_pk_mul_f32 v[246:247], v[122:123], v[122:123]
	v_pk_mul_f32 v[248:249], v[126:127], v[126:127]
	v_add_f32_e32 v206, v243, v242
	v_add_f32_e32 v207, v245, v244
	v_add_f32_e32 v206, v246, v206
	v_add_f32_e32 v207, v248, v207
	v_add_f32_e32 v206, v247, v206
	v_add_f32_e32 v207, v249, v207
	v_add_f32_e32 v204, v205, v204
	v_add_f32_e32 v204, v204, v206
	v_add_f32_e32 v204, v204, v207
	ds_swizzle_b32 v205, v204 offset:swizzle(SWAP,1)
	s_waitcnt lgkmcnt(0)
	v_add_f32_e32 v204, v204, v205
	ds_swizzle_b32 v205, v204 offset:swizzle(SWAP,2)
	s_waitcnt lgkmcnt(0)
	v_add_f32_e32 v204, v204, v205
	ds_swizzle_b32 v205, v204 offset:swizzle(SWAP,4)
	s_waitcnt lgkmcnt(0)
	v_add_f32_e32 v204, v204, v205
	ds_swizzle_b32 v205, v204 offset:swizzle(SWAP,8)
	s_waitcnt lgkmcnt(0)
	v_add_f32_e32 v204, v204, v205
	ds_swizzle_b32 v205, v204 offset:swizzle(SWAP,16)
	s_waitcnt lgkmcnt(0)
	v_add_f32_e32 v204, v204, v205
	v_mov_b32_e32 v205, v204
	s_nop 1
	v_permlane32_swap_b32_e32 v204, v205
	v_add_f32_e32 v204, v204, v205
	v_mov_b32_e32 v205, 0x358637bd
	v_fmamk_f32 v204, v204, 0x3a800000, v205
	v_rsq_f32_e32 v204, v204
	s_nop 0
	v_pk_mul_f32 v[112:113], v[112:113], v[204:205] op_sel_hi:[1,0]
	v_pk_mul_f32 v[114:115], v[114:115], v[204:205] op_sel_hi:[1,0]
	v_pk_mul_f32 v[112:113], v[188:189], v[112:113]
	v_pk_mul_f32 v[114:115], v[190:191], v[114:115]
	v_pk_fma_f32 v[112:113], v[34:35], v[112:113], v[224:225]
	v_pk_fma_f32 v[114:115], v[36:37], v[114:115], v[226:227]
	v_cvt_pk_bf16_f32 v112, v112, v113
	v_cvt_pk_bf16_f32 v113, v114, v115
	global_store_dwordx2 v146, v[112:113], s[66:67]
	v_pk_mul_f32 v[116:117], v[116:117], v[204:205] op_sel_hi:[1,0]
	v_pk_mul_f32 v[118:119], v[118:119], v[204:205] op_sel_hi:[1,0]
	v_pk_mul_f32 v[116:117], v[192:193], v[116:117]
	v_pk_mul_f32 v[118:119], v[194:195], v[118:119]
	v_pk_fma_f32 v[116:117], v[38:39], v[116:117], v[228:229]
	v_pk_fma_f32 v[118:119], v[40:41], v[118:119], v[230:231]
	v_cvt_pk_bf16_f32 v116, v116, v117
	v_cvt_pk_bf16_f32 v117, v118, v119
	global_store_dwordx2 v146, v[116:117], s[66:67] offset:512
	v_pk_mul_f32 v[120:121], v[120:121], v[204:205] op_sel_hi:[1,0]
	v_pk_mul_f32 v[122:123], v[122:123], v[204:205] op_sel_hi:[1,0]
	v_pk_mul_f32 v[120:121], v[196:197], v[120:121]
	v_pk_mul_f32 v[122:123], v[198:199], v[122:123]
	v_pk_fma_f32 v[120:121], v[42:43], v[120:121], v[232:233]
	v_pk_fma_f32 v[122:123], v[44:45], v[122:123], v[234:235]
	v_cvt_pk_bf16_f32 v120, v120, v121
	v_cvt_pk_bf16_f32 v121, v122, v123
	global_store_dwordx2 v146, v[120:121], s[66:67] offset:1024
	v_pk_mul_f32 v[124:125], v[124:125], v[204:205] op_sel_hi:[1,0]
	v_pk_mul_f32 v[126:127], v[126:127], v[204:205] op_sel_hi:[1,0]
	v_pk_mul_f32 v[124:125], v[200:201], v[124:125]
	v_pk_mul_f32 v[126:127], v[202:203], v[126:127]
	v_pk_fma_f32 v[124:125], v[46:47], v[124:125], v[236:237]
	v_pk_fma_f32 v[126:127], v[48:49], v[126:127], v[238:239]
	v_cvt_pk_bf16_f32 v124, v124, v125
	v_cvt_pk_bf16_f32 v125, v126, v127
	global_store_dwordx2 v146, v[124:125], s[66:67] offset:1536
	v_add_u32_e32 v146, 0x800, v146
	s_waitcnt vmcnt(28)
	v_pk_mul_f32 v[242:243], v[128:129], v[128:129]
	v_pk_mul_f32 v[244:245], v[132:133], v[132:133]
	v_pk_mul_f32 v[246:247], v[130:131], v[130:131]
	v_pk_mul_f32 v[248:249], v[134:135], v[134:135]
	v_add_f32_e32 v204, v245, v244
	v_add_f32_e32 v205, v243, v242
	v_add_f32_e32 v204, v248, v204
	v_add_f32_e32 v205, v246, v205
	v_add_f32_e32 v204, v249, v204
	v_add_f32_e32 v205, v247, v205
	v_pk_mul_f32 v[242:243], v[136:137], v[136:137]
	v_pk_mul_f32 v[244:245], v[140:141], v[140:141]
	v_pk_mul_f32 v[246:247], v[138:139], v[138:139]
	v_pk_mul_f32 v[248:249], v[142:143], v[142:143]
	v_add_f32_e32 v206, v243, v242
	v_add_f32_e32 v207, v245, v244
	v_add_f32_e32 v206, v246, v206
	v_add_f32_e32 v207, v248, v207
	v_add_f32_e32 v206, v247, v206
	v_add_f32_e32 v207, v249, v207
	v_add_f32_e32 v204, v205, v204
	v_add_f32_e32 v204, v204, v206
	v_add_f32_e32 v204, v204, v207
	ds_swizzle_b32 v205, v204 offset:swizzle(SWAP,1)
	s_waitcnt lgkmcnt(0)
	v_add_f32_e32 v204, v204, v205
	ds_swizzle_b32 v205, v204 offset:swizzle(SWAP,2)
	s_waitcnt lgkmcnt(0)
	v_add_f32_e32 v204, v204, v205
	ds_swizzle_b32 v205, v204 offset:swizzle(SWAP,4)
	s_waitcnt lgkmcnt(0)
	v_add_f32_e32 v204, v204, v205
	ds_swizzle_b32 v205, v204 offset:swizzle(SWAP,8)
	s_waitcnt lgkmcnt(0)
	v_add_f32_e32 v204, v204, v205
	ds_swizzle_b32 v205, v204 offset:swizzle(SWAP,16)
	s_waitcnt lgkmcnt(0)
; __device__ __forceinline__ unsigned pk2(float lo, float hi) { const g_f32x2 f = {lo, hi}; return __builtin_bit_cast(unsigned, __builtin_convertvector(f, g_bf16x2)); }
; #define PN_LOAD(dst, rw) do { const float* s_ = (rw) < NLAT ? hlat + (size_t)(rw) * 1024 : hctx + (size_t)((rw) - NLAT) * 1024; \
;         _Pragma("unroll") for (int i = 0; i < 4; ++i) dst[i] = *(const float4*)(s_ + i * 256 + lane * 4); } while (0)
; __device__ __forceinline__ void p_norm(const float* hlat, const float* hctx, const float* g, const float* modl, int sh_off, int sc_off, bf16_t* A, int M,
;                                        const float* part, const float* cgate, float* hcout) {
;     ...
;     if (row < M) PN_LOAD(v, row);
;     while (row < M) {
;         const int nrow = row + stride;
;         if (nrow < M) PN_LOAD(nv, nrow);
;         const int r = row < NLAT ? (row >> 11) : 16;
;         float ss = 0.f;
; #pragma unroll
;         for (int i = 0; i < 4; ++i) {
;             if (part != nullptr && row >= NLAT) {
;                 const size_t po = (size_t)(row - NLAT) * 1024 + i * 256 + lane * 4;
;                 const float4 p0 = *(const float4*)(part + po), p1 = *(const float4*)(part + (size_t)4096 * 1024 + po), cg = *(const float4*)(cgate + i * 256 + lane * 4);
;                 v[i].x += cg.x * (p0.x + p1.x); v[i].y += cg.y * (p0.y + p1.y); v[i].z += cg.z * (p0.z + p1.z); v[i].w += cg.w * (p0.w + p1.w);
;                 *(float4*)(hcout + po) = v[i];
;             }
;             ss += v[i].x * v[i].x + v[i].y * v[i].y + v[i].z * v[i].z + v[i].w * v[i].w; }
;         ss = wave_sum(ss);
;         const float rstd = rsqrtf(ss * (1.0f / 1024.0f) + EPS);
;         const float* mr = modl + (size_t)r * 6144;
; #pragma unroll
;         for (int i = 0; i < 4; ++i) {
;             const int k = i * 256 + lane * 4;
;             const float4 gg = *(const float4*)(g + k), scv = *(const float4*)(mr + sc_off + k), shv = *(const float4*)(mr + sh_off + k);
;             const float o0 = v[i].x * rstd * gg.x * (1.0f + scv.x) + shv.x, o1 = v[i].y * rstd * gg.y * (1.0f + scv.y) + shv.y;
;             const float o2 = v[i].z * rstd * gg.z * (1.0f + scv.z) + shv.z, o3 = v[i].w * rstd * gg.w * (1.0f + scv.w) + shv.w;
;             uint2 w; w.x = pk2(o0, o1); w.y = pk2(o2, o3);
;             *(uint2*)(A + (size_t)row * 1024 + k) = w;
;         }
	v_add_f32_e32 v204, v204, v205
	v_mov_b32_e32 v205, v204
	s_nop 1
	v_permlane32_swap_b32_e32 v204, v205
	v_add_f32_e32 v204, v204, v205
	v_mov_b32_e32 v205, 0x358637bd
	v_fmamk_f32 v204, v204, 0x3a800000, v205
	v_rsq_f32_e32 v204, v204
	s_nop 0
	v_pk_mul_f32 v[128:129], v[128:129], v[204:205] op_sel_hi:[1,0]
	v_pk_mul_f32 v[130:131], v[130:131], v[204:205] op_sel_hi:[1,0]
	v_pk_mul_f32 v[128:129], v[188:189], v[128:129]
	v_pk_mul_f32 v[130:131], v[190:191], v[130:131]
	v_pk_fma_f32 v[128:129], v[34:35], v[128:129], v[224:225]
	v_pk_fma_f32 v[130:131], v[36:37], v[130:131], v[226:227]
	v_cvt_pk_bf16_f32 v128, v128, v129
	v_cvt_pk_bf16_f32 v129, v130, v131
	global_store_dwordx2 v146, v[128:129], s[66:67]
	v_pk_mul_f32 v[132:133], v[132:133], v[204:205] op_sel_hi:[1,0]
	v_pk_mul_f32 v[134:135], v[134:135], v[204:205] op_sel_hi:[1,0]
	v_pk_mul_f32 v[132:133], v[192:193], v[132:133]
	v_pk_mul_f32 v[134:135], v[194:195], v[134:135]
	v_pk_fma_f32 v[132:133], v[38:39], v[132:133], v[228:229]
	v_pk_fma_f32 v[134:135], v[40:41], v[134:135], v[230:231]
	v_cvt_pk_bf16_f32 v132, v132, v133
	v_cvt_pk_bf16_f32 v133, v134, v135
	global_store_dwordx2 v146, v[132:133], s[66:67] offset:512
	v_pk_mul_f32 v[136:137], v[136:137], v[204:205] op_sel_hi:[1,0]
	v_pk_mul_f32 v[138:139], v[138:139], v[204:205] op_sel_hi:[1,0]
	v_pk_mul_f32 v[136:137], v[196:197], v[136:137]
	v_pk_mul_f32 v[138:139], v[198:199], v[138:139]
	v_pk_fma_f32 v[136:137], v[42:43], v[136:137], v[232:233]
	v_pk_fma_f32 v[138:139], v[44:45], v[138:139], v[234:235]
	v_cvt_pk_bf16_f32 v136, v136, v137
	v_cvt_pk_bf16_f32 v137, v138, v139
	global_store_dwordx2 v146, v[136:137], s[66:67] offset:1024
	v_pk_mul_f32 v[140:141], v[140:141], v[204:205] op_sel_hi:[1,0]
	v_pk_mul_f32 v[142:143], v[142:143], v[204:205] op_sel_hi:[1,0]
	v_pk_mul_f32 v[140:141], v[200:201], v[140:141]
	v_pk_mul_f32 v[142:143], v[202:203], v[142:143]
	v_pk_fma_f32 v[140:141], v[46:47], v[140:141], v[236:237]
	v_pk_fma_f32 v[142:143], v[48:49], v[142:143], v[238:239]
	v_cvt_pk_bf16_f32 v140, v140, v141
	v_cvt_pk_bf16_f32 v141, v142, v143
	global_store_dwordx2 v146, v[140:141], s[66:67] offset:1536
	v_add_u32_e32 v146, 0x800, v146
	v_add_u32_e32 v151, 0x60000, v241
	global_load_dwordx4 v[34:37], v151, s[98:99]
	global_load_dwordx4 v[38:41], v151, s[98:99] offset:1024
	global_load_dwordx4 v[42:45], v151, s[98:99] offset:2048
	global_load_dwordx4 v[46:49], v151, s[98:99] offset:3072
	global_load_dwordx4 v[224:227], v151, s[50:51]
	global_load_dwordx4 v[228:231], v151, s[50:51] offset:1024
	global_load_dwordx4 v[232:235], v151, s[50:51] offset:2048
	global_load_dwordx4 v[236:239], v151, s[50:51] offset:3072
	s_waitcnt vmcnt(32)
	v_pk_mul_f32 v[242:243], v[156:157], v[156:157]
	v_pk_mul_f32 v[244:245], v[160:161], v[160:161]
	v_pk_mul_f32 v[246:247], v[158:159], v[158:159]
	v_pk_mul_f32 v[248:249], v[162:163], v[162:163]
	v_add_f32_e32 v204, v245, v244
	v_add_f32_e32 v205, v243, v242
	v_add_f32_e32 v204, v248, v204
	v_add_f32_e32 v205, v246, v205
	v_add_f32_e32 v204, v249, v204
	v_add_f32_e32 v205, v247, v205
	v_pk_mul_f32 v[242:243], v[164:165], v[164:165]
	v_pk_mul_f32 v[244:245], v[168:169], v[168:169]
	v_pk_mul_f32 v[246:247], v[166:167], v[166:167]
	v_pk_mul_f32 v[248:249], v[170:171], v[170:171]
	v_add_f32_e32 v206, v243, v242
	v_add_f32_e32 v207, v245, v244
	v_add_f32_e32 v206, v246, v206
	v_add_f32_e32 v207, v248, v207
	v_add_f32_e32 v206, v247, v206
	v_add_f32_e32 v207, v249, v207
	v_add_f32_e32 v204, v205, v204
	v_add_f32_e32 v204, v204, v206
	v_add_f32_e32 v204, v204, v207
	ds_swizzle_b32 v205, v204 offset:swizzle(SWAP,1)
	s_waitcnt lgkmcnt(0)
	v_add_f32_e32 v204, v204, v205
	ds_swizzle_b32 v205, v204 offset:swizzle(SWAP,2)
	s_waitcnt lgkmcnt(0)
	v_add_f32_e32 v204, v204, v205
	ds_swizzle_b32 v205, v204 offset:swizzle(SWAP,4)
	s_waitcnt lgkmcnt(0)
	v_add_f32_e32 v204, v204, v205
	ds_swizzle_b32 v205, v204 offset:swizzle(SWAP,8)
	s_waitcnt lgkmcnt(0)
	v_add_f32_e32 v204, v204, v205
	ds_swizzle_b32 v205, v204 offset:swizzle(SWAP,16)
	s_waitcnt lgkmcnt(0)
	v_add_f32_e32 v204, v204, v205
	v_mov_b32_e32 v205, v204
	s_nop 1
	v_permlane32_swap_b32_e32 v204, v205
	v_add_f32_e32 v204, v204, v205
	v_mov_b32_e32 v205, 0x358637bd
	v_fmamk_f32 v204, v204, 0x3a800000, v205
	v_rsq_f32_e32 v204, v204
	s_nop 0
	s_waitcnt vmcnt(0)
; __device__ __forceinline__ unsigned pk2(float lo, float hi) { const g_f32x2 f = {lo, hi}; return __builtin_bit_cast(unsigned, __builtin_convertvector(f, g_bf16x2)); }
; #define PN_LOAD(dst, rw) do { const float* s_ = (rw) < NLAT ? hlat + (size_t)(rw) * 1024 : hctx + (size_t)((rw) - NLAT) * 1024; \
;         _Pragma("unroll") for (int i = 0; i < 4; ++i) dst[i] = *(const float4*)(s_ + i * 256 + lane * 4); } while (0)
; __device__ __forceinline__ void p_norm(const float* hlat, const float* hctx, const float* g, const float* modl, int sh_off, int sc_off, bf16_t* A, int M,
;                                        const float* part, const float* cgate, float* hcout) {
;     ...
;     if (row < M) PN_LOAD(v, row);
;     while (row < M) {
;         const int nrow = row + stride;
;         if (nrow < M) PN_LOAD(nv, nrow);
;         const int r = row < NLAT ? (row >> 11) : 16;
;         float ss = 0.f;
; #pragma unroll
;         for (int i = 0; i < 4; ++i) {
;             if (part != nullptr && row >= NLAT) {
;                 const size_t po = (size_t)(row - NLAT) * 1024 + i * 256 + lane * 4;
;                 const float4 p0 = *(const float4*)(part + po), p1 = *(const float4*)(part + (size_t)4096 * 1024 + po), cg = *(const float4*)(cgate + i * 256 + lane * 4);
;                 v[i].x += cg.x * (p0.x + p1.x); v[i].y += cg.y * (p0.y + p1.y); v[i].z += cg.z * (p0.z + p1.z); v[i].w += cg.w * (p0.w + p1.w);
;                 *(float4*)(hcout + po) = v[i];
;             }
;             ss += v[i].x * v[i].x + v[i].y * v[i].y + v[i].z * v[i].z + v[i].w * v[i].w; }
;         ss = wave_sum(ss);
;         const float rstd = rsqrtf(ss * (1.0f / 1024.0f) + EPS);
;         const float* mr = modl + (size_t)r * 6144;
; #pragma unroll
;         for (int i = 0; i < 4; ++i) {
;             const int k = i * 256 + lane * 4;
;             const float4 gg = *(const float4*)(g + k), scv = *(const float4*)(mr + sc_off + k), shv = *(const float4*)(mr + sh_off + k);
;             const float o0 = v[i].x * rstd * gg.x * (1.0f + scv.x) + shv.x, o1 = v[i].y * rstd * gg.y * (1.0f + scv.y) + shv.y;
;             const float o2 = v[i].z * rstd * gg.z * (1.0f + scv.z) + shv.z, o3 = v[i].w * rstd * gg.w * (1.0f + scv.w) + shv.w;
;             uint2 w; w.x = pk2(o0, o1); w.y = pk2(o2, o3);
;             *(uint2*)(A + (size_t)row * 1024 + k) = w;
;         }
	v_pk_add_f32 v[34:35], v[34:35], 1.0 op_sel_hi:[1,0]
	v_pk_add_f32 v[36:37], v[36:37], 1.0 op_sel_hi:[1,0]
	v_pk_add_f32 v[38:39], v[38:39], 1.0 op_sel_hi:[1,0]
	v_pk_add_f32 v[40:41], v[40:41], 1.0 op_sel_hi:[1,0]
	v_pk_add_f32 v[42:43], v[42:43], 1.0 op_sel_hi:[1,0]
	v_pk_add_f32 v[44:45], v[44:45], 1.0 op_sel_hi:[1,0]
	v_pk_add_f32 v[46:47], v[46:47], 1.0 op_sel_hi:[1,0]
	v_pk_add_f32 v[48:49], v[48:49], 1.0 op_sel_hi:[1,0]
	v_lshlrev_b32_e32 v146, 12, v50
	v_lshl_add_u32 v146, v240, 3, v146
	v_add_u32_e32 v146, 0x4000000, v146
	v_pk_mul_f32 v[156:157], v[156:157], v[204:205] op_sel_hi:[1,0]
	v_pk_mul_f32 v[158:159], v[158:159], v[204:205] op_sel_hi:[1,0]
	v_pk_mul_f32 v[156:157], v[188:189], v[156:157]
	v_pk_mul_f32 v[158:159], v[190:191], v[158:159]
	v_pk_fma_f32 v[156:157], v[34:35], v[156:157], v[224:225]
	v_pk_fma_f32 v[158:159], v[36:37], v[158:159], v[226:227]
	v_cvt_pk_bf16_f32 v156, v156, v157
	v_cvt_pk_bf16_f32 v157, v158, v159
	global_store_dwordx2 v146, v[156:157], s[66:67]
	v_pk_mul_f32 v[160:161], v[160:161], v[204:205] op_sel_hi:[1,0]
	v_pk_mul_f32 v[162:163], v[162:163], v[204:205] op_sel_hi:[1,0]
	v_pk_mul_f32 v[160:161], v[192:193], v[160:161]
	v_pk_mul_f32 v[162:163], v[194:195], v[162:163]
	v_pk_fma_f32 v[160:161], v[38:39], v[160:161], v[228:229]
	v_pk_fma_f32 v[162:163], v[40:41], v[162:163], v[230:231]
	v_cvt_pk_bf16_f32 v160, v160, v161
	v_cvt_pk_bf16_f32 v161, v162, v163
	global_store_dwordx2 v146, v[160:161], s[66:67] offset:512
	v_pk_mul_f32 v[164:165], v[164:165], v[204:205] op_sel_hi:[1,0]
	v_pk_mul_f32 v[166:167], v[166:167], v[204:205] op_sel_hi:[1,0]
	v_pk_mul_f32 v[164:165], v[196:197], v[164:165]
	v_pk_mul_f32 v[166:167], v[198:199], v[166:167]
	v_pk_fma_f32 v[164:165], v[42:43], v[164:165], v[232:233]
	v_pk_fma_f32 v[166:167], v[44:45], v[166:167], v[234:235]
	v_cvt_pk_bf16_f32 v164, v164, v165
	v_cvt_pk_bf16_f32 v165, v166, v167
	global_store_dwordx2 v146, v[164:165], s[66:67] offset:1024
	v_pk_mul_f32 v[168:169], v[168:169], v[204:205] op_sel_hi:[1,0]
	v_pk_mul_f32 v[170:171], v[170:171], v[204:205] op_sel_hi:[1,0]
	v_pk_mul_f32 v[168:169], v[200:201], v[168:169]
	v_pk_mul_f32 v[170:171], v[202:203], v[170:171]
	v_pk_fma_f32 v[168:169], v[46:47], v[168:169], v[236:237]
	v_pk_fma_f32 v[170:171], v[48:49], v[170:171], v[238:239]
	v_cvt_pk_bf16_f32 v168, v168, v169
	v_cvt_pk_bf16_f32 v169, v170, v171
	global_store_dwordx2 v146, v[168:169], s[66:67] offset:1536
	v_add_u32_e32 v146, 0x800, v146
	v_pk_mul_f32 v[242:243], v[172:173], v[172:173]
	v_pk_mul_f32 v[244:245], v[176:177], v[176:177]
	v_pk_mul_f32 v[246:247], v[174:175], v[174:175]
	v_pk_mul_f32 v[248:249], v[178:179], v[178:179]
	v_add_f32_e32 v204, v245, v244
	v_add_f32_e32 v205, v243, v242
	v_add_f32_e32 v204, v248, v204
	v_add_f32_e32 v205, v246, v205
	v_add_f32_e32 v204, v249, v204
	v_add_f32_e32 v205, v247, v205
	v_pk_mul_f32 v[242:243], v[180:181], v[180:181]
	v_pk_mul_f32 v[244:245], v[184:185], v[184:185]
	v_pk_mul_f32 v[246:247], v[182:183], v[182:183]
	v_pk_mul_f32 v[248:249], v[186:187], v[186:187]
	v_add_f32_e32 v206, v243, v242
	v_add_f32_e32 v207, v245, v244
	v_add_f32_e32 v206, v246, v206
	v_add_f32_e32 v207, v248, v207
	v_add_f32_e32 v206, v247, v206
	v_add_f32_e32 v207, v249, v207
	v_add_f32_e32 v204, v205, v204
	v_add_f32_e32 v204, v204, v206
	v_add_f32_e32 v204, v204, v207
	ds_swizzle_b32 v205, v204 offset:swizzle(SWAP,1)
	s_waitcnt lgkmcnt(0)
	v_add_f32_e32 v204, v204, v205
	ds_swizzle_b32 v205, v204 offset:swizzle(SWAP,2)
	s_waitcnt lgkmcnt(0)
	v_add_f32_e32 v204, v204, v205
	ds_swizzle_b32 v205, v204 offset:swizzle(SWAP,4)
	s_waitcnt lgkmcnt(0)
	v_add_f32_e32 v204, v204, v205
	ds_swizzle_b32 v205, v204 offset:swizzle(SWAP,8)
	s_waitcnt lgkmcnt(0)
	v_add_f32_e32 v204, v204, v205
	ds_swizzle_b32 v205, v204 offset:swizzle(SWAP,16)
	s_waitcnt lgkmcnt(0)
	v_add_f32_e32 v204, v204, v205
	v_mov_b32_e32 v205, v204
	s_nop 1
	v_permlane32_swap_b32_e32 v204, v205
	v_add_f32_e32 v204, v204, v205
	v_mov_b32_e32 v205, 0x358637bd
	v_fmamk_f32 v204, v204, 0x3a800000, v205
	v_rsq_f32_e32 v204, v204
	s_nop 0
	v_pk_mul_f32 v[172:173], v[172:173], v[204:205] op_sel_hi:[1,0]
	v_pk_mul_f32 v[174:175], v[174:175], v[204:205] op_sel_hi:[1,0]
	v_pk_mul_f32 v[172:173], v[188:189], v[172:173]
	v_pk_mul_f32 v[174:175], v[190:191], v[174:175]
	v_pk_fma_f32 v[172:173], v[34:35], v[172:173], v[224:225]
	v_pk_fma_f32 v[174:175], v[36:37], v[174:175], v[226:227]
	v_cvt_pk_bf16_f32 v172, v172, v173
	v_cvt_pk_bf16_f32 v173, v174, v175
	global_store_dwordx2 v146, v[172:173], s[66:67]
	v_pk_mul_f32 v[176:177], v[176:177], v[204:205] op_sel_hi:[1,0]
	v_pk_mul_f32 v[178:179], v[178:179], v[204:205] op_sel_hi:[1,0]
	v_pk_mul_f32 v[176:177], v[192:193], v[176:177]
	v_pk_mul_f32 v[178:179], v[194:195], v[178:179]
	v_pk_fma_f32 v[176:177], v[38:39], v[176:177], v[228:229]
	v_pk_fma_f32 v[178:179], v[40:41], v[178:179], v[230:231]
	v_cvt_pk_bf16_f32 v176, v176, v177
	v_cvt_pk_bf16_f32 v177, v178, v179
	global_store_dwordx2 v146, v[176:177], s[66:67] offset:512
	v_pk_mul_f32 v[180:181], v[180:181], v[204:205] op_sel_hi:[1,0]
	v_pk_mul_f32 v[182:183], v[182:183], v[204:205] op_sel_hi:[1,0]
	v_pk_mul_f32 v[180:181], v[196:197], v[180:181]
	v_pk_mul_f32 v[182:183], v[198:199], v[182:183]
	v_pk_fma_f32 v[180:181], v[42:43], v[180:181], v[232:233]
	v_pk_fma_f32 v[182:183], v[44:45], v[182:183], v[234:235]
	v_cvt_pk_bf16_f32 v180, v180, v181
	v_cvt_pk_bf16_f32 v181, v182, v183
	global_store_dwordx2 v146, v[180:181], s[66:67] offset:1024
	v_pk_mul_f32 v[184:185], v[184:185], v[204:205] op_sel_hi:[1,0]
	v_pk_mul_f32 v[186:187], v[186:187], v[204:205] op_sel_hi:[1,0]
	v_pk_mul_f32 v[184:185], v[200:201], v[184:185]
	v_pk_mul_f32 v[186:187], v[202:203], v[186:187]
	v_pk_fma_f32 v[184:185], v[46:47], v[184:185], v[236:237]
	v_pk_fma_f32 v[186:187], v[48:49], v[186:187], v[238:239]
	v_cvt_pk_bf16_f32 v184, v184, v185
	v_cvt_pk_bf16_f32 v185, v186, v187
	global_store_dwordx2 v146, v[184:185], s[66:67] offset:1536
	v_add_u32_e32 v146, 0x800, v146

; __device__ __forceinline__ unsigned pk2(float lo, float hi) { const g_f32x2 f = {lo, hi}; return __builtin_bit_cast(unsigned, __builtin_convertvector(f, g_bf16x2)); }
; __device__ __forceinline__ int obid() { int b = blockIdx.x; asm volatile("" : "+s"(b)); return b; }
; __device__ __forceinline__ void p_norm(const float* hlat, const float* hctx, const float* g, const float* modl, int sh_off, int sc_off, bf16_t* A, int M,
;                                        const float* part, const float* cgate, float* hcout) {
;     const int tid = otid(), lane = tid & 63, wave = tid >> 6;
;     const int stride = gridDim.x * 8;
;     int row = obid() * 8 + wave;
;     float4 v[4], nv[4];
;     ...
;     if (row < M) PN_LOAD(v, row);
;     while (row < M) {
;         const int nrow = row + stride;
;         if (nrow < M) PN_LOAD(nv, nrow);
;         const int r = row < NLAT ? (row >> 11) : 16;
;         float ss = 0.f;
; #pragma unroll
;         for (int i = 0; i < 4; ++i) {
;             if (part != nullptr && row >= NLAT) {
;                 const size_t po = (size_t)(row - NLAT) * 1024 + i * 256 + lane * 4;
;                 const float4 p0 = *(const float4*)(part + po), p1 = *(const float4*)(part + (size_t)4096 * 1024 + po), cg = *(const float4*)(cgate + i * 256 + lane * 4);
;                 v[i].x += cg.x * (p0.x + p1.x); v[i].y += cg.y * (p0.y + p1.y); v[i].z += cg.z * (p0.z + p1.z); v[i].w += cg.w * (p0.w + p1.w);
;                 *(float4*)(hcout + po) = v[i];
;             }
;             ss += v[i].x * v[i].x + v[i].y * v[i].y + v[i].z * v[i].z + v[i].w * v[i].w; }
;         ss = wave_sum(ss);
;         const float rstd = rsqrtf(ss * (1.0f / 1024.0f) + EPS);
;         const float* mr = modl + (size_t)r * 6144;
; #pragma unroll
;         for (int i = 0; i < 4; ++i) {
;             const int k = i * 256 + lane * 4;
;             const float4 gg = *(const float4*)(g + k), scv = *(const float4*)(mr + sc_off + k), shv = *(const float4*)(mr + sh_off + k);
;             const float o0 = v[i].x * rstd * gg.x * (1.0f + scv.x) + shv.x, o1 = v[i].y * rstd * gg.y * (1.0f + scv.y) + shv.y;
;             const float o2 = v[i].z * rstd * gg.z * (1.0f + scv.z) + shv.z, o3 = v[i].w * rstd * gg.w * (1.0f + scv.w) + shv.w;
;             uint2 w; w.x = pk2(o0, o1); w.y = pk2(o2, o3);
;             *(uint2*)(A + (size_t)row * 1024 + k) = w;
;         }
.LBB0_1037:
	s_or_b64 exec, exec, s[2:3]
	s_and_b64 s[2:3], s[18:19], exec
	s_mov_b32 s2, 0x8000
	s_cselect_b32 s7, s2, 0x9000
	v_mov_b32_e32 v6, v253
	s_mov_b32 s2, s63
	s_waitcnt lgkmcnt(0)
	s_barrier
	s_lshl_b32 s5, s2, 3
	v_ashrrev_i32_e32 v1, 6, v6
	v_add_u32_e32 v50, s5, v1
	s_waitcnt vmcnt(0) lgkmcnt(0)
	v_readlane_b32 s100, v255, 45
	s_load_dwordx2 s[48:49], s[0:1], 0x38
	s_movk_i32 s101, 0xe8
	s_load_dwordx2 s[46:47], s[0:1], s101
	s_load_dwordx2 s[16:17], s[0:1], 0x10
	s_mul_i32 s101, s100, 0x66000
	s_add_u32 s50, s56, s101
	s_addc_u32 s51, s57, 0
	s_add_u32 s20, s101, 0x62000
	s_add_u32 s20, s56, s20
	s_addc_u32 s21, s57, 0
	s_add_u32 s98, s50, 0x4000
	s_addc_u32 s99, s51, 0
	s_add_u32 s50, s50, 0x3000
	s_addc_u32 s51, s51, 0
	s_lshl_b32 s101, s100, 12
	v_and_b32_e32 v240, 63, v253
	v_lshlrev_b32_e32 v241, 4, v240
	v_lshrrev_b32_e32 v148, 7, v50
	v_lshlrev_b32_e32 v146, 4, v50
	v_lshl_add_u32 v144, v146, 12, v241
	v_lshlrev_b32_e32 v146, 11, v146
	v_lshl_add_u32 v146, v240, 3, v146
	v_mul_u32_u24_e32 v148, 0x6000, v148
	v_add_u32_e32 v148, v148, v241
	s_waitcnt lgkmcnt(0)
	s_add_u32 s48, s48, s101
	s_addc_u32 s49, s49, 0
	s_cmp_eq_u32 s100, 0
	s_cselect_b32 s16, s16, s64
	s_cselect_b32 s17, s17, s65
	s_cmp_eq_u32 s100, 3
	s_cbranch_scc1 .Lnorm_P6_alt
	global_load_dwordx4 v[80:83], v144, s[46:47] nt
	global_load_dwordx4 v[84:87], v144, s[46:47] offset:1024 nt
	global_load_dwordx4 v[88:91], v144, s[46:47] offset:2048 nt
	global_load_dwordx4 v[92:95], v144, s[46:47] offset:3072 nt
	v_add_u32_e32 v144, 0x1000, v144
	global_load_dwordx4 v[34:37], v148, s[98:99]
	global_load_dwordx4 v[38:41], v148, s[98:99] offset:1024
	global_load_dwordx4 v[42:45], v148, s[98:99] offset:2048
	global_load_dwordx4 v[46:49], v148, s[98:99] offset:3072
	global_load_dwordx4 v[224:227], v148, s[50:51]
	global_load_dwordx4 v[228:231], v148, s[50:51] offset:1024
	global_load_dwordx4 v[232:235], v148, s[50:51] offset:2048
	global_load_dwordx4 v[236:239], v148, s[50:51] offset:3072
	global_load_dwordx4 v[188:191], v241, s[48:49]
	global_load_dwordx4 v[192:195], v241, s[48:49] offset:1024
	global_load_dwordx4 v[196:199], v241, s[48:49] offset:2048
	global_load_dwordx4 v[200:203], v241, s[48:49] offset:3072
	global_load_dwordx4 v[96:99], v144, s[46:47] nt
	global_load_dwordx4 v[100:103], v144, s[46:47] offset:1024 nt
	global_load_dwordx4 v[104:107], v144, s[46:47] offset:2048 nt
	global_load_dwordx4 v[108:111], v144, s[46:47] offset:3072 nt
	v_add_u32_e32 v144, 0x1000, v144
	global_load_dwordx4 v[112:115], v144, s[46:47] nt
	global_load_dwordx4 v[116:119], v144, s[46:47] offset:1024 nt
	global_load_dwordx4 v[120:123], v144, s[46:47] offset:2048 nt
	global_load_dwordx4 v[124:127], v144, s[46:47] offset:3072 nt
	v_add_u32_e32 v144, 0x1000, v144
	global_load_dwordx4 v[128:131], v144, s[46:47] nt
	global_load_dwordx4 v[132:135], v144, s[46:47] offset:1024 nt
	global_load_dwordx4 v[136:139], v144, s[46:47] offset:2048 nt
	global_load_dwordx4 v[140:143], v144, s[46:47] offset:3072 nt
	v_add_u32_e32 v144, 0x1000, v144
	global_load_dwordx4 v[156:159], v144, s[46:47] nt
	global_load_dwordx4 v[160:163], v144, s[46:47] offset:1024 nt
	global_load_dwordx4 v[164:167], v144, s[46:47] offset:2048 nt
	global_load_dwordx4 v[168:171], v144, s[46:47] offset:3072 nt
	v_add_u32_e32 v144, 0x1000, v144
	global_load_dwordx4 v[172:175], v144, s[46:47] nt
	global_load_dwordx4 v[176:179], v144, s[46:47] offset:1024 nt
	global_load_dwordx4 v[180:183], v144, s[46:47] offset:2048 nt
	global_load_dwordx4 v[184:187], v144, s[46:47] offset:3072 nt
	v_add_u32_e32 v144, 0x1000, v144
	s_waitcnt vmcnt(32)
	v_pk_mul_f32 v[242:243], v[80:81], v[80:81]
	v_pk_mul_f32 v[244:245], v[84:85], v[84:85]
	v_pk_mul_f32 v[246:247], v[82:83], v[82:83]
	v_pk_mul_f32 v[248:249], v[86:87], v[86:87]
	v_add_f32_e32 v204, v245, v244
	v_add_f32_e32 v205, v243, v242
	v_add_f32_e32 v204, v248, v204
	v_add_f32_e32 v205, v246, v205
	v_add_f32_e32 v204, v249, v204
	v_add_f32_e32 v205, v247, v205
	v_pk_mul_f32 v[242:243], v[88:89], v[88:89]
	v_pk_mul_f32 v[244:245], v[92:93], v[92:93]
	v_pk_mul_f32 v[246:247], v[90:91], v[90:91]
	v_pk_mul_f32 v[248:249], v[94:95], v[94:95]
	v_add_f32_e32 v206, v243, v242
	v_add_f32_e32 v207, v245, v244
	v_add_f32_e32 v206, v246, v206
	v_add_f32_e32 v207, v248, v207
	v_add_f32_e32 v206, v247, v206
	v_add_f32_e32 v207, v249, v207
	v_add_f32_e32 v204, v205, v204
	v_add_f32_e32 v204, v204, v206
	v_add_f32_e32 v204, v204, v207
	ds_swizzle_b32 v205, v204 offset:swizzle(SWAP,1)
	s_waitcnt lgkmcnt(0)
	v_add_f32_e32 v204, v204, v205
	ds_swizzle_b32 v205, v204 offset:swizzle(SWAP,2)
	s_waitcnt lgkmcnt(0)
	v_add_f32_e32 v204, v204, v205
	ds_swizzle_b32 v205, v204 offset:swizzle(SWAP,4)
	s_waitcnt lgkmcnt(0)
	v_add_f32_e32 v204, v204, v205
	ds_swizzle_b32 v205, v204 offset:swizzle(SWAP,8)
	s_waitcnt lgkmcnt(0)
	v_add_f32_e32 v204, v204, v205
	ds_swizzle_b32 v205, v204 offset:swizzle(SWAP,16)
	s_waitcnt lgkmcnt(0)
	v_add_f32_e32 v204, v204, v205
	v_mov_b32_e32 v205, v204
	s_nop 1
	v_permlane32_swap_b32_e32 v204, v205
	v_add_f32_e32 v204, v204, v205
	v_mov_b32_e32 v205, 0x358637bd
	v_fmamk_f32 v204, v204, 0x3a800000, v205
	v_rsq_f32_e32 v204, v204
	s_nop 0
	s_waitcnt vmcnt(20)
; __device__ __forceinline__ unsigned pk2(float lo, float hi) { const g_f32x2 f = {lo, hi}; return __builtin_bit_cast(unsigned, __builtin_convertvector(f, g_bf16x2)); }
; #define PN_LOAD(dst, rw) do { const float* s_ = (rw) < NLAT ? hlat + (size_t)(rw) * 1024 : hctx + (size_t)((rw) - NLAT) * 1024; \
;         _Pragma("unroll") for (int i = 0; i < 4; ++i) dst[i] = *(const float4*)(s_ + i * 256 + lane * 4); } while (0)
; __device__ __forceinline__ void p_norm(const float* hlat, const float* hctx, const float* g, const float* modl, int sh_off, int sc_off, bf16_t* A, int M,
;                                        const float* part, const float* cgate, float* hcout) {
;     ...
;     if (row < M) PN_LOAD(v, row);
;     while (row < M) {
;         const int nrow = row + stride;
;         if (nrow < M) PN_LOAD(nv, nrow);
;         const int r = row < NLAT ? (row >> 11) : 16;
;         float ss = 0.f;
; #pragma unroll
;         for (int i = 0; i < 4; ++i) {
;             if (part != nullptr && row >= NLAT) {
;                 const size_t po = (size_t)(row - NLAT) * 1024 + i * 256 + lane * 4;
;                 const float4 p0 = *(const float4*)(part + po), p1 = *(const float4*)(part + (size_t)4096 * 1024 + po), cg = *(const float4*)(cgate + i * 256 + lane * 4);
;                 v[i].x += cg.x * (p0.x + p1.x); v[i].y += cg.y * (p0.y + p1.y); v[i].z += cg.z * (p0.z + p1.z); v[i].w += cg.w * (p0.w + p1.w);
;                 *(float4*)(hcout + po) = v[i];
;             }
;             ss += v[i].x * v[i].x + v[i].y * v[i].y + v[i].z * v[i].z + v[i].w * v[i].w; }
;         ss = wave_sum(ss);
;         const float rstd = rsqrtf(ss * (1.0f / 1024.0f) + EPS);
;         const float* mr = modl + (size_t)r * 6144;
; #pragma unroll
;         for (int i = 0; i < 4; ++i) {
;             const int k = i * 256 + lane * 4;
;             const float4 gg = *(const float4*)(g + k), scv = *(const float4*)(mr + sc_off + k), shv = *(const float4*)(mr + sh_off + k);
;             const float o0 = v[i].x * rstd * gg.x * (1.0f + scv.x) + shv.x, o1 = v[i].y * rstd * gg.y * (1.0f + scv.y) + shv.y;
;             const float o2 = v[i].z * rstd * gg.z * (1.0f + scv.z) + shv.z, o3 = v[i].w * rstd * gg.w * (1.0f + scv.w) + shv.w;
;             uint2 w; w.x = pk2(o0, o1); w.y = pk2(o2, o3);
;             *(uint2*)(A + (size_t)row * 1024 + k) = w;
;         }
	v_pk_add_f32 v[34:35], v[34:35], 1.0 op_sel_hi:[1,0]
	v_pk_add_f32 v[36:37], v[36:37], 1.0 op_sel_hi:[1,0]
	v_pk_add_f32 v[38:39], v[38:39], 1.0 op_sel_hi:[1,0]
	v_pk_add_f32 v[40:41], v[40:41], 1.0 op_sel_hi:[1,0]
	v_pk_add_f32 v[42:43], v[42:43], 1.0 op_sel_hi:[1,0]
	v_pk_add_f32 v[44:45], v[44:45], 1.0 op_sel_hi:[1,0]
	v_pk_add_f32 v[46:47], v[46:47], 1.0 op_sel_hi:[1,0]
	v_pk_add_f32 v[48:49], v[48:49], 1.0 op_sel_hi:[1,0]
	v_pk_mul_f32 v[80:81], v[80:81], v[204:205] op_sel_hi:[1,0]
	v_pk_mul_f32 v[82:83], v[82:83], v[204:205] op_sel_hi:[1,0]
	v_pk_mul_f32 v[80:81], v[188:189], v[80:81]
	v_pk_mul_f32 v[82:83], v[190:191], v[82:83]
	v_pk_fma_f32 v[80:81], v[34:35], v[80:81], v[224:225]
	v_pk_fma_f32 v[82:83], v[36:37], v[82:83], v[226:227]
	v_cvt_pk_bf16_f32 v80, v80, v81
	v_cvt_pk_bf16_f32 v81, v82, v83
	global_store_dwordx2 v146, v[80:81], s[66:67]
	v_pk_mul_f32 v[84:85], v[84:85], v[204:205] op_sel_hi:[1,0]
	v_pk_mul_f32 v[86:87], v[86:87], v[204:205] op_sel_hi:[1,0]
	v_pk_mul_f32 v[84:85], v[192:193], v[84:85]
	v_pk_mul_f32 v[86:87], v[194:195], v[86:87]
	v_pk_fma_f32 v[84:85], v[38:39], v[84:85], v[228:229]
	v_pk_fma_f32 v[86:87], v[40:41], v[86:87], v[230:231]
	v_cvt_pk_bf16_f32 v84, v84, v85
	v_cvt_pk_bf16_f32 v85, v86, v87
	global_store_dwordx2 v146, v[84:85], s[66:67] offset:512
	v_pk_mul_f32 v[88:89], v[88:89], v[204:205] op_sel_hi:[1,0]
	v_pk_mul_f32 v[90:91], v[90:91], v[204:205] op_sel_hi:[1,0]
	v_pk_mul_f32 v[88:89], v[196:197], v[88:89]
	v_pk_mul_f32 v[90:91], v[198:199], v[90:91]
	v_pk_fma_f32 v[88:89], v[42:43], v[88:89], v[232:233]
	v_pk_fma_f32 v[90:91], v[44:45], v[90:91], v[234:235]
	v_cvt_pk_bf16_f32 v88, v88, v89
	v_cvt_pk_bf16_f32 v89, v90, v91
	global_store_dwordx2 v146, v[88:89], s[66:67] offset:1024
	v_pk_mul_f32 v[92:93], v[92:93], v[204:205] op_sel_hi:[1,0]
	v_pk_mul_f32 v[94:95], v[94:95], v[204:205] op_sel_hi:[1,0]
	v_pk_mul_f32 v[92:93], v[200:201], v[92:93]
	v_pk_mul_f32 v[94:95], v[202:203], v[94:95]
	v_pk_fma_f32 v[92:93], v[46:47], v[92:93], v[236:237]
	v_pk_fma_f32 v[94:95], v[48:49], v[94:95], v[238:239]
	v_cvt_pk_bf16_f32 v92, v92, v93
	v_cvt_pk_bf16_f32 v93, v94, v95
	global_store_dwordx2 v146, v[92:93], s[66:67] offset:1536
	v_add_u32_e32 v146, 0x800, v146
	global_load_dwordx4 v[80:83], v144, s[46:47] nt
	global_load_dwordx4 v[84:87], v144, s[46:47] offset:1024 nt
	global_load_dwordx4 v[88:91], v144, s[46:47] offset:2048 nt
	global_load_dwordx4 v[92:95], v144, s[46:47] offset:3072 nt
	v_add_u32_e32 v144, 0x1000, v144
	s_waitcnt vmcnt(24)
	v_pk_mul_f32 v[242:243], v[96:97], v[96:97]
	v_pk_mul_f32 v[244:245], v[100:101], v[100:101]
	v_pk_mul_f32 v[246:247], v[98:99], v[98:99]
	v_pk_mul_f32 v[248:249], v[102:103], v[102:103]
	v_add_f32_e32 v204, v245, v244
	v_add_f32_e32 v205, v243, v242
	v_add_f32_e32 v204, v248, v204
	v_add_f32_e32 v205, v246, v205
	v_add_f32_e32 v204, v249, v204
	v_add_f32_e32 v205, v247, v205
	v_pk_mul_f32 v[242:243], v[104:105], v[104:105]
	v_pk_mul_f32 v[244:245], v[108:109], v[108:109]
	v_pk_mul_f32 v[246:247], v[106:107], v[106:107]
	v_pk_mul_f32 v[248:249], v[110:111], v[110:111]
	v_add_f32_e32 v206, v243, v242
	v_add_f32_e32 v207, v245, v244
	v_add_f32_e32 v206, v246, v206
	v_add_f32_e32 v207, v248, v207
	v_add_f32_e32 v206, v247, v206
	v_add_f32_e32 v207, v249, v207
	v_add_f32_e32 v204, v205, v204
	v_add_f32_e32 v204, v204, v206
	v_add_f32_e32 v204, v204, v207
	ds_swizzle_b32 v205, v204 offset:swizzle(SWAP,1)
	s_waitcnt lgkmcnt(0)
	v_add_f32_e32 v204, v204, v205
	ds_swizzle_b32 v205, v204 offset:swizzle(SWAP,2)
	s_waitcnt lgkmcnt(0)
	v_add_f32_e32 v204, v204, v205
	ds_swizzle_b32 v205, v204 offset:swizzle(SWAP,4)
	s_waitcnt lgkmcnt(0)
	v_add_f32_e32 v204, v204, v205
	ds_swizzle_b32 v205, v204 offset:swizzle(SWAP,8)
	s_waitcnt lgkmcnt(0)
	v_add_f32_e32 v204, v204, v205
	ds_swizzle_b32 v205, v204 offset:swizzle(SWAP,16)
	s_waitcnt lgkmcnt(0)
	v_add_f32_e32 v204, v204, v205
	v_mov_b32_e32 v205, v204
	s_nop 1
	v_permlane32_swap_b32_e32 v204, v205
	v_add_f32_e32 v204, v204, v205
	v_mov_b32_e32 v205, 0x358637bd
	v_fmamk_f32 v204, v204, 0x3a800000, v205
	v_rsq_f32_e32 v204, v204
	s_nop 0
	v_pk_mul_f32 v[96:97], v[96:97], v[204:205] op_sel_hi:[1,0]
	v_pk_mul_f32 v[98:99], v[98:99], v[204:205] op_sel_hi:[1,0]
	v_pk_mul_f32 v[96:97], v[188:189], v[96:97]
	v_pk_mul_f32 v[98:99], v[190:191], v[98:99]
	v_pk_fma_f32 v[96:97], v[34:35], v[96:97], v[224:225]
	v_pk_fma_f32 v[98:99], v[36:37], v[98:99], v[226:227]
	v_cvt_pk_bf16_f32 v96, v96, v97
	v_cvt_pk_bf16_f32 v97, v98, v99
	global_store_dwordx2 v146, v[96:97], s[66:67]
	v_pk_mul_f32 v[100:101], v[100:101], v[204:205] op_sel_hi:[1,0]
	v_pk_mul_f32 v[102:103], v[102:103], v[204:205] op_sel_hi:[1,0]
	v_pk_mul_f32 v[100:101], v[192:193], v[100:101]
	v_pk_mul_f32 v[102:103], v[194:195], v[102:103]
	v_pk_fma_f32 v[100:101], v[38:39], v[100:101], v[228:229]
	v_pk_fma_f32 v[102:103], v[40:41], v[102:103], v[230:231]
	v_cvt_pk_bf16_f32 v100, v100, v101
	v_cvt_pk_bf16_f32 v101, v102, v103
	global_store_dwordx2 v146, v[100:101], s[66:67] offset:512
	v_pk_mul_f32 v[104:105], v[104:105], v[204:205] op_sel_hi:[1,0]
	v_pk_mul_f32 v[106:107], v[106:107], v[204:205] op_sel_hi:[1,0]
	v_pk_mul_f32 v[104:105], v[196:197], v[104:105]
	v_pk_mul_f32 v[106:107], v[198:199], v[106:107]
	v_pk_fma_f32 v[104:105], v[42:43], v[104:105], v[232:233]
	v_pk_fma_f32 v[106:107], v[44:45], v[106:107], v[234:235]
	v_cvt_pk_bf16_f32 v104, v104, v105
	v_cvt_pk_bf16_f32 v105, v106, v107
	global_store_dwordx2 v146, v[104:105], s[66:67] offset:1024
	v_pk_mul_f32 v[108:109], v[108:109], v[204:205] op_sel_hi:[1,0]
	v_pk_mul_f32 v[110:111], v[110:111], v[204:205] op_sel_hi:[1,0]
	v_pk_mul_f32 v[108:109], v[200:201], v[108:109]
	v_pk_mul_f32 v[110:111], v[202:203], v[110:111]
	v_pk_fma_f32 v[108:109], v[46:47], v[108:109], v[236:237]
	v_pk_fma_f32 v[110:111], v[48:49], v[110:111], v[238:239]
	v_cvt_pk_bf16_f32 v108, v108, v109
	v_cvt_pk_bf16_f32 v109, v110, v111
	global_store_dwordx2 v146, v[108:109], s[66:67] offset:1536
	v_add_u32_e32 v146, 0x800, v146
	global_load_dwordx4 v[96:99], v144, s[46:47] nt
	global_load_dwordx4 v[100:103], v144, s[46:47] offset:1024 nt
	global_load_dwordx4 v[104:107], v144, s[46:47] offset:2048 nt
	global_load_dwordx4 v[108:111], v144, s[46:47] offset:3072 nt
	v_add_u32_e32 v144, 0x1000, v144
	s_waitcnt vmcnt(28)
; __device__ __forceinline__ unsigned pk2(float lo, float hi) { const g_f32x2 f = {lo, hi}; return __builtin_bit_cast(unsigned, __builtin_convertvector(f, g_bf16x2)); }
; #define PN_LOAD(dst, rw) do { const float* s_ = (rw) < NLAT ? hlat + (size_t)(rw) * 1024 : hctx + (size_t)((rw) - NLAT) * 1024; \
;         _Pragma("unroll") for (int i = 0; i < 4; ++i) dst[i] = *(const float4*)(s_ + i * 256 + lane * 4); } while (0)
; __device__ __forceinline__ void p_norm(const float* hlat, const float* hctx, const float* g, const float* modl, int sh_off, int sc_off, bf16_t* A, int M,
;                                        const float* part, const float* cgate, float* hcout) {
;     ...
;     if (row < M) PN_LOAD(v, row);
;     while (row < M) {
;         const int nrow = row + stride;
;         if (nrow < M) PN_LOAD(nv, nrow);
;         const int r = row < NLAT ? (row >> 11) : 16;
;         float ss = 0.f;
; #pragma unroll
;         for (int i = 0; i < 4; ++i) {
;             if (part != nullptr && row >= NLAT) {
;                 const size_t po = (size_t)(row - NLAT) * 1024 + i * 256 + lane * 4;
;                 const float4 p0 = *(const float4*)(part + po), p1 = *(const float4*)(part + (size_t)4096 * 1024 + po), cg = *(const float4*)(cgate + i * 256 + lane * 4);
;                 v[i].x += cg.x * (p0.x + p1.x); v[i].y += cg.y * (p0.y + p1.y); v[i].z += cg.z * (p0.z + p1.z); v[i].w += cg.w * (p0.w + p1.w);
;                 *(float4*)(hcout + po) = v[i];
;             }
;             ss += v[i].x * v[i].x + v[i].y * v[i].y + v[i].z * v[i].z + v[i].w * v[i].w; }
;         ss = wave_sum(ss);
;         const float rstd = rsqrtf(ss * (1.0f / 1024.0f) + EPS);
;         const float* mr = modl + (size_t)r * 6144;
; #pragma unroll
;         for (int i = 0; i < 4; ++i) {
;             const int k = i * 256 + lane * 4;
;             const float4 gg = *(const float4*)(g + k), scv = *(const float4*)(mr + sc_off + k), shv = *(const float4*)(mr + sh_off + k);
;             const float o0 = v[i].x * rstd * gg.x * (1.0f + scv.x) + shv.x, o1 = v[i].y * rstd * gg.y * (1.0f + scv.y) + shv.y;
;             const float o2 = v[i].z * rstd * gg.z * (1.0f + scv.z) + shv.z, o3 = v[i].w * rstd * gg.w * (1.0f + scv.w) + shv.w;
;             uint2 w; w.x = pk2(o0, o1); w.y = pk2(o2, o3);
;             *(uint2*)(A + (size_t)row * 1024 + k) = w;
;         }
	v_pk_mul_f32 v[242:243], v[112:113], v[112:113]
	v_pk_mul_f32 v[244:245], v[116:117], v[116:117]
	v_pk_mul_f32 v[246:247], v[114:115], v[114:115]
	v_pk_mul_f32 v[248:249], v[118:119], v[118:119]
	v_add_f32_e32 v204, v245, v244
	v_add_f32_e32 v205, v243, v242
	v_add_f32_e32 v204, v248, v204
	v_add_f32_e32 v205, v246, v205
	v_add_f32_e32 v204, v249, v204
	v_add_f32_e32 v205, v247, v205
	v_pk_mul_f32 v[242:243], v[120:121], v[120:121]
	v_pk_mul_f32 v[244:245], v[124:125], v[124:125]
	v_pk_mul_f32 v[246:247], v[122:123], v[122:123]
	v_pk_mul_f32 v[248:249], v[126:127], v[126:127]
	v_add_f32_e32 v206, v243, v242
	v_add_f32_e32 v207, v245, v244
	v_add_f32_e32 v206, v246, v206
	v_add_f32_e32 v207, v248, v207
	v_add_f32_e32 v206, v247, v206
	v_add_f32_e32 v207, v249, v207
	v_add_f32_e32 v204, v205, v204
	v_add_f32_e32 v204, v204, v206
	v_add_f32_e32 v204, v204, v207
	ds_swizzle_b32 v205, v204 offset:swizzle(SWAP,1)
	s_waitcnt lgkmcnt(0)
	v_add_f32_e32 v204, v204, v205
	ds_swizzle_b32 v205, v204 offset:swizzle(SWAP,2)
	s_waitcnt lgkmcnt(0)
	v_add_f32_e32 v204, v204, v205
	ds_swizzle_b32 v205, v204 offset:swizzle(SWAP,4)
	s_waitcnt lgkmcnt(0)
	v_add_f32_e32 v204, v204, v205
	ds_swizzle_b32 v205, v204 offset:swizzle(SWAP,8)
	s_waitcnt lgkmcnt(0)
	v_add_f32_e32 v204, v204, v205
	ds_swizzle_b32 v205, v204 offset:swizzle(SWAP,16)
	s_waitcnt lgkmcnt(0)
	v_add_f32_e32 v204, v204, v205
	v_mov_b32_e32 v205, v204
	s_nop 1
	v_permlane32_swap_b32_e32 v204, v205
	v_add_f32_e32 v204, v204, v205
	v_mov_b32_e32 v205, 0x358637bd
	v_fmamk_f32 v204, v204, 0x3a800000, v205
	v_rsq_f32_e32 v204, v204
	s_nop 0
	v_pk_mul_f32 v[112:113], v[112:113], v[204:205] op_sel_hi:[1,0]
	v_pk_mul_f32 v[114:115], v[114:115], v[204:205] op_sel_hi:[1,0]
	v_pk_mul_f32 v[112:113], v[188:189], v[112:113]
	v_pk_mul_f32 v[114:115], v[190:191], v[114:115]
	v_pk_fma_f32 v[112:113], v[34:35], v[112:113], v[224:225]
	v_pk_fma_f32 v[114:115], v[36:37], v[114:115], v[226:227]
	v_cvt_pk_bf16_f32 v112, v112, v113
	v_cvt_pk_bf16_f32 v113, v114, v115
	global_store_dwordx2 v146, v[112:113], s[66:67]
	v_pk_mul_f32 v[116:117], v[116:117], v[204:205] op_sel_hi:[1,0]
	v_pk_mul_f32 v[118:119], v[118:119], v[204:205] op_sel_hi:[1,0]
	v_pk_mul_f32 v[116:117], v[192:193], v[116:117]
	v_pk_mul_f32 v[118:119], v[194:195], v[118:119]
	v_pk_fma_f32 v[116:117], v[38:39], v[116:117], v[228:229]
	v_pk_fma_f32 v[118:119], v[40:41], v[118:119], v[230:231]
	v_cvt_pk_bf16_f32 v116, v116, v117
	v_cvt_pk_bf16_f32 v117, v118, v119
	global_store_dwordx2 v146, v[116:117], s[66:67] offset:512
	v_pk_mul_f32 v[120:121], v[120:121], v[204:205] op_sel_hi:[1,0]
	v_pk_mul_f32 v[122:123], v[122:123], v[204:205] op_sel_hi:[1,0]
	v_pk_mul_f32 v[120:121], v[196:197], v[120:121]
	v_pk_mul_f32 v[122:123], v[198:199], v[122:123]
	v_pk_fma_f32 v[120:121], v[42:43], v[120:121], v[232:233]
	v_pk_fma_f32 v[122:123], v[44:45], v[122:123], v[234:235]
	v_cvt_pk_bf16_f32 v120, v120, v121
	v_cvt_pk_bf16_f32 v121, v122, v123
	global_store_dwordx2 v146, v[120:121], s[66:67] offset:1024
	v_pk_mul_f32 v[124:125], v[124:125], v[204:205] op_sel_hi:[1,0]
	v_pk_mul_f32 v[126:127], v[126:127], v[204:205] op_sel_hi:[1,0]
	v_pk_mul_f32 v[124:125], v[200:201], v[124:125]
	v_pk_mul_f32 v[126:127], v[202:203], v[126:127]
	v_pk_fma_f32 v[124:125], v[46:47], v[124:125], v[236:237]
	v_pk_fma_f32 v[126:127], v[48:49], v[126:127], v[238:239]
	v_cvt_pk_bf16_f32 v124, v124, v125
	v_cvt_pk_bf16_f32 v125, v126, v127
	global_store_dwordx2 v146, v[124:125], s[66:67] offset:1536
	v_add_u32_e32 v146, 0x800, v146
	global_load_dwordx4 v[112:115], v144, s[46:47] nt
	global_load_dwordx4 v[116:119], v144, s[46:47] offset:1024 nt
	global_load_dwordx4 v[120:123], v144, s[46:47] offset:2048 nt
	global_load_dwordx4 v[124:127], v144, s[46:47] offset:3072 nt
	v_add_u32_e32 v144, 0x1000, v144
	s_waitcnt vmcnt(32)
	v_pk_mul_f32 v[242:243], v[128:129], v[128:129]
	v_pk_mul_f32 v[244:245], v[132:133], v[132:133]
	v_pk_mul_f32 v[246:247], v[130:131], v[130:131]
	v_pk_mul_f32 v[248:249], v[134:135], v[134:135]
	v_add_f32_e32 v204, v245, v244
	v_add_f32_e32 v205, v243, v242
	v_add_f32_e32 v204, v248, v204
	v_add_f32_e32 v205, v246, v205
	v_add_f32_e32 v204, v249, v204
	v_add_f32_e32 v205, v247, v205
	v_pk_mul_f32 v[242:243], v[136:137], v[136:137]
	v_pk_mul_f32 v[244:245], v[140:141], v[140:141]
	v_pk_mul_f32 v[246:247], v[138:139], v[138:139]
	v_pk_mul_f32 v[248:249], v[142:143], v[142:143]
	v_add_f32_e32 v206, v243, v242
	v_add_f32_e32 v207, v245, v244
	v_add_f32_e32 v206, v246, v206
	v_add_f32_e32 v207, v248, v207
	v_add_f32_e32 v206, v247, v206
	v_add_f32_e32 v207, v249, v207
	v_add_f32_e32 v204, v205, v204
	v_add_f32_e32 v204, v204, v206
	v_add_f32_e32 v204, v204, v207
	ds_swizzle_b32 v205, v204 offset:swizzle(SWAP,1)
	s_waitcnt lgkmcnt(0)
	v_add_f32_e32 v204, v204, v205
	ds_swizzle_b32 v205, v204 offset:swizzle(SWAP,2)
	s_waitcnt lgkmcnt(0)
	v_add_f32_e32 v204, v204, v205
	ds_swizzle_b32 v205, v204 offset:swizzle(SWAP,4)
	s_waitcnt lgkmcnt(0)
	v_add_f32_e32 v204, v204, v205
	ds_swizzle_b32 v205, v204 offset:swizzle(SWAP,8)
	s_waitcnt lgkmcnt(0)
	v_add_f32_e32 v204, v204, v205
	ds_swizzle_b32 v205, v204 offset:swizzle(SWAP,16)
	s_waitcnt lgkmcnt(0)
; __device__ __forceinline__ unsigned pk2(float lo, float hi) { const g_f32x2 f = {lo, hi}; return __builtin_bit_cast(unsigned, __builtin_convertvector(f, g_bf16x2)); }
; #define PN_LOAD(dst, rw) do { const float* s_ = (rw) < NLAT ? hlat + (size_t)(rw) * 1024 : hctx + (size_t)((rw) - NLAT) * 1024; \
;         _Pragma("unroll") for (int i = 0; i < 4; ++i) dst[i] = *(const float4*)(s_ + i * 256 + lane * 4); } while (0)
; __device__ __forceinline__ void p_norm(const float* hlat, const float* hctx, const float* g, const float* modl, int sh_off, int sc_off, bf16_t* A, int M,
;                                        const float* part, const float* cgate, float* hcout) {
;     ...
;     if (row < M) PN_LOAD(v, row);
;     while (row < M) {
;         const int nrow = row + stride;
;         if (nrow < M) PN_LOAD(nv, nrow);
;         const int r = row < NLAT ? (row >> 11) : 16;
;         float ss = 0.f;
; #pragma unroll
;         for (int i = 0; i < 4; ++i) {
;             if (part != nullptr && row >= NLAT) {
;                 const size_t po = (size_t)(row - NLAT) * 1024 + i * 256 + lane * 4;
;                 const float4 p0 = *(const float4*)(part + po), p1 = *(const float4*)(part + (size_t)4096 * 1024 + po), cg = *(const float4*)(cgate + i * 256 + lane * 4);
;                 v[i].x += cg.x * (p0.x + p1.x); v[i].y += cg.y * (p0.y + p1.y); v[i].z += cg.z * (p0.z + p1.z); v[i].w += cg.w * (p0.w + p1.w);
;                 *(float4*)(hcout + po) = v[i];
;             }
;             ss += v[i].x * v[i].x + v[i].y * v[i].y + v[i].z * v[i].z + v[i].w * v[i].w; }
;         ss = wave_sum(ss);
;         const float rstd = rsqrtf(ss * (1.0f / 1024.0f) + EPS);
;         const float* mr = modl + (size_t)r * 6144;
; #pragma unroll
;         for (int i = 0; i < 4; ++i) {
;             const int k = i * 256 + lane * 4;
;             const float4 gg = *(const float4*)(g + k), scv = *(const float4*)(mr + sc_off + k), shv = *(const float4*)(mr + sh_off + k);
;             const float o0 = v[i].x * rstd * gg.x * (1.0f + scv.x) + shv.x, o1 = v[i].y * rstd * gg.y * (1.0f + scv.y) + shv.y;
;             const float o2 = v[i].z * rstd * gg.z * (1.0f + scv.z) + shv.z, o3 = v[i].w * rstd * gg.w * (1.0f + scv.w) + shv.w;
;             uint2 w; w.x = pk2(o0, o1); w.y = pk2(o2, o3);
;             *(uint2*)(A + (size_t)row * 1024 + k) = w;
;         }
	v_add_f32_e32 v204, v204, v205
	v_mov_b32_e32 v205, v204
	s_nop 1
	v_permlane32_swap_b32_e32 v204, v205
	v_add_f32_e32 v204, v204, v205
	v_mov_b32_e32 v205, 0x358637bd
	v_fmamk_f32 v204, v204, 0x3a800000, v205
	v_rsq_f32_e32 v204, v204
	s_nop 0
	v_pk_mul_f32 v[128:129], v[128:129], v[204:205] op_sel_hi:[1,0]
	v_pk_mul_f32 v[130:131], v[130:131], v[204:205] op_sel_hi:[1,0]
	v_pk_mul_f32 v[128:129], v[188:189], v[128:129]
	v_pk_mul_f32 v[130:131], v[190:191], v[130:131]
	v_pk_fma_f32 v[128:129], v[34:35], v[128:129], v[224:225]
	v_pk_fma_f32 v[130:131], v[36:37], v[130:131], v[226:227]
	v_cvt_pk_bf16_f32 v128, v128, v129
	v_cvt_pk_bf16_f32 v129, v130, v131
	global_store_dwordx2 v146, v[128:129], s[66:67]
	v_pk_mul_f32 v[132:133], v[132:133], v[204:205] op_sel_hi:[1,0]
	v_pk_mul_f32 v[134:135], v[134:135], v[204:205] op_sel_hi:[1,0]
	v_pk_mul_f32 v[132:133], v[192:193], v[132:133]
	v_pk_mul_f32 v[134:135], v[194:195], v[134:135]
	v_pk_fma_f32 v[132:133], v[38:39], v[132:133], v[228:229]
	v_pk_fma_f32 v[134:135], v[40:41], v[134:135], v[230:231]
	v_cvt_pk_bf16_f32 v132, v132, v133
	v_cvt_pk_bf16_f32 v133, v134, v135
	global_store_dwordx2 v146, v[132:133], s[66:67] offset:512
	v_pk_mul_f32 v[136:137], v[136:137], v[204:205] op_sel_hi:[1,0]
	v_pk_mul_f32 v[138:139], v[138:139], v[204:205] op_sel_hi:[1,0]
	v_pk_mul_f32 v[136:137], v[196:197], v[136:137]
	v_pk_mul_f32 v[138:139], v[198:199], v[138:139]
	v_pk_fma_f32 v[136:137], v[42:43], v[136:137], v[232:233]
	v_pk_fma_f32 v[138:139], v[44:45], v[138:139], v[234:235]
	v_cvt_pk_bf16_f32 v136, v136, v137
	v_cvt_pk_bf16_f32 v137, v138, v139
	global_store_dwordx2 v146, v[136:137], s[66:67] offset:1024
	v_pk_mul_f32 v[140:141], v[140:141], v[204:205] op_sel_hi:[1,0]
	v_pk_mul_f32 v[142:143], v[142:143], v[204:205] op_sel_hi:[1,0]
	v_pk_mul_f32 v[140:141], v[200:201], v[140:141]
	v_pk_mul_f32 v[142:143], v[202:203], v[142:143]
	v_pk_fma_f32 v[140:141], v[46:47], v[140:141], v[236:237]
	v_pk_fma_f32 v[142:143], v[48:49], v[142:143], v[238:239]
	v_cvt_pk_bf16_f32 v140, v140, v141
	v_cvt_pk_bf16_f32 v141, v142, v143
	global_store_dwordx2 v146, v[140:141], s[66:67] offset:1536
	v_add_u32_e32 v146, 0x800, v146
	global_load_dwordx4 v[128:131], v144, s[46:47] nt
	global_load_dwordx4 v[132:135], v144, s[46:47] offset:1024 nt
	global_load_dwordx4 v[136:139], v144, s[46:47] offset:2048 nt
	global_load_dwordx4 v[140:143], v144, s[46:47] offset:3072 nt
	v_add_u32_e32 v144, 0x1000, v144
	s_waitcnt vmcnt(36)
	v_pk_mul_f32 v[242:243], v[156:157], v[156:157]
	v_pk_mul_f32 v[244:245], v[160:161], v[160:161]
	v_pk_mul_f32 v[246:247], v[158:159], v[158:159]
	v_pk_mul_f32 v[248:249], v[162:163], v[162:163]
	v_add_f32_e32 v204, v245, v244
	v_add_f32_e32 v205, v243, v242
	v_add_f32_e32 v204, v248, v204
	v_add_f32_e32 v205, v246, v205
	v_add_f32_e32 v204, v249, v204
	v_add_f32_e32 v205, v247, v205
	v_pk_mul_f32 v[242:243], v[164:165], v[164:165]
	v_pk_mul_f32 v[244:245], v[168:169], v[168:169]
	v_pk_mul_f32 v[246:247], v[166:167], v[166:167]
	v_pk_mul_f32 v[248:249], v[170:171], v[170:171]
	v_add_f32_e32 v206, v243, v242
	v_add_f32_e32 v207, v245, v244
	v_add_f32_e32 v206, v246, v206
	v_add_f32_e32 v207, v248, v207
	v_add_f32_e32 v206, v247, v206
	v_add_f32_e32 v207, v249, v207
	v_add_f32_e32 v204, v205, v204
	v_add_f32_e32 v204, v204, v206
	v_add_f32_e32 v204, v204, v207
	ds_swizzle_b32 v205, v204 offset:swizzle(SWAP,1)
	s_waitcnt lgkmcnt(0)
	v_add_f32_e32 v204, v204, v205
	ds_swizzle_b32 v205, v204 offset:swizzle(SWAP,2)
	s_waitcnt lgkmcnt(0)
	v_add_f32_e32 v204, v204, v205
	ds_swizzle_b32 v205, v204 offset:swizzle(SWAP,4)
	s_waitcnt lgkmcnt(0)
	v_add_f32_e32 v204, v204, v205
	ds_swizzle_b32 v205, v204 offset:swizzle(SWAP,8)
	s_waitcnt lgkmcnt(0)
	v_add_f32_e32 v204, v204, v205
	ds_swizzle_b32 v205, v204 offset:swizzle(SWAP,16)
	s_waitcnt lgkmcnt(0)
	v_add_f32_e32 v204, v204, v205
	v_mov_b32_e32 v205, v204
	s_nop 1
	v_permlane32_swap_b32_e32 v204, v205
	v_add_f32_e32 v204, v204, v205
	v_mov_b32_e32 v205, 0x358637bd
	v_fmamk_f32 v204, v204, 0x3a800000, v205
	v_rsq_f32_e32 v204, v204
	s_nop 0
	v_pk_mul_f32 v[156:157], v[156:157], v[204:205] op_sel_hi:[1,0]
	v_pk_mul_f32 v[158:159], v[158:159], v[204:205] op_sel_hi:[1,0]
	v_pk_mul_f32 v[156:157], v[188:189], v[156:157]
	v_pk_mul_f32 v[158:159], v[190:191], v[158:159]
	v_pk_fma_f32 v[156:157], v[34:35], v[156:157], v[224:225]
	v_pk_fma_f32 v[158:159], v[36:37], v[158:159], v[226:227]
	v_cvt_pk_bf16_f32 v156, v156, v157
	v_cvt_pk_bf16_f32 v157, v158, v159
	global_store_dwordx2 v146, v[156:157], s[66:67]
	v_pk_mul_f32 v[160:161], v[160:161], v[204:205] op_sel_hi:[1,0]
	v_pk_mul_f32 v[162:163], v[162:163], v[204:205] op_sel_hi:[1,0]
	v_pk_mul_f32 v[160:161], v[192:193], v[160:161]
	v_pk_mul_f32 v[162:163], v[194:195], v[162:163]
	v_pk_fma_f32 v[160:161], v[38:39], v[160:161], v[228:229]
	v_pk_fma_f32 v[162:163], v[40:41], v[162:163], v[230:231]
	v_cvt_pk_bf16_f32 v160, v160, v161
	v_cvt_pk_bf16_f32 v161, v162, v163
	global_store_dwordx2 v146, v[160:161], s[66:67] offset:512
	v_pk_mul_f32 v[164:165], v[164:165], v[204:205] op_sel_hi:[1,0]
	v_pk_mul_f32 v[166:167], v[166:167], v[204:205] op_sel_hi:[1,0]
	v_pk_mul_f32 v[164:165], v[196:197], v[164:165]
	v_pk_mul_f32 v[166:167], v[198:199], v[166:167]
	v_pk_fma_f32 v[164:165], v[42:43], v[164:165], v[232:233]
	v_pk_fma_f32 v[166:167], v[44:45], v[166:167], v[234:235]
	v_cvt_pk_bf16_f32 v164, v164, v165
	v_cvt_pk_bf16_f32 v165, v166, v167
	global_store_dwordx2 v146, v[164:165], s[66:67] offset:1024
	v_pk_mul_f32 v[168:169], v[168:169], v[204:205] op_sel_hi:[1,0]
	v_pk_mul_f32 v[170:171], v[170:171], v[204:205] op_sel_hi:[1,0]
	v_pk_mul_f32 v[168:169], v[200:201], v[168:169]
	v_pk_mul_f32 v[170:171], v[202:203], v[170:171]
	v_pk_fma_f32 v[168:169], v[46:47], v[168:169], v[236:237]
	v_pk_fma_f32 v[170:171], v[48:49], v[170:171], v[238:239]
	v_cvt_pk_bf16_f32 v168, v168, v169
	v_cvt_pk_bf16_f32 v169, v170, v171
	global_store_dwordx2 v146, v[168:169], s[66:67] offset:1536
	v_add_u32_e32 v146, 0x800, v146
	global_load_dwordx4 v[156:159], v144, s[46:47] nt
	global_load_dwordx4 v[160:163], v144, s[46:47] offset:1024 nt
	global_load_dwordx4 v[164:167], v144, s[46:47] offset:2048 nt
	global_load_dwordx4 v[168:171], v144, s[46:47] offset:3072 nt
	v_add_u32_e32 v144, 0x1000, v144
	s_waitcnt vmcnt(40)
; __device__ __forceinline__ unsigned pk2(float lo, float hi) { const g_f32x2 f = {lo, hi}; return __builtin_bit_cast(unsigned, __builtin_convertvector(f, g_bf16x2)); }
; #define PN_LOAD(dst, rw) do { const float* s_ = (rw) < NLAT ? hlat + (size_t)(rw) * 1024 : hctx + (size_t)((rw) - NLAT) * 1024; \
;         _Pragma("unroll") for (int i = 0; i < 4; ++i) dst[i] = *(const float4*)(s_ + i * 256 + lane * 4); } while (0)
; __device__ __forceinline__ void p_norm(const float* hlat, const float* hctx, const float* g, const float* modl, int sh_off, int sc_off, bf16_t* A, int M,
;                                        const float* part, const float* cgate, float* hcout) {
;     ...
;     if (row < M) PN_LOAD(v, row);
;     while (row < M) {
;         const int nrow = row + stride;
;         if (nrow < M) PN_LOAD(nv, nrow);
;         const int r = row < NLAT ? (row >> 11) : 16;
;         float ss = 0.f;
; #pragma unroll
;         for (int i = 0; i < 4; ++i) {
;             if (part != nullptr && row >= NLAT) {
;                 const size_t po = (size_t)(row - NLAT) * 1024 + i * 256 + lane * 4;
;                 const float4 p0 = *(const float4*)(part + po), p1 = *(const float4*)(part + (size_t)4096 * 1024 + po), cg = *(const float4*)(cgate + i * 256 + lane * 4);
;                 v[i].x += cg.x * (p0.x + p1.x); v[i].y += cg.y * (p0.y + p1.y); v[i].z += cg.z * (p0.z + p1.z); v[i].w += cg.w * (p0.w + p1.w);
;                 *(float4*)(hcout + po) = v[i];
;             }
;             ss += v[i].x * v[i].x + v[i].y * v[i].y + v[i].z * v[i].z + v[i].w * v[i].w; }
;         ss = wave_sum(ss);
;         const float rstd = rsqrtf(ss * (1.0f / 1024.0f) + EPS);
;         const float* mr = modl + (size_t)r * 6144;
; #pragma unroll
;         for (int i = 0; i < 4; ++i) {
;             const int k = i * 256 + lane * 4;
;             const float4 gg = *(const float4*)(g + k), scv = *(const float4*)(mr + sc_off + k), shv = *(const float4*)(mr + sh_off + k);
;             const float o0 = v[i].x * rstd * gg.x * (1.0f + scv.x) + shv.x, o1 = v[i].y * rstd * gg.y * (1.0f + scv.y) + shv.y;
;             const float o2 = v[i].z * rstd * gg.z * (1.0f + scv.z) + shv.z, o3 = v[i].w * rstd * gg.w * (1.0f + scv.w) + shv.w;
;             uint2 w; w.x = pk2(o0, o1); w.y = pk2(o2, o3);
;             *(uint2*)(A + (size_t)row * 1024 + k) = w;
;         }
	v_pk_mul_f32 v[242:243], v[172:173], v[172:173]
	v_pk_mul_f32 v[244:245], v[176:177], v[176:177]
	v_pk_mul_f32 v[246:247], v[174:175], v[174:175]
	v_pk_mul_f32 v[248:249], v[178:179], v[178:179]
	v_add_f32_e32 v204, v245, v244
	v_add_f32_e32 v205, v243, v242
	v_add_f32_e32 v204, v248, v204
	v_add_f32_e32 v205, v246, v205
	v_add_f32_e32 v204, v249, v204
	v_add_f32_e32 v205, v247, v205
	v_pk_mul_f32 v[242:243], v[180:181], v[180:181]
	v_pk_mul_f32 v[244:245], v[184:185], v[184:185]
	v_pk_mul_f32 v[246:247], v[182:183], v[182:183]
	v_pk_mul_f32 v[248:249], v[186:187], v[186:187]
	v_add_f32_e32 v206, v243, v242
	v_add_f32_e32 v207, v245, v244
	v_add_f32_e32 v206, v246, v206
	v_add_f32_e32 v207, v248, v207
	v_add_f32_e32 v206, v247, v206
	v_add_f32_e32 v207, v249, v207
	v_add_f32_e32 v204, v205, v204
	v_add_f32_e32 v204, v204, v206
	v_add_f32_e32 v204, v204, v207
	ds_swizzle_b32 v205, v204 offset:swizzle(SWAP,1)
	s_waitcnt lgkmcnt(0)
	v_add_f32_e32 v204, v204, v205
	ds_swizzle_b32 v205, v204 offset:swizzle(SWAP,2)
	s_waitcnt lgkmcnt(0)
	v_add_f32_e32 v204, v204, v205
	ds_swizzle_b32 v205, v204 offset:swizzle(SWAP,4)
	s_waitcnt lgkmcnt(0)
	v_add_f32_e32 v204, v204, v205
	ds_swizzle_b32 v205, v204 offset:swizzle(SWAP,8)
	s_waitcnt lgkmcnt(0)
	v_add_f32_e32 v204, v204, v205
	ds_swizzle_b32 v205, v204 offset:swizzle(SWAP,16)
	s_waitcnt lgkmcnt(0)
	v_add_f32_e32 v204, v204, v205
	v_mov_b32_e32 v205, v204
	s_nop 1
	v_permlane32_swap_b32_e32 v204, v205
	v_add_f32_e32 v204, v204, v205
	v_mov_b32_e32 v205, 0x358637bd
	v_fmamk_f32 v204, v204, 0x3a800000, v205
	v_rsq_f32_e32 v204, v204
	s_nop 0
	v_pk_mul_f32 v[172:173], v[172:173], v[204:205] op_sel_hi:[1,0]
	v_pk_mul_f32 v[174:175], v[174:175], v[204:205] op_sel_hi:[1,0]
	v_pk_mul_f32 v[172:173], v[188:189], v[172:173]
	v_pk_mul_f32 v[174:175], v[190:191], v[174:175]
	v_pk_fma_f32 v[172:173], v[34:35], v[172:173], v[224:225]
	v_pk_fma_f32 v[174:175], v[36:37], v[174:175], v[226:227]
	v_cvt_pk_bf16_f32 v172, v172, v173
	v_cvt_pk_bf16_f32 v173, v174, v175
	global_store_dwordx2 v146, v[172:173], s[66:67]
	v_pk_mul_f32 v[176:177], v[176:177], v[204:205] op_sel_hi:[1,0]
	v_pk_mul_f32 v[178:179], v[178:179], v[204:205] op_sel_hi:[1,0]
	v_pk_mul_f32 v[176:177], v[192:193], v[176:177]
	v_pk_mul_f32 v[178:179], v[194:195], v[178:179]
	v_pk_fma_f32 v[176:177], v[38:39], v[176:177], v[228:229]
	v_pk_fma_f32 v[178:179], v[40:41], v[178:179], v[230:231]
	v_cvt_pk_bf16_f32 v176, v176, v177
	v_cvt_pk_bf16_f32 v177, v178, v179
	global_store_dwordx2 v146, v[176:177], s[66:67] offset:512
	v_pk_mul_f32 v[180:181], v[180:181], v[204:205] op_sel_hi:[1,0]
	v_pk_mul_f32 v[182:183], v[182:183], v[204:205] op_sel_hi:[1,0]
	v_pk_mul_f32 v[180:181], v[196:197], v[180:181]
	v_pk_mul_f32 v[182:183], v[198:199], v[182:183]
	v_pk_fma_f32 v[180:181], v[42:43], v[180:181], v[232:233]
	v_pk_fma_f32 v[182:183], v[44:45], v[182:183], v[234:235]
	v_cvt_pk_bf16_f32 v180, v180, v181
	v_cvt_pk_bf16_f32 v181, v182, v183
	global_store_dwordx2 v146, v[180:181], s[66:67] offset:1024
	v_pk_mul_f32 v[184:185], v[184:185], v[204:205] op_sel_hi:[1,0]
	v_pk_mul_f32 v[186:187], v[186:187], v[204:205] op_sel_hi:[1,0]
	v_pk_mul_f32 v[184:185], v[200:201], v[184:185]
	v_pk_mul_f32 v[186:187], v[202:203], v[186:187]
	v_pk_fma_f32 v[184:185], v[46:47], v[184:185], v[236:237]
	v_pk_fma_f32 v[186:187], v[48:49], v[186:187], v[238:239]
	v_cvt_pk_bf16_f32 v184, v184, v185
	v_cvt_pk_bf16_f32 v185, v186, v187
	global_store_dwordx2 v146, v[184:185], s[66:67] offset:1536
	v_add_u32_e32 v146, 0x800, v146
	global_load_dwordx4 v[172:175], v144, s[46:47] nt
	global_load_dwordx4 v[176:179], v144, s[46:47] offset:1024 nt
	global_load_dwordx4 v[180:183], v144, s[46:47] offset:2048 nt
	global_load_dwordx4 v[184:187], v144, s[46:47] offset:3072 nt
	v_add_u32_e32 v144, 0x1000, v144
	s_waitcnt vmcnt(40)
	v_pk_mul_f32 v[242:243], v[80:81], v[80:81]
	v_pk_mul_f32 v[244:245], v[84:85], v[84:85]
	v_pk_mul_f32 v[246:247], v[82:83], v[82:83]
	v_pk_mul_f32 v[248:249], v[86:87], v[86:87]
	v_add_f32_e32 v204, v245, v244
	v_add_f32_e32 v205, v243, v242
	v_add_f32_e32 v204, v248, v204
	v_add_f32_e32 v205, v246, v205
	v_add_f32_e32 v204, v249, v204
	v_add_f32_e32 v205, v247, v205
	v_pk_mul_f32 v[242:243], v[88:89], v[88:89]
	v_pk_mul_f32 v[244:245], v[92:93], v[92:93]
	v_pk_mul_f32 v[246:247], v[90:91], v[90:91]
	v_pk_mul_f32 v[248:249], v[94:95], v[94:95]
	v_add_f32_e32 v206, v243, v242
	v_add_f32_e32 v207, v245, v244
	v_add_f32_e32 v206, v246, v206
	v_add_f32_e32 v207, v248, v207
	v_add_f32_e32 v206, v247, v206
	v_add_f32_e32 v207, v249, v207
	v_add_f32_e32 v204, v205, v204
	v_add_f32_e32 v204, v204, v206
	v_add_f32_e32 v204, v204, v207
	ds_swizzle_b32 v205, v204 offset:swizzle(SWAP,1)
	s_waitcnt lgkmcnt(0)
	v_add_f32_e32 v204, v204, v205
	ds_swizzle_b32 v205, v204 offset:swizzle(SWAP,2)
	s_waitcnt lgkmcnt(0)
	v_add_f32_e32 v204, v204, v205
	ds_swizzle_b32 v205, v204 offset:swizzle(SWAP,4)
	s_waitcnt lgkmcnt(0)
	v_add_f32_e32 v204, v204, v205
	ds_swizzle_b32 v205, v204 offset:swizzle(SWAP,8)
	s_waitcnt lgkmcnt(0)
	v_add_f32_e32 v204, v204, v205
	ds_swizzle_b32 v205, v204 offset:swizzle(SWAP,16)
	s_waitcnt lgkmcnt(0)
; __device__ __forceinline__ unsigned pk2(float lo, float hi) { const g_f32x2 f = {lo, hi}; return __builtin_bit_cast(unsigned, __builtin_convertvector(f, g_bf16x2)); }
; #define PN_LOAD(dst, rw) do { const float* s_ = (rw) < NLAT ? hlat + (size_t)(rw) * 1024 : hctx + (size_t)((rw) - NLAT) * 1024; \
;         _Pragma("unroll") for (int i = 0; i < 4; ++i) dst[i] = *(const float4*)(s_ + i * 256 + lane * 4); } while (0)
; __device__ __forceinline__ void p_norm(const float* hlat, const float* hctx, const float* g, const float* modl, int sh_off, int sc_off, bf16_t* A, int M,
;                                        const float* part, const float* cgate, float* hcout) {
;     ...
;     if (row < M) PN_LOAD(v, row);
;     while (row < M) {
;         const int nrow = row + stride;
;         if (nrow < M) PN_LOAD(nv, nrow);
;         const int r = row < NLAT ? (row >> 11) : 16;
;         float ss = 0.f;
; #pragma unroll
;         for (int i = 0; i < 4; ++i) {
;             if (part != nullptr && row >= NLAT) {
;                 const size_t po = (size_t)(row - NLAT) * 1024 + i * 256 + lane * 4;
;                 const float4 p0 = *(const float4*)(part + po), p1 = *(const float4*)(part + (size_t)4096 * 1024 + po), cg = *(const float4*)(cgate + i * 256 + lane * 4);
;                 v[i].x += cg.x * (p0.x + p1.x); v[i].y += cg.y * (p0.y + p1.y); v[i].z += cg.z * (p0.z + p1.z); v[i].w += cg.w * (p0.w + p1.w);
;                 *(float4*)(hcout + po) = v[i];
;             }
;             ss += v[i].x * v[i].x + v[i].y * v[i].y + v[i].z * v[i].z + v[i].w * v[i].w; }
;         ss = wave_sum(ss);
;         const float rstd = rsqrtf(ss * (1.0f / 1024.0f) + EPS);
;         const float* mr = modl + (size_t)r * 6144;
; #pragma unroll
;         for (int i = 0; i < 4; ++i) {
;             const int k = i * 256 + lane * 4;
;             const float4 gg = *(const float4*)(g + k), scv = *(const float4*)(mr + sc_off + k), shv = *(const float4*)(mr + sh_off + k);
;             const float o0 = v[i].x * rstd * gg.x * (1.0f + scv.x) + shv.x, o1 = v[i].y * rstd * gg.y * (1.0f + scv.y) + shv.y;
;             const float o2 = v[i].z * rstd * gg.z * (1.0f + scv.z) + shv.z, o3 = v[i].w * rstd * gg.w * (1.0f + scv.w) + shv.w;
;             uint2 w; w.x = pk2(o0, o1); w.y = pk2(o2, o3);
;             *(uint2*)(A + (size_t)row * 1024 + k) = w;
;         }
	v_add_f32_e32 v204, v204, v205
	v_mov_b32_e32 v205, v204
	s_nop 1
	v_permlane32_swap_b32_e32 v204, v205
	v_add_f32_e32 v204, v204, v205
	v_mov_b32_e32 v205, 0x358637bd
	v_fmamk_f32 v204, v204, 0x3a800000, v205
	v_rsq_f32_e32 v204, v204
	s_nop 0
	v_pk_mul_f32 v[80:81], v[80:81], v[204:205] op_sel_hi:[1,0]
	v_pk_mul_f32 v[82:83], v[82:83], v[204:205] op_sel_hi:[1,0]
	v_pk_mul_f32 v[80:81], v[188:189], v[80:81]
	v_pk_mul_f32 v[82:83], v[190:191], v[82:83]
	v_pk_fma_f32 v[80:81], v[34:35], v[80:81], v[224:225]
	v_pk_fma_f32 v[82:83], v[36:37], v[82:83], v[226:227]
	v_cvt_pk_bf16_f32 v80, v80, v81
	v_cvt_pk_bf16_f32 v81, v82, v83
	global_store_dwordx2 v146, v[80:81], s[66:67]
	v_pk_mul_f32 v[84:85], v[84:85], v[204:205] op_sel_hi:[1,0]
	v_pk_mul_f32 v[86:87], v[86:87], v[204:205] op_sel_hi:[1,0]
	v_pk_mul_f32 v[84:85], v[192:193], v[84:85]
	v_pk_mul_f32 v[86:87], v[194:195], v[86:87]
	v_pk_fma_f32 v[84:85], v[38:39], v[84:85], v[228:229]
	v_pk_fma_f32 v[86:87], v[40:41], v[86:87], v[230:231]
	v_cvt_pk_bf16_f32 v84, v84, v85
	v_cvt_pk_bf16_f32 v85, v86, v87
	global_store_dwordx2 v146, v[84:85], s[66:67] offset:512
	v_pk_mul_f32 v[88:89], v[88:89], v[204:205] op_sel_hi:[1,0]
	v_pk_mul_f32 v[90:91], v[90:91], v[204:205] op_sel_hi:[1,0]
	v_pk_mul_f32 v[88:89], v[196:197], v[88:89]
	v_pk_mul_f32 v[90:91], v[198:199], v[90:91]
	v_pk_fma_f32 v[88:89], v[42:43], v[88:89], v[232:233]
	v_pk_fma_f32 v[90:91], v[44:45], v[90:91], v[234:235]
	v_cvt_pk_bf16_f32 v88, v88, v89
	v_cvt_pk_bf16_f32 v89, v90, v91
	global_store_dwordx2 v146, v[88:89], s[66:67] offset:1024
	v_pk_mul_f32 v[92:93], v[92:93], v[204:205] op_sel_hi:[1,0]
	v_pk_mul_f32 v[94:95], v[94:95], v[204:205] op_sel_hi:[1,0]
	v_pk_mul_f32 v[92:93], v[200:201], v[92:93]
	v_pk_mul_f32 v[94:95], v[202:203], v[94:95]
	v_pk_fma_f32 v[92:93], v[46:47], v[92:93], v[236:237]
	v_pk_fma_f32 v[94:95], v[48:49], v[94:95], v[238:239]
	v_cvt_pk_bf16_f32 v92, v92, v93
	v_cvt_pk_bf16_f32 v93, v94, v95
	global_store_dwordx2 v146, v[92:93], s[66:67] offset:1536
	v_add_u32_e32 v146, 0x800, v146
	global_load_dwordx4 v[80:83], v144, s[46:47] nt
	global_load_dwordx4 v[84:87], v144, s[46:47] offset:1024 nt
	global_load_dwordx4 v[88:91], v144, s[46:47] offset:2048 nt
	global_load_dwordx4 v[92:95], v144, s[46:47] offset:3072 nt
	v_add_u32_e32 v144, 0x1000, v144
	s_waitcnt vmcnt(40)
	v_pk_mul_f32 v[242:243], v[96:97], v[96:97]
	v_pk_mul_f32 v[244:245], v[100:101], v[100:101]
	v_pk_mul_f32 v[246:247], v[98:99], v[98:99]
	v_pk_mul_f32 v[248:249], v[102:103], v[102:103]
	v_add_f32_e32 v204, v245, v244
	v_add_f32_e32 v205, v243, v242
	v_add_f32_e32 v204, v248, v204
	v_add_f32_e32 v205, v246, v205
	v_add_f32_e32 v204, v249, v204
	v_add_f32_e32 v205, v247, v205
	v_pk_mul_f32 v[242:243], v[104:105], v[104:105]
	v_pk_mul_f32 v[244:245], v[108:109], v[108:109]
	v_pk_mul_f32 v[246:247], v[106:107], v[106:107]
	v_pk_mul_f32 v[248:249], v[110:111], v[110:111]
	v_add_f32_e32 v206, v243, v242
	v_add_f32_e32 v207, v245, v244
	v_add_f32_e32 v206, v246, v206
	v_add_f32_e32 v207, v248, v207
	v_add_f32_e32 v206, v247, v206
	v_add_f32_e32 v207, v249, v207
	v_add_f32_e32 v204, v205, v204
	v_add_f32_e32 v204, v204, v206
	v_add_f32_e32 v204, v204, v207
	ds_swizzle_b32 v205, v204 offset:swizzle(SWAP,1)
	s_waitcnt lgkmcnt(0)
	v_add_f32_e32 v204, v204, v205
	ds_swizzle_b32 v205, v204 offset:swizzle(SWAP,2)
	s_waitcnt lgkmcnt(0)
	v_add_f32_e32 v204, v204, v205
	ds_swizzle_b32 v205, v204 offset:swizzle(SWAP,4)
	s_waitcnt lgkmcnt(0)
	v_add_f32_e32 v204, v204, v205
	ds_swizzle_b32 v205, v204 offset:swizzle(SWAP,8)
	s_waitcnt lgkmcnt(0)
	v_add_f32_e32 v204, v204, v205
	ds_swizzle_b32 v205, v204 offset:swizzle(SWAP,16)
	s_waitcnt lgkmcnt(0)
	v_add_f32_e32 v204, v204, v205
	v_mov_b32_e32 v205, v204
	s_nop 1
	v_permlane32_swap_b32_e32 v204, v205
	v_add_f32_e32 v204, v204, v205
	v_mov_b32_e32 v205, 0x358637bd
	v_fmamk_f32 v204, v204, 0x3a800000, v205
	v_rsq_f32_e32 v204, v204
	s_nop 0
	v_pk_mul_f32 v[96:97], v[96:97], v[204:205] op_sel_hi:[1,0]
	v_pk_mul_f32 v[98:99], v[98:99], v[204:205] op_sel_hi:[1,0]
	v_pk_mul_f32 v[96:97], v[188:189], v[96:97]
	v_pk_mul_f32 v[98:99], v[190:191], v[98:99]
	v_pk_fma_f32 v[96:97], v[34:35], v[96:97], v[224:225]
	v_pk_fma_f32 v[98:99], v[36:37], v[98:99], v[226:227]
	v_cvt_pk_bf16_f32 v96, v96, v97
	v_cvt_pk_bf16_f32 v97, v98, v99
	global_store_dwordx2 v146, v[96:97], s[66:67]
	v_pk_mul_f32 v[100:101], v[100:101], v[204:205] op_sel_hi:[1,0]
	v_pk_mul_f32 v[102:103], v[102:103], v[204:205] op_sel_hi:[1,0]
	v_pk_mul_f32 v[100:101], v[192:193], v[100:101]
	v_pk_mul_f32 v[102:103], v[194:195], v[102:103]
	v_pk_fma_f32 v[100:101], v[38:39], v[100:101], v[228:229]
	v_pk_fma_f32 v[102:103], v[40:41], v[102:103], v[230:231]
	v_cvt_pk_bf16_f32 v100, v100, v101
	v_cvt_pk_bf16_f32 v101, v102, v103
	global_store_dwordx2 v146, v[100:101], s[66:67] offset:512
	v_pk_mul_f32 v[104:105], v[104:105], v[204:205] op_sel_hi:[1,0]
	v_pk_mul_f32 v[106:107], v[106:107], v[204:205] op_sel_hi:[1,0]
	v_pk_mul_f32 v[104:105], v[196:197], v[104:105]
	v_pk_mul_f32 v[106:107], v[198:199], v[106:107]
	v_pk_fma_f32 v[104:105], v[42:43], v[104:105], v[232:233]
	v_pk_fma_f32 v[106:107], v[44:45], v[106:107], v[234:235]
	v_cvt_pk_bf16_f32 v104, v104, v105
	v_cvt_pk_bf16_f32 v105, v106, v107
	global_store_dwordx2 v146, v[104:105], s[66:67] offset:1024
	v_pk_mul_f32 v[108:109], v[108:109], v[204:205] op_sel_hi:[1,0]
	v_pk_mul_f32 v[110:111], v[110:111], v[204:205] op_sel_hi:[1,0]
	v_pk_mul_f32 v[108:109], v[200:201], v[108:109]
	v_pk_mul_f32 v[110:111], v[202:203], v[110:111]
	v_pk_fma_f32 v[108:109], v[46:47], v[108:109], v[236:237]
	v_pk_fma_f32 v[110:111], v[48:49], v[110:111], v[238:239]
	v_cvt_pk_bf16_f32 v108, v108, v109
	v_cvt_pk_bf16_f32 v109, v110, v111
	global_store_dwordx2 v146, v[108:109], s[66:67] offset:1536
	v_add_u32_e32 v146, 0x800, v146
	global_load_dwordx4 v[96:99], v144, s[46:47] nt
	global_load_dwordx4 v[100:103], v144, s[46:47] offset:1024 nt
	global_load_dwordx4 v[104:107], v144, s[46:47] offset:2048 nt
	global_load_dwordx4 v[108:111], v144, s[46:47] offset:3072 nt
	v_add_u32_e32 v144, 0x1000, v144
	s_waitcnt vmcnt(40)
; __device__ __forceinline__ unsigned pk2(float lo, float hi) { const g_f32x2 f = {lo, hi}; return __builtin_bit_cast(unsigned, __builtin_convertvector(f, g_bf16x2)); }
; #define PN_LOAD(dst, rw) do { const float* s_ = (rw) < NLAT ? hlat + (size_t)(rw) * 1024 : hctx + (size_t)((rw) - NLAT) * 1024; \
;         _Pragma("unroll") for (int i = 0; i < 4; ++i) dst[i] = *(const float4*)(s_ + i * 256 + lane * 4); } while (0)
; __device__ __forceinline__ void p_norm(const float* hlat, const float* hctx, const float* g, const float* modl, int sh_off, int sc_off, bf16_t* A, int M,
;                                        const float* part, const float* cgate, float* hcout) {
;     ...
;     if (row < M) PN_LOAD(v, row);
;     while (row < M) {
;         const int nrow = row + stride;
;         if (nrow < M) PN_LOAD(nv, nrow);
;         const int r = row < NLAT ? (row >> 11) : 16;
;         float ss = 0.f;
; #pragma unroll
;         for (int i = 0; i < 4; ++i) {
;             if (part != nullptr && row >= NLAT) {
;                 const size_t po = (size_t)(row - NLAT) * 1024 + i * 256 + lane * 4;
;                 const float4 p0 = *(const float4*)(part + po), p1 = *(const float4*)(part + (size_t)4096 * 1024 + po), cg = *(const float4*)(cgate + i * 256 + lane * 4);
;                 v[i].x += cg.x * (p0.x + p1.x); v[i].y += cg.y * (p0.y + p1.y); v[i].z += cg.z * (p0.z + p1.z); v[i].w += cg.w * (p0.w + p1.w);
;                 *(float4*)(hcout + po) = v[i];
;             }
;             ss += v[i].x * v[i].x + v[i].y * v[i].y + v[i].z * v[i].z + v[i].w * v[i].w; }
;         ss = wave_sum(ss);
;         const float rstd = rsqrtf(ss * (1.0f / 1024.0f) + EPS);
;         const float* mr = modl + (size_t)r * 6144;
; #pragma unroll
;         for (int i = 0; i < 4; ++i) {
;             const int k = i * 256 + lane * 4;
;             const float4 gg = *(const float4*)(g + k), scv = *(const float4*)(mr + sc_off + k), shv = *(const float4*)(mr + sh_off + k);
;             const float o0 = v[i].x * rstd * gg.x * (1.0f + scv.x) + shv.x, o1 = v[i].y * rstd * gg.y * (1.0f + scv.y) + shv.y;
;             const float o2 = v[i].z * rstd * gg.z * (1.0f + scv.z) + shv.z, o3 = v[i].w * rstd * gg.w * (1.0f + scv.w) + shv.w;
;             uint2 w; w.x = pk2(o0, o1); w.y = pk2(o2, o3);
;             *(uint2*)(A + (size_t)row * 1024 + k) = w;
;         }
	v_pk_mul_f32 v[242:243], v[112:113], v[112:113]
	v_pk_mul_f32 v[244:245], v[116:117], v[116:117]
	v_pk_mul_f32 v[246:247], v[114:115], v[114:115]
	v_pk_mul_f32 v[248:249], v[118:119], v[118:119]
	v_add_f32_e32 v204, v245, v244
	v_add_f32_e32 v205, v243, v242
	v_add_f32_e32 v204, v248, v204
	v_add_f32_e32 v205, v246, v205
	v_add_f32_e32 v204, v249, v204
	v_add_f32_e32 v205, v247, v205
	v_pk_mul_f32 v[242:243], v[120:121], v[120:121]
	v_pk_mul_f32 v[244:245], v[124:125], v[124:125]
	v_pk_mul_f32 v[246:247], v[122:123], v[122:123]
	v_pk_mul_f32 v[248:249], v[126:127], v[126:127]
	v_add_f32_e32 v206, v243, v242
	v_add_f32_e32 v207, v245, v244
	v_add_f32_e32 v206, v246, v206
	v_add_f32_e32 v207, v248, v207
	v_add_f32_e32 v206, v247, v206
	v_add_f32_e32 v207, v249, v207
	v_add_f32_e32 v204, v205, v204
	v_add_f32_e32 v204, v204, v206
	v_add_f32_e32 v204, v204, v207
	ds_swizzle_b32 v205, v204 offset:swizzle(SWAP,1)
	s_waitcnt lgkmcnt(0)
	v_add_f32_e32 v204, v204, v205
	ds_swizzle_b32 v205, v204 offset:swizzle(SWAP,2)
	s_waitcnt lgkmcnt(0)
	v_add_f32_e32 v204, v204, v205
	ds_swizzle_b32 v205, v204 offset:swizzle(SWAP,4)
	s_waitcnt lgkmcnt(0)
	v_add_f32_e32 v204, v204, v205
	ds_swizzle_b32 v205, v204 offset:swizzle(SWAP,8)
	s_waitcnt lgkmcnt(0)
	v_add_f32_e32 v204, v204, v205
	ds_swizzle_b32 v205, v204 offset:swizzle(SWAP,16)
	s_waitcnt lgkmcnt(0)
	v_add_f32_e32 v204, v204, v205
	v_mov_b32_e32 v205, v204
	s_nop 1
	v_permlane32_swap_b32_e32 v204, v205
	v_add_f32_e32 v204, v204, v205
	v_mov_b32_e32 v205, 0x358637bd
	v_fmamk_f32 v204, v204, 0x3a800000, v205
	v_rsq_f32_e32 v204, v204
	s_nop 0
	v_pk_mul_f32 v[112:113], v[112:113], v[204:205] op_sel_hi:[1,0]
	v_pk_mul_f32 v[114:115], v[114:115], v[204:205] op_sel_hi:[1,0]
	v_pk_mul_f32 v[112:113], v[188:189], v[112:113]
	v_pk_mul_f32 v[114:115], v[190:191], v[114:115]
	v_pk_fma_f32 v[112:113], v[34:35], v[112:113], v[224:225]
	v_pk_fma_f32 v[114:115], v[36:37], v[114:115], v[226:227]
	v_cvt_pk_bf16_f32 v112, v112, v113
	v_cvt_pk_bf16_f32 v113, v114, v115
	global_store_dwordx2 v146, v[112:113], s[66:67]
	v_pk_mul_f32 v[116:117], v[116:117], v[204:205] op_sel_hi:[1,0]
	v_pk_mul_f32 v[118:119], v[118:119], v[204:205] op_sel_hi:[1,0]
	v_pk_mul_f32 v[116:117], v[192:193], v[116:117]
	v_pk_mul_f32 v[118:119], v[194:195], v[118:119]
	v_pk_fma_f32 v[116:117], v[38:39], v[116:117], v[228:229]
	v_pk_fma_f32 v[118:119], v[40:41], v[118:119], v[230:231]
	v_cvt_pk_bf16_f32 v116, v116, v117
	v_cvt_pk_bf16_f32 v117, v118, v119
	global_store_dwordx2 v146, v[116:117], s[66:67] offset:512
	v_pk_mul_f32 v[120:121], v[120:121], v[204:205] op_sel_hi:[1,0]
	v_pk_mul_f32 v[122:123], v[122:123], v[204:205] op_sel_hi:[1,0]
	v_pk_mul_f32 v[120:121], v[196:197], v[120:121]
	v_pk_mul_f32 v[122:123], v[198:199], v[122:123]
	v_pk_fma_f32 v[120:121], v[42:43], v[120:121], v[232:233]
	v_pk_fma_f32 v[122:123], v[44:45], v[122:123], v[234:235]
	v_cvt_pk_bf16_f32 v120, v120, v121
	v_cvt_pk_bf16_f32 v121, v122, v123
	global_store_dwordx2 v146, v[120:121], s[66:67] offset:1024
	v_pk_mul_f32 v[124:125], v[124:125], v[204:205] op_sel_hi:[1,0]
	v_pk_mul_f32 v[126:127], v[126:127], v[204:205] op_sel_hi:[1,0]
	v_pk_mul_f32 v[124:125], v[200:201], v[124:125]
	v_pk_mul_f32 v[126:127], v[202:203], v[126:127]
	v_pk_fma_f32 v[124:125], v[46:47], v[124:125], v[236:237]
	v_pk_fma_f32 v[126:127], v[48:49], v[126:127], v[238:239]
	v_cvt_pk_bf16_f32 v124, v124, v125
	v_cvt_pk_bf16_f32 v125, v126, v127
	global_store_dwordx2 v146, v[124:125], s[66:67] offset:1536
	v_add_u32_e32 v146, 0x800, v146
	global_load_dwordx4 v[112:115], v144, s[46:47] nt
	global_load_dwordx4 v[116:119], v144, s[46:47] offset:1024 nt
	global_load_dwordx4 v[120:123], v144, s[46:47] offset:2048 nt
	global_load_dwordx4 v[124:127], v144, s[46:47] offset:3072 nt
	v_add_u32_e32 v144, 0x1000, v144
	s_waitcnt vmcnt(40)
	v_pk_mul_f32 v[242:243], v[128:129], v[128:129]
	v_pk_mul_f32 v[244:245], v[132:133], v[132:133]
	v_pk_mul_f32 v[246:247], v[130:131], v[130:131]
	v_pk_mul_f32 v[248:249], v[134:135], v[134:135]
	v_add_f32_e32 v204, v245, v244
	v_add_f32_e32 v205, v243, v242
	v_add_f32_e32 v204, v248, v204
	v_add_f32_e32 v205, v246, v205
	v_add_f32_e32 v204, v249, v204
	v_add_f32_e32 v205, v247, v205
	v_pk_mul_f32 v[242:243], v[136:137], v[136:137]
	v_pk_mul_f32 v[244:245], v[140:141], v[140:141]
	v_pk_mul_f32 v[246:247], v[138:139], v[138:139]
	v_pk_mul_f32 v[248:249], v[142:143], v[142:143]
	v_add_f32_e32 v206, v243, v242
	v_add_f32_e32 v207, v245, v244
	v_add_f32_e32 v206, v246, v206
	v_add_f32_e32 v207, v248, v207
	v_add_f32_e32 v206, v247, v206
	v_add_f32_e32 v207, v249, v207
	v_add_f32_e32 v204, v205, v204
	v_add_f32_e32 v204, v204, v206
	v_add_f32_e32 v204, v204, v207
	ds_swizzle_b32 v205, v204 offset:swizzle(SWAP,1)
	s_waitcnt lgkmcnt(0)
	v_add_f32_e32 v204, v204, v205
	ds_swizzle_b32 v205, v204 offset:swizzle(SWAP,2)
	s_waitcnt lgkmcnt(0)
	v_add_f32_e32 v204, v204, v205
	ds_swizzle_b32 v205, v204 offset:swizzle(SWAP,4)
	s_waitcnt lgkmcnt(0)
	v_add_f32_e32 v204, v204, v205
	ds_swizzle_b32 v205, v204 offset:swizzle(SWAP,8)
	s_waitcnt lgkmcnt(0)
	v_add_f32_e32 v204, v204, v205
	ds_swizzle_b32 v205, v204 offset:swizzle(SWAP,16)
	s_waitcnt lgkmcnt(0)
; __device__ __forceinline__ unsigned pk2(float lo, float hi) { const g_f32x2 f = {lo, hi}; return __builtin_bit_cast(unsigned, __builtin_convertvector(f, g_bf16x2)); }
; #define PN_LOAD(dst, rw) do { const float* s_ = (rw) < NLAT ? hlat + (size_t)(rw) * 1024 : hctx + (size_t)((rw) - NLAT) * 1024; \
;         _Pragma("unroll") for (int i = 0; i < 4; ++i) dst[i] = *(const float4*)(s_ + i * 256 + lane * 4); } while (0)
; __device__ __forceinline__ void p_norm(const float* hlat, const float* hctx, const float* g, const float* modl, int sh_off, int sc_off, bf16_t* A, int M,
;                                        const float* part, const float* cgate, float* hcout) {
;     ...
;     if (row < M) PN_LOAD(v, row);
;     while (row < M) {
;         const int nrow = row + stride;
;         if (nrow < M) PN_LOAD(nv, nrow);
;         const int r = row < NLAT ? (row >> 11) : 16;
;         float ss = 0.f;
; #pragma unroll
;         for (int i = 0; i < 4; ++i) {
;             if (part != nullptr && row >= NLAT) {
;                 const size_t po = (size_t)(row - NLAT) * 1024 + i * 256 + lane * 4;
;                 const float4 p0 = *(const float4*)(part + po), p1 = *(const float4*)(part + (size_t)4096 * 1024 + po), cg = *(const float4*)(cgate + i * 256 + lane * 4);
;                 v[i].x += cg.x * (p0.x + p1.x); v[i].y += cg.y * (p0.y + p1.y); v[i].z += cg.z * (p0.z + p1.z); v[i].w += cg.w * (p0.w + p1.w);
;                 *(float4*)(hcout + po) = v[i];
;             }
;             ss += v[i].x * v[i].x + v[i].y * v[i].y + v[i].z * v[i].z + v[i].w * v[i].w; }
;         ss = wave_sum(ss);
;         const float rstd = rsqrtf(ss * (1.0f / 1024.0f) + EPS);
;         const float* mr = modl + (size_t)r * 6144;
; #pragma unroll
;         for (int i = 0; i < 4; ++i) {
;             const int k = i * 256 + lane * 4;
;             const float4 gg = *(const float4*)(g + k), scv = *(const float4*)(mr + sc_off + k), shv = *(const float4*)(mr + sh_off + k);
;             const float o0 = v[i].x * rstd * gg.x * (1.0f + scv.x) + shv.x, o1 = v[i].y * rstd * gg.y * (1.0f + scv.y) + shv.y;
;             const float o2 = v[i].z * rstd * gg.z * (1.0f + scv.z) + shv.z, o3 = v[i].w * rstd * gg.w * (1.0f + scv.w) + shv.w;
;             uint2 w; w.x = pk2(o0, o1); w.y = pk2(o2, o3);
;             *(uint2*)(A + (size_t)row * 1024 + k) = w;
;         }
	v_add_f32_e32 v204, v204, v205
	v_mov_b32_e32 v205, v204
	s_nop 1
	v_permlane32_swap_b32_e32 v204, v205
	v_add_f32_e32 v204, v204, v205
	v_mov_b32_e32 v205, 0x358637bd
	v_fmamk_f32 v204, v204, 0x3a800000, v205
	v_rsq_f32_e32 v204, v204
	s_nop 0
	v_pk_mul_f32 v[128:129], v[128:129], v[204:205] op_sel_hi:[1,0]
	v_pk_mul_f32 v[130:131], v[130:131], v[204:205] op_sel_hi:[1,0]
	v_pk_mul_f32 v[128:129], v[188:189], v[128:129]
	v_pk_mul_f32 v[130:131], v[190:191], v[130:131]
	v_pk_fma_f32 v[128:129], v[34:35], v[128:129], v[224:225]
	v_pk_fma_f32 v[130:131], v[36:37], v[130:131], v[226:227]
	v_cvt_pk_bf16_f32 v128, v128, v129
	v_cvt_pk_bf16_f32 v129, v130, v131
	global_store_dwordx2 v146, v[128:129], s[66:67]
	v_pk_mul_f32 v[132:133], v[132:133], v[204:205] op_sel_hi:[1,0]
	v_pk_mul_f32 v[134:135], v[134:135], v[204:205] op_sel_hi:[1,0]
	v_pk_mul_f32 v[132:133], v[192:193], v[132:133]
	v_pk_mul_f32 v[134:135], v[194:195], v[134:135]
	v_pk_fma_f32 v[132:133], v[38:39], v[132:133], v[228:229]
	v_pk_fma_f32 v[134:135], v[40:41], v[134:135], v[230:231]
	v_cvt_pk_bf16_f32 v132, v132, v133
	v_cvt_pk_bf16_f32 v133, v134, v135
	global_store_dwordx2 v146, v[132:133], s[66:67] offset:512
	v_pk_mul_f32 v[136:137], v[136:137], v[204:205] op_sel_hi:[1,0]
	v_pk_mul_f32 v[138:139], v[138:139], v[204:205] op_sel_hi:[1,0]
	v_pk_mul_f32 v[136:137], v[196:197], v[136:137]
	v_pk_mul_f32 v[138:139], v[198:199], v[138:139]
	v_pk_fma_f32 v[136:137], v[42:43], v[136:137], v[232:233]
	v_pk_fma_f32 v[138:139], v[44:45], v[138:139], v[234:235]
	v_cvt_pk_bf16_f32 v136, v136, v137
	v_cvt_pk_bf16_f32 v137, v138, v139
	global_store_dwordx2 v146, v[136:137], s[66:67] offset:1024
	v_pk_mul_f32 v[140:141], v[140:141], v[204:205] op_sel_hi:[1,0]
	v_pk_mul_f32 v[142:143], v[142:143], v[204:205] op_sel_hi:[1,0]
	v_pk_mul_f32 v[140:141], v[200:201], v[140:141]
	v_pk_mul_f32 v[142:143], v[202:203], v[142:143]
	v_pk_fma_f32 v[140:141], v[46:47], v[140:141], v[236:237]
	v_pk_fma_f32 v[142:143], v[48:49], v[142:143], v[238:239]
	v_cvt_pk_bf16_f32 v140, v140, v141
	v_cvt_pk_bf16_f32 v141, v142, v143
	global_store_dwordx2 v146, v[140:141], s[66:67] offset:1536
	v_add_u32_e32 v146, 0x800, v146
	global_load_dwordx4 v[128:131], v144, s[46:47] nt
	global_load_dwordx4 v[132:135], v144, s[46:47] offset:1024 nt
	global_load_dwordx4 v[136:139], v144, s[46:47] offset:2048 nt
	global_load_dwordx4 v[140:143], v144, s[46:47] offset:3072 nt
	v_add_u32_e32 v144, 0x1000, v144
	s_waitcnt vmcnt(40)
	v_pk_mul_f32 v[242:243], v[156:157], v[156:157]
	v_pk_mul_f32 v[244:245], v[160:161], v[160:161]
	v_pk_mul_f32 v[246:247], v[158:159], v[158:159]
	v_pk_mul_f32 v[248:249], v[162:163], v[162:163]
	v_add_f32_e32 v204, v245, v244
	v_add_f32_e32 v205, v243, v242
	v_add_f32_e32 v204, v248, v204
	v_add_f32_e32 v205, v246, v205
	v_add_f32_e32 v204, v249, v204
	v_add_f32_e32 v205, v247, v205
	v_pk_mul_f32 v[242:243], v[164:165], v[164:165]
	v_pk_mul_f32 v[244:245], v[168:169], v[168:169]
	v_pk_mul_f32 v[246:247], v[166:167], v[166:167]
	v_pk_mul_f32 v[248:249], v[170:171], v[170:171]
	v_add_f32_e32 v206, v243, v242
	v_add_f32_e32 v207, v245, v244
	v_add_f32_e32 v206, v246, v206
	v_add_f32_e32 v207, v248, v207
	v_add_f32_e32 v206, v247, v206
	v_add_f32_e32 v207, v249, v207
	v_add_f32_e32 v204, v205, v204
	v_add_f32_e32 v204, v204, v206
	v_add_f32_e32 v204, v204, v207
	ds_swizzle_b32 v205, v204 offset:swizzle(SWAP,1)
	s_waitcnt lgkmcnt(0)
	v_add_f32_e32 v204, v204, v205
	ds_swizzle_b32 v205, v204 offset:swizzle(SWAP,2)
	s_waitcnt lgkmcnt(0)
	v_add_f32_e32 v204, v204, v205
	ds_swizzle_b32 v205, v204 offset:swizzle(SWAP,4)
	s_waitcnt lgkmcnt(0)
	v_add_f32_e32 v204, v204, v205
	ds_swizzle_b32 v205, v204 offset:swizzle(SWAP,8)
	s_waitcnt lgkmcnt(0)
	v_add_f32_e32 v204, v204, v205
	ds_swizzle_b32 v205, v204 offset:swizzle(SWAP,16)
	s_waitcnt lgkmcnt(0)
	v_add_f32_e32 v204, v204, v205
	v_mov_b32_e32 v205, v204
	s_nop 1
	v_permlane32_swap_b32_e32 v204, v205
	v_add_f32_e32 v204, v204, v205
	v_mov_b32_e32 v205, 0x358637bd
	v_fmamk_f32 v204, v204, 0x3a800000, v205
	v_rsq_f32_e32 v204, v204
	s_nop 0
	v_pk_mul_f32 v[156:157], v[156:157], v[204:205] op_sel_hi:[1,0]
	v_pk_mul_f32 v[158:159], v[158:159], v[204:205] op_sel_hi:[1,0]
	v_pk_mul_f32 v[156:157], v[188:189], v[156:157]
	v_pk_mul_f32 v[158:159], v[190:191], v[158:159]
	v_pk_fma_f32 v[156:157], v[34:35], v[156:157], v[224:225]
	v_pk_fma_f32 v[158:159], v[36:37], v[158:159], v[226:227]
	v_cvt_pk_bf16_f32 v156, v156, v157
	v_cvt_pk_bf16_f32 v157, v158, v159
	global_store_dwordx2 v146, v[156:157], s[66:67]
	v_pk_mul_f32 v[160:161], v[160:161], v[204:205] op_sel_hi:[1,0]
	v_pk_mul_f32 v[162:163], v[162:163], v[204:205] op_sel_hi:[1,0]
	v_pk_mul_f32 v[160:161], v[192:193], v[160:161]
	v_pk_mul_f32 v[162:163], v[194:195], v[162:163]
	v_pk_fma_f32 v[160:161], v[38:39], v[160:161], v[228:229]
	v_pk_fma_f32 v[162:163], v[40:41], v[162:163], v[230:231]
	v_cvt_pk_bf16_f32 v160, v160, v161
	v_cvt_pk_bf16_f32 v161, v162, v163
	global_store_dwordx2 v146, v[160:161], s[66:67] offset:512
	v_pk_mul_f32 v[164:165], v[164:165], v[204:205] op_sel_hi:[1,0]
	v_pk_mul_f32 v[166:167], v[166:167], v[204:205] op_sel_hi:[1,0]
	v_pk_mul_f32 v[164:165], v[196:197], v[164:165]
	v_pk_mul_f32 v[166:167], v[198:199], v[166:167]
	v_pk_fma_f32 v[164:165], v[42:43], v[164:165], v[232:233]
	v_pk_fma_f32 v[166:167], v[44:45], v[166:167], v[234:235]
	v_cvt_pk_bf16_f32 v164, v164, v165
	v_cvt_pk_bf16_f32 v165, v166, v167
	global_store_dwordx2 v146, v[164:165], s[66:67] offset:1024
	v_pk_mul_f32 v[168:169], v[168:169], v[204:205] op_sel_hi:[1,0]
	v_pk_mul_f32 v[170:171], v[170:171], v[204:205] op_sel_hi:[1,0]
	v_pk_mul_f32 v[168:169], v[200:201], v[168:169]
	v_pk_mul_f32 v[170:171], v[202:203], v[170:171]
	v_pk_fma_f32 v[168:169], v[46:47], v[168:169], v[236:237]
	v_pk_fma_f32 v[170:171], v[48:49], v[170:171], v[238:239]
	v_cvt_pk_bf16_f32 v168, v168, v169
	v_cvt_pk_bf16_f32 v169, v170, v171
	global_store_dwordx2 v146, v[168:169], s[66:67] offset:1536
	v_add_u32_e32 v146, 0x800, v146
	v_lshl_add_u32 v144, v50, 13, v241
	v_mov_b32_e32 v152, v144
	v_add_u32_e32 v150, 0x1000000, v144
	global_load_dwordx4 v[156:159], v144, s[16:17]
	global_load_dwordx4 v[160:163], v144, s[16:17] offset:1024
	global_load_dwordx4 v[164:167], v144, s[16:17] offset:2048
	global_load_dwordx4 v[168:171], v144, s[16:17] offset:3072
	v_add_u32_e32 v144, 0x1000, v144
	s_waitcnt vmcnt(40)
; __device__ __forceinline__ unsigned pk2(float lo, float hi) { const g_f32x2 f = {lo, hi}; return __builtin_bit_cast(unsigned, __builtin_convertvector(f, g_bf16x2)); }
; #define PN_LOAD(dst, rw) do { const float* s_ = (rw) < NLAT ? hlat + (size_t)(rw) * 1024 : hctx + (size_t)((rw) - NLAT) * 1024; \
;         _Pragma("unroll") for (int i = 0; i < 4; ++i) dst[i] = *(const float4*)(s_ + i * 256 + lane * 4); } while (0)
; __device__ __forceinline__ void p_norm(const float* hlat, const float* hctx, const float* g, const float* modl, int sh_off, int sc_off, bf16_t* A, int M,
;                                        const float* part, const float* cgate, float* hcout) {
;     ...
;     if (row < M) PN_LOAD(v, row);
;     while (row < M) {
;         const int nrow = row + stride;
;         if (nrow < M) PN_LOAD(nv, nrow);
;         const int r = row < NLAT ? (row >> 11) : 16;
;         float ss = 0.f;
; #pragma unroll
;         for (int i = 0; i < 4; ++i) {
;             if (part != nullptr && row >= NLAT) {
;                 const size_t po = (size_t)(row - NLAT) * 1024 + i * 256 + lane * 4;
;                 const float4 p0 = *(const float4*)(part + po), p1 = *(const float4*)(part + (size_t)4096 * 1024 + po), cg = *(const float4*)(cgate + i * 256 + lane * 4);
;                 v[i].x += cg.x * (p0.x + p1.x); v[i].y += cg.y * (p0.y + p1.y); v[i].z += cg.z * (p0.z + p1.z); v[i].w += cg.w * (p0.w + p1.w);
;                 *(float4*)(hcout + po) = v[i];
;             }
;             ss += v[i].x * v[i].x + v[i].y * v[i].y + v[i].z * v[i].z + v[i].w * v[i].w; }
;         ss = wave_sum(ss);
;         const float rstd = rsqrtf(ss * (1.0f / 1024.0f) + EPS);
;         const float* mr = modl + (size_t)r * 6144;
; #pragma unroll
;         for (int i = 0; i < 4; ++i) {
;             const int k = i * 256 + lane * 4;
;             const float4 gg = *(const float4*)(g + k), scv = *(const float4*)(mr + sc_off + k), shv = *(const float4*)(mr + sh_off + k);
;             const float o0 = v[i].x * rstd * gg.x * (1.0f + scv.x) + shv.x, o1 = v[i].y * rstd * gg.y * (1.0f + scv.y) + shv.y;
;             const float o2 = v[i].z * rstd * gg.z * (1.0f + scv.z) + shv.z, o3 = v[i].w * rstd * gg.w * (1.0f + scv.w) + shv.w;
;             uint2 w; w.x = pk2(o0, o1); w.y = pk2(o2, o3);
;             *(uint2*)(A + (size_t)row * 1024 + k) = w;
;         }
	v_pk_mul_f32 v[242:243], v[172:173], v[172:173]
	v_pk_mul_f32 v[244:245], v[176:177], v[176:177]
	v_pk_mul_f32 v[246:247], v[174:175], v[174:175]
	v_pk_mul_f32 v[248:249], v[178:179], v[178:179]
	v_add_f32_e32 v204, v245, v244
	v_add_f32_e32 v205, v243, v242
	v_add_f32_e32 v204, v248, v204
	v_add_f32_e32 v205, v246, v205
	v_add_f32_e32 v204, v249, v204
	v_add_f32_e32 v205, v247, v205
	v_pk_mul_f32 v[242:243], v[180:181], v[180:181]
	v_pk_mul_f32 v[244:245], v[184:185], v[184:185]
	v_pk_mul_f32 v[246:247], v[182:183], v[182:183]
	v_pk_mul_f32 v[248:249], v[186:187], v[186:187]
	v_add_f32_e32 v206, v243, v242
	v_add_f32_e32 v207, v245, v244
	v_add_f32_e32 v206, v246, v206
	v_add_f32_e32 v207, v248, v207
	v_add_f32_e32 v206, v247, v206
	v_add_f32_e32 v207, v249, v207
	v_add_f32_e32 v204, v205, v204
	v_add_f32_e32 v204, v204, v206
	v_add_f32_e32 v204, v204, v207
	ds_swizzle_b32 v205, v204 offset:swizzle(SWAP,1)
	s_waitcnt lgkmcnt(0)
	v_add_f32_e32 v204, v204, v205
	ds_swizzle_b32 v205, v204 offset:swizzle(SWAP,2)
	s_waitcnt lgkmcnt(0)
	v_add_f32_e32 v204, v204, v205
	ds_swizzle_b32 v205, v204 offset:swizzle(SWAP,4)
	s_waitcnt lgkmcnt(0)
	v_add_f32_e32 v204, v204, v205
	ds_swizzle_b32 v205, v204 offset:swizzle(SWAP,8)
	s_waitcnt lgkmcnt(0)
	v_add_f32_e32 v204, v204, v205
	ds_swizzle_b32 v205, v204 offset:swizzle(SWAP,16)
	s_waitcnt lgkmcnt(0)
	v_add_f32_e32 v204, v204, v205
	v_mov_b32_e32 v205, v204
	s_nop 1
	v_permlane32_swap_b32_e32 v204, v205
	v_add_f32_e32 v204, v204, v205
	v_mov_b32_e32 v205, 0x358637bd
	v_fmamk_f32 v204, v204, 0x3a800000, v205
	v_rsq_f32_e32 v204, v204
	s_nop 0
	v_pk_mul_f32 v[172:173], v[172:173], v[204:205] op_sel_hi:[1,0]
	v_pk_mul_f32 v[174:175], v[174:175], v[204:205] op_sel_hi:[1,0]
	v_pk_mul_f32 v[172:173], v[188:189], v[172:173]
	v_pk_mul_f32 v[174:175], v[190:191], v[174:175]
	v_pk_fma_f32 v[172:173], v[34:35], v[172:173], v[224:225]
	v_pk_fma_f32 v[174:175], v[36:37], v[174:175], v[226:227]
	v_cvt_pk_bf16_f32 v172, v172, v173
	v_cvt_pk_bf16_f32 v173, v174, v175
	global_store_dwordx2 v146, v[172:173], s[66:67]
	v_pk_mul_f32 v[176:177], v[176:177], v[204:205] op_sel_hi:[1,0]
	v_pk_mul_f32 v[178:179], v[178:179], v[204:205] op_sel_hi:[1,0]
	v_pk_mul_f32 v[176:177], v[192:193], v[176:177]
	v_pk_mul_f32 v[178:179], v[194:195], v[178:179]
	v_pk_fma_f32 v[176:177], v[38:39], v[176:177], v[228:229]
	v_pk_fma_f32 v[178:179], v[40:41], v[178:179], v[230:231]
	v_cvt_pk_bf16_f32 v176, v176, v177
	v_cvt_pk_bf16_f32 v177, v178, v179
	global_store_dwordx2 v146, v[176:177], s[66:67] offset:512
	v_pk_mul_f32 v[180:181], v[180:181], v[204:205] op_sel_hi:[1,0]
	v_pk_mul_f32 v[182:183], v[182:183], v[204:205] op_sel_hi:[1,0]
	v_pk_mul_f32 v[180:181], v[196:197], v[180:181]
	v_pk_mul_f32 v[182:183], v[198:199], v[182:183]
	v_pk_fma_f32 v[180:181], v[42:43], v[180:181], v[232:233]
	v_pk_fma_f32 v[182:183], v[44:45], v[182:183], v[234:235]
	v_cvt_pk_bf16_f32 v180, v180, v181
	v_cvt_pk_bf16_f32 v181, v182, v183
	global_store_dwordx2 v146, v[180:181], s[66:67] offset:1024
	v_pk_mul_f32 v[184:185], v[184:185], v[204:205] op_sel_hi:[1,0]
	v_pk_mul_f32 v[186:187], v[186:187], v[204:205] op_sel_hi:[1,0]
	v_pk_mul_f32 v[184:185], v[200:201], v[184:185]
	v_pk_mul_f32 v[186:187], v[202:203], v[186:187]
	v_pk_fma_f32 v[184:185], v[46:47], v[184:185], v[236:237]
	v_pk_fma_f32 v[186:187], v[48:49], v[186:187], v[238:239]
	v_cvt_pk_bf16_f32 v184, v184, v185
	v_cvt_pk_bf16_f32 v185, v186, v187
	global_store_dwordx2 v146, v[184:185], s[66:67] offset:1536
	v_add_u32_e32 v146, 0x800, v146
	global_load_dwordx4 v[172:175], v144, s[16:17]
	global_load_dwordx4 v[176:179], v144, s[16:17] offset:1024
	global_load_dwordx4 v[180:183], v144, s[16:17] offset:2048
	global_load_dwordx4 v[184:187], v144, s[16:17] offset:3072
	v_add_u32_e32 v144, 0x1000, v144
	s_waitcnt vmcnt(40)
	v_pk_mul_f32 v[242:243], v[80:81], v[80:81]
	v_pk_mul_f32 v[244:245], v[84:85], v[84:85]
	v_pk_mul_f32 v[246:247], v[82:83], v[82:83]
	v_pk_mul_f32 v[248:249], v[86:87], v[86:87]
	v_add_f32_e32 v204, v245, v244
	v_add_f32_e32 v205, v243, v242
	v_add_f32_e32 v204, v248, v204
	v_add_f32_e32 v205, v246, v205
	v_add_f32_e32 v204, v249, v204
	v_add_f32_e32 v205, v247, v205
	v_pk_mul_f32 v[242:243], v[88:89], v[88:89]
	v_pk_mul_f32 v[244:245], v[92:93], v[92:93]
	v_pk_mul_f32 v[246:247], v[90:91], v[90:91]
	v_pk_mul_f32 v[248:249], v[94:95], v[94:95]
	v_add_f32_e32 v206, v243, v242
	v_add_f32_e32 v207, v245, v244
	v_add_f32_e32 v206, v246, v206
	v_add_f32_e32 v207, v248, v207
	v_add_f32_e32 v206, v247, v206
	v_add_f32_e32 v207, v249, v207
	v_add_f32_e32 v204, v205, v204
	v_add_f32_e32 v204, v204, v206
	v_add_f32_e32 v204, v204, v207
	ds_swizzle_b32 v205, v204 offset:swizzle(SWAP,1)
	s_waitcnt lgkmcnt(0)
	v_add_f32_e32 v204, v204, v205
	ds_swizzle_b32 v205, v204 offset:swizzle(SWAP,2)
	s_waitcnt lgkmcnt(0)
	v_add_f32_e32 v204, v204, v205
	ds_swizzle_b32 v205, v204 offset:swizzle(SWAP,4)
	s_waitcnt lgkmcnt(0)
	v_add_f32_e32 v204, v204, v205
	ds_swizzle_b32 v205, v204 offset:swizzle(SWAP,8)
	s_waitcnt lgkmcnt(0)
	v_add_f32_e32 v204, v204, v205
	ds_swizzle_b32 v205, v204 offset:swizzle(SWAP,16)
	s_waitcnt lgkmcnt(0)
; __device__ __forceinline__ unsigned pk2(float lo, float hi) { const g_f32x2 f = {lo, hi}; return __builtin_bit_cast(unsigned, __builtin_convertvector(f, g_bf16x2)); }
; #define PN_LOAD(dst, rw) do { const float* s_ = (rw) < NLAT ? hlat + (size_t)(rw) * 1024 : hctx + (size_t)((rw) - NLAT) * 1024; \
;         _Pragma("unroll") for (int i = 0; i < 4; ++i) dst[i] = *(const float4*)(s_ + i * 256 + lane * 4); } while (0)
; __device__ __forceinline__ void p_norm(const float* hlat, const float* hctx, const float* g, const float* modl, int sh_off, int sc_off, bf16_t* A, int M,
;                                        const float* part, const float* cgate, float* hcout) {
;     ...
;     if (row < M) PN_LOAD(v, row);
;     while (row < M) {
;         const int nrow = row + stride;
;         if (nrow < M) PN_LOAD(nv, nrow);
;         const int r = row < NLAT ? (row >> 11) : 16;
;         float ss = 0.f;
; #pragma unroll
;         for (int i = 0; i < 4; ++i) {
;             if (part != nullptr && row >= NLAT) {
;                 const size_t po = (size_t)(row - NLAT) * 1024 + i * 256 + lane * 4;
;                 const float4 p0 = *(const float4*)(part + po), p1 = *(const float4*)(part + (size_t)4096 * 1024 + po), cg = *(const float4*)(cgate + i * 256 + lane * 4);
;                 v[i].x += cg.x * (p0.x + p1.x); v[i].y += cg.y * (p0.y + p1.y); v[i].z += cg.z * (p0.z + p1.z); v[i].w += cg.w * (p0.w + p1.w);
;                 *(float4*)(hcout + po) = v[i];
;             }
;             ss += v[i].x * v[i].x + v[i].y * v[i].y + v[i].z * v[i].z + v[i].w * v[i].w; }
;         ss = wave_sum(ss);
;         const float rstd = rsqrtf(ss * (1.0f / 1024.0f) + EPS);
;         const float* mr = modl + (size_t)r * 6144;
; #pragma unroll
;         for (int i = 0; i < 4; ++i) {
;             const int k = i * 256 + lane * 4;
;             const float4 gg = *(const float4*)(g + k), scv = *(const float4*)(mr + sc_off + k), shv = *(const float4*)(mr + sh_off + k);
;             const float o0 = v[i].x * rstd * gg.x * (1.0f + scv.x) + shv.x, o1 = v[i].y * rstd * gg.y * (1.0f + scv.y) + shv.y;
;             const float o2 = v[i].z * rstd * gg.z * (1.0f + scv.z) + shv.z, o3 = v[i].w * rstd * gg.w * (1.0f + scv.w) + shv.w;
;             uint2 w; w.x = pk2(o0, o1); w.y = pk2(o2, o3);
;             *(uint2*)(A + (size_t)row * 1024 + k) = w;
;         }
	v_add_f32_e32 v204, v204, v205
	v_mov_b32_e32 v205, v204
	s_nop 1
	v_permlane32_swap_b32_e32 v204, v205
	v_add_f32_e32 v204, v204, v205
	v_mov_b32_e32 v205, 0x358637bd
	v_fmamk_f32 v204, v204, 0x3a800000, v205
	v_rsq_f32_e32 v204, v204
	s_nop 0
	v_pk_mul_f32 v[80:81], v[80:81], v[204:205] op_sel_hi:[1,0]
	v_pk_mul_f32 v[82:83], v[82:83], v[204:205] op_sel_hi:[1,0]
	v_pk_mul_f32 v[80:81], v[188:189], v[80:81]
	v_pk_mul_f32 v[82:83], v[190:191], v[82:83]
	v_pk_fma_f32 v[80:81], v[34:35], v[80:81], v[224:225]
	v_pk_fma_f32 v[82:83], v[36:37], v[82:83], v[226:227]
	v_cvt_pk_bf16_f32 v80, v80, v81
	v_cvt_pk_bf16_f32 v81, v82, v83
	global_store_dwordx2 v146, v[80:81], s[66:67]
	v_pk_mul_f32 v[84:85], v[84:85], v[204:205] op_sel_hi:[1,0]
	v_pk_mul_f32 v[86:87], v[86:87], v[204:205] op_sel_hi:[1,0]
	v_pk_mul_f32 v[84:85], v[192:193], v[84:85]
	v_pk_mul_f32 v[86:87], v[194:195], v[86:87]
	v_pk_fma_f32 v[84:85], v[38:39], v[84:85], v[228:229]
	v_pk_fma_f32 v[86:87], v[40:41], v[86:87], v[230:231]
	v_cvt_pk_bf16_f32 v84, v84, v85
	v_cvt_pk_bf16_f32 v85, v86, v87
	global_store_dwordx2 v146, v[84:85], s[66:67] offset:512
	v_pk_mul_f32 v[88:89], v[88:89], v[204:205] op_sel_hi:[1,0]
	v_pk_mul_f32 v[90:91], v[90:91], v[204:205] op_sel_hi:[1,0]
	v_pk_mul_f32 v[88:89], v[196:197], v[88:89]
	v_pk_mul_f32 v[90:91], v[198:199], v[90:91]
	v_pk_fma_f32 v[88:89], v[42:43], v[88:89], v[232:233]
	v_pk_fma_f32 v[90:91], v[44:45], v[90:91], v[234:235]
	v_cvt_pk_bf16_f32 v88, v88, v89
	v_cvt_pk_bf16_f32 v89, v90, v91
	global_store_dwordx2 v146, v[88:89], s[66:67] offset:1024
	v_pk_mul_f32 v[92:93], v[92:93], v[204:205] op_sel_hi:[1,0]
	v_pk_mul_f32 v[94:95], v[94:95], v[204:205] op_sel_hi:[1,0]
	v_pk_mul_f32 v[92:93], v[200:201], v[92:93]
	v_pk_mul_f32 v[94:95], v[202:203], v[94:95]
	v_pk_fma_f32 v[92:93], v[46:47], v[92:93], v[236:237]
	v_pk_fma_f32 v[94:95], v[48:49], v[94:95], v[238:239]
	v_cvt_pk_bf16_f32 v92, v92, v93
	v_cvt_pk_bf16_f32 v93, v94, v95
	global_store_dwordx2 v146, v[92:93], s[66:67] offset:1536
	v_add_u32_e32 v146, 0x800, v146
	global_load_dwordx4 v[8:11], v241, s[20:21]
	global_load_dwordx4 v[52:55], v241, s[20:21] offset:1024
	global_load_dwordx4 v[60:63], v241, s[20:21] offset:2048
	global_load_dwordx4 v[64:67], v241, s[20:21] offset:3072
	s_waitcnt vmcnt(40)
	v_pk_mul_f32 v[242:243], v[96:97], v[96:97]
	v_pk_mul_f32 v[244:245], v[100:101], v[100:101]
	v_pk_mul_f32 v[246:247], v[98:99], v[98:99]
	v_pk_mul_f32 v[248:249], v[102:103], v[102:103]
	v_add_f32_e32 v204, v245, v244
	v_add_f32_e32 v205, v243, v242
	v_add_f32_e32 v204, v248, v204
	v_add_f32_e32 v205, v246, v205
	v_add_f32_e32 v204, v249, v204
	v_add_f32_e32 v205, v247, v205
	v_pk_mul_f32 v[242:243], v[104:105], v[104:105]
	v_pk_mul_f32 v[244:245], v[108:109], v[108:109]
	v_pk_mul_f32 v[246:247], v[106:107], v[106:107]
	v_pk_mul_f32 v[248:249], v[110:111], v[110:111]
	v_add_f32_e32 v206, v243, v242
	v_add_f32_e32 v207, v245, v244
	v_add_f32_e32 v206, v246, v206
	v_add_f32_e32 v207, v248, v207
	v_add_f32_e32 v206, v247, v206
	v_add_f32_e32 v207, v249, v207
	v_add_f32_e32 v204, v205, v204
	v_add_f32_e32 v204, v204, v206
	v_add_f32_e32 v204, v204, v207
	ds_swizzle_b32 v205, v204 offset:swizzle(SWAP,1)
	s_waitcnt lgkmcnt(0)
	v_add_f32_e32 v204, v204, v205
	ds_swizzle_b32 v205, v204 offset:swizzle(SWAP,2)
	s_waitcnt lgkmcnt(0)
	v_add_f32_e32 v204, v204, v205
	ds_swizzle_b32 v205, v204 offset:swizzle(SWAP,4)
	s_waitcnt lgkmcnt(0)
	v_add_f32_e32 v204, v204, v205
	ds_swizzle_b32 v205, v204 offset:swizzle(SWAP,8)
	s_waitcnt lgkmcnt(0)
	v_add_f32_e32 v204, v204, v205
	ds_swizzle_b32 v205, v204 offset:swizzle(SWAP,16)
	s_waitcnt lgkmcnt(0)
	v_add_f32_e32 v204, v204, v205
	v_mov_b32_e32 v205, v204
	s_nop 1
	v_permlane32_swap_b32_e32 v204, v205
	v_add_f32_e32 v204, v204, v205
	v_mov_b32_e32 v205, 0x358637bd
	v_fmamk_f32 v204, v204, 0x3a800000, v205
	v_rsq_f32_e32 v204, v204
	s_nop 0
	v_pk_mul_f32 v[96:97], v[96:97], v[204:205] op_sel_hi:[1,0]
	v_pk_mul_f32 v[98:99], v[98:99], v[204:205] op_sel_hi:[1,0]
	v_pk_mul_f32 v[96:97], v[188:189], v[96:97]
	v_pk_mul_f32 v[98:99], v[190:191], v[98:99]
	v_pk_fma_f32 v[96:97], v[34:35], v[96:97], v[224:225]
	v_pk_fma_f32 v[98:99], v[36:37], v[98:99], v[226:227]
	v_cvt_pk_bf16_f32 v96, v96, v97
	v_cvt_pk_bf16_f32 v97, v98, v99
	global_store_dwordx2 v146, v[96:97], s[66:67]
	v_pk_mul_f32 v[100:101], v[100:101], v[204:205] op_sel_hi:[1,0]
	v_pk_mul_f32 v[102:103], v[102:103], v[204:205] op_sel_hi:[1,0]
	v_pk_mul_f32 v[100:101], v[192:193], v[100:101]
	v_pk_mul_f32 v[102:103], v[194:195], v[102:103]
	v_pk_fma_f32 v[100:101], v[38:39], v[100:101], v[228:229]
	v_pk_fma_f32 v[102:103], v[40:41], v[102:103], v[230:231]
	v_cvt_pk_bf16_f32 v100, v100, v101
	v_cvt_pk_bf16_f32 v101, v102, v103
	global_store_dwordx2 v146, v[100:101], s[66:67] offset:512
	v_pk_mul_f32 v[104:105], v[104:105], v[204:205] op_sel_hi:[1,0]
	v_pk_mul_f32 v[106:107], v[106:107], v[204:205] op_sel_hi:[1,0]
	v_pk_mul_f32 v[104:105], v[196:197], v[104:105]
	v_pk_mul_f32 v[106:107], v[198:199], v[106:107]
	v_pk_fma_f32 v[104:105], v[42:43], v[104:105], v[232:233]
	v_pk_fma_f32 v[106:107], v[44:45], v[106:107], v[234:235]
	v_cvt_pk_bf16_f32 v104, v104, v105
	v_cvt_pk_bf16_f32 v105, v106, v107
	global_store_dwordx2 v146, v[104:105], s[66:67] offset:1024
	v_pk_mul_f32 v[108:109], v[108:109], v[204:205] op_sel_hi:[1,0]
	v_pk_mul_f32 v[110:111], v[110:111], v[204:205] op_sel_hi:[1,0]
	v_pk_mul_f32 v[108:109], v[200:201], v[108:109]
	v_pk_mul_f32 v[110:111], v[202:203], v[110:111]
	v_pk_fma_f32 v[108:109], v[46:47], v[108:109], v[236:237]
	v_pk_fma_f32 v[110:111], v[48:49], v[110:111], v[238:239]
	v_cvt_pk_bf16_f32 v108, v108, v109
	v_cvt_pk_bf16_f32 v109, v110, v111
	global_store_dwordx2 v146, v[108:109], s[66:67] offset:1536
	v_add_u32_e32 v146, 0x800, v146
	global_load_dwordx4 v[80:83], v152, s[70:71]
	global_load_dwordx4 v[84:87], v152, s[70:71] offset:1024
	global_load_dwordx4 v[88:91], v152, s[70:71] offset:2048
	global_load_dwordx4 v[92:95], v152, s[70:71] offset:3072
	global_load_dwordx4 v[96:99], v150, s[70:71]
	global_load_dwordx4 v[100:103], v150, s[70:71] offset:1024
	global_load_dwordx4 v[104:107], v150, s[70:71] offset:2048
	global_load_dwordx4 v[108:111], v150, s[70:71] offset:3072
	s_waitcnt vmcnt(44)
; __device__ __forceinline__ unsigned pk2(float lo, float hi) { const g_f32x2 f = {lo, hi}; return __builtin_bit_cast(unsigned, __builtin_convertvector(f, g_bf16x2)); }
; __device__ __forceinline__ void p_norm(const float* hlat, const float* hctx, const float* g, const float* modl, int sh_off, int sc_off, bf16_t* A, int M,
;                                        const float* part, const float* cgate, float* hcout) {
;     ...
;             if (part != nullptr && row >= NLAT) {
;                 const size_t po = (size_t)(row - NLAT) * 1024 + i * 256 + lane * 4;
;                 const float4 p0 = *(const float4*)(part + po), p1 = *(const float4*)(part + (size_t)4096 * 1024 + po), cg = *(const float4*)(cgate + i * 256 + lane * 4);
;                 v[i].x += cg.x * (p0.x + p1.x); v[i].y += cg.y * (p0.y + p1.y); v[i].z += cg.z * (p0.z + p1.z); v[i].w += cg.w * (p0.w + p1.w);
;                 *(float4*)(hcout + po) = v[i];
;             }
;             ss += v[i].x * v[i].x + v[i].y * v[i].y + v[i].z * v[i].z + v[i].w * v[i].w; }
;         ss = wave_sum(ss);
;         const float rstd = rsqrtf(ss * (1.0f / 1024.0f) + EPS);
;         const float* mr = modl + (size_t)r * 6144;
; #pragma unroll
;         for (int i = 0; i < 4; ++i) {
;             const int k = i * 256 + lane * 4;
;             const float4 gg = *(const float4*)(g + k), scv = *(const float4*)(mr + sc_off + k), shv = *(const float4*)(mr + sh_off + k);
;             const float o0 = v[i].x * rstd * gg.x * (1.0f + scv.x) + shv.x, o1 = v[i].y * rstd * gg.y * (1.0f + scv.y) + shv.y;
;             const float o2 = v[i].z * rstd * gg.z * (1.0f + scv.z) + shv.z, o3 = v[i].w * rstd * gg.w * (1.0f + scv.w) + shv.w;
;             uint2 w; w.x = pk2(o0, o1); w.y = pk2(o2, o3);
;             *(uint2*)(A + (size_t)row * 1024 + k) = w;
;         }
	v_pk_mul_f32 v[242:243], v[112:113], v[112:113]
	v_pk_mul_f32 v[244:245], v[116:117], v[116:117]
	v_pk_mul_f32 v[246:247], v[114:115], v[114:115]
	v_pk_mul_f32 v[248:249], v[118:119], v[118:119]
	v_add_f32_e32 v204, v245, v244
	v_add_f32_e32 v205, v243, v242
	v_add_f32_e32 v204, v248, v204
	v_add_f32_e32 v205, v246, v205
	v_add_f32_e32 v204, v249, v204
	v_add_f32_e32 v205, v247, v205
	v_pk_mul_f32 v[242:243], v[120:121], v[120:121]
	v_pk_mul_f32 v[244:245], v[124:125], v[124:125]
	v_pk_mul_f32 v[246:247], v[122:123], v[122:123]
	v_pk_mul_f32 v[248:249], v[126:127], v[126:127]
	v_add_f32_e32 v206, v243, v242
	v_add_f32_e32 v207, v245, v244
	v_add_f32_e32 v206, v246, v206
	v_add_f32_e32 v207, v248, v207
	v_add_f32_e32 v206, v247, v206
	v_add_f32_e32 v207, v249, v207
	v_add_f32_e32 v204, v205, v204
	v_add_f32_e32 v204, v204, v206
	v_add_f32_e32 v204, v204, v207
	ds_swizzle_b32 v205, v204 offset:swizzle(SWAP,1)
	s_waitcnt lgkmcnt(0)
	v_add_f32_e32 v204, v204, v205
	ds_swizzle_b32 v205, v204 offset:swizzle(SWAP,2)
	s_waitcnt lgkmcnt(0)
	v_add_f32_e32 v204, v204, v205
	ds_swizzle_b32 v205, v204 offset:swizzle(SWAP,4)
	s_waitcnt lgkmcnt(0)
	v_add_f32_e32 v204, v204, v205
	ds_swizzle_b32 v205, v204 offset:swizzle(SWAP,8)
	s_waitcnt lgkmcnt(0)
	v_add_f32_e32 v204, v204, v205
	ds_swizzle_b32 v205, v204 offset:swizzle(SWAP,16)
	s_waitcnt lgkmcnt(0)
	v_add_f32_e32 v204, v204, v205
	v_mov_b32_e32 v205, v204
	s_nop 1
	v_permlane32_swap_b32_e32 v204, v205
	v_add_f32_e32 v204, v204, v205
	v_mov_b32_e32 v205, 0x358637bd
	v_fmamk_f32 v204, v204, 0x3a800000, v205
	v_rsq_f32_e32 v204, v204
	s_nop 0
	v_pk_mul_f32 v[112:113], v[112:113], v[204:205] op_sel_hi:[1,0]
	v_pk_mul_f32 v[114:115], v[114:115], v[204:205] op_sel_hi:[1,0]
	v_pk_mul_f32 v[112:113], v[188:189], v[112:113]
	v_pk_mul_f32 v[114:115], v[190:191], v[114:115]
	v_pk_fma_f32 v[112:113], v[34:35], v[112:113], v[224:225]
	v_pk_fma_f32 v[114:115], v[36:37], v[114:115], v[226:227]
	v_cvt_pk_bf16_f32 v112, v112, v113
	v_cvt_pk_bf16_f32 v113, v114, v115
	global_store_dwordx2 v146, v[112:113], s[66:67]
	v_pk_mul_f32 v[116:117], v[116:117], v[204:205] op_sel_hi:[1,0]
	v_pk_mul_f32 v[118:119], v[118:119], v[204:205] op_sel_hi:[1,0]
	v_pk_mul_f32 v[116:117], v[192:193], v[116:117]
	v_pk_mul_f32 v[118:119], v[194:195], v[118:119]
	v_pk_fma_f32 v[116:117], v[38:39], v[116:117], v[228:229]
	v_pk_fma_f32 v[118:119], v[40:41], v[118:119], v[230:231]
	v_cvt_pk_bf16_f32 v116, v116, v117
	v_cvt_pk_bf16_f32 v117, v118, v119
	global_store_dwordx2 v146, v[116:117], s[66:67] offset:512
	v_pk_mul_f32 v[120:121], v[120:121], v[204:205] op_sel_hi:[1,0]
	v_pk_mul_f32 v[122:123], v[122:123], v[204:205] op_sel_hi:[1,0]
	v_pk_mul_f32 v[120:121], v[196:197], v[120:121]
	v_pk_mul_f32 v[122:123], v[198:199], v[122:123]
	v_pk_fma_f32 v[120:121], v[42:43], v[120:121], v[232:233]
	v_pk_fma_f32 v[122:123], v[44:45], v[122:123], v[234:235]
	v_cvt_pk_bf16_f32 v120, v120, v121
	v_cvt_pk_bf16_f32 v121, v122, v123
	global_store_dwordx2 v146, v[120:121], s[66:67] offset:1024
	v_pk_mul_f32 v[124:125], v[124:125], v[204:205] op_sel_hi:[1,0]
	v_pk_mul_f32 v[126:127], v[126:127], v[204:205] op_sel_hi:[1,0]
	v_pk_mul_f32 v[124:125], v[200:201], v[124:125]
	v_pk_mul_f32 v[126:127], v[202:203], v[126:127]
	v_pk_fma_f32 v[124:125], v[46:47], v[124:125], v[236:237]
	v_pk_fma_f32 v[126:127], v[48:49], v[126:127], v[238:239]
	v_cvt_pk_bf16_f32 v124, v124, v125
	v_cvt_pk_bf16_f32 v125, v126, v127
	global_store_dwordx2 v146, v[124:125], s[66:67] offset:1536
	v_add_u32_e32 v146, 0x800, v146
	v_add_u32_e32 v207, 0x1000, v152
	global_load_dwordx4 v[112:115], v207, s[70:71]
	global_load_dwordx4 v[116:119], v207, s[70:71] offset:1024
	global_load_dwordx4 v[120:123], v207, s[70:71] offset:2048
	global_load_dwordx4 v[124:127], v207, s[70:71] offset:3072
	s_waitcnt vmcnt(44)
	v_pk_mul_f32 v[242:243], v[128:129], v[128:129]
	v_pk_mul_f32 v[244:245], v[132:133], v[132:133]
	v_pk_mul_f32 v[246:247], v[130:131], v[130:131]
	v_pk_mul_f32 v[248:249], v[134:135], v[134:135]
	v_add_f32_e32 v204, v245, v244
	v_add_f32_e32 v205, v243, v242
	v_add_f32_e32 v204, v248, v204
	v_add_f32_e32 v205, v246, v205
	v_add_f32_e32 v204, v249, v204
	v_add_f32_e32 v205, v247, v205
	v_pk_mul_f32 v[242:243], v[136:137], v[136:137]
	v_pk_mul_f32 v[244:245], v[140:141], v[140:141]
	v_pk_mul_f32 v[246:247], v[138:139], v[138:139]
	v_pk_mul_f32 v[248:249], v[142:143], v[142:143]
	v_add_f32_e32 v206, v243, v242
	v_add_f32_e32 v207, v245, v244
	v_add_f32_e32 v206, v246, v206
	v_add_f32_e32 v207, v248, v207
	v_add_f32_e32 v206, v247, v206
	v_add_f32_e32 v207, v249, v207
	v_add_f32_e32 v204, v205, v204
	v_add_f32_e32 v204, v204, v206
	v_add_f32_e32 v204, v204, v207
	ds_swizzle_b32 v205, v204 offset:swizzle(SWAP,1)
	s_waitcnt lgkmcnt(0)
	v_add_f32_e32 v204, v204, v205
	ds_swizzle_b32 v205, v204 offset:swizzle(SWAP,2)
	s_waitcnt lgkmcnt(0)
	v_add_f32_e32 v204, v204, v205
	ds_swizzle_b32 v205, v204 offset:swizzle(SWAP,4)
	s_waitcnt lgkmcnt(0)
	v_add_f32_e32 v204, v204, v205
	ds_swizzle_b32 v205, v204 offset:swizzle(SWAP,8)
	s_waitcnt lgkmcnt(0)
	v_add_f32_e32 v204, v204, v205
	ds_swizzle_b32 v205, v204 offset:swizzle(SWAP,16)
	s_waitcnt lgkmcnt(0)
; __device__ __forceinline__ unsigned pk2(float lo, float hi) { const g_f32x2 f = {lo, hi}; return __builtin_bit_cast(unsigned, __builtin_convertvector(f, g_bf16x2)); }
; __device__ __forceinline__ void p_norm(const float* hlat, const float* hctx, const float* g, const float* modl, int sh_off, int sc_off, bf16_t* A, int M,
;                                        const float* part, const float* cgate, float* hcout) {
;     ...
;             if (part != nullptr && row >= NLAT) {
;                 const size_t po = (size_t)(row - NLAT) * 1024 + i * 256 + lane * 4;
;                 const float4 p0 = *(const float4*)(part + po), p1 = *(const float4*)(part + (size_t)4096 * 1024 + po), cg = *(const float4*)(cgate + i * 256 + lane * 4);
;                 v[i].x += cg.x * (p0.x + p1.x); v[i].y += cg.y * (p0.y + p1.y); v[i].z += cg.z * (p0.z + p1.z); v[i].w += cg.w * (p0.w + p1.w);
;                 *(float4*)(hcout + po) = v[i];
;             }
;             ss += v[i].x * v[i].x + v[i].y * v[i].y + v[i].z * v[i].z + v[i].w * v[i].w; }
;         ss = wave_sum(ss);
;         const float rstd = rsqrtf(ss * (1.0f / 1024.0f) + EPS);
;         const float* mr = modl + (size_t)r * 6144;
; #pragma unroll
;         for (int i = 0; i < 4; ++i) {
;             const int k = i * 256 + lane * 4;
;             const float4 gg = *(const float4*)(g + k), scv = *(const float4*)(mr + sc_off + k), shv = *(const float4*)(mr + sh_off + k);
;             const float o0 = v[i].x * rstd * gg.x * (1.0f + scv.x) + shv.x, o1 = v[i].y * rstd * gg.y * (1.0f + scv.y) + shv.y;
;             const float o2 = v[i].z * rstd * gg.z * (1.0f + scv.z) + shv.z, o3 = v[i].w * rstd * gg.w * (1.0f + scv.w) + shv.w;
;             uint2 w; w.x = pk2(o0, o1); w.y = pk2(o2, o3);
;             *(uint2*)(A + (size_t)row * 1024 + k) = w;
;         }
	v_add_f32_e32 v204, v204, v205
	v_mov_b32_e32 v205, v204
	s_nop 1
	v_permlane32_swap_b32_e32 v204, v205
	v_add_f32_e32 v204, v204, v205
	v_mov_b32_e32 v205, 0x358637bd
	v_fmamk_f32 v204, v204, 0x3a800000, v205
	v_rsq_f32_e32 v204, v204
	s_nop 0
	v_pk_mul_f32 v[128:129], v[128:129], v[204:205] op_sel_hi:[1,0]
	v_pk_mul_f32 v[130:131], v[130:131], v[204:205] op_sel_hi:[1,0]
	v_pk_mul_f32 v[128:129], v[188:189], v[128:129]
	v_pk_mul_f32 v[130:131], v[190:191], v[130:131]
	v_pk_fma_f32 v[128:129], v[34:35], v[128:129], v[224:225]
	v_pk_fma_f32 v[130:131], v[36:37], v[130:131], v[226:227]
	v_cvt_pk_bf16_f32 v128, v128, v129
	v_cvt_pk_bf16_f32 v129, v130, v131
	global_store_dwordx2 v146, v[128:129], s[66:67]
	v_pk_mul_f32 v[132:133], v[132:133], v[204:205] op_sel_hi:[1,0]
	v_pk_mul_f32 v[134:135], v[134:135], v[204:205] op_sel_hi:[1,0]
	v_pk_mul_f32 v[132:133], v[192:193], v[132:133]
	v_pk_mul_f32 v[134:135], v[194:195], v[134:135]
	v_pk_fma_f32 v[132:133], v[38:39], v[132:133], v[228:229]
	v_pk_fma_f32 v[134:135], v[40:41], v[134:135], v[230:231]
	v_cvt_pk_bf16_f32 v132, v132, v133
	v_cvt_pk_bf16_f32 v133, v134, v135
	global_store_dwordx2 v146, v[132:133], s[66:67] offset:512
	v_pk_mul_f32 v[136:137], v[136:137], v[204:205] op_sel_hi:[1,0]
	v_pk_mul_f32 v[138:139], v[138:139], v[204:205] op_sel_hi:[1,0]
	v_pk_mul_f32 v[136:137], v[196:197], v[136:137]
	v_pk_mul_f32 v[138:139], v[198:199], v[138:139]
	v_pk_fma_f32 v[136:137], v[42:43], v[136:137], v[232:233]
	v_pk_fma_f32 v[138:139], v[44:45], v[138:139], v[234:235]
	v_cvt_pk_bf16_f32 v136, v136, v137
	v_cvt_pk_bf16_f32 v137, v138, v139
	global_store_dwordx2 v146, v[136:137], s[66:67] offset:1024
	v_pk_mul_f32 v[140:141], v[140:141], v[204:205] op_sel_hi:[1,0]
	v_pk_mul_f32 v[142:143], v[142:143], v[204:205] op_sel_hi:[1,0]
	v_pk_mul_f32 v[140:141], v[200:201], v[140:141]
	v_pk_mul_f32 v[142:143], v[202:203], v[142:143]
	v_pk_fma_f32 v[140:141], v[46:47], v[140:141], v[236:237]
	v_pk_fma_f32 v[142:143], v[48:49], v[142:143], v[238:239]
	v_cvt_pk_bf16_f32 v140, v140, v141
	v_cvt_pk_bf16_f32 v141, v142, v143
	global_store_dwordx2 v146, v[140:141], s[66:67] offset:1536
	v_add_u32_e32 v146, 0x800, v146
	v_add_u32_e32 v151, 0x60000, v241
	global_load_dwordx4 v[34:37], v151, s[98:99]
	global_load_dwordx4 v[38:41], v151, s[98:99] offset:1024
	global_load_dwordx4 v[42:45], v151, s[98:99] offset:2048
	global_load_dwordx4 v[46:49], v151, s[98:99] offset:3072
	global_load_dwordx4 v[224:227], v151, s[50:51]
	global_load_dwordx4 v[228:231], v151, s[50:51] offset:1024
	global_load_dwordx4 v[232:235], v151, s[50:51] offset:2048
	global_load_dwordx4 v[236:239], v151, s[50:51] offset:3072
	v_add_u32_e32 v207, 0x1000, v150
	global_load_dwordx4 v[128:131], v207, s[70:71]
	global_load_dwordx4 v[132:135], v207, s[70:71] offset:1024
	global_load_dwordx4 v[136:139], v207, s[70:71] offset:2048
	global_load_dwordx4 v[140:143], v207, s[70:71] offset:3072
	s_waitcnt vmcnt(24)
	v_pk_add_f32 v[80:81], v[80:81], v[96:97]
	v_pk_add_f32 v[82:83], v[82:83], v[98:99]
	v_pk_fma_f32 v[156:157], v[80:81], v[8:9], v[156:157]
	v_pk_fma_f32 v[158:159], v[82:83], v[10:11], v[158:159]
	global_store_dwordx4 v152, v[156:159], s[64:65]
	v_pk_add_f32 v[84:85], v[84:85], v[100:101]
	v_pk_add_f32 v[86:87], v[86:87], v[102:103]
	v_pk_fma_f32 v[160:161], v[84:85], v[52:53], v[160:161]
	v_pk_fma_f32 v[162:163], v[86:87], v[54:55], v[162:163]
	global_store_dwordx4 v152, v[160:163], s[64:65] offset:1024
	v_pk_add_f32 v[88:89], v[88:89], v[104:105]
	v_pk_add_f32 v[90:91], v[90:91], v[106:107]
	v_pk_fma_f32 v[164:165], v[88:89], v[60:61], v[164:165]
	v_pk_fma_f32 v[166:167], v[90:91], v[62:63], v[166:167]
	global_store_dwordx4 v152, v[164:167], s[64:65] offset:2048
	v_pk_add_f32 v[92:93], v[92:93], v[108:109]
	v_pk_add_f32 v[94:95], v[94:95], v[110:111]
	v_pk_fma_f32 v[168:169], v[92:93], v[64:65], v[168:169]
	v_pk_fma_f32 v[170:171], v[94:95], v[66:67], v[170:171]
	global_store_dwordx4 v152, v[168:171], s[64:65] offset:3072
	v_add_u32_e32 v152, 0x1000, v152
	v_pk_mul_f32 v[242:243], v[156:157], v[156:157]
	v_pk_mul_f32 v[244:245], v[160:161], v[160:161]
	v_pk_mul_f32 v[246:247], v[158:159], v[158:159]
	v_pk_mul_f32 v[248:249], v[162:163], v[162:163]
	v_add_f32_e32 v204, v245, v244
	v_add_f32_e32 v205, v243, v242
	v_add_f32_e32 v204, v248, v204
	v_add_f32_e32 v205, v246, v205
	v_add_f32_e32 v204, v249, v204
	v_add_f32_e32 v205, v247, v205
	v_pk_mul_f32 v[242:243], v[164:165], v[164:165]
	v_pk_mul_f32 v[244:245], v[168:169], v[168:169]
	v_pk_mul_f32 v[246:247], v[166:167], v[166:167]
	v_pk_mul_f32 v[248:249], v[170:171], v[170:171]
	v_add_f32_e32 v206, v243, v242
	v_add_f32_e32 v207, v245, v244
	v_add_f32_e32 v206, v246, v206
	v_add_f32_e32 v207, v248, v207
	v_add_f32_e32 v206, v247, v206
	v_add_f32_e32 v207, v249, v207
	v_add_f32_e32 v204, v205, v204
	v_add_f32_e32 v204, v204, v206
	v_add_f32_e32 v204, v204, v207
	ds_swizzle_b32 v205, v204 offset:swizzle(SWAP,1)
	s_waitcnt lgkmcnt(0)
	v_add_f32_e32 v204, v204, v205
	ds_swizzle_b32 v205, v204 offset:swizzle(SWAP,2)
	s_waitcnt lgkmcnt(0)
	v_add_f32_e32 v204, v204, v205
	ds_swizzle_b32 v205, v204 offset:swizzle(SWAP,4)
	s_waitcnt lgkmcnt(0)
	v_add_f32_e32 v204, v204, v205
	ds_swizzle_b32 v205, v204 offset:swizzle(SWAP,8)
	s_waitcnt lgkmcnt(0)
	v_add_f32_e32 v204, v204, v205
	ds_swizzle_b32 v205, v204 offset:swizzle(SWAP,16)
	s_waitcnt lgkmcnt(0)
	v_add_f32_e32 v204, v204, v205
	v_mov_b32_e32 v205, v204
	s_nop 1
	v_permlane32_swap_b32_e32 v204, v205
	v_add_f32_e32 v204, v204, v205
	v_mov_b32_e32 v205, 0x358637bd
	v_fmamk_f32 v204, v204, 0x3a800000, v205
	v_rsq_f32_e32 v204, v204
	s_nop 0
	s_waitcnt vmcnt(8)
; __device__ __forceinline__ unsigned pk2(float lo, float hi) { const g_f32x2 f = {lo, hi}; return __builtin_bit_cast(unsigned, __builtin_convertvector(f, g_bf16x2)); }
; __device__ __forceinline__ void p_norm(const float* hlat, const float* hctx, const float* g, const float* modl, int sh_off, int sc_off, bf16_t* A, int M,
;                                        const float* part, const float* cgate, float* hcout) {
;     ...
;             if (part != nullptr && row >= NLAT) {
;                 const size_t po = (size_t)(row - NLAT) * 1024 + i * 256 + lane * 4;
;                 const float4 p0 = *(const float4*)(part + po), p1 = *(const float4*)(part + (size_t)4096 * 1024 + po), cg = *(const float4*)(cgate + i * 256 + lane * 4);
;                 v[i].x += cg.x * (p0.x + p1.x); v[i].y += cg.y * (p0.y + p1.y); v[i].z += cg.z * (p0.z + p1.z); v[i].w += cg.w * (p0.w + p1.w);
;                 *(float4*)(hcout + po) = v[i];
;             }
;             ss += v[i].x * v[i].x + v[i].y * v[i].y + v[i].z * v[i].z + v[i].w * v[i].w; }
;         ss = wave_sum(ss);
;         const float rstd = rsqrtf(ss * (1.0f / 1024.0f) + EPS);
;         const float* mr = modl + (size_t)r * 6144;
; #pragma unroll
;         for (int i = 0; i < 4; ++i) {
;             const int k = i * 256 + lane * 4;
;             const float4 gg = *(const float4*)(g + k), scv = *(const float4*)(mr + sc_off + k), shv = *(const float4*)(mr + sh_off + k);
;             const float o0 = v[i].x * rstd * gg.x * (1.0f + scv.x) + shv.x, o1 = v[i].y * rstd * gg.y * (1.0f + scv.y) + shv.y;
;             const float o2 = v[i].z * rstd * gg.z * (1.0f + scv.z) + shv.z, o3 = v[i].w * rstd * gg.w * (1.0f + scv.w) + shv.w;
;             uint2 w; w.x = pk2(o0, o1); w.y = pk2(o2, o3);
;             *(uint2*)(A + (size_t)row * 1024 + k) = w;
;         }
	v_pk_add_f32 v[34:35], v[34:35], 1.0 op_sel_hi:[1,0]
	v_pk_add_f32 v[36:37], v[36:37], 1.0 op_sel_hi:[1,0]
	v_pk_add_f32 v[38:39], v[38:39], 1.0 op_sel_hi:[1,0]
	v_pk_add_f32 v[40:41], v[40:41], 1.0 op_sel_hi:[1,0]
	v_pk_add_f32 v[42:43], v[42:43], 1.0 op_sel_hi:[1,0]
	v_pk_add_f32 v[44:45], v[44:45], 1.0 op_sel_hi:[1,0]
	v_pk_add_f32 v[46:47], v[46:47], 1.0 op_sel_hi:[1,0]
	v_pk_add_f32 v[48:49], v[48:49], 1.0 op_sel_hi:[1,0]
	v_lshlrev_b32_e32 v146, 12, v50
	v_lshl_add_u32 v146, v240, 3, v146
	v_add_u32_e32 v146, 0x4000000, v146
	v_pk_mul_f32 v[156:157], v[156:157], v[204:205] op_sel_hi:[1,0]
	v_pk_mul_f32 v[158:159], v[158:159], v[204:205] op_sel_hi:[1,0]
	v_pk_mul_f32 v[156:157], v[188:189], v[156:157]
	v_pk_mul_f32 v[158:159], v[190:191], v[158:159]
	v_pk_fma_f32 v[156:157], v[34:35], v[156:157], v[224:225]
	v_pk_fma_f32 v[158:159], v[36:37], v[158:159], v[226:227]
	v_cvt_pk_bf16_f32 v156, v156, v157
	v_cvt_pk_bf16_f32 v157, v158, v159
	global_store_dwordx2 v146, v[156:157], s[66:67]
	v_pk_mul_f32 v[160:161], v[160:161], v[204:205] op_sel_hi:[1,0]
	v_pk_mul_f32 v[162:163], v[162:163], v[204:205] op_sel_hi:[1,0]
	v_pk_mul_f32 v[160:161], v[192:193], v[160:161]
	v_pk_mul_f32 v[162:163], v[194:195], v[162:163]
	v_pk_fma_f32 v[160:161], v[38:39], v[160:161], v[228:229]
	v_pk_fma_f32 v[162:163], v[40:41], v[162:163], v[230:231]
	v_cvt_pk_bf16_f32 v160, v160, v161
	v_cvt_pk_bf16_f32 v161, v162, v163
	global_store_dwordx2 v146, v[160:161], s[66:67] offset:512
	v_pk_mul_f32 v[164:165], v[164:165], v[204:205] op_sel_hi:[1,0]
	v_pk_mul_f32 v[166:167], v[166:167], v[204:205] op_sel_hi:[1,0]
	v_pk_mul_f32 v[164:165], v[196:197], v[164:165]
	v_pk_mul_f32 v[166:167], v[198:199], v[166:167]
	v_pk_fma_f32 v[164:165], v[42:43], v[164:165], v[232:233]
	v_pk_fma_f32 v[166:167], v[44:45], v[166:167], v[234:235]
	v_cvt_pk_bf16_f32 v164, v164, v165
	v_cvt_pk_bf16_f32 v165, v166, v167
	global_store_dwordx2 v146, v[164:165], s[66:67] offset:1024
	v_pk_mul_f32 v[168:169], v[168:169], v[204:205] op_sel_hi:[1,0]
	v_pk_mul_f32 v[170:171], v[170:171], v[204:205] op_sel_hi:[1,0]
	v_pk_mul_f32 v[168:169], v[200:201], v[168:169]
	v_pk_mul_f32 v[170:171], v[202:203], v[170:171]
	v_pk_fma_f32 v[168:169], v[46:47], v[168:169], v[236:237]
	v_pk_fma_f32 v[170:171], v[48:49], v[170:171], v[238:239]
	v_cvt_pk_bf16_f32 v168, v168, v169
	v_cvt_pk_bf16_f32 v169, v170, v171
	global_store_dwordx2 v146, v[168:169], s[66:67] offset:1536
	v_add_u32_e32 v146, 0x800, v146
	s_waitcnt vmcnt(8)
	v_pk_add_f32 v[112:113], v[112:113], v[128:129]
	v_pk_add_f32 v[114:115], v[114:115], v[130:131]
	v_pk_fma_f32 v[172:173], v[112:113], v[8:9], v[172:173]
	v_pk_fma_f32 v[174:175], v[114:115], v[10:11], v[174:175]
	global_store_dwordx4 v152, v[172:175], s[64:65]
	v_pk_add_f32 v[116:117], v[116:117], v[132:133]
	v_pk_add_f32 v[118:119], v[118:119], v[134:135]
	v_pk_fma_f32 v[176:177], v[116:117], v[52:53], v[176:177]
	v_pk_fma_f32 v[178:179], v[118:119], v[54:55], v[178:179]
	global_store_dwordx4 v152, v[176:179], s[64:65] offset:1024
	v_pk_add_f32 v[120:121], v[120:121], v[136:137]
	v_pk_add_f32 v[122:123], v[122:123], v[138:139]
	v_pk_fma_f32 v[180:181], v[120:121], v[60:61], v[180:181]
	v_pk_fma_f32 v[182:183], v[122:123], v[62:63], v[182:183]
	global_store_dwordx4 v152, v[180:183], s[64:65] offset:2048
	v_pk_add_f32 v[124:125], v[124:125], v[140:141]
	v_pk_add_f32 v[126:127], v[126:127], v[142:143]
	v_pk_fma_f32 v[184:185], v[124:125], v[64:65], v[184:185]
	v_pk_fma_f32 v[186:187], v[126:127], v[66:67], v[186:187]
	global_store_dwordx4 v152, v[184:187], s[64:65] offset:3072
	v_add_u32_e32 v152, 0x1000, v152
	v_pk_mul_f32 v[242:243], v[172:173], v[172:173]
	v_pk_mul_f32 v[244:245], v[176:177], v[176:177]
	v_pk_mul_f32 v[246:247], v[174:175], v[174:175]
	v_pk_mul_f32 v[248:249], v[178:179], v[178:179]
	v_add_f32_e32 v204, v245, v244
	v_add_f32_e32 v205, v243, v242
	v_add_f32_e32 v204, v248, v204
	v_add_f32_e32 v205, v246, v205
	v_add_f32_e32 v204, v249, v204
	v_add_f32_e32 v205, v247, v205
	v_pk_mul_f32 v[242:243], v[180:181], v[180:181]
	v_pk_mul_f32 v[244:245], v[184:185], v[184:185]
	v_pk_mul_f32 v[246:247], v[182:183], v[182:183]
	v_pk_mul_f32 v[248:249], v[186:187], v[186:187]
	v_add_f32_e32 v206, v243, v242
	v_add_f32_e32 v207, v245, v244
	v_add_f32_e32 v206, v246, v206
	v_add_f32_e32 v207, v248, v207
	v_add_f32_e32 v206, v247, v206
	v_add_f32_e32 v207, v249, v207
	v_add_f32_e32 v204, v205, v204
	v_add_f32_e32 v204, v204, v206
	v_add_f32_e32 v204, v204, v207
	ds_swizzle_b32 v205, v204 offset:swizzle(SWAP,1)
	s_waitcnt lgkmcnt(0)
	v_add_f32_e32 v204, v204, v205
	ds_swizzle_b32 v205, v204 offset:swizzle(SWAP,2)
	s_waitcnt lgkmcnt(0)
	v_add_f32_e32 v204, v204, v205
	ds_swizzle_b32 v205, v204 offset:swizzle(SWAP,4)
	s_waitcnt lgkmcnt(0)
	v_add_f32_e32 v204, v204, v205
	ds_swizzle_b32 v205, v204 offset:swizzle(SWAP,8)
	s_waitcnt lgkmcnt(0)
	v_add_f32_e32 v204, v204, v205
	ds_swizzle_b32 v205, v204 offset:swizzle(SWAP,16)
	s_waitcnt lgkmcnt(0)
; __device__ __forceinline__ unsigned pk2(float lo, float hi) { const g_f32x2 f = {lo, hi}; return __builtin_bit_cast(unsigned, __builtin_convertvector(f, g_bf16x2)); }
; #define PN_LOAD(dst, rw) do { const float* s_ = (rw) < NLAT ? hlat + (size_t)(rw) * 1024 : hctx + (size_t)((rw) - NLAT) * 1024; \
;         _Pragma("unroll") for (int i = 0; i < 4; ++i) dst[i] = *(const float4*)(s_ + i * 256 + lane * 4); } while (0)
; __device__ __forceinline__ void p_norm(const float* hlat, const float* hctx, const float* g, const float* modl, int sh_off, int sc_off, bf16_t* A, int M,
;                                        const float* part, const float* cgate, float* hcout) {
;     ...
;     if (row < M) PN_LOAD(v, row);
;     while (row < M) {
;         const int nrow = row + stride;
;         if (nrow < M) PN_LOAD(nv, nrow);
;         const int r = row < NLAT ? (row >> 11) : 16;
;         float ss = 0.f;
; #pragma unroll
;         for (int i = 0; i < 4; ++i) {
;             if (part != nullptr && row >= NLAT) {
;                 const size_t po = (size_t)(row - NLAT) * 1024 + i * 256 + lane * 4;
;                 const float4 p0 = *(const float4*)(part + po), p1 = *(const float4*)(part + (size_t)4096 * 1024 + po), cg = *(const float4*)(cgate + i * 256 + lane * 4);
;                 v[i].x += cg.x * (p0.x + p1.x); v[i].y += cg.y * (p0.y + p1.y); v[i].z += cg.z * (p0.z + p1.z); v[i].w += cg.w * (p0.w + p1.w);
;                 *(float4*)(hcout + po) = v[i];
;             }
;             ss += v[i].x * v[i].x + v[i].y * v[i].y + v[i].z * v[i].z + v[i].w * v[i].w; }
;         ss = wave_sum(ss);
;         const float rstd = rsqrtf(ss * (1.0f / 1024.0f) + EPS);
;         const float* mr = modl + (size_t)r * 6144;
; #pragma unroll
;         for (int i = 0; i < 4; ++i) {
;             const int k = i * 256 + lane * 4;
;             const float4 gg = *(const float4*)(g + k), scv = *(const float4*)(mr + sc_off + k), shv = *(const float4*)(mr + sh_off + k);
;             const float o0 = v[i].x * rstd * gg.x * (1.0f + scv.x) + shv.x, o1 = v[i].y * rstd * gg.y * (1.0f + scv.y) + shv.y;
;             const float o2 = v[i].z * rstd * gg.z * (1.0f + scv.z) + shv.z, o3 = v[i].w * rstd * gg.w * (1.0f + scv.w) + shv.w;
;             uint2 w; w.x = pk2(o0, o1); w.y = pk2(o2, o3);
;             *(uint2*)(A + (size_t)row * 1024 + k) = w;
;         }
	v_add_f32_e32 v204, v204, v205
	v_mov_b32_e32 v205, v204
	s_nop 1
	v_permlane32_swap_b32_e32 v204, v205
	v_add_f32_e32 v204, v204, v205
	v_mov_b32_e32 v205, 0x358637bd
	v_fmamk_f32 v204, v204, 0x3a800000, v205
	v_rsq_f32_e32 v204, v204
	s_nop 0
	v_pk_mul_f32 v[172:173], v[172:173], v[204:205] op_sel_hi:[1,0]
	v_pk_mul_f32 v[174:175], v[174:175], v[204:205] op_sel_hi:[1,0]
	v_pk_mul_f32 v[172:173], v[188:189], v[172:173]
	v_pk_mul_f32 v[174:175], v[190:191], v[174:175]
	v_pk_fma_f32 v[172:173], v[34:35], v[172:173], v[224:225]
	v_pk_fma_f32 v[174:175], v[36:37], v[174:175], v[226:227]
	v_cvt_pk_bf16_f32 v172, v172, v173
	v_cvt_pk_bf16_f32 v173, v174, v175
	global_store_dwordx2 v146, v[172:173], s[66:67]
	v_pk_mul_f32 v[176:177], v[176:177], v[204:205] op_sel_hi:[1,0]
	v_pk_mul_f32 v[178:179], v[178:179], v[204:205] op_sel_hi:[1,0]
	v_pk_mul_f32 v[176:177], v[192:193], v[176:177]
	v_pk_mul_f32 v[178:179], v[194:195], v[178:179]
	v_pk_fma_f32 v[176:177], v[38:39], v[176:177], v[228:229]
	v_pk_fma_f32 v[178:179], v[40:41], v[178:179], v[230:231]
	v_cvt_pk_bf16_f32 v176, v176, v177
	v_cvt_pk_bf16_f32 v177, v178, v179
	global_store_dwordx2 v146, v[176:177], s[66:67] offset:512
	v_pk_mul_f32 v[180:181], v[180:181], v[204:205] op_sel_hi:[1,0]
	v_pk_mul_f32 v[182:183], v[182:183], v[204:205] op_sel_hi:[1,0]
	v_pk_mul_f32 v[180:181], v[196:197], v[180:181]
	v_pk_mul_f32 v[182:183], v[198:199], v[182:183]
	v_pk_fma_f32 v[180:181], v[42:43], v[180:181], v[232:233]
	v_pk_fma_f32 v[182:183], v[44:45], v[182:183], v[234:235]
	v_cvt_pk_bf16_f32 v180, v180, v181
	v_cvt_pk_bf16_f32 v181, v182, v183
	global_store_dwordx2 v146, v[180:181], s[66:67] offset:1024
	v_pk_mul_f32 v[184:185], v[184:185], v[204:205] op_sel_hi:[1,0]
	v_pk_mul_f32 v[186:187], v[186:187], v[204:205] op_sel_hi:[1,0]
	v_pk_mul_f32 v[184:185], v[200:201], v[184:185]
	v_pk_mul_f32 v[186:187], v[202:203], v[186:187]
	v_pk_fma_f32 v[184:185], v[46:47], v[184:185], v[236:237]
	v_pk_fma_f32 v[186:187], v[48:49], v[186:187], v[238:239]
	v_cvt_pk_bf16_f32 v184, v184, v185
	v_cvt_pk_bf16_f32 v185, v186, v187
	global_store_dwordx2 v146, v[184:185], s[66:67] offset:1536
	v_add_u32_e32 v146, 0x800, v146
	s_branch .Lnorm_P6_end
.Lnorm_P6_alt:
	global_load_dwordx4 v[80:83], v144, s[46:47] nt
	global_load_dwordx4 v[84:87], v144, s[46:47] offset:1024 nt
	global_load_dwordx4 v[88:91], v144, s[46:47] offset:2048 nt
	global_load_dwordx4 v[92:95], v144, s[46:47] offset:3072 nt
	v_add_u32_e32 v144, 0x1000, v144
	global_load_dwordx4 v[34:37], v148, s[98:99]
	global_load_dwordx4 v[38:41], v148, s[98:99] offset:1024
	global_load_dwordx4 v[42:45], v148, s[98:99] offset:2048
	global_load_dwordx4 v[46:49], v148, s[98:99] offset:3072
	global_load_dwordx4 v[224:227], v148, s[50:51]
	global_load_dwordx4 v[228:231], v148, s[50:51] offset:1024
	global_load_dwordx4 v[232:235], v148, s[50:51] offset:2048
	global_load_dwordx4 v[236:239], v148, s[50:51] offset:3072
	global_load_dwordx4 v[188:191], v241, s[48:49]
	global_load_dwordx4 v[192:195], v241, s[48:49] offset:1024
	global_load_dwordx4 v[196:199], v241, s[48:49] offset:2048
	global_load_dwordx4 v[200:203], v241, s[48:49] offset:3072
	global_load_dwordx4 v[96:99], v144, s[46:47] nt
	global_load_dwordx4 v[100:103], v144, s[46:47] offset:1024 nt
	global_load_dwordx4 v[104:107], v144, s[46:47] offset:2048 nt
	global_load_dwordx4 v[108:111], v144, s[46:47] offset:3072 nt
	v_add_u32_e32 v144, 0x1000, v144
	global_load_dwordx4 v[112:115], v144, s[46:47] nt
	global_load_dwordx4 v[116:119], v144, s[46:47] offset:1024 nt
	global_load_dwordx4 v[120:123], v144, s[46:47] offset:2048 nt
	global_load_dwordx4 v[124:127], v144, s[46:47] offset:3072 nt
	v_add_u32_e32 v144, 0x1000, v144
	global_load_dwordx4 v[128:131], v144, s[46:47] nt
	global_load_dwordx4 v[132:135], v144, s[46:47] offset:1024 nt
	global_load_dwordx4 v[136:139], v144, s[46:47] offset:2048 nt
	global_load_dwordx4 v[140:143], v144, s[46:47] offset:3072 nt
	v_add_u32_e32 v144, 0x1000, v144
	global_load_dwordx4 v[156:159], v144, s[46:47] nt
	global_load_dwordx4 v[160:163], v144, s[46:47] offset:1024 nt
	global_load_dwordx4 v[164:167], v144, s[46:47] offset:2048 nt
	global_load_dwordx4 v[168:171], v144, s[46:47] offset:3072 nt
	v_add_u32_e32 v144, 0x1000, v144
	global_load_dwordx4 v[172:175], v144, s[46:47] nt
	global_load_dwordx4 v[176:179], v144, s[46:47] offset:1024 nt
	global_load_dwordx4 v[180:183], v144, s[46:47] offset:2048 nt
	global_load_dwordx4 v[184:187], v144, s[46:47] offset:3072 nt
	v_add_u32_e32 v144, 0x1000, v144
	s_waitcnt vmcnt(32)
	v_pk_mul_f32 v[242:243], v[80:81], v[80:81]
	v_pk_mul_f32 v[244:245], v[84:85], v[84:85]
	v_pk_mul_f32 v[246:247], v[82:83], v[82:83]
	v_pk_mul_f32 v[248:249], v[86:87], v[86:87]
	v_add_f32_e32 v204, v245, v244
	v_add_f32_e32 v205, v243, v242
	v_add_f32_e32 v204, v248, v204
	v_add_f32_e32 v205, v246, v205
	v_add_f32_e32 v204, v249, v204
	v_add_f32_e32 v205, v247, v205
	v_pk_mul_f32 v[242:243], v[88:89], v[88:89]
	v_pk_mul_f32 v[244:245], v[92:93], v[92:93]
	v_pk_mul_f32 v[246:247], v[90:91], v[90:91]
	v_pk_mul_f32 v[248:249], v[94:95], v[94:95]
	v_add_f32_e32 v206, v243, v242
	v_add_f32_e32 v207, v245, v244
	v_add_f32_e32 v206, v246, v206
	v_add_f32_e32 v207, v248, v207
	v_add_f32_e32 v206, v247, v206
	v_add_f32_e32 v207, v249, v207
	v_add_f32_e32 v204, v205, v204
	v_add_f32_e32 v204, v204, v206
	v_add_f32_e32 v204, v204, v207
	ds_swizzle_b32 v205, v204 offset:swizzle(SWAP,1)
	s_waitcnt lgkmcnt(0)
	v_add_f32_e32 v204, v204, v205
	ds_swizzle_b32 v205, v204 offset:swizzle(SWAP,2)
	s_waitcnt lgkmcnt(0)
	v_add_f32_e32 v204, v204, v205
	ds_swizzle_b32 v205, v204 offset:swizzle(SWAP,4)
	s_waitcnt lgkmcnt(0)
; __device__ __forceinline__ unsigned pk2(float lo, float hi) { const g_f32x2 f = {lo, hi}; return __builtin_bit_cast(unsigned, __builtin_convertvector(f, g_bf16x2)); }
; #define PN_LOAD(dst, rw) do { const float* s_ = (rw) < NLAT ? hlat + (size_t)(rw) * 1024 : hctx + (size_t)((rw) - NLAT) * 1024; \
;         _Pragma("unroll") for (int i = 0; i < 4; ++i) dst[i] = *(const float4*)(s_ + i * 256 + lane * 4); } while (0)
; __device__ __forceinline__ void p_norm(const float* hlat, const float* hctx, const float* g, const float* modl, int sh_off, int sc_off, bf16_t* A, int M,
;                                        const float* part, const float* cgate, float* hcout) {
;     ...
;     if (row < M) PN_LOAD(v, row);
;     while (row < M) {
;         const int nrow = row + stride;
;         if (nrow < M) PN_LOAD(nv, nrow);
;         const int r = row < NLAT ? (row >> 11) : 16;
;         float ss = 0.f;
; #pragma unroll
;         for (int i = 0; i < 4; ++i) {
;             if (part != nullptr && row >= NLAT) {
;                 const size_t po = (size_t)(row - NLAT) * 1024 + i * 256 + lane * 4;
;                 const float4 p0 = *(const float4*)(part + po), p1 = *(const float4*)(part + (size_t)4096 * 1024 + po), cg = *(const float4*)(cgate + i * 256 + lane * 4);
;                 v[i].x += cg.x * (p0.x + p1.x); v[i].y += cg.y * (p0.y + p1.y); v[i].z += cg.z * (p0.z + p1.z); v[i].w += cg.w * (p0.w + p1.w);
;                 *(float4*)(hcout + po) = v[i];
;             }
;             ss += v[i].x * v[i].x + v[i].y * v[i].y + v[i].z * v[i].z + v[i].w * v[i].w; }
;         ss = wave_sum(ss);
;         const float rstd = rsqrtf(ss * (1.0f / 1024.0f) + EPS);
;         const float* mr = modl + (size_t)r * 6144;
; #pragma unroll
;         for (int i = 0; i < 4; ++i) {
;             const int k = i * 256 + lane * 4;
;             const float4 gg = *(const float4*)(g + k), scv = *(const float4*)(mr + sc_off + k), shv = *(const float4*)(mr + sh_off + k);
;             const float o0 = v[i].x * rstd * gg.x * (1.0f + scv.x) + shv.x, o1 = v[i].y * rstd * gg.y * (1.0f + scv.y) + shv.y;
;             const float o2 = v[i].z * rstd * gg.z * (1.0f + scv.z) + shv.z, o3 = v[i].w * rstd * gg.w * (1.0f + scv.w) + shv.w;
;             uint2 w; w.x = pk2(o0, o1); w.y = pk2(o2, o3);
;             *(uint2*)(A + (size_t)row * 1024 + k) = w;
;         }
	v_add_f32_e32 v204, v204, v205
	ds_swizzle_b32 v205, v204 offset:swizzle(SWAP,8)
	s_waitcnt lgkmcnt(0)
	v_add_f32_e32 v204, v204, v205
	ds_swizzle_b32 v205, v204 offset:swizzle(SWAP,16)
	s_waitcnt lgkmcnt(0)
	v_add_f32_e32 v204, v204, v205
	v_mov_b32_e32 v205, v204
	s_nop 1
	v_permlane32_swap_b32_e32 v204, v205
	v_add_f32_e32 v204, v204, v205
	v_mov_b32_e32 v205, 0x358637bd
	v_fmamk_f32 v204, v204, 0x3a800000, v205
	v_rsq_f32_e32 v204, v204
	s_nop 0
	s_waitcnt vmcnt(20)
	v_pk_add_f32 v[34:35], v[34:35], 1.0 op_sel_hi:[1,0]
	v_pk_add_f32 v[36:37], v[36:37], 1.0 op_sel_hi:[1,0]
	v_pk_add_f32 v[38:39], v[38:39], 1.0 op_sel_hi:[1,0]
	v_pk_add_f32 v[40:41], v[40:41], 1.0 op_sel_hi:[1,0]
	v_pk_add_f32 v[42:43], v[42:43], 1.0 op_sel_hi:[1,0]
	v_pk_add_f32 v[44:45], v[44:45], 1.0 op_sel_hi:[1,0]
	v_pk_add_f32 v[46:47], v[46:47], 1.0 op_sel_hi:[1,0]
	v_pk_add_f32 v[48:49], v[48:49], 1.0 op_sel_hi:[1,0]
	v_pk_mul_f32 v[80:81], v[80:81], v[204:205] op_sel_hi:[1,0]
	v_pk_mul_f32 v[82:83], v[82:83], v[204:205] op_sel_hi:[1,0]
	v_pk_mul_f32 v[80:81], v[188:189], v[80:81]
	v_pk_mul_f32 v[82:83], v[190:191], v[82:83]
	v_pk_fma_f32 v[80:81], v[34:35], v[80:81], v[224:225]
	v_pk_fma_f32 v[82:83], v[36:37], v[82:83], v[226:227]
	v_cvt_pk_bf16_f32 v80, v80, v81
	v_cvt_pk_bf16_f32 v81, v82, v83
	global_store_dwordx2 v146, v[80:81], s[66:67]
	v_pk_mul_f32 v[84:85], v[84:85], v[204:205] op_sel_hi:[1,0]
	v_pk_mul_f32 v[86:87], v[86:87], v[204:205] op_sel_hi:[1,0]
	v_pk_mul_f32 v[84:85], v[192:193], v[84:85]
	v_pk_mul_f32 v[86:87], v[194:195], v[86:87]
	v_pk_fma_f32 v[84:85], v[38:39], v[84:85], v[228:229]
	v_pk_fma_f32 v[86:87], v[40:41], v[86:87], v[230:231]
	v_cvt_pk_bf16_f32 v84, v84, v85
	v_cvt_pk_bf16_f32 v85, v86, v87
	global_store_dwordx2 v146, v[84:85], s[66:67] offset:512
	v_pk_mul_f32 v[88:89], v[88:89], v[204:205] op_sel_hi:[1,0]
	v_pk_mul_f32 v[90:91], v[90:91], v[204:205] op_sel_hi:[1,0]
	v_pk_mul_f32 v[88:89], v[196:197], v[88:89]
	v_pk_mul_f32 v[90:91], v[198:199], v[90:91]
	v_pk_fma_f32 v[88:89], v[42:43], v[88:89], v[232:233]
	v_pk_fma_f32 v[90:91], v[44:45], v[90:91], v[234:235]
	v_cvt_pk_bf16_f32 v88, v88, v89
	v_cvt_pk_bf16_f32 v89, v90, v91
	global_store_dwordx2 v146, v[88:89], s[66:67] offset:1024
	v_pk_mul_f32 v[92:93], v[92:93], v[204:205] op_sel_hi:[1,0]
	v_pk_mul_f32 v[94:95], v[94:95], v[204:205] op_sel_hi:[1,0]
	v_pk_mul_f32 v[92:93], v[200:201], v[92:93]
	v_pk_mul_f32 v[94:95], v[202:203], v[94:95]
	v_pk_fma_f32 v[92:93], v[46:47], v[92:93], v[236:237]
	v_pk_fma_f32 v[94:95], v[48:49], v[94:95], v[238:239]
	v_cvt_pk_bf16_f32 v92, v92, v93
	v_cvt_pk_bf16_f32 v93, v94, v95
	global_store_dwordx2 v146, v[92:93], s[66:67] offset:1536
	v_add_u32_e32 v146, 0x800, v146
	global_load_dwordx4 v[80:83], v144, s[46:47] nt
	global_load_dwordx4 v[84:87], v144, s[46:47] offset:1024 nt
	global_load_dwordx4 v[88:91], v144, s[46:47] offset:2048 nt
	global_load_dwordx4 v[92:95], v144, s[46:47] offset:3072 nt
	v_add_u32_e32 v144, 0x1000, v144
	s_waitcnt vmcnt(24)
	v_pk_mul_f32 v[242:243], v[96:97], v[96:97]
	v_pk_mul_f32 v[244:245], v[100:101], v[100:101]
	v_pk_mul_f32 v[246:247], v[98:99], v[98:99]
	v_pk_mul_f32 v[248:249], v[102:103], v[102:103]
	v_add_f32_e32 v204, v245, v244
	v_add_f32_e32 v205, v243, v242
	v_add_f32_e32 v204, v248, v204
	v_add_f32_e32 v205, v246, v205
	v_add_f32_e32 v204, v249, v204
	v_add_f32_e32 v205, v247, v205
	v_pk_mul_f32 v[242:243], v[104:105], v[104:105]
	v_pk_mul_f32 v[244:245], v[108:109], v[108:109]
	v_pk_mul_f32 v[246:247], v[106:107], v[106:107]
	v_pk_mul_f32 v[248:249], v[110:111], v[110:111]
	v_add_f32_e32 v206, v243, v242
	v_add_f32_e32 v207, v245, v244
	v_add_f32_e32 v206, v246, v206
	v_add_f32_e32 v207, v248, v207
	v_add_f32_e32 v206, v247, v206
	v_add_f32_e32 v207, v249, v207
	v_add_f32_e32 v204, v205, v204
	v_add_f32_e32 v204, v204, v206
	v_add_f32_e32 v204, v204, v207
	ds_swizzle_b32 v205, v204 offset:swizzle(SWAP,1)
	s_waitcnt lgkmcnt(0)
	v_add_f32_e32 v204, v204, v205
	ds_swizzle_b32 v205, v204 offset:swizzle(SWAP,2)
	s_waitcnt lgkmcnt(0)
	v_add_f32_e32 v204, v204, v205
	ds_swizzle_b32 v205, v204 offset:swizzle(SWAP,4)
	s_waitcnt lgkmcnt(0)
	v_add_f32_e32 v204, v204, v205
	ds_swizzle_b32 v205, v204 offset:swizzle(SWAP,8)
	s_waitcnt lgkmcnt(0)
	v_add_f32_e32 v204, v204, v205
	ds_swizzle_b32 v205, v204 offset:swizzle(SWAP,16)
	s_waitcnt lgkmcnt(0)
	v_add_f32_e32 v204, v204, v205
	v_mov_b32_e32 v205, v204
	s_nop 1
	v_permlane32_swap_b32_e32 v204, v205
	v_add_f32_e32 v204, v204, v205
	v_mov_b32_e32 v205, 0x358637bd
	v_fmamk_f32 v204, v204, 0x3a800000, v205
	v_rsq_f32_e32 v204, v204
	s_nop 0
	v_pk_mul_f32 v[96:97], v[96:97], v[204:205] op_sel_hi:[1,0]
	v_pk_mul_f32 v[98:99], v[98:99], v[204:205] op_sel_hi:[1,0]
	v_pk_mul_f32 v[96:97], v[188:189], v[96:97]
	v_pk_mul_f32 v[98:99], v[190:191], v[98:99]
	v_pk_fma_f32 v[96:97], v[34:35], v[96:97], v[224:225]
	v_pk_fma_f32 v[98:99], v[36:37], v[98:99], v[226:227]
	v_cvt_pk_bf16_f32 v96, v96, v97
	v_cvt_pk_bf16_f32 v97, v98, v99
	global_store_dwordx2 v146, v[96:97], s[66:67]
	v_pk_mul_f32 v[100:101], v[100:101], v[204:205] op_sel_hi:[1,0]
	v_pk_mul_f32 v[102:103], v[102:103], v[204:205] op_sel_hi:[1,0]
	v_pk_mul_f32 v[100:101], v[192:193], v[100:101]
	v_pk_mul_f32 v[102:103], v[194:195], v[102:103]
	v_pk_fma_f32 v[100:101], v[38:39], v[100:101], v[228:229]
	v_pk_fma_f32 v[102:103], v[40:41], v[102:103], v[230:231]
	v_cvt_pk_bf16_f32 v100, v100, v101
	v_cvt_pk_bf16_f32 v101, v102, v103
	global_store_dwordx2 v146, v[100:101], s[66:67] offset:512
	v_pk_mul_f32 v[104:105], v[104:105], v[204:205] op_sel_hi:[1,0]
	v_pk_mul_f32 v[106:107], v[106:107], v[204:205] op_sel_hi:[1,0]
	v_pk_mul_f32 v[104:105], v[196:197], v[104:105]
	v_pk_mul_f32 v[106:107], v[198:199], v[106:107]
	v_pk_fma_f32 v[104:105], v[42:43], v[104:105], v[232:233]
	v_pk_fma_f32 v[106:107], v[44:45], v[106:107], v[234:235]
	v_cvt_pk_bf16_f32 v104, v104, v105
	v_cvt_pk_bf16_f32 v105, v106, v107
	global_store_dwordx2 v146, v[104:105], s[66:67] offset:1024
	v_pk_mul_f32 v[108:109], v[108:109], v[204:205] op_sel_hi:[1,0]
	v_pk_mul_f32 v[110:111], v[110:111], v[204:205] op_sel_hi:[1,0]
	v_pk_mul_f32 v[108:109], v[200:201], v[108:109]
	v_pk_mul_f32 v[110:111], v[202:203], v[110:111]
	v_pk_fma_f32 v[108:109], v[46:47], v[108:109], v[236:237]
	v_pk_fma_f32 v[110:111], v[48:49], v[110:111], v[238:239]
	v_cvt_pk_bf16_f32 v108, v108, v109
	v_cvt_pk_bf16_f32 v109, v110, v111
	global_store_dwordx2 v146, v[108:109], s[66:67] offset:1536
	v_add_u32_e32 v146, 0x800, v146
	global_load_dwordx4 v[96:99], v144, s[46:47] nt
	global_load_dwordx4 v[100:103], v144, s[46:47] offset:1024 nt
	global_load_dwordx4 v[104:107], v144, s[46:47] offset:2048 nt
	global_load_dwordx4 v[108:111], v144, s[46:47] offset:3072 nt
	v_add_u32_e32 v144, 0x1000, v144
	s_waitcnt vmcnt(28)
; __device__ __forceinline__ unsigned pk2(float lo, float hi) { const g_f32x2 f = {lo, hi}; return __builtin_bit_cast(unsigned, __builtin_convertvector(f, g_bf16x2)); }
; #define PN_LOAD(dst, rw) do { const float* s_ = (rw) < NLAT ? hlat + (size_t)(rw) * 1024 : hctx + (size_t)((rw) - NLAT) * 1024; \
;         _Pragma("unroll") for (int i = 0; i < 4; ++i) dst[i] = *(const float4*)(s_ + i * 256 + lane * 4); } while (0)
; __device__ __forceinline__ void p_norm(const float* hlat, const float* hctx, const float* g, const float* modl, int sh_off, int sc_off, bf16_t* A, int M,
;                                        const float* part, const float* cgate, float* hcout) {
;     ...
;     if (row < M) PN_LOAD(v, row);
;     while (row < M) {
;         const int nrow = row + stride;
;         if (nrow < M) PN_LOAD(nv, nrow);
;         const int r = row < NLAT ? (row >> 11) : 16;
;         float ss = 0.f;
; #pragma unroll
;         for (int i = 0; i < 4; ++i) {
;             if (part != nullptr && row >= NLAT) {
;                 const size_t po = (size_t)(row - NLAT) * 1024 + i * 256 + lane * 4;
;                 const float4 p0 = *(const float4*)(part + po), p1 = *(const float4*)(part + (size_t)4096 * 1024 + po), cg = *(const float4*)(cgate + i * 256 + lane * 4);
;                 v[i].x += cg.x * (p0.x + p1.x); v[i].y += cg.y * (p0.y + p1.y); v[i].z += cg.z * (p0.z + p1.z); v[i].w += cg.w * (p0.w + p1.w);
;                 *(float4*)(hcout + po) = v[i];
;             }
;             ss += v[i].x * v[i].x + v[i].y * v[i].y + v[i].z * v[i].z + v[i].w * v[i].w; }
;         ss = wave_sum(ss);
;         const float rstd = rsqrtf(ss * (1.0f / 1024.0f) + EPS);
;         const float* mr = modl + (size_t)r * 6144;
; #pragma unroll
;         for (int i = 0; i < 4; ++i) {
;             const int k = i * 256 + lane * 4;
;             const float4 gg = *(const float4*)(g + k), scv = *(const float4*)(mr + sc_off + k), shv = *(const float4*)(mr + sh_off + k);
;             const float o0 = v[i].x * rstd * gg.x * (1.0f + scv.x) + shv.x, o1 = v[i].y * rstd * gg.y * (1.0f + scv.y) + shv.y;
;             const float o2 = v[i].z * rstd * gg.z * (1.0f + scv.z) + shv.z, o3 = v[i].w * rstd * gg.w * (1.0f + scv.w) + shv.w;
;             uint2 w; w.x = pk2(o0, o1); w.y = pk2(o2, o3);
;             *(uint2*)(A + (size_t)row * 1024 + k) = w;
;         }
	v_pk_mul_f32 v[242:243], v[112:113], v[112:113]
	v_pk_mul_f32 v[244:245], v[116:117], v[116:117]
	v_pk_mul_f32 v[246:247], v[114:115], v[114:115]
	v_pk_mul_f32 v[248:249], v[118:119], v[118:119]
	v_add_f32_e32 v204, v245, v244
	v_add_f32_e32 v205, v243, v242
	v_add_f32_e32 v204, v248, v204
	v_add_f32_e32 v205, v246, v205
	v_add_f32_e32 v204, v249, v204
	v_add_f32_e32 v205, v247, v205
	v_pk_mul_f32 v[242:243], v[120:121], v[120:121]
	v_pk_mul_f32 v[244:245], v[124:125], v[124:125]
	v_pk_mul_f32 v[246:247], v[122:123], v[122:123]
	v_pk_mul_f32 v[248:249], v[126:127], v[126:127]
	v_add_f32_e32 v206, v243, v242
	v_add_f32_e32 v207, v245, v244
	v_add_f32_e32 v206, v246, v206
	v_add_f32_e32 v207, v248, v207
	v_add_f32_e32 v206, v247, v206
	v_add_f32_e32 v207, v249, v207
	v_add_f32_e32 v204, v205, v204
	v_add_f32_e32 v204, v204, v206
	v_add_f32_e32 v204, v204, v207
	ds_swizzle_b32 v205, v204 offset:swizzle(SWAP,1)
	s_waitcnt lgkmcnt(0)
	v_add_f32_e32 v204, v204, v205
	ds_swizzle_b32 v205, v204 offset:swizzle(SWAP,2)
	s_waitcnt lgkmcnt(0)
	v_add_f32_e32 v204, v204, v205
	ds_swizzle_b32 v205, v204 offset:swizzle(SWAP,4)
	s_waitcnt lgkmcnt(0)
	v_add_f32_e32 v204, v204, v205
	ds_swizzle_b32 v205, v204 offset:swizzle(SWAP,8)
	s_waitcnt lgkmcnt(0)
	v_add_f32_e32 v204, v204, v205
	ds_swizzle_b32 v205, v204 offset:swizzle(SWAP,16)
	s_waitcnt lgkmcnt(0)
	v_add_f32_e32 v204, v204, v205
	v_mov_b32_e32 v205, v204
	s_nop 1
	v_permlane32_swap_b32_e32 v204, v205
	v_add_f32_e32 v204, v204, v205
	v_mov_b32_e32 v205, 0x358637bd
	v_fmamk_f32 v204, v204, 0x3a800000, v205
	v_rsq_f32_e32 v204, v204
	s_nop 0
	v_pk_mul_f32 v[112:113], v[112:113], v[204:205] op_sel_hi:[1,0]
	v_pk_mul_f32 v[114:115], v[114:115], v[204:205] op_sel_hi:[1,0]
	v_pk_mul_f32 v[112:113], v[188:189], v[112:113]
	v_pk_mul_f32 v[114:115], v[190:191], v[114:115]
	v_pk_fma_f32 v[112:113], v[34:35], v[112:113], v[224:225]
	v_pk_fma_f32 v[114:115], v[36:37], v[114:115], v[226:227]
	v_cvt_pk_bf16_f32 v112, v112, v113
	v_cvt_pk_bf16_f32 v113, v114, v115
	global_store_dwordx2 v146, v[112:113], s[66:67]
	v_pk_mul_f32 v[116:117], v[116:117], v[204:205] op_sel_hi:[1,0]
	v_pk_mul_f32 v[118:119], v[118:119], v[204:205] op_sel_hi:[1,0]
	v_pk_mul_f32 v[116:117], v[192:193], v[116:117]
	v_pk_mul_f32 v[118:119], v[194:195], v[118:119]
	v_pk_fma_f32 v[116:117], v[38:39], v[116:117], v[228:229]
	v_pk_fma_f32 v[118:119], v[40:41], v[118:119], v[230:231]
	v_cvt_pk_bf16_f32 v116, v116, v117
	v_cvt_pk_bf16_f32 v117, v118, v119
	global_store_dwordx2 v146, v[116:117], s[66:67] offset:512
	v_pk_mul_f32 v[120:121], v[120:121], v[204:205] op_sel_hi:[1,0]
	v_pk_mul_f32 v[122:123], v[122:123], v[204:205] op_sel_hi:[1,0]
	v_pk_mul_f32 v[120:121], v[196:197], v[120:121]
	v_pk_mul_f32 v[122:123], v[198:199], v[122:123]
	v_pk_fma_f32 v[120:121], v[42:43], v[120:121], v[232:233]
	v_pk_fma_f32 v[122:123], v[44:45], v[122:123], v[234:235]
	v_cvt_pk_bf16_f32 v120, v120, v121
	v_cvt_pk_bf16_f32 v121, v122, v123
	global_store_dwordx2 v146, v[120:121], s[66:67] offset:1024
	v_pk_mul_f32 v[124:125], v[124:125], v[204:205] op_sel_hi:[1,0]
	v_pk_mul_f32 v[126:127], v[126:127], v[204:205] op_sel_hi:[1,0]
	v_pk_mul_f32 v[124:125], v[200:201], v[124:125]
	v_pk_mul_f32 v[126:127], v[202:203], v[126:127]
	v_pk_fma_f32 v[124:125], v[46:47], v[124:125], v[236:237]
	v_pk_fma_f32 v[126:127], v[48:49], v[126:127], v[238:239]
	v_cvt_pk_bf16_f32 v124, v124, v125
	v_cvt_pk_bf16_f32 v125, v126, v127
	global_store_dwordx2 v146, v[124:125], s[66:67] offset:1536
	v_add_u32_e32 v146, 0x800, v146
	global_load_dwordx4 v[112:115], v144, s[46:47] nt
	global_load_dwordx4 v[116:119], v144, s[46:47] offset:1024 nt
	global_load_dwordx4 v[120:123], v144, s[46:47] offset:2048 nt
	global_load_dwordx4 v[124:127], v144, s[46:47] offset:3072 nt
	v_add_u32_e32 v144, 0x1000, v144
	s_waitcnt vmcnt(32)
	v_pk_mul_f32 v[242:243], v[128:129], v[128:129]
	v_pk_mul_f32 v[244:245], v[132:133], v[132:133]
	v_pk_mul_f32 v[246:247], v[130:131], v[130:131]
	v_pk_mul_f32 v[248:249], v[134:135], v[134:135]
	v_add_f32_e32 v204, v245, v244
	v_add_f32_e32 v205, v243, v242
	v_add_f32_e32 v204, v248, v204
	v_add_f32_e32 v205, v246, v205
	v_add_f32_e32 v204, v249, v204
	v_add_f32_e32 v205, v247, v205
	v_pk_mul_f32 v[242:243], v[136:137], v[136:137]
	v_pk_mul_f32 v[244:245], v[140:141], v[140:141]
	v_pk_mul_f32 v[246:247], v[138:139], v[138:139]
	v_pk_mul_f32 v[248:249], v[142:143], v[142:143]
	v_add_f32_e32 v206, v243, v242
	v_add_f32_e32 v207, v245, v244
	v_add_f32_e32 v206, v246, v206
	v_add_f32_e32 v207, v248, v207
	v_add_f32_e32 v206, v247, v206
	v_add_f32_e32 v207, v249, v207
	v_add_f32_e32 v204, v205, v204
	v_add_f32_e32 v204, v204, v206
	v_add_f32_e32 v204, v204, v207
	ds_swizzle_b32 v205, v204 offset:swizzle(SWAP,1)
	s_waitcnt lgkmcnt(0)
	v_add_f32_e32 v204, v204, v205
	ds_swizzle_b32 v205, v204 offset:swizzle(SWAP,2)
	s_waitcnt lgkmcnt(0)
	v_add_f32_e32 v204, v204, v205
	ds_swizzle_b32 v205, v204 offset:swizzle(SWAP,4)
	s_waitcnt lgkmcnt(0)
	v_add_f32_e32 v204, v204, v205
	ds_swizzle_b32 v205, v204 offset:swizzle(SWAP,8)
	s_waitcnt lgkmcnt(0)
	v_add_f32_e32 v204, v204, v205
	ds_swizzle_b32 v205, v204 offset:swizzle(SWAP,16)
	s_waitcnt lgkmcnt(0)
; __device__ __forceinline__ unsigned pk2(float lo, float hi) { const g_f32x2 f = {lo, hi}; return __builtin_bit_cast(unsigned, __builtin_convertvector(f, g_bf16x2)); }
; #define PN_LOAD(dst, rw) do { const float* s_ = (rw) < NLAT ? hlat + (size_t)(rw) * 1024 : hctx + (size_t)((rw) - NLAT) * 1024; \
;         _Pragma("unroll") for (int i = 0; i < 4; ++i) dst[i] = *(const float4*)(s_ + i * 256 + lane * 4); } while (0)
; __device__ __forceinline__ void p_norm(const float* hlat, const float* hctx, const float* g, const float* modl, int sh_off, int sc_off, bf16_t* A, int M,
;                                        const float* part, const float* cgate, float* hcout) {
;     ...
;     if (row < M) PN_LOAD(v, row);
;     while (row < M) {
;         const int nrow = row + stride;
;         if (nrow < M) PN_LOAD(nv, nrow);
;         const int r = row < NLAT ? (row >> 11) : 16;
;         float ss = 0.f;
; #pragma unroll
;         for (int i = 0; i < 4; ++i) {
;             if (part != nullptr && row >= NLAT) {
;                 const size_t po = (size_t)(row - NLAT) * 1024 + i * 256 + lane * 4;
;                 const float4 p0 = *(const float4*)(part + po), p1 = *(const float4*)(part + (size_t)4096 * 1024 + po), cg = *(const float4*)(cgate + i * 256 + lane * 4);
;                 v[i].x += cg.x * (p0.x + p1.x); v[i].y += cg.y * (p0.y + p1.y); v[i].z += cg.z * (p0.z + p1.z); v[i].w += cg.w * (p0.w + p1.w);
;                 *(float4*)(hcout + po) = v[i];
;             }
;             ss += v[i].x * v[i].x + v[i].y * v[i].y + v[i].z * v[i].z + v[i].w * v[i].w; }
;         ss = wave_sum(ss);
;         const float rstd = rsqrtf(ss * (1.0f / 1024.0f) + EPS);
;         const float* mr = modl + (size_t)r * 6144;
; #pragma unroll
;         for (int i = 0; i < 4; ++i) {
;             const int k = i * 256 + lane * 4;
;             const float4 gg = *(const float4*)(g + k), scv = *(const float4*)(mr + sc_off + k), shv = *(const float4*)(mr + sh_off + k);
;             const float o0 = v[i].x * rstd * gg.x * (1.0f + scv.x) + shv.x, o1 = v[i].y * rstd * gg.y * (1.0f + scv.y) + shv.y;
;             const float o2 = v[i].z * rstd * gg.z * (1.0f + scv.z) + shv.z, o3 = v[i].w * rstd * gg.w * (1.0f + scv.w) + shv.w;
;             uint2 w; w.x = pk2(o0, o1); w.y = pk2(o2, o3);
;             *(uint2*)(A + (size_t)row * 1024 + k) = w;
;         }
	v_add_f32_e32 v204, v204, v205
	v_mov_b32_e32 v205, v204
	s_nop 1
	v_permlane32_swap_b32_e32 v204, v205
	v_add_f32_e32 v204, v204, v205
	v_mov_b32_e32 v205, 0x358637bd
	v_fmamk_f32 v204, v204, 0x3a800000, v205
	v_rsq_f32_e32 v204, v204
	s_nop 0
	v_pk_mul_f32 v[128:129], v[128:129], v[204:205] op_sel_hi:[1,0]
	v_pk_mul_f32 v[130:131], v[130:131], v[204:205] op_sel_hi:[1,0]
	v_pk_mul_f32 v[128:129], v[188:189], v[128:129]
	v_pk_mul_f32 v[130:131], v[190:191], v[130:131]
	v_pk_fma_f32 v[128:129], v[34:35], v[128:129], v[224:225]
	v_pk_fma_f32 v[130:131], v[36:37], v[130:131], v[226:227]
	v_cvt_pk_bf16_f32 v128, v128, v129
	v_cvt_pk_bf16_f32 v129, v130, v131
	global_store_dwordx2 v146, v[128:129], s[66:67]
	v_pk_mul_f32 v[132:133], v[132:133], v[204:205] op_sel_hi:[1,0]
	v_pk_mul_f32 v[134:135], v[134:135], v[204:205] op_sel_hi:[1,0]
	v_pk_mul_f32 v[132:133], v[192:193], v[132:133]
	v_pk_mul_f32 v[134:135], v[194:195], v[134:135]
	v_pk_fma_f32 v[132:133], v[38:39], v[132:133], v[228:229]
	v_pk_fma_f32 v[134:135], v[40:41], v[134:135], v[230:231]
	v_cvt_pk_bf16_f32 v132, v132, v133
	v_cvt_pk_bf16_f32 v133, v134, v135
	global_store_dwordx2 v146, v[132:133], s[66:67] offset:512
	v_pk_mul_f32 v[136:137], v[136:137], v[204:205] op_sel_hi:[1,0]
	v_pk_mul_f32 v[138:139], v[138:139], v[204:205] op_sel_hi:[1,0]
	v_pk_mul_f32 v[136:137], v[196:197], v[136:137]
	v_pk_mul_f32 v[138:139], v[198:199], v[138:139]
	v_pk_fma_f32 v[136:137], v[42:43], v[136:137], v[232:233]
	v_pk_fma_f32 v[138:139], v[44:45], v[138:139], v[234:235]
	v_cvt_pk_bf16_f32 v136, v136, v137
	v_cvt_pk_bf16_f32 v137, v138, v139
	global_store_dwordx2 v146, v[136:137], s[66:67] offset:1024
	v_pk_mul_f32 v[140:141], v[140:141], v[204:205] op_sel_hi:[1,0]
	v_pk_mul_f32 v[142:143], v[142:143], v[204:205] op_sel_hi:[1,0]
	v_pk_mul_f32 v[140:141], v[200:201], v[140:141]
	v_pk_mul_f32 v[142:143], v[202:203], v[142:143]
	v_pk_fma_f32 v[140:141], v[46:47], v[140:141], v[236:237]
	v_pk_fma_f32 v[142:143], v[48:49], v[142:143], v[238:239]
	v_cvt_pk_bf16_f32 v140, v140, v141
	v_cvt_pk_bf16_f32 v141, v142, v143
	global_store_dwordx2 v146, v[140:141], s[66:67] offset:1536
	v_add_u32_e32 v146, 0x800, v146
	global_load_dwordx4 v[128:131], v144, s[46:47] nt
	global_load_dwordx4 v[132:135], v144, s[46:47] offset:1024 nt
	global_load_dwordx4 v[136:139], v144, s[46:47] offset:2048 nt
	global_load_dwordx4 v[140:143], v144, s[46:47] offset:3072 nt
	v_add_u32_e32 v144, 0x1000, v144
	s_waitcnt vmcnt(36)
	v_pk_mul_f32 v[242:243], v[156:157], v[156:157]
	v_pk_mul_f32 v[244:245], v[160:161], v[160:161]
	v_pk_mul_f32 v[246:247], v[158:159], v[158:159]
	v_pk_mul_f32 v[248:249], v[162:163], v[162:163]
	v_add_f32_e32 v204, v245, v244
	v_add_f32_e32 v205, v243, v242
	v_add_f32_e32 v204, v248, v204
	v_add_f32_e32 v205, v246, v205
	v_add_f32_e32 v204, v249, v204
	v_add_f32_e32 v205, v247, v205
	v_pk_mul_f32 v[242:243], v[164:165], v[164:165]
	v_pk_mul_f32 v[244:245], v[168:169], v[168:169]
	v_pk_mul_f32 v[246:247], v[166:167], v[166:167]
	v_pk_mul_f32 v[248:249], v[170:171], v[170:171]
	v_add_f32_e32 v206, v243, v242
	v_add_f32_e32 v207, v245, v244
	v_add_f32_e32 v206, v246, v206
	v_add_f32_e32 v207, v248, v207
	v_add_f32_e32 v206, v247, v206
	v_add_f32_e32 v207, v249, v207
	v_add_f32_e32 v204, v205, v204
	v_add_f32_e32 v204, v204, v206
	v_add_f32_e32 v204, v204, v207
	ds_swizzle_b32 v205, v204 offset:swizzle(SWAP,1)
	s_waitcnt lgkmcnt(0)
	v_add_f32_e32 v204, v204, v205
	ds_swizzle_b32 v205, v204 offset:swizzle(SWAP,2)
	s_waitcnt lgkmcnt(0)
	v_add_f32_e32 v204, v204, v205
	ds_swizzle_b32 v205, v204 offset:swizzle(SWAP,4)
	s_waitcnt lgkmcnt(0)
	v_add_f32_e32 v204, v204, v205
	ds_swizzle_b32 v205, v204 offset:swizzle(SWAP,8)
	s_waitcnt lgkmcnt(0)
	v_add_f32_e32 v204, v204, v205
	ds_swizzle_b32 v205, v204 offset:swizzle(SWAP,16)
	s_waitcnt lgkmcnt(0)
	v_add_f32_e32 v204, v204, v205
	v_mov_b32_e32 v205, v204
	s_nop 1
	v_permlane32_swap_b32_e32 v204, v205
	v_add_f32_e32 v204, v204, v205
	v_mov_b32_e32 v205, 0x358637bd
	v_fmamk_f32 v204, v204, 0x3a800000, v205
	v_rsq_f32_e32 v204, v204
	s_nop 0
	v_pk_mul_f32 v[156:157], v[156:157], v[204:205] op_sel_hi:[1,0]
	v_pk_mul_f32 v[158:159], v[158:159], v[204:205] op_sel_hi:[1,0]
	v_pk_mul_f32 v[156:157], v[188:189], v[156:157]
	v_pk_mul_f32 v[158:159], v[190:191], v[158:159]
	v_pk_fma_f32 v[156:157], v[34:35], v[156:157], v[224:225]
	v_pk_fma_f32 v[158:159], v[36:37], v[158:159], v[226:227]
	v_cvt_pk_bf16_f32 v156, v156, v157
	v_cvt_pk_bf16_f32 v157, v158, v159
	global_store_dwordx2 v146, v[156:157], s[66:67]
	v_pk_mul_f32 v[160:161], v[160:161], v[204:205] op_sel_hi:[1,0]
	v_pk_mul_f32 v[162:163], v[162:163], v[204:205] op_sel_hi:[1,0]
	v_pk_mul_f32 v[160:161], v[192:193], v[160:161]
	v_pk_mul_f32 v[162:163], v[194:195], v[162:163]
	v_pk_fma_f32 v[160:161], v[38:39], v[160:161], v[228:229]
	v_pk_fma_f32 v[162:163], v[40:41], v[162:163], v[230:231]
	v_cvt_pk_bf16_f32 v160, v160, v161
	v_cvt_pk_bf16_f32 v161, v162, v163
	global_store_dwordx2 v146, v[160:161], s[66:67] offset:512
	v_pk_mul_f32 v[164:165], v[164:165], v[204:205] op_sel_hi:[1,0]
	v_pk_mul_f32 v[166:167], v[166:167], v[204:205] op_sel_hi:[1,0]
	v_pk_mul_f32 v[164:165], v[196:197], v[164:165]
	v_pk_mul_f32 v[166:167], v[198:199], v[166:167]
	v_pk_fma_f32 v[164:165], v[42:43], v[164:165], v[232:233]
	v_pk_fma_f32 v[166:167], v[44:45], v[166:167], v[234:235]
	v_cvt_pk_bf16_f32 v164, v164, v165
	v_cvt_pk_bf16_f32 v165, v166, v167
	global_store_dwordx2 v146, v[164:165], s[66:67] offset:1024
	v_pk_mul_f32 v[168:169], v[168:169], v[204:205] op_sel_hi:[1,0]
	v_pk_mul_f32 v[170:171], v[170:171], v[204:205] op_sel_hi:[1,0]
	v_pk_mul_f32 v[168:169], v[200:201], v[168:169]
	v_pk_mul_f32 v[170:171], v[202:203], v[170:171]
	v_pk_fma_f32 v[168:169], v[46:47], v[168:169], v[236:237]
	v_pk_fma_f32 v[170:171], v[48:49], v[170:171], v[238:239]
	v_cvt_pk_bf16_f32 v168, v168, v169
	v_cvt_pk_bf16_f32 v169, v170, v171
	global_store_dwordx2 v146, v[168:169], s[66:67] offset:1536
	v_add_u32_e32 v146, 0x800, v146
	global_load_dwordx4 v[156:159], v144, s[46:47] nt
	global_load_dwordx4 v[160:163], v144, s[46:47] offset:1024 nt
	global_load_dwordx4 v[164:167], v144, s[46:47] offset:2048 nt
	global_load_dwordx4 v[168:171], v144, s[46:47] offset:3072 nt
	v_add_u32_e32 v144, 0x1000, v144
	s_waitcnt vmcnt(40)
; __device__ __forceinline__ unsigned pk2(float lo, float hi) { const g_f32x2 f = {lo, hi}; return __builtin_bit_cast(unsigned, __builtin_convertvector(f, g_bf16x2)); }
; #define PN_LOAD(dst, rw) do { const float* s_ = (rw) < NLAT ? hlat + (size_t)(rw) * 1024 : hctx + (size_t)((rw) - NLAT) * 1024; \
;         _Pragma("unroll") for (int i = 0; i < 4; ++i) dst[i] = *(const float4*)(s_ + i * 256 + lane * 4); } while (0)
; __device__ __forceinline__ void p_norm(const float* hlat, const float* hctx, const float* g, const float* modl, int sh_off, int sc_off, bf16_t* A, int M,
;                                        const float* part, const float* cgate, float* hcout) {
;     ...
;     if (row < M) PN_LOAD(v, row);
;     while (row < M) {
;         const int nrow = row + stride;
;         if (nrow < M) PN_LOAD(nv, nrow);
;         const int r = row < NLAT ? (row >> 11) : 16;
;         float ss = 0.f;
; #pragma unroll
;         for (int i = 0; i < 4; ++i) {
;             if (part != nullptr && row >= NLAT) {
;                 const size_t po = (size_t)(row - NLAT) * 1024 + i * 256 + lane * 4;
;                 const float4 p0 = *(const float4*)(part + po), p1 = *(const float4*)(part + (size_t)4096 * 1024 + po), cg = *(const float4*)(cgate + i * 256 + lane * 4);
;                 v[i].x += cg.x * (p0.x + p1.x); v[i].y += cg.y * (p0.y + p1.y); v[i].z += cg.z * (p0.z + p1.z); v[i].w += cg.w * (p0.w + p1.w);
;                 *(float4*)(hcout + po) = v[i];
;             }
;             ss += v[i].x * v[i].x + v[i].y * v[i].y + v[i].z * v[i].z + v[i].w * v[i].w; }
;         ss = wave_sum(ss);
;         const float rstd = rsqrtf(ss * (1.0f / 1024.0f) + EPS);
;         const float* mr = modl + (size_t)r * 6144;
; #pragma unroll
;         for (int i = 0; i < 4; ++i) {
;             const int k = i * 256 + lane * 4;
;             const float4 gg = *(const float4*)(g + k), scv = *(const float4*)(mr + sc_off + k), shv = *(const float4*)(mr + sh_off + k);
;             const float o0 = v[i].x * rstd * gg.x * (1.0f + scv.x) + shv.x, o1 = v[i].y * rstd * gg.y * (1.0f + scv.y) + shv.y;
;             const float o2 = v[i].z * rstd * gg.z * (1.0f + scv.z) + shv.z, o3 = v[i].w * rstd * gg.w * (1.0f + scv.w) + shv.w;
;             uint2 w; w.x = pk2(o0, o1); w.y = pk2(o2, o3);
;             *(uint2*)(A + (size_t)row * 1024 + k) = w;
;         }
	v_pk_mul_f32 v[242:243], v[172:173], v[172:173]
	v_pk_mul_f32 v[244:245], v[176:177], v[176:177]
	v_pk_mul_f32 v[246:247], v[174:175], v[174:175]
	v_pk_mul_f32 v[248:249], v[178:179], v[178:179]
	v_add_f32_e32 v204, v245, v244
	v_add_f32_e32 v205, v243, v242
	v_add_f32_e32 v204, v248, v204
	v_add_f32_e32 v205, v246, v205
	v_add_f32_e32 v204, v249, v204
	v_add_f32_e32 v205, v247, v205
	v_pk_mul_f32 v[242:243], v[180:181], v[180:181]
	v_pk_mul_f32 v[244:245], v[184:185], v[184:185]
	v_pk_mul_f32 v[246:247], v[182:183], v[182:183]
	v_pk_mul_f32 v[248:249], v[186:187], v[186:187]
	v_add_f32_e32 v206, v243, v242
	v_add_f32_e32 v207, v245, v244
	v_add_f32_e32 v206, v246, v206
	v_add_f32_e32 v207, v248, v207
	v_add_f32_e32 v206, v247, v206
	v_add_f32_e32 v207, v249, v207
	v_add_f32_e32 v204, v205, v204
	v_add_f32_e32 v204, v204, v206
	v_add_f32_e32 v204, v204, v207
	ds_swizzle_b32 v205, v204 offset:swizzle(SWAP,1)
	s_waitcnt lgkmcnt(0)
	v_add_f32_e32 v204, v204, v205
	ds_swizzle_b32 v205, v204 offset:swizzle(SWAP,2)
	s_waitcnt lgkmcnt(0)
	v_add_f32_e32 v204, v204, v205
	ds_swizzle_b32 v205, v204 offset:swizzle(SWAP,4)
	s_waitcnt lgkmcnt(0)
	v_add_f32_e32 v204, v204, v205
	ds_swizzle_b32 v205, v204 offset:swizzle(SWAP,8)
	s_waitcnt lgkmcnt(0)
	v_add_f32_e32 v204, v204, v205
	ds_swizzle_b32 v205, v204 offset:swizzle(SWAP,16)
	s_waitcnt lgkmcnt(0)
	v_add_f32_e32 v204, v204, v205
	v_mov_b32_e32 v205, v204
	s_nop 1
	v_permlane32_swap_b32_e32 v204, v205
	v_add_f32_e32 v204, v204, v205
	v_mov_b32_e32 v205, 0x358637bd
	v_fmamk_f32 v204, v204, 0x3a800000, v205
	v_rsq_f32_e32 v204, v204
	s_nop 0
	v_pk_mul_f32 v[172:173], v[172:173], v[204:205] op_sel_hi:[1,0]
	v_pk_mul_f32 v[174:175], v[174:175], v[204:205] op_sel_hi:[1,0]
	v_pk_mul_f32 v[172:173], v[188:189], v[172:173]
	v_pk_mul_f32 v[174:175], v[190:191], v[174:175]
	v_pk_fma_f32 v[172:173], v[34:35], v[172:173], v[224:225]
	v_pk_fma_f32 v[174:175], v[36:37], v[174:175], v[226:227]
	v_cvt_pk_bf16_f32 v172, v172, v173
	v_cvt_pk_bf16_f32 v173, v174, v175
	global_store_dwordx2 v146, v[172:173], s[66:67]
	v_pk_mul_f32 v[176:177], v[176:177], v[204:205] op_sel_hi:[1,0]
	v_pk_mul_f32 v[178:179], v[178:179], v[204:205] op_sel_hi:[1,0]
	v_pk_mul_f32 v[176:177], v[192:193], v[176:177]
	v_pk_mul_f32 v[178:179], v[194:195], v[178:179]
	v_pk_fma_f32 v[176:177], v[38:39], v[176:177], v[228:229]
	v_pk_fma_f32 v[178:179], v[40:41], v[178:179], v[230:231]
	v_cvt_pk_bf16_f32 v176, v176, v177
	v_cvt_pk_bf16_f32 v177, v178, v179
	global_store_dwordx2 v146, v[176:177], s[66:67] offset:512
	v_pk_mul_f32 v[180:181], v[180:181], v[204:205] op_sel_hi:[1,0]
	v_pk_mul_f32 v[182:183], v[182:183], v[204:205] op_sel_hi:[1,0]
	v_pk_mul_f32 v[180:181], v[196:197], v[180:181]
	v_pk_mul_f32 v[182:183], v[198:199], v[182:183]
	v_pk_fma_f32 v[180:181], v[42:43], v[180:181], v[232:233]
	v_pk_fma_f32 v[182:183], v[44:45], v[182:183], v[234:235]
	v_cvt_pk_bf16_f32 v180, v180, v181
	v_cvt_pk_bf16_f32 v181, v182, v183
	global_store_dwordx2 v146, v[180:181], s[66:67] offset:1024
	v_pk_mul_f32 v[184:185], v[184:185], v[204:205] op_sel_hi:[1,0]
	v_pk_mul_f32 v[186:187], v[186:187], v[204:205] op_sel_hi:[1,0]
	v_pk_mul_f32 v[184:185], v[200:201], v[184:185]
	v_pk_mul_f32 v[186:187], v[202:203], v[186:187]
	v_pk_fma_f32 v[184:185], v[46:47], v[184:185], v[236:237]
	v_pk_fma_f32 v[186:187], v[48:49], v[186:187], v[238:239]
	v_cvt_pk_bf16_f32 v184, v184, v185
	v_cvt_pk_bf16_f32 v185, v186, v187
	global_store_dwordx2 v146, v[184:185], s[66:67] offset:1536
	v_add_u32_e32 v146, 0x800, v146
	global_load_dwordx4 v[172:175], v144, s[46:47] nt
	global_load_dwordx4 v[176:179], v144, s[46:47] offset:1024 nt
	global_load_dwordx4 v[180:183], v144, s[46:47] offset:2048 nt
	global_load_dwordx4 v[184:187], v144, s[46:47] offset:3072 nt
	v_add_u32_e32 v144, 0x1000, v144
	s_waitcnt vmcnt(40)
	v_pk_mul_f32 v[242:243], v[80:81], v[80:81]
	v_pk_mul_f32 v[244:245], v[84:85], v[84:85]
	v_pk_mul_f32 v[246:247], v[82:83], v[82:83]
	v_pk_mul_f32 v[248:249], v[86:87], v[86:87]
	v_add_f32_e32 v204, v245, v244
	v_add_f32_e32 v205, v243, v242
	v_add_f32_e32 v204, v248, v204
	v_add_f32_e32 v205, v246, v205
	v_add_f32_e32 v204, v249, v204
	v_add_f32_e32 v205, v247, v205
	v_pk_mul_f32 v[242:243], v[88:89], v[88:89]
	v_pk_mul_f32 v[244:245], v[92:93], v[92:93]
	v_pk_mul_f32 v[246:247], v[90:91], v[90:91]
	v_pk_mul_f32 v[248:249], v[94:95], v[94:95]
	v_add_f32_e32 v206, v243, v242
	v_add_f32_e32 v207, v245, v244
	v_add_f32_e32 v206, v246, v206
	v_add_f32_e32 v207, v248, v207
	v_add_f32_e32 v206, v247, v206
	v_add_f32_e32 v207, v249, v207
	v_add_f32_e32 v204, v205, v204
	v_add_f32_e32 v204, v204, v206
	v_add_f32_e32 v204, v204, v207
	ds_swizzle_b32 v205, v204 offset:swizzle(SWAP,1)
	s_waitcnt lgkmcnt(0)
	v_add_f32_e32 v204, v204, v205
	ds_swizzle_b32 v205, v204 offset:swizzle(SWAP,2)
	s_waitcnt lgkmcnt(0)
	v_add_f32_e32 v204, v204, v205
	ds_swizzle_b32 v205, v204 offset:swizzle(SWAP,4)
	s_waitcnt lgkmcnt(0)
	v_add_f32_e32 v204, v204, v205
	ds_swizzle_b32 v205, v204 offset:swizzle(SWAP,8)
	s_waitcnt lgkmcnt(0)
	v_add_f32_e32 v204, v204, v205
	ds_swizzle_b32 v205, v204 offset:swizzle(SWAP,16)
	s_waitcnt lgkmcnt(0)
; __device__ __forceinline__ unsigned pk2(float lo, float hi) { const g_f32x2 f = {lo, hi}; return __builtin_bit_cast(unsigned, __builtin_convertvector(f, g_bf16x2)); }
; #define PN_LOAD(dst, rw) do { const float* s_ = (rw) < NLAT ? hlat + (size_t)(rw) * 1024 : hctx + (size_t)((rw) - NLAT) * 1024; \
;         _Pragma("unroll") for (int i = 0; i < 4; ++i) dst[i] = *(const float4*)(s_ + i * 256 + lane * 4); } while (0)
; __device__ __forceinline__ void p_norm(const float* hlat, const float* hctx, const float* g, const float* modl, int sh_off, int sc_off, bf16_t* A, int M,
;                                        const float* part, const float* cgate, float* hcout) {
;     ...
;     if (row < M) PN_LOAD(v, row);
;     while (row < M) {
;         const int nrow = row + stride;
;         if (nrow < M) PN_LOAD(nv, nrow);
;         const int r = row < NLAT ? (row >> 11) : 16;
;         float ss = 0.f;
; #pragma unroll
;         for (int i = 0; i < 4; ++i) {
;             if (part != nullptr && row >= NLAT) {
;                 const size_t po = (size_t)(row - NLAT) * 1024 + i * 256 + lane * 4;
;                 const float4 p0 = *(const float4*)(part + po), p1 = *(const float4*)(part + (size_t)4096 * 1024 + po), cg = *(const float4*)(cgate + i * 256 + lane * 4);
;                 v[i].x += cg.x * (p0.x + p1.x); v[i].y += cg.y * (p0.y + p1.y); v[i].z += cg.z * (p0.z + p1.z); v[i].w += cg.w * (p0.w + p1.w);
;                 *(float4*)(hcout + po) = v[i];
;             }
;             ss += v[i].x * v[i].x + v[i].y * v[i].y + v[i].z * v[i].z + v[i].w * v[i].w; }
;         ss = wave_sum(ss);
;         const float rstd = rsqrtf(ss * (1.0f / 1024.0f) + EPS);
;         const float* mr = modl + (size_t)r * 6144;
; #pragma unroll
;         for (int i = 0; i < 4; ++i) {
;             const int k = i * 256 + lane * 4;
;             const float4 gg = *(const float4*)(g + k), scv = *(const float4*)(mr + sc_off + k), shv = *(const float4*)(mr + sh_off + k);
;             const float o0 = v[i].x * rstd * gg.x * (1.0f + scv.x) + shv.x, o1 = v[i].y * rstd * gg.y * (1.0f + scv.y) + shv.y;
;             const float o2 = v[i].z * rstd * gg.z * (1.0f + scv.z) + shv.z, o3 = v[i].w * rstd * gg.w * (1.0f + scv.w) + shv.w;
;             uint2 w; w.x = pk2(o0, o1); w.y = pk2(o2, o3);
;             *(uint2*)(A + (size_t)row * 1024 + k) = w;
;         }
	v_add_f32_e32 v204, v204, v205
	v_mov_b32_e32 v205, v204
	s_nop 1
	v_permlane32_swap_b32_e32 v204, v205
	v_add_f32_e32 v204, v204, v205
	v_mov_b32_e32 v205, 0x358637bd
	v_fmamk_f32 v204, v204, 0x3a800000, v205
	v_rsq_f32_e32 v204, v204
	s_nop 0
	v_pk_mul_f32 v[80:81], v[80:81], v[204:205] op_sel_hi:[1,0]
	v_pk_mul_f32 v[82:83], v[82:83], v[204:205] op_sel_hi:[1,0]
	v_pk_mul_f32 v[80:81], v[188:189], v[80:81]
	v_pk_mul_f32 v[82:83], v[190:191], v[82:83]
	v_pk_fma_f32 v[80:81], v[34:35], v[80:81], v[224:225]
	v_pk_fma_f32 v[82:83], v[36:37], v[82:83], v[226:227]
	v_cvt_pk_bf16_f32 v80, v80, v81
	v_cvt_pk_bf16_f32 v81, v82, v83
	global_store_dwordx2 v146, v[80:81], s[66:67]
	v_pk_mul_f32 v[84:85], v[84:85], v[204:205] op_sel_hi:[1,0]
	v_pk_mul_f32 v[86:87], v[86:87], v[204:205] op_sel_hi:[1,0]
	v_pk_mul_f32 v[84:85], v[192:193], v[84:85]
	v_pk_mul_f32 v[86:87], v[194:195], v[86:87]
	v_pk_fma_f32 v[84:85], v[38:39], v[84:85], v[228:229]
	v_pk_fma_f32 v[86:87], v[40:41], v[86:87], v[230:231]
	v_cvt_pk_bf16_f32 v84, v84, v85
	v_cvt_pk_bf16_f32 v85, v86, v87
	global_store_dwordx2 v146, v[84:85], s[66:67] offset:512
	v_pk_mul_f32 v[88:89], v[88:89], v[204:205] op_sel_hi:[1,0]
	v_pk_mul_f32 v[90:91], v[90:91], v[204:205] op_sel_hi:[1,0]
	v_pk_mul_f32 v[88:89], v[196:197], v[88:89]
	v_pk_mul_f32 v[90:91], v[198:199], v[90:91]
	v_pk_fma_f32 v[88:89], v[42:43], v[88:89], v[232:233]
	v_pk_fma_f32 v[90:91], v[44:45], v[90:91], v[234:235]
	v_cvt_pk_bf16_f32 v88, v88, v89
	v_cvt_pk_bf16_f32 v89, v90, v91
	global_store_dwordx2 v146, v[88:89], s[66:67] offset:1024
	v_pk_mul_f32 v[92:93], v[92:93], v[204:205] op_sel_hi:[1,0]
	v_pk_mul_f32 v[94:95], v[94:95], v[204:205] op_sel_hi:[1,0]
	v_pk_mul_f32 v[92:93], v[200:201], v[92:93]
	v_pk_mul_f32 v[94:95], v[202:203], v[94:95]
	v_pk_fma_f32 v[92:93], v[46:47], v[92:93], v[236:237]
	v_pk_fma_f32 v[94:95], v[48:49], v[94:95], v[238:239]
	v_cvt_pk_bf16_f32 v92, v92, v93
	v_cvt_pk_bf16_f32 v93, v94, v95
	global_store_dwordx2 v146, v[92:93], s[66:67] offset:1536
	v_add_u32_e32 v146, 0x800, v146
	global_load_dwordx4 v[80:83], v144, s[46:47] nt
	global_load_dwordx4 v[84:87], v144, s[46:47] offset:1024 nt
	global_load_dwordx4 v[88:91], v144, s[46:47] offset:2048 nt
	global_load_dwordx4 v[92:95], v144, s[46:47] offset:3072 nt
	v_add_u32_e32 v144, 0x1000, v144
	s_waitcnt vmcnt(40)
	v_pk_mul_f32 v[242:243], v[96:97], v[96:97]
	v_pk_mul_f32 v[244:245], v[100:101], v[100:101]
	v_pk_mul_f32 v[246:247], v[98:99], v[98:99]
	v_pk_mul_f32 v[248:249], v[102:103], v[102:103]
	v_add_f32_e32 v204, v245, v244
	v_add_f32_e32 v205, v243, v242
	v_add_f32_e32 v204, v248, v204
	v_add_f32_e32 v205, v246, v205
	v_add_f32_e32 v204, v249, v204
	v_add_f32_e32 v205, v247, v205
	v_pk_mul_f32 v[242:243], v[104:105], v[104:105]
	v_pk_mul_f32 v[244:245], v[108:109], v[108:109]
	v_pk_mul_f32 v[246:247], v[106:107], v[106:107]
	v_pk_mul_f32 v[248:249], v[110:111], v[110:111]
	v_add_f32_e32 v206, v243, v242
	v_add_f32_e32 v207, v245, v244
	v_add_f32_e32 v206, v246, v206
	v_add_f32_e32 v207, v248, v207
	v_add_f32_e32 v206, v247, v206
	v_add_f32_e32 v207, v249, v207
	v_add_f32_e32 v204, v205, v204
	v_add_f32_e32 v204, v204, v206
	v_add_f32_e32 v204, v204, v207
	ds_swizzle_b32 v205, v204 offset:swizzle(SWAP,1)
	s_waitcnt lgkmcnt(0)
	v_add_f32_e32 v204, v204, v205
	ds_swizzle_b32 v205, v204 offset:swizzle(SWAP,2)
	s_waitcnt lgkmcnt(0)
	v_add_f32_e32 v204, v204, v205
	ds_swizzle_b32 v205, v204 offset:swizzle(SWAP,4)
	s_waitcnt lgkmcnt(0)
	v_add_f32_e32 v204, v204, v205
	ds_swizzle_b32 v205, v204 offset:swizzle(SWAP,8)
	s_waitcnt lgkmcnt(0)
	v_add_f32_e32 v204, v204, v205
	ds_swizzle_b32 v205, v204 offset:swizzle(SWAP,16)
	s_waitcnt lgkmcnt(0)
	v_add_f32_e32 v204, v204, v205
	v_mov_b32_e32 v205, v204
	s_nop 1
	v_permlane32_swap_b32_e32 v204, v205
	v_add_f32_e32 v204, v204, v205
	v_mov_b32_e32 v205, 0x358637bd
	v_fmamk_f32 v204, v204, 0x3a800000, v205
	v_rsq_f32_e32 v204, v204
	s_nop 0
	v_pk_mul_f32 v[96:97], v[96:97], v[204:205] op_sel_hi:[1,0]
	v_pk_mul_f32 v[98:99], v[98:99], v[204:205] op_sel_hi:[1,0]
	v_pk_mul_f32 v[96:97], v[188:189], v[96:97]
	v_pk_mul_f32 v[98:99], v[190:191], v[98:99]
	v_pk_fma_f32 v[96:97], v[34:35], v[96:97], v[224:225]
	v_pk_fma_f32 v[98:99], v[36:37], v[98:99], v[226:227]
	v_cvt_pk_bf16_f32 v96, v96, v97
	v_cvt_pk_bf16_f32 v97, v98, v99
	global_store_dwordx2 v146, v[96:97], s[66:67]
	v_pk_mul_f32 v[100:101], v[100:101], v[204:205] op_sel_hi:[1,0]
	v_pk_mul_f32 v[102:103], v[102:103], v[204:205] op_sel_hi:[1,0]
	v_pk_mul_f32 v[100:101], v[192:193], v[100:101]
	v_pk_mul_f32 v[102:103], v[194:195], v[102:103]
	v_pk_fma_f32 v[100:101], v[38:39], v[100:101], v[228:229]
	v_pk_fma_f32 v[102:103], v[40:41], v[102:103], v[230:231]
	v_cvt_pk_bf16_f32 v100, v100, v101
	v_cvt_pk_bf16_f32 v101, v102, v103
	global_store_dwordx2 v146, v[100:101], s[66:67] offset:512
	v_pk_mul_f32 v[104:105], v[104:105], v[204:205] op_sel_hi:[1,0]
	v_pk_mul_f32 v[106:107], v[106:107], v[204:205] op_sel_hi:[1,0]
	v_pk_mul_f32 v[104:105], v[196:197], v[104:105]
	v_pk_mul_f32 v[106:107], v[198:199], v[106:107]
	v_pk_fma_f32 v[104:105], v[42:43], v[104:105], v[232:233]
	v_pk_fma_f32 v[106:107], v[44:45], v[106:107], v[234:235]
	v_cvt_pk_bf16_f32 v104, v104, v105
	v_cvt_pk_bf16_f32 v105, v106, v107
	global_store_dwordx2 v146, v[104:105], s[66:67] offset:1024
	v_pk_mul_f32 v[108:109], v[108:109], v[204:205] op_sel_hi:[1,0]
	v_pk_mul_f32 v[110:111], v[110:111], v[204:205] op_sel_hi:[1,0]
	v_pk_mul_f32 v[108:109], v[200:201], v[108:109]
	v_pk_mul_f32 v[110:111], v[202:203], v[110:111]
	v_pk_fma_f32 v[108:109], v[46:47], v[108:109], v[236:237]
	v_pk_fma_f32 v[110:111], v[48:49], v[110:111], v[238:239]
	v_cvt_pk_bf16_f32 v108, v108, v109
	v_cvt_pk_bf16_f32 v109, v110, v111
	global_store_dwordx2 v146, v[108:109], s[66:67] offset:1536
	v_add_u32_e32 v146, 0x800, v146
	global_load_dwordx4 v[96:99], v144, s[46:47] nt
	global_load_dwordx4 v[100:103], v144, s[46:47] offset:1024 nt
	global_load_dwordx4 v[104:107], v144, s[46:47] offset:2048 nt
	global_load_dwordx4 v[108:111], v144, s[46:47] offset:3072 nt
	v_add_u32_e32 v144, 0x1000, v144
	s_waitcnt vmcnt(40)
; __device__ __forceinline__ unsigned pk2(float lo, float hi) { const g_f32x2 f = {lo, hi}; return __builtin_bit_cast(unsigned, __builtin_convertvector(f, g_bf16x2)); }
; #define PN_LOAD(dst, rw) do { const float* s_ = (rw) < NLAT ? hlat + (size_t)(rw) * 1024 : hctx + (size_t)((rw) - NLAT) * 1024; \
;         _Pragma("unroll") for (int i = 0; i < 4; ++i) dst[i] = *(const float4*)(s_ + i * 256 + lane * 4); } while (0)
; __device__ __forceinline__ void p_norm(const float* hlat, const float* hctx, const float* g, const float* modl, int sh_off, int sc_off, bf16_t* A, int M,
;                                        const float* part, const float* cgate, float* hcout) {
;     ...
;     if (row < M) PN_LOAD(v, row);
;     while (row < M) {
;         const int nrow = row + stride;
;         if (nrow < M) PN_LOAD(nv, nrow);
;         const int r = row < NLAT ? (row >> 11) : 16;
;         float ss = 0.f;
; #pragma unroll
;         for (int i = 0; i < 4; ++i) {
;             if (part != nullptr && row >= NLAT) {
;                 const size_t po = (size_t)(row - NLAT) * 1024 + i * 256 + lane * 4;
;                 const float4 p0 = *(const float4*)(part + po), p1 = *(const float4*)(part + (size_t)4096 * 1024 + po), cg = *(const float4*)(cgate + i * 256 + lane * 4);
;                 v[i].x += cg.x * (p0.x + p1.x); v[i].y += cg.y * (p0.y + p1.y); v[i].z += cg.z * (p0.z + p1.z); v[i].w += cg.w * (p0.w + p1.w);
;                 *(float4*)(hcout + po) = v[i];
;             }
;             ss += v[i].x * v[i].x + v[i].y * v[i].y + v[i].z * v[i].z + v[i].w * v[i].w; }
;         ss = wave_sum(ss);
;         const float rstd = rsqrtf(ss * (1.0f / 1024.0f) + EPS);
;         const float* mr = modl + (size_t)r * 6144;
; #pragma unroll
;         for (int i = 0; i < 4; ++i) {
;             const int k = i * 256 + lane * 4;
;             const float4 gg = *(const float4*)(g + k), scv = *(const float4*)(mr + sc_off + k), shv = *(const float4*)(mr + sh_off + k);
;             const float o0 = v[i].x * rstd * gg.x * (1.0f + scv.x) + shv.x, o1 = v[i].y * rstd * gg.y * (1.0f + scv.y) + shv.y;
;             const float o2 = v[i].z * rstd * gg.z * (1.0f + scv.z) + shv.z, o3 = v[i].w * rstd * gg.w * (1.0f + scv.w) + shv.w;
;             uint2 w; w.x = pk2(o0, o1); w.y = pk2(o2, o3);
;             *(uint2*)(A + (size_t)row * 1024 + k) = w;
;         }
	v_pk_mul_f32 v[242:243], v[112:113], v[112:113]
	v_pk_mul_f32 v[244:245], v[116:117], v[116:117]
	v_pk_mul_f32 v[246:247], v[114:115], v[114:115]
	v_pk_mul_f32 v[248:249], v[118:119], v[118:119]
	v_add_f32_e32 v204, v245, v244
	v_add_f32_e32 v205, v243, v242
	v_add_f32_e32 v204, v248, v204
	v_add_f32_e32 v205, v246, v205
	v_add_f32_e32 v204, v249, v204
	v_add_f32_e32 v205, v247, v205
	v_pk_mul_f32 v[242:243], v[120:121], v[120:121]
	v_pk_mul_f32 v[244:245], v[124:125], v[124:125]
	v_pk_mul_f32 v[246:247], v[122:123], v[122:123]
	v_pk_mul_f32 v[248:249], v[126:127], v[126:127]
	v_add_f32_e32 v206, v243, v242
	v_add_f32_e32 v207, v245, v244
	v_add_f32_e32 v206, v246, v206
	v_add_f32_e32 v207, v248, v207
	v_add_f32_e32 v206, v247, v206
	v_add_f32_e32 v207, v249, v207
	v_add_f32_e32 v204, v205, v204
	v_add_f32_e32 v204, v204, v206
	v_add_f32_e32 v204, v204, v207
	ds_swizzle_b32 v205, v204 offset:swizzle(SWAP,1)
	s_waitcnt lgkmcnt(0)
	v_add_f32_e32 v204, v204, v205
	ds_swizzle_b32 v205, v204 offset:swizzle(SWAP,2)
	s_waitcnt lgkmcnt(0)
	v_add_f32_e32 v204, v204, v205
	ds_swizzle_b32 v205, v204 offset:swizzle(SWAP,4)
	s_waitcnt lgkmcnt(0)
	v_add_f32_e32 v204, v204, v205
	ds_swizzle_b32 v205, v204 offset:swizzle(SWAP,8)
	s_waitcnt lgkmcnt(0)
	v_add_f32_e32 v204, v204, v205
	ds_swizzle_b32 v205, v204 offset:swizzle(SWAP,16)
	s_waitcnt lgkmcnt(0)
	v_add_f32_e32 v204, v204, v205
	v_mov_b32_e32 v205, v204
	s_nop 1
	v_permlane32_swap_b32_e32 v204, v205
	v_add_f32_e32 v204, v204, v205
	v_mov_b32_e32 v205, 0x358637bd
	v_fmamk_f32 v204, v204, 0x3a800000, v205
	v_rsq_f32_e32 v204, v204
	s_nop 0
	v_pk_mul_f32 v[112:113], v[112:113], v[204:205] op_sel_hi:[1,0]
	v_pk_mul_f32 v[114:115], v[114:115], v[204:205] op_sel_hi:[1,0]
	v_pk_mul_f32 v[112:113], v[188:189], v[112:113]
	v_pk_mul_f32 v[114:115], v[190:191], v[114:115]
	v_pk_fma_f32 v[112:113], v[34:35], v[112:113], v[224:225]
	v_pk_fma_f32 v[114:115], v[36:37], v[114:115], v[226:227]
	v_cvt_pk_bf16_f32 v112, v112, v113
	v_cvt_pk_bf16_f32 v113, v114, v115
	global_store_dwordx2 v146, v[112:113], s[66:67]
	v_pk_mul_f32 v[116:117], v[116:117], v[204:205] op_sel_hi:[1,0]
	v_pk_mul_f32 v[118:119], v[118:119], v[204:205] op_sel_hi:[1,0]
	v_pk_mul_f32 v[116:117], v[192:193], v[116:117]
	v_pk_mul_f32 v[118:119], v[194:195], v[118:119]
	v_pk_fma_f32 v[116:117], v[38:39], v[116:117], v[228:229]
	v_pk_fma_f32 v[118:119], v[40:41], v[118:119], v[230:231]
	v_cvt_pk_bf16_f32 v116, v116, v117
	v_cvt_pk_bf16_f32 v117, v118, v119
	global_store_dwordx2 v146, v[116:117], s[66:67] offset:512
	v_pk_mul_f32 v[120:121], v[120:121], v[204:205] op_sel_hi:[1,0]
	v_pk_mul_f32 v[122:123], v[122:123], v[204:205] op_sel_hi:[1,0]
	v_pk_mul_f32 v[120:121], v[196:197], v[120:121]
	v_pk_mul_f32 v[122:123], v[198:199], v[122:123]
	v_pk_fma_f32 v[120:121], v[42:43], v[120:121], v[232:233]
	v_pk_fma_f32 v[122:123], v[44:45], v[122:123], v[234:235]
	v_cvt_pk_bf16_f32 v120, v120, v121
	v_cvt_pk_bf16_f32 v121, v122, v123
	global_store_dwordx2 v146, v[120:121], s[66:67] offset:1024
	v_pk_mul_f32 v[124:125], v[124:125], v[204:205] op_sel_hi:[1,0]
	v_pk_mul_f32 v[126:127], v[126:127], v[204:205] op_sel_hi:[1,0]
	v_pk_mul_f32 v[124:125], v[200:201], v[124:125]
	v_pk_mul_f32 v[126:127], v[202:203], v[126:127]
	v_pk_fma_f32 v[124:125], v[46:47], v[124:125], v[236:237]
	v_pk_fma_f32 v[126:127], v[48:49], v[126:127], v[238:239]
	v_cvt_pk_bf16_f32 v124, v124, v125
	v_cvt_pk_bf16_f32 v125, v126, v127
	global_store_dwordx2 v146, v[124:125], s[66:67] offset:1536
	v_add_u32_e32 v146, 0x800, v146
	global_load_dwordx4 v[112:115], v144, s[46:47] nt
	global_load_dwordx4 v[116:119], v144, s[46:47] offset:1024 nt
	global_load_dwordx4 v[120:123], v144, s[46:47] offset:2048 nt
	global_load_dwordx4 v[124:127], v144, s[46:47] offset:3072 nt
	v_add_u32_e32 v144, 0x1000, v144
	s_waitcnt vmcnt(40)
	v_pk_mul_f32 v[242:243], v[128:129], v[128:129]
	v_pk_mul_f32 v[244:245], v[132:133], v[132:133]
	v_pk_mul_f32 v[246:247], v[130:131], v[130:131]
	v_pk_mul_f32 v[248:249], v[134:135], v[134:135]
	v_add_f32_e32 v204, v245, v244
	v_add_f32_e32 v205, v243, v242
	v_add_f32_e32 v204, v248, v204
	v_add_f32_e32 v205, v246, v205
	v_add_f32_e32 v204, v249, v204
	v_add_f32_e32 v205, v247, v205
	v_pk_mul_f32 v[242:243], v[136:137], v[136:137]
	v_pk_mul_f32 v[244:245], v[140:141], v[140:141]
	v_pk_mul_f32 v[246:247], v[138:139], v[138:139]
	v_pk_mul_f32 v[248:249], v[142:143], v[142:143]
	v_add_f32_e32 v206, v243, v242
	v_add_f32_e32 v207, v245, v244
	v_add_f32_e32 v206, v246, v206
	v_add_f32_e32 v207, v248, v207
	v_add_f32_e32 v206, v247, v206
	v_add_f32_e32 v207, v249, v207
	v_add_f32_e32 v204, v205, v204
	v_add_f32_e32 v204, v204, v206
	v_add_f32_e32 v204, v204, v207
	ds_swizzle_b32 v205, v204 offset:swizzle(SWAP,1)
	s_waitcnt lgkmcnt(0)
	v_add_f32_e32 v204, v204, v205
	ds_swizzle_b32 v205, v204 offset:swizzle(SWAP,2)
	s_waitcnt lgkmcnt(0)
	v_add_f32_e32 v204, v204, v205
	ds_swizzle_b32 v205, v204 offset:swizzle(SWAP,4)
	s_waitcnt lgkmcnt(0)
	v_add_f32_e32 v204, v204, v205
	ds_swizzle_b32 v205, v204 offset:swizzle(SWAP,8)
	s_waitcnt lgkmcnt(0)
	v_add_f32_e32 v204, v204, v205
	ds_swizzle_b32 v205, v204 offset:swizzle(SWAP,16)
	s_waitcnt lgkmcnt(0)
; __device__ __forceinline__ unsigned pk2(float lo, float hi) { const g_f32x2 f = {lo, hi}; return __builtin_bit_cast(unsigned, __builtin_convertvector(f, g_bf16x2)); }
; #define PN_LOAD(dst, rw) do { const float* s_ = (rw) < NLAT ? hlat + (size_t)(rw) * 1024 : hctx + (size_t)((rw) - NLAT) * 1024; \
;         _Pragma("unroll") for (int i = 0; i < 4; ++i) dst[i] = *(const float4*)(s_ + i * 256 + lane * 4); } while (0)
; __device__ __forceinline__ void p_norm(const float* hlat, const float* hctx, const float* g, const float* modl, int sh_off, int sc_off, bf16_t* A, int M,
;                                        const float* part, const float* cgate, float* hcout) {
;     ...
;     if (row < M) PN_LOAD(v, row);
;     while (row < M) {
;         const int nrow = row + stride;
;         if (nrow < M) PN_LOAD(nv, nrow);
;         const int r = row < NLAT ? (row >> 11) : 16;
;         float ss = 0.f;
; #pragma unroll
;         for (int i = 0; i < 4; ++i) {
;             if (part != nullptr && row >= NLAT) {
;                 const size_t po = (size_t)(row - NLAT) * 1024 + i * 256 + lane * 4;
;                 const float4 p0 = *(const float4*)(part + po), p1 = *(const float4*)(part + (size_t)4096 * 1024 + po), cg = *(const float4*)(cgate + i * 256 + lane * 4);
;                 v[i].x += cg.x * (p0.x + p1.x); v[i].y += cg.y * (p0.y + p1.y); v[i].z += cg.z * (p0.z + p1.z); v[i].w += cg.w * (p0.w + p1.w);
;                 *(float4*)(hcout + po) = v[i];
;             }
;             ss += v[i].x * v[i].x + v[i].y * v[i].y + v[i].z * v[i].z + v[i].w * v[i].w; }
;         ss = wave_sum(ss);
;         const float rstd = rsqrtf(ss * (1.0f / 1024.0f) + EPS);
;         const float* mr = modl + (size_t)r * 6144;
; #pragma unroll
;         for (int i = 0; i < 4; ++i) {
;             const int k = i * 256 + lane * 4;
;             const float4 gg = *(const float4*)(g + k), scv = *(const float4*)(mr + sc_off + k), shv = *(const float4*)(mr + sh_off + k);
;             const float o0 = v[i].x * rstd * gg.x * (1.0f + scv.x) + shv.x, o1 = v[i].y * rstd * gg.y * (1.0f + scv.y) + shv.y;
;             const float o2 = v[i].z * rstd * gg.z * (1.0f + scv.z) + shv.z, o3 = v[i].w * rstd * gg.w * (1.0f + scv.w) + shv.w;
;             uint2 w; w.x = pk2(o0, o1); w.y = pk2(o2, o3);
;             *(uint2*)(A + (size_t)row * 1024 + k) = w;
;         }
	v_add_f32_e32 v204, v204, v205
	v_mov_b32_e32 v205, v204
	s_nop 1
	v_permlane32_swap_b32_e32 v204, v205
	v_add_f32_e32 v204, v204, v205
	v_mov_b32_e32 v205, 0x358637bd
	v_fmamk_f32 v204, v204, 0x3a800000, v205
	v_rsq_f32_e32 v204, v204
	s_nop 0
	v_pk_mul_f32 v[128:129], v[128:129], v[204:205] op_sel_hi:[1,0]
	v_pk_mul_f32 v[130:131], v[130:131], v[204:205] op_sel_hi:[1,0]
	v_pk_mul_f32 v[128:129], v[188:189], v[128:129]
	v_pk_mul_f32 v[130:131], v[190:191], v[130:131]
	v_pk_fma_f32 v[128:129], v[34:35], v[128:129], v[224:225]
	v_pk_fma_f32 v[130:131], v[36:37], v[130:131], v[226:227]
	v_cvt_pk_bf16_f32 v128, v128, v129
	v_cvt_pk_bf16_f32 v129, v130, v131
	global_store_dwordx2 v146, v[128:129], s[66:67]
	v_pk_mul_f32 v[132:133], v[132:133], v[204:205] op_sel_hi:[1,0]
	v_pk_mul_f32 v[134:135], v[134:135], v[204:205] op_sel_hi:[1,0]
	v_pk_mul_f32 v[132:133], v[192:193], v[132:133]
	v_pk_mul_f32 v[134:135], v[194:195], v[134:135]
	v_pk_fma_f32 v[132:133], v[38:39], v[132:133], v[228:229]
	v_pk_fma_f32 v[134:135], v[40:41], v[134:135], v[230:231]
	v_cvt_pk_bf16_f32 v132, v132, v133
	v_cvt_pk_bf16_f32 v133, v134, v135
	global_store_dwordx2 v146, v[132:133], s[66:67] offset:512
	v_pk_mul_f32 v[136:137], v[136:137], v[204:205] op_sel_hi:[1,0]
	v_pk_mul_f32 v[138:139], v[138:139], v[204:205] op_sel_hi:[1,0]
	v_pk_mul_f32 v[136:137], v[196:197], v[136:137]
	v_pk_mul_f32 v[138:139], v[198:199], v[138:139]
	v_pk_fma_f32 v[136:137], v[42:43], v[136:137], v[232:233]
	v_pk_fma_f32 v[138:139], v[44:45], v[138:139], v[234:235]
	v_cvt_pk_bf16_f32 v136, v136, v137
	v_cvt_pk_bf16_f32 v137, v138, v139
	global_store_dwordx2 v146, v[136:137], s[66:67] offset:1024
	v_pk_mul_f32 v[140:141], v[140:141], v[204:205] op_sel_hi:[1,0]
	v_pk_mul_f32 v[142:143], v[142:143], v[204:205] op_sel_hi:[1,0]
	v_pk_mul_f32 v[140:141], v[200:201], v[140:141]
	v_pk_mul_f32 v[142:143], v[202:203], v[142:143]
	v_pk_fma_f32 v[140:141], v[46:47], v[140:141], v[236:237]
	v_pk_fma_f32 v[142:143], v[48:49], v[142:143], v[238:239]
	v_cvt_pk_bf16_f32 v140, v140, v141
	v_cvt_pk_bf16_f32 v141, v142, v143
	global_store_dwordx2 v146, v[140:141], s[66:67] offset:1536
	v_add_u32_e32 v146, 0x800, v146
	global_load_dwordx4 v[128:131], v144, s[46:47] nt
	global_load_dwordx4 v[132:135], v144, s[46:47] offset:1024 nt
	global_load_dwordx4 v[136:139], v144, s[46:47] offset:2048 nt
	global_load_dwordx4 v[140:143], v144, s[46:47] offset:3072 nt
	v_add_u32_e32 v144, 0x1000, v144
	s_waitcnt vmcnt(40)
	v_pk_mul_f32 v[242:243], v[156:157], v[156:157]
	v_pk_mul_f32 v[244:245], v[160:161], v[160:161]
	v_pk_mul_f32 v[246:247], v[158:159], v[158:159]
	v_pk_mul_f32 v[248:249], v[162:163], v[162:163]
	v_add_f32_e32 v204, v245, v244
	v_add_f32_e32 v205, v243, v242
	v_add_f32_e32 v204, v248, v204
	v_add_f32_e32 v205, v246, v205
	v_add_f32_e32 v204, v249, v204
	v_add_f32_e32 v205, v247, v205
	v_pk_mul_f32 v[242:243], v[164:165], v[164:165]
	v_pk_mul_f32 v[244:245], v[168:169], v[168:169]
	v_pk_mul_f32 v[246:247], v[166:167], v[166:167]
	v_pk_mul_f32 v[248:249], v[170:171], v[170:171]
	v_add_f32_e32 v206, v243, v242
	v_add_f32_e32 v207, v245, v244
	v_add_f32_e32 v206, v246, v206
	v_add_f32_e32 v207, v248, v207
	v_add_f32_e32 v206, v247, v206
	v_add_f32_e32 v207, v249, v207
	v_add_f32_e32 v204, v205, v204
	v_add_f32_e32 v204, v204, v206
	v_add_f32_e32 v204, v204, v207
	ds_swizzle_b32 v205, v204 offset:swizzle(SWAP,1)
	s_waitcnt lgkmcnt(0)
	v_add_f32_e32 v204, v204, v205
	ds_swizzle_b32 v205, v204 offset:swizzle(SWAP,2)
	s_waitcnt lgkmcnt(0)
	v_add_f32_e32 v204, v204, v205
	ds_swizzle_b32 v205, v204 offset:swizzle(SWAP,4)
	s_waitcnt lgkmcnt(0)
	v_add_f32_e32 v204, v204, v205
	ds_swizzle_b32 v205, v204 offset:swizzle(SWAP,8)
	s_waitcnt lgkmcnt(0)
	v_add_f32_e32 v204, v204, v205
	ds_swizzle_b32 v205, v204 offset:swizzle(SWAP,16)
	s_waitcnt lgkmcnt(0)
	v_add_f32_e32 v204, v204, v205
	v_mov_b32_e32 v205, v204
	s_nop 1
	v_permlane32_swap_b32_e32 v204, v205
	v_add_f32_e32 v204, v204, v205
	v_mov_b32_e32 v205, 0x358637bd
	v_fmamk_f32 v204, v204, 0x3a800000, v205
	v_rsq_f32_e32 v204, v204
	s_nop 0
	v_pk_mul_f32 v[156:157], v[156:157], v[204:205] op_sel_hi:[1,0]
	v_pk_mul_f32 v[158:159], v[158:159], v[204:205] op_sel_hi:[1,0]
	v_pk_mul_f32 v[156:157], v[188:189], v[156:157]
	v_pk_mul_f32 v[158:159], v[190:191], v[158:159]
	v_pk_fma_f32 v[156:157], v[34:35], v[156:157], v[224:225]
	v_pk_fma_f32 v[158:159], v[36:37], v[158:159], v[226:227]
	v_cvt_pk_bf16_f32 v156, v156, v157
	v_cvt_pk_bf16_f32 v157, v158, v159
	global_store_dwordx2 v146, v[156:157], s[66:67]
	v_pk_mul_f32 v[160:161], v[160:161], v[204:205] op_sel_hi:[1,0]
	v_pk_mul_f32 v[162:163], v[162:163], v[204:205] op_sel_hi:[1,0]
	v_pk_mul_f32 v[160:161], v[192:193], v[160:161]
	v_pk_mul_f32 v[162:163], v[194:195], v[162:163]
	v_pk_fma_f32 v[160:161], v[38:39], v[160:161], v[228:229]
	v_pk_fma_f32 v[162:163], v[40:41], v[162:163], v[230:231]
	v_cvt_pk_bf16_f32 v160, v160, v161
	v_cvt_pk_bf16_f32 v161, v162, v163
	global_store_dwordx2 v146, v[160:161], s[66:67] offset:512
	v_pk_mul_f32 v[164:165], v[164:165], v[204:205] op_sel_hi:[1,0]
	v_pk_mul_f32 v[166:167], v[166:167], v[204:205] op_sel_hi:[1,0]
	v_pk_mul_f32 v[164:165], v[196:197], v[164:165]
	v_pk_mul_f32 v[166:167], v[198:199], v[166:167]
	v_pk_fma_f32 v[164:165], v[42:43], v[164:165], v[232:233]
	v_pk_fma_f32 v[166:167], v[44:45], v[166:167], v[234:235]
	v_cvt_pk_bf16_f32 v164, v164, v165
	v_cvt_pk_bf16_f32 v165, v166, v167
	global_store_dwordx2 v146, v[164:165], s[66:67] offset:1024
	v_pk_mul_f32 v[168:169], v[168:169], v[204:205] op_sel_hi:[1,0]
	v_pk_mul_f32 v[170:171], v[170:171], v[204:205] op_sel_hi:[1,0]
	v_pk_mul_f32 v[168:169], v[200:201], v[168:169]
	v_pk_mul_f32 v[170:171], v[202:203], v[170:171]
	v_pk_fma_f32 v[168:169], v[46:47], v[168:169], v[236:237]
	v_pk_fma_f32 v[170:171], v[48:49], v[170:171], v[238:239]
	v_cvt_pk_bf16_f32 v168, v168, v169
	v_cvt_pk_bf16_f32 v169, v170, v171
	global_store_dwordx2 v146, v[168:169], s[66:67] offset:1536
	v_add_u32_e32 v146, 0x800, v146
	s_waitcnt vmcnt(36)
; __device__ __forceinline__ unsigned pk2(float lo, float hi) { const g_f32x2 f = {lo, hi}; return __builtin_bit_cast(unsigned, __builtin_convertvector(f, g_bf16x2)); }
; __device__ __forceinline__ void p_norm(const float* hlat, const float* hctx, const float* g, const float* modl, int sh_off, int sc_off, bf16_t* A, int M,
;                                        const float* part, const float* cgate, float* hcout) {
;     ...
;         float ss = 0.f;
; #pragma unroll
;         for (int i = 0; i < 4; ++i) {
;             if (part != nullptr && row >= NLAT) {
;                 const size_t po = (size_t)(row - NLAT) * 1024 + i * 256 + lane * 4;
;                 const float4 p0 = *(const float4*)(part + po), p1 = *(const float4*)(part + (size_t)4096 * 1024 + po), cg = *(const float4*)(cgate + i * 256 + lane * 4);
;                 v[i].x += cg.x * (p0.x + p1.x); v[i].y += cg.y * (p0.y + p1.y); v[i].z += cg.z * (p0.z + p1.z); v[i].w += cg.w * (p0.w + p1.w);
;                 *(float4*)(hcout + po) = v[i];
;             }
;             ss += v[i].x * v[i].x + v[i].y * v[i].y + v[i].z * v[i].z + v[i].w * v[i].w; }
;         ss = wave_sum(ss);
;         const float rstd = rsqrtf(ss * (1.0f / 1024.0f) + EPS);
;         const float* mr = modl + (size_t)r * 6144;
; #pragma unroll
;         for (int i = 0; i < 4; ++i) {
;             const int k = i * 256 + lane * 4;
;             const float4 gg = *(const float4*)(g + k), scv = *(const float4*)(mr + sc_off + k), shv = *(const float4*)(mr + sh_off + k);
;             const float o0 = v[i].x * rstd * gg.x * (1.0f + scv.x) + shv.x, o1 = v[i].y * rstd * gg.y * (1.0f + scv.y) + shv.y;
;             const float o2 = v[i].z * rstd * gg.z * (1.0f + scv.z) + shv.z, o3 = v[i].w * rstd * gg.w * (1.0f + scv.w) + shv.w;
;             uint2 w; w.x = pk2(o0, o1); w.y = pk2(o2, o3);
;             *(uint2*)(A + (size_t)row * 1024 + k) = w;
;         }
	v_pk_mul_f32 v[242:243], v[172:173], v[172:173]
	v_pk_mul_f32 v[244:245], v[176:177], v[176:177]
	v_pk_mul_f32 v[246:247], v[174:175], v[174:175]
	v_pk_mul_f32 v[248:249], v[178:179], v[178:179]
	v_add_f32_e32 v204, v245, v244
	v_add_f32_e32 v205, v243, v242
	v_add_f32_e32 v204, v248, v204
	v_add_f32_e32 v205, v246, v205
	v_add_f32_e32 v204, v249, v204
	v_add_f32_e32 v205, v247, v205
	v_pk_mul_f32 v[242:243], v[180:181], v[180:181]
	v_pk_mul_f32 v[244:245], v[184:185], v[184:185]
	v_pk_mul_f32 v[246:247], v[182:183], v[182:183]
	v_pk_mul_f32 v[248:249], v[186:187], v[186:187]
	v_add_f32_e32 v206, v243, v242
	v_add_f32_e32 v207, v245, v244
	v_add_f32_e32 v206, v246, v206
	v_add_f32_e32 v207, v248, v207
	v_add_f32_e32 v206, v247, v206
	v_add_f32_e32 v207, v249, v207
	v_add_f32_e32 v204, v205, v204
	v_add_f32_e32 v204, v204, v206
	v_add_f32_e32 v204, v204, v207
	ds_swizzle_b32 v205, v204 offset:swizzle(SWAP,1)
	s_waitcnt lgkmcnt(0)
	v_add_f32_e32 v204, v204, v205
	ds_swizzle_b32 v205, v204 offset:swizzle(SWAP,2)
	s_waitcnt lgkmcnt(0)
	v_add_f32_e32 v204, v204, v205
	ds_swizzle_b32 v205, v204 offset:swizzle(SWAP,4)
	s_waitcnt lgkmcnt(0)
	v_add_f32_e32 v204, v204, v205
	ds_swizzle_b32 v205, v204 offset:swizzle(SWAP,8)
	s_waitcnt lgkmcnt(0)
	v_add_f32_e32 v204, v204, v205
	ds_swizzle_b32 v205, v204 offset:swizzle(SWAP,16)
	s_waitcnt lgkmcnt(0)
	v_add_f32_e32 v204, v204, v205
	v_mov_b32_e32 v205, v204
	s_nop 1
	v_permlane32_swap_b32_e32 v204, v205
	v_add_f32_e32 v204, v204, v205
	v_mov_b32_e32 v205, 0x358637bd
	v_fmamk_f32 v204, v204, 0x3a800000, v205
	v_rsq_f32_e32 v204, v204
	s_nop 0
	v_pk_mul_f32 v[172:173], v[172:173], v[204:205] op_sel_hi:[1,0]
	v_pk_mul_f32 v[174:175], v[174:175], v[204:205] op_sel_hi:[1,0]
	v_pk_mul_f32 v[172:173], v[188:189], v[172:173]
	v_pk_mul_f32 v[174:175], v[190:191], v[174:175]
	v_pk_fma_f32 v[172:173], v[34:35], v[172:173], v[224:225]
	v_pk_fma_f32 v[174:175], v[36:37], v[174:175], v[226:227]
	v_cvt_pk_bf16_f32 v172, v172, v173
	v_cvt_pk_bf16_f32 v173, v174, v175
	global_store_dwordx2 v146, v[172:173], s[66:67]
	v_pk_mul_f32 v[176:177], v[176:177], v[204:205] op_sel_hi:[1,0]
	v_pk_mul_f32 v[178:179], v[178:179], v[204:205] op_sel_hi:[1,0]
	v_pk_mul_f32 v[176:177], v[192:193], v[176:177]
	v_pk_mul_f32 v[178:179], v[194:195], v[178:179]
	v_pk_fma_f32 v[176:177], v[38:39], v[176:177], v[228:229]
	v_pk_fma_f32 v[178:179], v[40:41], v[178:179], v[230:231]
	v_cvt_pk_bf16_f32 v176, v176, v177
	v_cvt_pk_bf16_f32 v177, v178, v179
	global_store_dwordx2 v146, v[176:177], s[66:67] offset:512
	v_pk_mul_f32 v[180:181], v[180:181], v[204:205] op_sel_hi:[1,0]
	v_pk_mul_f32 v[182:183], v[182:183], v[204:205] op_sel_hi:[1,0]
	v_pk_mul_f32 v[180:181], v[196:197], v[180:181]
	v_pk_mul_f32 v[182:183], v[198:199], v[182:183]
	v_pk_fma_f32 v[180:181], v[42:43], v[180:181], v[232:233]
	v_pk_fma_f32 v[182:183], v[44:45], v[182:183], v[234:235]
	v_cvt_pk_bf16_f32 v180, v180, v181
	v_cvt_pk_bf16_f32 v181, v182, v183
	global_store_dwordx2 v146, v[180:181], s[66:67] offset:1024
	v_pk_mul_f32 v[184:185], v[184:185], v[204:205] op_sel_hi:[1,0]
	v_pk_mul_f32 v[186:187], v[186:187], v[204:205] op_sel_hi:[1,0]
	v_pk_mul_f32 v[184:185], v[200:201], v[184:185]
	v_pk_mul_f32 v[186:187], v[202:203], v[186:187]
	v_pk_fma_f32 v[184:185], v[46:47], v[184:185], v[236:237]
	v_pk_fma_f32 v[186:187], v[48:49], v[186:187], v[238:239]
	v_cvt_pk_bf16_f32 v184, v184, v185
	v_cvt_pk_bf16_f32 v185, v186, v187
	global_store_dwordx2 v146, v[184:185], s[66:67] offset:1536
	v_add_u32_e32 v146, 0x800, v146
	s_waitcnt vmcnt(32)
	v_pk_mul_f32 v[242:243], v[80:81], v[80:81]
	v_pk_mul_f32 v[244:245], v[84:85], v[84:85]
	v_pk_mul_f32 v[246:247], v[82:83], v[82:83]
	v_pk_mul_f32 v[248:249], v[86:87], v[86:87]
	v_add_f32_e32 v204, v245, v244
	v_add_f32_e32 v205, v243, v242
	v_add_f32_e32 v204, v248, v204
	v_add_f32_e32 v205, v246, v205
	v_add_f32_e32 v204, v249, v204
	v_add_f32_e32 v205, v247, v205
	v_pk_mul_f32 v[242:243], v[88:89], v[88:89]
	v_pk_mul_f32 v[244:245], v[92:93], v[92:93]
	v_pk_mul_f32 v[246:247], v[90:91], v[90:91]
	v_pk_mul_f32 v[248:249], v[94:95], v[94:95]
	v_add_f32_e32 v206, v243, v242
	v_add_f32_e32 v207, v245, v244
	v_add_f32_e32 v206, v246, v206
	v_add_f32_e32 v207, v248, v207
	v_add_f32_e32 v206, v247, v206
	v_add_f32_e32 v207, v249, v207
	v_add_f32_e32 v204, v205, v204
	v_add_f32_e32 v204, v204, v206
	v_add_f32_e32 v204, v204, v207
	ds_swizzle_b32 v205, v204 offset:swizzle(SWAP,1)
	s_waitcnt lgkmcnt(0)
	v_add_f32_e32 v204, v204, v205
	ds_swizzle_b32 v205, v204 offset:swizzle(SWAP,2)
	s_waitcnt lgkmcnt(0)
	v_add_f32_e32 v204, v204, v205
	ds_swizzle_b32 v205, v204 offset:swizzle(SWAP,4)
	s_waitcnt lgkmcnt(0)
	v_add_f32_e32 v204, v204, v205
	ds_swizzle_b32 v205, v204 offset:swizzle(SWAP,8)
	s_waitcnt lgkmcnt(0)
	v_add_f32_e32 v204, v204, v205
	ds_swizzle_b32 v205, v204 offset:swizzle(SWAP,16)
	s_waitcnt lgkmcnt(0)
; __device__ __forceinline__ unsigned pk2(float lo, float hi) { const g_f32x2 f = {lo, hi}; return __builtin_bit_cast(unsigned, __builtin_convertvector(f, g_bf16x2)); }
; __device__ __forceinline__ void p_norm(const float* hlat, const float* hctx, const float* g, const float* modl, int sh_off, int sc_off, bf16_t* A, int M,
;                                        const float* part, const float* cgate, float* hcout) {
;     ...
;         float ss = 0.f;
; #pragma unroll
;         for (int i = 0; i < 4; ++i) {
;             if (part != nullptr && row >= NLAT) {
;                 const size_t po = (size_t)(row - NLAT) * 1024 + i * 256 + lane * 4;
;                 const float4 p0 = *(const float4*)(part + po), p1 = *(const float4*)(part + (size_t)4096 * 1024 + po), cg = *(const float4*)(cgate + i * 256 + lane * 4);
;                 v[i].x += cg.x * (p0.x + p1.x); v[i].y += cg.y * (p0.y + p1.y); v[i].z += cg.z * (p0.z + p1.z); v[i].w += cg.w * (p0.w + p1.w);
;                 *(float4*)(hcout + po) = v[i];
;             }
;             ss += v[i].x * v[i].x + v[i].y * v[i].y + v[i].z * v[i].z + v[i].w * v[i].w; }
;         ss = wave_sum(ss);
;         const float rstd = rsqrtf(ss * (1.0f / 1024.0f) + EPS);
;         const float* mr = modl + (size_t)r * 6144;
; #pragma unroll
;         for (int i = 0; i < 4; ++i) {
;             const int k = i * 256 + lane * 4;
;             const float4 gg = *(const float4*)(g + k), scv = *(const float4*)(mr + sc_off + k), shv = *(const float4*)(mr + sh_off + k);
;             const float o0 = v[i].x * rstd * gg.x * (1.0f + scv.x) + shv.x, o1 = v[i].y * rstd * gg.y * (1.0f + scv.y) + shv.y;
;             const float o2 = v[i].z * rstd * gg.z * (1.0f + scv.z) + shv.z, o3 = v[i].w * rstd * gg.w * (1.0f + scv.w) + shv.w;
;             uint2 w; w.x = pk2(o0, o1); w.y = pk2(o2, o3);
;             *(uint2*)(A + (size_t)row * 1024 + k) = w;
;         }
	v_add_f32_e32 v204, v204, v205
	v_mov_b32_e32 v205, v204
	s_nop 1
	v_permlane32_swap_b32_e32 v204, v205
	v_add_f32_e32 v204, v204, v205
	v_mov_b32_e32 v205, 0x358637bd
	v_fmamk_f32 v204, v204, 0x3a800000, v205
	v_rsq_f32_e32 v204, v204
	s_nop 0
	v_pk_mul_f32 v[80:81], v[80:81], v[204:205] op_sel_hi:[1,0]
	v_pk_mul_f32 v[82:83], v[82:83], v[204:205] op_sel_hi:[1,0]
	v_pk_mul_f32 v[80:81], v[188:189], v[80:81]
	v_pk_mul_f32 v[82:83], v[190:191], v[82:83]
	v_pk_fma_f32 v[80:81], v[34:35], v[80:81], v[224:225]
	v_pk_fma_f32 v[82:83], v[36:37], v[82:83], v[226:227]
	v_cvt_pk_bf16_f32 v80, v80, v81
	v_cvt_pk_bf16_f32 v81, v82, v83
	global_store_dwordx2 v146, v[80:81], s[66:67]
	v_pk_mul_f32 v[84:85], v[84:85], v[204:205] op_sel_hi:[1,0]
	v_pk_mul_f32 v[86:87], v[86:87], v[204:205] op_sel_hi:[1,0]
	v_pk_mul_f32 v[84:85], v[192:193], v[84:85]
	v_pk_mul_f32 v[86:87], v[194:195], v[86:87]
	v_pk_fma_f32 v[84:85], v[38:39], v[84:85], v[228:229]
	v_pk_fma_f32 v[86:87], v[40:41], v[86:87], v[230:231]
	v_cvt_pk_bf16_f32 v84, v84, v85
	v_cvt_pk_bf16_f32 v85, v86, v87
	global_store_dwordx2 v146, v[84:85], s[66:67] offset:512
	v_pk_mul_f32 v[88:89], v[88:89], v[204:205] op_sel_hi:[1,0]
	v_pk_mul_f32 v[90:91], v[90:91], v[204:205] op_sel_hi:[1,0]
	v_pk_mul_f32 v[88:89], v[196:197], v[88:89]
	v_pk_mul_f32 v[90:91], v[198:199], v[90:91]
	v_pk_fma_f32 v[88:89], v[42:43], v[88:89], v[232:233]
	v_pk_fma_f32 v[90:91], v[44:45], v[90:91], v[234:235]
	v_cvt_pk_bf16_f32 v88, v88, v89
	v_cvt_pk_bf16_f32 v89, v90, v91
	global_store_dwordx2 v146, v[88:89], s[66:67] offset:1024
	v_pk_mul_f32 v[92:93], v[92:93], v[204:205] op_sel_hi:[1,0]
	v_pk_mul_f32 v[94:95], v[94:95], v[204:205] op_sel_hi:[1,0]
	v_pk_mul_f32 v[92:93], v[200:201], v[92:93]
	v_pk_mul_f32 v[94:95], v[202:203], v[94:95]
	v_pk_fma_f32 v[92:93], v[46:47], v[92:93], v[236:237]
	v_pk_fma_f32 v[94:95], v[48:49], v[94:95], v[238:239]
	v_cvt_pk_bf16_f32 v92, v92, v93
	v_cvt_pk_bf16_f32 v93, v94, v95
	global_store_dwordx2 v146, v[92:93], s[66:67] offset:1536
	v_add_u32_e32 v146, 0x800, v146
	s_waitcnt vmcnt(28)
	v_pk_mul_f32 v[242:243], v[96:97], v[96:97]
	v_pk_mul_f32 v[244:245], v[100:101], v[100:101]
	v_pk_mul_f32 v[246:247], v[98:99], v[98:99]
	v_pk_mul_f32 v[248:249], v[102:103], v[102:103]
	v_add_f32_e32 v204, v245, v244
	v_add_f32_e32 v205, v243, v242
	v_add_f32_e32 v204, v248, v204
	v_add_f32_e32 v205, v246, v205
	v_add_f32_e32 v204, v249, v204
	v_add_f32_e32 v205, v247, v205
	v_pk_mul_f32 v[242:243], v[104:105], v[104:105]
	v_pk_mul_f32 v[244:245], v[108:109], v[108:109]
	v_pk_mul_f32 v[246:247], v[106:107], v[106:107]
	v_pk_mul_f32 v[248:249], v[110:111], v[110:111]
	v_add_f32_e32 v206, v243, v242
	v_add_f32_e32 v207, v245, v244
	v_add_f32_e32 v206, v246, v206
	v_add_f32_e32 v207, v248, v207
	v_add_f32_e32 v206, v247, v206
	v_add_f32_e32 v207, v249, v207
	v_add_f32_e32 v204, v205, v204
	v_add_f32_e32 v204, v204, v206
	v_add_f32_e32 v204, v204, v207
	ds_swizzle_b32 v205, v204 offset:swizzle(SWAP,1)
	s_waitcnt lgkmcnt(0)
	v_add_f32_e32 v204, v204, v205
	ds_swizzle_b32 v205, v204 offset:swizzle(SWAP,2)
	s_waitcnt lgkmcnt(0)
	v_add_f32_e32 v204, v204, v205
	ds_swizzle_b32 v205, v204 offset:swizzle(SWAP,4)
	s_waitcnt lgkmcnt(0)
	v_add_f32_e32 v204, v204, v205
	ds_swizzle_b32 v205, v204 offset:swizzle(SWAP,8)
	s_waitcnt lgkmcnt(0)
	v_add_f32_e32 v204, v204, v205
	ds_swizzle_b32 v205, v204 offset:swizzle(SWAP,16)
	s_waitcnt lgkmcnt(0)
	v_add_f32_e32 v204, v204, v205
	v_mov_b32_e32 v205, v204
	s_nop 1
	v_permlane32_swap_b32_e32 v204, v205
	v_add_f32_e32 v204, v204, v205
	v_mov_b32_e32 v205, 0x358637bd
	v_fmamk_f32 v204, v204, 0x3a800000, v205
	v_rsq_f32_e32 v204, v204
	s_nop 0
	v_pk_mul_f32 v[96:97], v[96:97], v[204:205] op_sel_hi:[1,0]
	v_pk_mul_f32 v[98:99], v[98:99], v[204:205] op_sel_hi:[1,0]
	v_pk_mul_f32 v[96:97], v[188:189], v[96:97]
	v_pk_mul_f32 v[98:99], v[190:191], v[98:99]
	v_pk_fma_f32 v[96:97], v[34:35], v[96:97], v[224:225]
	v_pk_fma_f32 v[98:99], v[36:37], v[98:99], v[226:227]
	v_cvt_pk_bf16_f32 v96, v96, v97
	v_cvt_pk_bf16_f32 v97, v98, v99
	global_store_dwordx2 v146, v[96:97], s[66:67]
	v_pk_mul_f32 v[100:101], v[100:101], v[204:205] op_sel_hi:[1,0]
	v_pk_mul_f32 v[102:103], v[102:103], v[204:205] op_sel_hi:[1,0]
	v_pk_mul_f32 v[100:101], v[192:193], v[100:101]
	v_pk_mul_f32 v[102:103], v[194:195], v[102:103]
	v_pk_fma_f32 v[100:101], v[38:39], v[100:101], v[228:229]
	v_pk_fma_f32 v[102:103], v[40:41], v[102:103], v[230:231]
	v_cvt_pk_bf16_f32 v100, v100, v101
	v_cvt_pk_bf16_f32 v101, v102, v103
	global_store_dwordx2 v146, v[100:101], s[66:67] offset:512
	v_pk_mul_f32 v[104:105], v[104:105], v[204:205] op_sel_hi:[1,0]
	v_pk_mul_f32 v[106:107], v[106:107], v[204:205] op_sel_hi:[1,0]
	v_pk_mul_f32 v[104:105], v[196:197], v[104:105]
	v_pk_mul_f32 v[106:107], v[198:199], v[106:107]
	v_pk_fma_f32 v[104:105], v[42:43], v[104:105], v[232:233]
	v_pk_fma_f32 v[106:107], v[44:45], v[106:107], v[234:235]
	v_cvt_pk_bf16_f32 v104, v104, v105
	v_cvt_pk_bf16_f32 v105, v106, v107
	global_store_dwordx2 v146, v[104:105], s[66:67] offset:1024
	v_pk_mul_f32 v[108:109], v[108:109], v[204:205] op_sel_hi:[1,0]
	v_pk_mul_f32 v[110:111], v[110:111], v[204:205] op_sel_hi:[1,0]
	v_pk_mul_f32 v[108:109], v[200:201], v[108:109]
	v_pk_mul_f32 v[110:111], v[202:203], v[110:111]
	v_pk_fma_f32 v[108:109], v[46:47], v[108:109], v[236:237]
	v_pk_fma_f32 v[110:111], v[48:49], v[110:111], v[238:239]
	v_cvt_pk_bf16_f32 v108, v108, v109
	v_cvt_pk_bf16_f32 v109, v110, v111
	global_store_dwordx2 v146, v[108:109], s[66:67] offset:1536
	v_add_u32_e32 v146, 0x800, v146
	s_waitcnt vmcnt(24)
; __device__ __forceinline__ unsigned pk2(float lo, float hi) { const g_f32x2 f = {lo, hi}; return __builtin_bit_cast(unsigned, __builtin_convertvector(f, g_bf16x2)); }
; __device__ __forceinline__ void p_norm(const float* hlat, const float* hctx, const float* g, const float* modl, int sh_off, int sc_off, bf16_t* A, int M,
;                                        const float* part, const float* cgate, float* hcout) {
;     ...
;         float ss = 0.f;
; #pragma unroll
;         for (int i = 0; i < 4; ++i) {
;             if (part != nullptr && row >= NLAT) {
;                 const size_t po = (size_t)(row - NLAT) * 1024 + i * 256 + lane * 4;
;                 const float4 p0 = *(const float4*)(part + po), p1 = *(const float4*)(part + (size_t)4096 * 1024 + po), cg = *(const float4*)(cgate + i * 256 + lane * 4);
;                 v[i].x += cg.x * (p0.x + p1.x); v[i].y += cg.y * (p0.y + p1.y); v[i].z += cg.z * (p0.z + p1.z); v[i].w += cg.w * (p0.w + p1.w);
;                 *(float4*)(hcout + po) = v[i];
;             }
;             ss += v[i].x * v[i].x + v[i].y * v[i].y + v[i].z * v[i].z + v[i].w * v[i].w; }
;         ss = wave_sum(ss);
;         const float rstd = rsqrtf(ss * (1.0f / 1024.0f) + EPS);
;         const float* mr = modl + (size_t)r * 6144;
; #pragma unroll
;         for (int i = 0; i < 4; ++i) {
;             const int k = i * 256 + lane * 4;
;             const float4 gg = *(const float4*)(g + k), scv = *(const float4*)(mr + sc_off + k), shv = *(const float4*)(mr + sh_off + k);
;             const float o0 = v[i].x * rstd * gg.x * (1.0f + scv.x) + shv.x, o1 = v[i].y * rstd * gg.y * (1.0f + scv.y) + shv.y;
;             const float o2 = v[i].z * rstd * gg.z * (1.0f + scv.z) + shv.z, o3 = v[i].w * rstd * gg.w * (1.0f + scv.w) + shv.w;
;             uint2 w; w.x = pk2(o0, o1); w.y = pk2(o2, o3);
;             *(uint2*)(A + (size_t)row * 1024 + k) = w;
;         }
	v_pk_mul_f32 v[242:243], v[112:113], v[112:113]
	v_pk_mul_f32 v[244:245], v[116:117], v[116:117]
	v_pk_mul_f32 v[246:247], v[114:115], v[114:115]
	v_pk_mul_f32 v[248:249], v[118:119], v[118:119]
	v_add_f32_e32 v204, v245, v244
	v_add_f32_e32 v205, v243, v242
	v_add_f32_e32 v204, v248, v204
	v_add_f32_e32 v205, v246, v205
	v_add_f32_e32 v204, v249, v204
	v_add_f32_e32 v205, v247, v205
	v_pk_mul_f32 v[242:243], v[120:121], v[120:121]
	v_pk_mul_f32 v[244:245], v[124:125], v[124:125]
	v_pk_mul_f32 v[246:247], v[122:123], v[122:123]
	v_pk_mul_f32 v[248:249], v[126:127], v[126:127]
	v_add_f32_e32 v206, v243, v242
	v_add_f32_e32 v207, v245, v244
	v_add_f32_e32 v206, v246, v206
	v_add_f32_e32 v207, v248, v207
	v_add_f32_e32 v206, v247, v206
	v_add_f32_e32 v207, v249, v207
	v_add_f32_e32 v204, v205, v204
	v_add_f32_e32 v204, v204, v206
	v_add_f32_e32 v204, v204, v207
	ds_swizzle_b32 v205, v204 offset:swizzle(SWAP,1)
	s_waitcnt lgkmcnt(0)
	v_add_f32_e32 v204, v204, v205
	ds_swizzle_b32 v205, v204 offset:swizzle(SWAP,2)
	s_waitcnt lgkmcnt(0)
	v_add_f32_e32 v204, v204, v205
	ds_swizzle_b32 v205, v204 offset:swizzle(SWAP,4)
	s_waitcnt lgkmcnt(0)
	v_add_f32_e32 v204, v204, v205
	ds_swizzle_b32 v205, v204 offset:swizzle(SWAP,8)
	s_waitcnt lgkmcnt(0)
	v_add_f32_e32 v204, v204, v205
	ds_swizzle_b32 v205, v204 offset:swizzle(SWAP,16)
	s_waitcnt lgkmcnt(0)
	v_add_f32_e32 v204, v204, v205
	v_mov_b32_e32 v205, v204
	s_nop 1
	v_permlane32_swap_b32_e32 v204, v205
	v_add_f32_e32 v204, v204, v205
	v_mov_b32_e32 v205, 0x358637bd
	v_fmamk_f32 v204, v204, 0x3a800000, v205
	v_rsq_f32_e32 v204, v204
	s_nop 0
	v_pk_mul_f32 v[112:113], v[112:113], v[204:205] op_sel_hi:[1,0]
	v_pk_mul_f32 v[114:115], v[114:115], v[204:205] op_sel_hi:[1,0]
	v_pk_mul_f32 v[112:113], v[188:189], v[112:113]
	v_pk_mul_f32 v[114:115], v[190:191], v[114:115]
	v_pk_fma_f32 v[112:113], v[34:35], v[112:113], v[224:225]
	v_pk_fma_f32 v[114:115], v[36:37], v[114:115], v[226:227]
	v_cvt_pk_bf16_f32 v112, v112, v113
	v_cvt_pk_bf16_f32 v113, v114, v115
	global_store_dwordx2 v146, v[112:113], s[66:67]
	v_pk_mul_f32 v[116:117], v[116:117], v[204:205] op_sel_hi:[1,0]
	v_pk_mul_f32 v[118:119], v[118:119], v[204:205] op_sel_hi:[1,0]
	v_pk_mul_f32 v[116:117], v[192:193], v[116:117]
	v_pk_mul_f32 v[118:119], v[194:195], v[118:119]
	v_pk_fma_f32 v[116:117], v[38:39], v[116:117], v[228:229]
	v_pk_fma_f32 v[118:119], v[40:41], v[118:119], v[230:231]
	v_cvt_pk_bf16_f32 v116, v116, v117
	v_cvt_pk_bf16_f32 v117, v118, v119
	global_store_dwordx2 v146, v[116:117], s[66:67] offset:512
	v_pk_mul_f32 v[120:121], v[120:121], v[204:205] op_sel_hi:[1,0]
	v_pk_mul_f32 v[122:123], v[122:123], v[204:205] op_sel_hi:[1,0]
	v_pk_mul_f32 v[120:121], v[196:197], v[120:121]
	v_pk_mul_f32 v[122:123], v[198:199], v[122:123]
	v_pk_fma_f32 v[120:121], v[42:43], v[120:121], v[232:233]
	v_pk_fma_f32 v[122:123], v[44:45], v[122:123], v[234:235]
	v_cvt_pk_bf16_f32 v120, v120, v121
	v_cvt_pk_bf16_f32 v121, v122, v123
	global_store_dwordx2 v146, v[120:121], s[66:67] offset:1024
	v_pk_mul_f32 v[124:125], v[124:125], v[204:205] op_sel_hi:[1,0]
	v_pk_mul_f32 v[126:127], v[126:127], v[204:205] op_sel_hi:[1,0]
	v_pk_mul_f32 v[124:125], v[200:201], v[124:125]
	v_pk_mul_f32 v[126:127], v[202:203], v[126:127]
	v_pk_fma_f32 v[124:125], v[46:47], v[124:125], v[236:237]
	v_pk_fma_f32 v[126:127], v[48:49], v[126:127], v[238:239]
	v_cvt_pk_bf16_f32 v124, v124, v125
	v_cvt_pk_bf16_f32 v125, v126, v127
	global_store_dwordx2 v146, v[124:125], s[66:67] offset:1536
	v_add_u32_e32 v146, 0x800, v146
	s_waitcnt vmcnt(20)
; __device__ __forceinline__ unsigned pk2(float lo, float hi) { const g_f32x2 f = {lo, hi}; return __builtin_bit_cast(unsigned, __builtin_convertvector(f, g_bf16x2)); }
; __device__ __forceinline__ void p_norm(const float* hlat, const float* hctx, const float* g, const float* modl, int sh_off, int sc_off, bf16_t* A, int M,
;                                        const float* part, const float* cgate, float* hcout) {
;     ...
;         float ss = 0.f;
; #pragma unroll
;         for (int i = 0; i < 4; ++i) {
;             if (part != nullptr && row >= NLAT) {
;                 const size_t po = (size_t)(row - NLAT) * 1024 + i * 256 + lane * 4;
;                 const float4 p0 = *(const float4*)(part + po), p1 = *(const float4*)(part + (size_t)4096 * 1024 + po), cg = *(const float4*)(cgate + i * 256 + lane * 4);
;                 v[i].x += cg.x * (p0.x + p1.x); v[i].y += cg.y * (p0.y + p1.y); v[i].z += cg.z * (p0.z + p1.z); v[i].w += cg.w * (p0.w + p1.w);
;                 *(float4*)(hcout + po) = v[i];
;             }
;             ss += v[i].x * v[i].x + v[i].y * v[i].y + v[i].z * v[i].z + v[i].w * v[i].w; }
;         ss = wave_sum(ss);
;         const float rstd = rsqrtf(ss * (1.0f / 1024.0f) + EPS);
;         const float* mr = modl + (size_t)r * 6144;
; #pragma unroll
;         for (int i = 0; i < 4; ++i) {
;             const int k = i * 256 + lane * 4;
;             const float4 gg = *(const float4*)(g + k), scv = *(const float4*)(mr + sc_off + k), shv = *(const float4*)(mr + sh_off + k);
;             const float o0 = v[i].x * rstd * gg.x * (1.0f + scv.x) + shv.x, o1 = v[i].y * rstd * gg.y * (1.0f + scv.y) + shv.y;
;             const float o2 = v[i].z * rstd * gg.z * (1.0f + scv.z) + shv.z, o3 = v[i].w * rstd * gg.w * (1.0f + scv.w) + shv.w;
;             uint2 w; w.x = pk2(o0, o1); w.y = pk2(o2, o3);
;             *(uint2*)(A + (size_t)row * 1024 + k) = w;
;         }
	v_pk_mul_f32 v[242:243], v[128:129], v[128:129]
	v_pk_mul_f32 v[244:245], v[132:133], v[132:133]
	v_pk_mul_f32 v[246:247], v[130:131], v[130:131]
	v_pk_mul_f32 v[248:249], v[134:135], v[134:135]
	v_add_f32_e32 v204, v245, v244
	v_add_f32_e32 v205, v243, v242
	v_add_f32_e32 v204, v248, v204
	v_add_f32_e32 v205, v246, v205
	v_add_f32_e32 v204, v249, v204
	v_add_f32_e32 v205, v247, v205
	v_pk_mul_f32 v[242:243], v[136:137], v[136:137]
	v_pk_mul_f32 v[244:245], v[140:141], v[140:141]
	v_pk_mul_f32 v[246:247], v[138:139], v[138:139]
	v_pk_mul_f32 v[248:249], v[142:143], v[142:143]
	v_add_f32_e32 v206, v243, v242
	v_add_f32_e32 v207, v245, v244
	v_add_f32_e32 v206, v246, v206
	v_add_f32_e32 v207, v248, v207
	v_add_f32_e32 v206, v247, v206
	v_add_f32_e32 v207, v249, v207
	v_add_f32_e32 v204, v205, v204
	v_add_f32_e32 v204, v204, v206
	v_add_f32_e32 v204, v204, v207
	ds_swizzle_b32 v205, v204 offset:swizzle(SWAP,1)
	s_waitcnt lgkmcnt(0)
	v_add_f32_e32 v204, v204, v205
	ds_swizzle_b32 v205, v204 offset:swizzle(SWAP,2)
	s_waitcnt lgkmcnt(0)
	v_add_f32_e32 v204, v204, v205
	ds_swizzle_b32 v205, v204 offset:swizzle(SWAP,4)
	s_waitcnt lgkmcnt(0)
	v_add_f32_e32 v204, v204, v205
	ds_swizzle_b32 v205, v204 offset:swizzle(SWAP,8)
	s_waitcnt lgkmcnt(0)
	v_add_f32_e32 v204, v204, v205
	ds_swizzle_b32 v205, v204 offset:swizzle(SWAP,16)
	s_waitcnt lgkmcnt(0)
	v_add_f32_e32 v204, v204, v205
	v_mov_b32_e32 v205, v204
	s_nop 1
	v_permlane32_swap_b32_e32 v204, v205
	v_add_f32_e32 v204, v204, v205
	v_mov_b32_e32 v205, 0x358637bd
	v_fmamk_f32 v204, v204, 0x3a800000, v205
	v_rsq_f32_e32 v204, v204
	s_nop 0
	v_pk_mul_f32 v[128:129], v[128:129], v[204:205] op_sel_hi:[1,0]
	v_pk_mul_f32 v[130:131], v[130:131], v[204:205] op_sel_hi:[1,0]
	v_pk_mul_f32 v[128:129], v[188:189], v[128:129]
	v_pk_mul_f32 v[130:131], v[190:191], v[130:131]
	v_pk_fma_f32 v[128:129], v[34:35], v[128:129], v[224:225]
	v_pk_fma_f32 v[130:131], v[36:37], v[130:131], v[226:227]
	v_cvt_pk_bf16_f32 v128, v128, v129
	v_cvt_pk_bf16_f32 v129, v130, v131
	global_store_dwordx2 v146, v[128:129], s[66:67]
	v_pk_mul_f32 v[132:133], v[132:133], v[204:205] op_sel_hi:[1,0]
	v_pk_mul_f32 v[134:135], v[134:135], v[204:205] op_sel_hi:[1,0]
	v_pk_mul_f32 v[132:133], v[192:193], v[132:133]
	v_pk_mul_f32 v[134:135], v[194:195], v[134:135]
	v_pk_fma_f32 v[132:133], v[38:39], v[132:133], v[228:229]
	v_pk_fma_f32 v[134:135], v[40:41], v[134:135], v[230:231]
	v_cvt_pk_bf16_f32 v132, v132, v133
	v_cvt_pk_bf16_f32 v133, v134, v135
	global_store_dwordx2 v146, v[132:133], s[66:67] offset:512
	v_pk_mul_f32 v[136:137], v[136:137], v[204:205] op_sel_hi:[1,0]
	v_pk_mul_f32 v[138:139], v[138:139], v[204:205] op_sel_hi:[1,0]
	v_pk_mul_f32 v[136:137], v[196:197], v[136:137]
	v_pk_mul_f32 v[138:139], v[198:199], v[138:139]
	v_pk_fma_f32 v[136:137], v[42:43], v[136:137], v[232:233]
	v_pk_fma_f32 v[138:139], v[44:45], v[138:139], v[234:235]
	v_cvt_pk_bf16_f32 v136, v136, v137
	v_cvt_pk_bf16_f32 v137, v138, v139
	global_store_dwordx2 v146, v[136:137], s[66:67] offset:1024
	v_pk_mul_f32 v[140:141], v[140:141], v[204:205] op_sel_hi:[1,0]
	v_pk_mul_f32 v[142:143], v[142:143], v[204:205] op_sel_hi:[1,0]
	v_pk_mul_f32 v[140:141], v[200:201], v[140:141]
	v_pk_mul_f32 v[142:143], v[202:203], v[142:143]
	v_pk_fma_f32 v[140:141], v[46:47], v[140:141], v[236:237]
	v_pk_fma_f32 v[142:143], v[48:49], v[142:143], v[238:239]
	v_cvt_pk_bf16_f32 v140, v140, v141
	v_cvt_pk_bf16_f32 v141, v142, v143
	global_store_dwordx2 v146, v[140:141], s[66:67] offset:1536
	v_add_u32_e32 v146, 0x800, v146
